# scan phase: prefix-product scans via in-place v_mul_f32_dpp (no 1.0 init/pk_mul), RWKV sign/cvt folded into fma_mix modifiers; convert tile loads batched
# speedup vs baseline: 1.0820x; 1.0340x over previous
; #define TIDX ((wv_ << 6) | lane_id_l())
; __device__ __forceinline__ unsigned pk2(float lo, float hi) { f32x2n v = {lo, hi}; bf16x2n b = __builtin_convertvector(v, bf16x2n); return __builtin_bit_cast(unsigned, b); }
; __device__ __forceinline__ void conv_tile(const int wv_, const WDesc w, const int ti, float* tile  ) {
;   const int tid = TIDX;
;   const int tn = (w.N + 127) / 128;
;   const int k0 = (ti / tn) * 64, n0 = (ti % tn) * 128;
; #pragma unroll
;   for (int i = 0; i < 4; ++i) { const int idx = tid + 512 * i, k = idx >> 5, n4 = (idx & 31) * 4;
;     f32x4 v = (f32x4){0.f, 0.f, 0.f, 0.f};
;     if (n0 + n4 < w.N) v = *(const f32x4*)(w.src + (size_t)(k0 + k) * w.N + n0 + n4);
;     float* tp = tile + k * 129 + n4; tp[0] = v[0]; tp[1] = v[1]; tp[2] = v[2]; tp[3] = v[3]; }
;   __syncthreads();
;   { const int n = tid >> 2, ks = (tid & 3) * 16, ng = n0 + n;
;     if (ng < w.N) { const int row = ng < w.gap_at ? ng : ng + w.gap;
;       const float* tp = tile + ks * 129 + n;
;       u32x4 a, b;
;       a.x = pk2(tp[0 * 129], tp[1 * 129]); a.y = pk2(tp[2 * 129], tp[3 * 129]); a.z = pk2(tp[4 * 129], tp[5 * 129]); a.w = pk2(tp[6 * 129], tp[7 * 129]);
;       b.x = pk2(tp[8 * 129], tp[9 * 129]); b.y = pk2(tp[10 * 129], tp[11 * 129]); b.z = pk2(tp[12 * 129], tp[13 * 129]); b.w = pk2(tp[14 * 129], tp[15 * 129]);
;       bf16_t* dp = w.dst + (size_t)row * w.K + k0 + ks;
;       *(u32x4*)dp = a; *(u32x4*)(dp + 8) = b; } }
;   __syncthreads();
.LBB0_117:
	s_add_i32 s36, s53, 0x7f
	s_lshr_b32 s39, s36, 7
	v_cvt_f32_u32_e32 v0, s39
	s_sub_i32 s58, 0, s39
	s_abs_i32 s57, s38
	s_ashr_i32 s36, s38, 31
	v_rcp_iflag_f32_e32 v0, v0
	v_mov_b32_e32 v3, v153
	v_mov_b32_e32 v1, v2
	v_mul_f32_e32 v0, 0x4f7ffffe, v0
	v_cvt_u32_f32_e32 v0, v0
	v_or_b32_e32 v11, s72, v3
	v_ashrrev_i32_e32 v12, 5, v11
	v_mov_b32_e32 v4, 0
	v_readfirstlane_b32 s59, v0
	s_mul_i32 s58, s58, s59
	s_mul_hi_u32 s58, s59, s58
	s_add_i32 s59, s59, s58
	s_mul_hi_u32 s58, s57, s59
	s_mul_i32 s59, s58, s39
	s_sub_i32 s57, s57, s59
	s_add_i32 s70, s58, 1
	s_sub_i32 s59, s57, s39
	s_cmp_ge_u32 s57, s39
	s_cselect_b32 s58, s70, s58
	s_cselect_b32 s57, s59, s57
	s_add_i32 s59, s58, 1
	s_cmp_ge_u32 s57, s39
	s_cselect_b32 s57, s59, s58
	s_xor_b32 s57, s57, s36
	s_sub_i32 s57, s57, s36
	s_lshl_b32 s36, s57, 6
	s_mul_i32 s57, s57, s39
	s_sub_i32 s38, s38, s57
	s_lshl_b32 s38, s38, 7
	v_lshlrev_b32_e32 v0, 2, v3
	s_ashr_i32 s39, s38, 31
	v_and_b32_e32 v5, 0x7c, v0
	s_lshl_b64 s[58:59], s[38:39], 2
	v_or_b32_e32 v0, s38, v5
	s_add_u32 s34, s34, s58
	v_cmp_gt_i32_e32 vcc, s53, v0
	s_addc_u32 s35, s35, s59
	v_lshlrev_b32_e32 v0, 2, v5
	v_lshl_add_u64 v[0:1], s[34:35], 0, v[0:1]
	v_mov_b64_e32 v[88:89], 0
	v_mov_b64_e32 v[90:91], 0
	v_mov_b64_e32 v[92:93], 0
	v_mov_b64_e32 v[94:95], 0
	v_mov_b64_e32 v[96:97], 0
	v_mov_b64_e32 v[98:99], 0
	v_mov_b64_e32 v[100:101], 0
	v_mov_b64_e32 v[102:103], 0
	v_lshl_add_u32 v10, v5, 2, 0
	v_add_u32_e32 v104, 0x200, v11
	v_ashrrev_i32_e32 v104, 5, v104
	v_add_u32_e32 v105, 0x400, v11
	v_ashrrev_i32_e32 v105, 5, v105
	v_add_u32_e32 v106, 0x600, v11
	v_ashrrev_i32_e32 v106, 5, v106
	s_and_saveexec_b64 s[34:35], vcc
	s_cbranch_execz .Lcv_noload
	v_add_u32_e32 v6, s36, v12
	v_ashrrev_i32_e32 v9, 31, v6
	v_mad_u64_u32 v[6:7], s[58:59], v6, s53, 0
	v_mov_b32_e32 v8, v7
	v_mad_u64_u32 v[8:9], s[58:59], v9, s53, v[8:9]
	v_mov_b32_e32 v7, v8
	v_lshl_add_u64 v[6:7], v[6:7], 2, v[0:1]
	global_load_dwordx4 v[88:91], v[6:7], off
	v_add_u32_e32 v6, s36, v104
	v_ashrrev_i32_e32 v9, 31, v6
	v_mad_u64_u32 v[6:7], s[58:59], v6, s53, 0
	v_mov_b32_e32 v8, v7
	v_mad_u64_u32 v[8:9], s[58:59], v9, s53, v[8:9]
	v_mov_b32_e32 v7, v8
	v_lshl_add_u64 v[6:7], v[6:7], 2, v[0:1]
	global_load_dwordx4 v[92:95], v[6:7], off
	v_add_u32_e32 v6, s36, v105
	v_ashrrev_i32_e32 v9, 31, v6
	v_mad_u64_u32 v[6:7], s[58:59], v6, s53, 0
	v_mov_b32_e32 v8, v7
	v_mad_u64_u32 v[8:9], s[58:59], v9, s53, v[8:9]
	v_mov_b32_e32 v7, v8
	v_lshl_add_u64 v[6:7], v[6:7], 2, v[0:1]
	global_load_dwordx4 v[96:99], v[6:7], off
	v_add_u32_e32 v6, s36, v106
	v_ashrrev_i32_e32 v9, 31, v6
	v_mad_u64_u32 v[6:7], s[58:59], v6, s53, 0
	v_mov_b32_e32 v8, v7
	v_mad_u64_u32 v[8:9], s[58:59], v9, s53, v[8:9]
	v_mov_b32_e32 v7, v8
	v_lshl_add_u64 v[6:7], v[6:7], 2, v[0:1]
	global_load_dwordx4 v[100:103], v[6:7], off
.Lcv_noload:
	s_or_b64 exec, exec, s[34:35]
	v_mad_u64_u32 v[108:109], s[34:35], v104, s76, v[10:11]
	v_mad_u64_u32 v[110:111], s[34:35], v105, s76, v[10:11]
	v_mad_u64_u32 v[112:113], s[34:35], v106, s76, v[10:11]
	v_mad_u64_u32 v[12:13], s[34:35], v12, s76, v[10:11]
	v_ashrrev_i32_e32 v1, 2, v11
	s_waitcnt vmcnt(3)
	ds_write2_b32 v12, v88, v89 offset1:1
	ds_write2_b32 v12, v90, v91 offset0:2 offset1:3
	s_waitcnt vmcnt(2)
	ds_write2_b32 v108, v92, v93 offset1:1
	ds_write2_b32 v108, v94, v95 offset0:2 offset1:3
	s_waitcnt vmcnt(1)
	ds_write2_b32 v110, v96, v97 offset1:1
	ds_write2_b32 v110, v98, v99 offset0:2 offset1:3
	s_waitcnt vmcnt(0)
	ds_write2_b32 v112, v100, v101 offset1:1
	ds_write2_b32 v112, v102, v103 offset0:2 offset1:3
	v_add_u32_e32 v0, s38, v1
	v_cmp_gt_i32_e32 vcc, s53, v0
	s_waitcnt lgkmcnt(0)
	s_barrier
	s_and_saveexec_b64 s[34:35], vcc
	s_cbranch_execz .LBB0_87
	v_lshlrev_b32_e32 v3, 4, v3
	v_and_b32_e32 v3, 48, v3
	v_mul_u32_u24_e32 v4, 0x204, v3
	v_lshlrev_b32_e32 v1, 2, v1
	v_add3_u32 v14, 0, v4, v1
	v_add_u32_e32 v1, 0x400, v14
	ds_read2_b32 v[4:5], v14 offset1:129
	ds_read2_b32 v[6:7], v1 offset0:2 offset1:131
	v_add_u32_e32 v1, 0x800, v14
	ds_read2_b32 v[8:9], v1 offset0:4 offset1:133
	v_mov_b32_e32 v10, s56
	v_cmp_le_i32_e32 vcc, s37, v0
	s_waitcnt lgkmcnt(2)
	v_cvt_pk_bf16_f32 v4, v4, v5
	s_waitcnt lgkmcnt(1)
	v_cvt_pk_bf16_f32 v5, v6, v7
	v_cndmask_b32_e32 v1, 0, v10, vcc
	v_add_u32_e32 v7, 0x1000, v14
	v_add_u32_e32 v16, v1, v0
	s_waitcnt lgkmcnt(0)
	v_cvt_pk_bf16_f32 v6, v8, v9
	v_add_u32_e32 v0, 0xc00, v14
	ds_read2_b32 v[8:9], v7 offset0:8 offset1:137
	v_add_u32_e32 v7, 0x1400, v14
	ds_read2_b32 v[0:1], v0 offset0:6 offset1:135
	ds_read2_b32 v[10:11], v7 offset0:10 offset1:139
	v_add_u32_e32 v7, 0x1800, v14
	ds_read2_b32 v[12:13], v7 offset0:12 offset1:141
	v_add_u32_e32 v7, 0x1c00, v14
	ds_read2_b32 v[14:15], v7 offset0:14 offset1:143
	s_waitcnt lgkmcnt(3)
	v_cvt_pk_bf16_f32 v7, v0, v1
	v_ashrrev_i32_e32 v0, 31, v16
	v_cvt_pk_bf16_f32 v8, v8, v9
	s_waitcnt lgkmcnt(2)
	v_cvt_pk_bf16_f32 v9, v10, v11
	s_waitcnt lgkmcnt(1)
	v_cvt_pk_bf16_f32 v10, v12, v13
	v_mul_lo_u32 v12, s28, v0
	v_mul_lo_u32 v13, s29, v16
	v_mad_u64_u32 v[0:1], s[28:29], s28, v16, 0
	v_add3_u32 v1, v1, v12, v13
	v_lshl_add_u64 v[0:1], v[0:1], 1, s[30:31]
	s_ashr_i32 s37, s36, 31
	v_lshl_add_u64 v[0:1], s[36:37], 1, v[0:1]
	v_lshlrev_b32_e32 v12, 1, v3
	v_mov_b32_e32 v13, v2
	v_lshl_add_u64 v[0:1], v[0:1], 0, v[12:13]
	s_waitcnt lgkmcnt(0)
	v_cvt_pk_bf16_f32 v11, v14, v15
	global_store_dwordx4 v[0:1], v[4:7], off
	global_store_dwordx4 v[0:1], v[8:11], off offset:16
	s_branch .LBB0_87

; __device__ __forceinline__ unsigned pk2(float lo, float hi) { f32x2n v = {lo, hi}; bf16x2n b = __builtin_convertvector(v, bf16x2n); return __builtin_bit_cast(unsigned, b); }
;   template <int CTRL> static __device__ __forceinline__ float shr1(float x) { return __int_as_float(__builtin_amdgcn_update_dpp(__float_as_int(1.0f), __float_as_int(x), CTRL, 0xF, 0xF, false)); }
;   static __device__ __forceinline__ float scan16(float x) { x *= shr1<0x111>(x); x *= shr1<0x112>(x); x *= shr1<0x114>(x); x *= shr1<0x118>(x); return x; }
;   __device__ __forceinline__ void gl_prep(const h16x8 (&q)[4], const h16x8 (&k)[4], const h16x8 (&u)[4], const h16x8 (&v)[2], int tb) const {
;     ...
;     for (int it = 0; it < 4; ++it) { const int bidx = it * 4 + rho, sc = bidx >> 3, k0 = (bidx & 7) * 8, st = sc * 16 + tau;
;       float G[8], qt[8], kt[8];
; #pragma unroll
;       for (int e = 0; e < 8; ++e) { G[e] = scan16(1.f - (float)u[it][e]); qt[e] = (float)q[it][e] * G[e]; kt[e] = (float)k[it][e] * __builtin_amdgcn_rcpf(fmaxf(G[e], 1e-30f)); }
;       u32x2 a, b, c2, d; a.x = pk2(qt[0], qt[1]); a.y = pk2(qt[2], qt[3]); b.x = pk2(qt[4], qt[5]); b.y = pk2(qt[6], qt[7]);
;       c2.x = pk2(kt[0], kt[1]); c2.y = pk2(kt[2], kt[3]); d.x = pk2(kt[4], kt[5]); d.y = pk2(kt[6], kt[7]);
;       unsigned char* oq = tl + TL_GQ + st * GQS + k0 * 2; unsigned char* ok = tl + TL_GK + st * GQS + k0 * 2;
;       *(u32x2*)oq = a; *(u32x2*)(oq + 8) = b; *(u32x2*)ok = c2; *(u32x2*)(ok + 8) = d;
;       if (tau == 15) { float* ge = (float*)(tl + TL_GGE) + sc * 64 + k0; *(f32x4*)ge = (f32x4){G[0], G[1], G[2], G[3]}; *(f32x4*)(ge + 4) = (f32x4){G[4], G[5], G[6], G[7]}; } }
.LBB0_609:
	s_waitcnt vmcnt(11)
	v_cvt_f32_f16_sdwa v85, v24 dst_sel:DWORD dst_unused:UNUSED_PAD src0_sel:WORD_1
	v_cvt_f32_f16_e32 v84, v24
	v_cvt_f32_f16_sdwa v89, v16 dst_sel:DWORD dst_unused:UNUSED_PAD src0_sel:WORD_1
	v_pk_add_f32 v[84:85], v[84:85], 1.0 op_sel_hi:[1,0] neg_lo:[1,0] neg_hi:[1,0]
	v_cvt_f32_f16_e32 v88, v16
	v_cvt_f32_f16_sdwa v91, v17 dst_sel:DWORD dst_unused:UNUSED_PAD src0_sel:WORD_1
	v_mul_f32_dpp v84, v84, v84 row_shr:1 row_mask:0xf bank_mask:0xf
	v_mul_f32_dpp v85, v85, v85 row_shr:1 row_mask:0xf bank_mask:0xf
	v_cvt_f32_f16_e32 v90, v17
	v_mul_f32_dpp v84, v84, v84 row_shr:2 row_mask:0xf bank_mask:0xf
	v_mul_f32_dpp v85, v85, v85 row_shr:2 row_mask:0xf bank_mask:0xf
	v_cvt_f32_f16_sdwa v147, v22 dst_sel:DWORD dst_unused:UNUSED_PAD src0_sel:WORD_1
	v_mul_f32_dpp v84, v84, v84 row_shr:4 row_mask:0xf bank_mask:0xf
	v_mul_f32_dpp v85, v85, v85 row_shr:4 row_mask:0xf bank_mask:0xf
	v_cvt_f32_f16_e32 v146, v22
	v_mul_f32_dpp v84, v84, v84 row_shr:8 row_mask:0xf bank_mask:0xf
	v_mul_f32_dpp v85, v85, v85 row_shr:8 row_mask:0xf bank_mask:0xf
	v_max_f32_e32 v86, 0xda24260, v84
	v_max_f32_e32 v87, 0xda24260, v85
	v_rcp_f32_e32 v86, v86
	v_pk_mul_f32 v[118:119], v[84:85], v[88:89]
	v_rcp_f32_e32 v87, v87
	v_cvt_f32_f16_sdwa v89, v20 dst_sel:DWORD dst_unused:UNUSED_PAD src0_sel:WORD_1
	v_cvt_f32_f16_e32 v88, v20
	s_bitcmp1_b32 s23, 0
	s_cselect_b32 s10, 0x7200, 0
	v_pk_mul_f32 v[120:121], v[86:87], v[88:89]
	v_cvt_f32_f16_sdwa v87, v25 dst_sel:DWORD dst_unused:UNUSED_PAD src0_sel:WORD_1
	v_cvt_f32_f16_e32 v86, v25
	v_cvt_f32_f16_sdwa v145, v18 dst_sel:DWORD dst_unused:UNUSED_PAD src0_sel:WORD_1
	v_pk_add_f32 v[86:87], v[86:87], 1.0 op_sel_hi:[1,0] neg_lo:[1,0] neg_hi:[1,0]
	v_cvt_f32_f16_e32 v144, v18
	v_cvt_f32_f16_sdwa v151, v19 dst_sel:DWORD dst_unused:UNUSED_PAD src0_sel:WORD_1
	v_mul_f32_dpp v86, v86, v86 row_shr:1 row_mask:0xf bank_mask:0xf
	v_mul_f32_dpp v87, v87, v87 row_shr:1 row_mask:0xf bank_mask:0xf
	v_cvt_f32_f16_e32 v150, v19
	v_mul_f32_dpp v86, v86, v86 row_shr:2 row_mask:0xf bank_mask:0xf
	v_mul_f32_dpp v87, v87, v87 row_shr:2 row_mask:0xf bank_mask:0xf
	s_add_i32 s27, s10, 0
	v_mul_f32_dpp v86, v86, v86 row_shr:4 row_mask:0xf bank_mask:0xf
	v_mul_f32_dpp v87, v87, v87 row_shr:4 row_mask:0xf bank_mask:0xf
	v_cvt_f32_f16_sdwa v157, v23 dst_sel:DWORD dst_unused:UNUSED_PAD src0_sel:WORD_1
	v_mul_f32_dpp v86, v86, v86 row_shr:8 row_mask:0xf bank_mask:0xf
	v_mul_f32_dpp v87, v87, v87 row_shr:8 row_mask:0xf bank_mask:0xf
	v_cvt_f32_f16_e32 v156, v23
	v_max_f32_e32 v88, 0xda24260, v86
	v_max_f32_e32 v89, 0xda24260, v87
	v_rcp_f32_e32 v88, v88
	v_pk_mul_f32 v[140:141], v[86:87], v[90:91]
	v_rcp_f32_e32 v89, v89
	v_cvt_f32_f16_sdwa v91, v21 dst_sel:DWORD dst_unused:UNUSED_PAD src0_sel:WORD_1
	v_cvt_f32_f16_e32 v90, v21
	s_add_i32 s10, s27, 0xc000
	v_cvt_pk_bf16_f32 v118, v118, v119
	v_cvt_pk_bf16_f32 v119, v140, v141
	v_pk_mul_f32 v[142:143], v[88:89], v[90:91]
	v_cvt_f32_f16_sdwa v89, v26 dst_sel:DWORD dst_unused:UNUSED_PAD src0_sel:WORD_1
	v_cvt_f32_f16_e32 v88, v26
	v_add_u32_e32 v141, s10, v123
	v_pk_add_f32 v[88:89], v[88:89], 1.0 op_sel_hi:[1,0] neg_lo:[1,0] neg_hi:[1,0]
	v_add_u32_e32 v140, v141, v103
	v_cvt_pk_bf16_f32 v120, v120, v121
	v_mul_f32_dpp v88, v88, v88 row_shr:1 row_mask:0xf bank_mask:0xf
	v_mul_f32_dpp v89, v89, v89 row_shr:1 row_mask:0xf bank_mask:0xf
	v_cvt_pk_bf16_f32 v121, v142, v143
	v_mul_f32_dpp v88, v88, v88 row_shr:2 row_mask:0xf bank_mask:0xf
	v_mul_f32_dpp v89, v89, v89 row_shr:2 row_mask:0xf bank_mask:0xf
	s_nop 0
	v_mul_f32_dpp v88, v88, v88 row_shr:4 row_mask:0xf bank_mask:0xf
	v_mul_f32_dpp v89, v89, v89 row_shr:4 row_mask:0xf bank_mask:0xf
	s_nop 0
	v_mul_f32_dpp v88, v88, v88 row_shr:8 row_mask:0xf bank_mask:0xf
	v_mul_f32_dpp v89, v89, v89 row_shr:8 row_mask:0xf bank_mask:0xf
	s_nop 0
	v_max_f32_e32 v90, 0xda24260, v88
	v_max_f32_e32 v91, 0xda24260, v89
	v_rcp_f32_e32 v90, v90
	v_rcp_f32_e32 v91, v91
	v_pk_mul_f32 v[144:145], v[88:89], v[144:145]
	v_pk_mul_f32 v[146:147], v[90:91], v[146:147]
	v_cvt_f32_f16_sdwa v91, v27 dst_sel:DWORD dst_unused:UNUSED_PAD src0_sel:WORD_1
	v_cvt_f32_f16_e32 v90, v27
	v_cvt_pk_bf16_f32 v144, v144, v145
	v_cvt_pk_bf16_f32 v142, v146, v147
	v_add_u32_e32 v146, 0x5300, v140
	v_pk_add_f32 v[90:91], v[90:91], 1.0 op_sel_hi:[1,0] neg_lo:[1,0] neg_hi:[1,0]
	s_nop 1
	v_mul_f32_dpp v90, v90, v90 row_shr:1 row_mask:0xf bank_mask:0xf
	v_mul_f32_dpp v91, v91, v91 row_shr:1 row_mask:0xf bank_mask:0xf
	s_nop 0
	v_mul_f32_dpp v90, v90, v90 row_shr:2 row_mask:0xf bank_mask:0xf
	v_mul_f32_dpp v91, v91, v91 row_shr:2 row_mask:0xf bank_mask:0xf
	s_nop 0
	v_mul_f32_dpp v90, v90, v90 row_shr:4 row_mask:0xf bank_mask:0xf
	v_mul_f32_dpp v91, v91, v91 row_shr:4 row_mask:0xf bank_mask:0xf
	s_nop 0
	v_mul_f32_dpp v90, v90, v90 row_shr:8 row_mask:0xf bank_mask:0xf
	v_mul_f32_dpp v91, v91, v91 row_shr:8 row_mask:0xf bank_mask:0xf
	s_nop 0
	v_max_f32_e32 v139, 0xda24260, v90
	v_rcp_f32_e32 v148, v139
	v_max_f32_e32 v139, 0xda24260, v91
	v_rcp_f32_e32 v149, v139
	v_pk_mul_f32 v[150:151], v[90:91], v[150:151]
	v_add_u32_e32 v139, 0x4200, v140
	v_cvt_pk_bf16_f32 v145, v150, v151
	v_pk_mul_f32 v[148:149], v[148:149], v[156:157]
	s_nop 0
	v_cvt_pk_bf16_f32 v143, v148, v149
	ds_write2_b64 v139, v[118:119], v[144:145] offset1:1
	ds_write2_b64 v146, v[120:121], v[142:143] offset1:1
	v_lshl_add_u32 v139, v101, 2, s10
	s_and_saveexec_b64 s[10:11], s[8:9]
	s_cbranch_execz .LBB0_611
	ds_write_b128 v139, v[84:87] offset:28672
	ds_write_b128 v139, v[88:91] offset:28688
; __device__ __forceinline__ unsigned pk2(float lo, float hi) { f32x2n v = {lo, hi}; bf16x2n b = __builtin_convertvector(v, bf16x2n); return __builtin_bit_cast(unsigned, b); }
;   template <int CTRL> static __device__ __forceinline__ float shr1(float x) { return __int_as_float(__builtin_amdgcn_update_dpp(__float_as_int(1.0f), __float_as_int(x), CTRL, 0xF, 0xF, false)); }
;   static __device__ __forceinline__ float scan16(float x) { x *= shr1<0x111>(x); x *= shr1<0x112>(x); x *= shr1<0x114>(x); x *= shr1<0x118>(x); return x; }
;   __device__ __forceinline__ void gl_prep(const h16x8 (&q)[4], const h16x8 (&k)[4], const h16x8 (&u)[4], const h16x8 (&v)[2], int tb) const {
;     ...
;     for (int it = 0; it < 4; ++it) { const int bidx = it * 4 + rho, sc = bidx >> 3, k0 = (bidx & 7) * 8, st = sc * 16 + tau;
;       float G[8], qt[8], kt[8];
; #pragma unroll
;       for (int e = 0; e < 8; ++e) { G[e] = scan16(1.f - (float)u[it][e]); qt[e] = (float)q[it][e] * G[e]; kt[e] = (float)k[it][e] * __builtin_amdgcn_rcpf(fmaxf(G[e], 1e-30f)); }
;       u32x2 a, b, c2, d; a.x = pk2(qt[0], qt[1]); a.y = pk2(qt[2], qt[3]); b.x = pk2(qt[4], qt[5]); b.y = pk2(qt[6], qt[7]);
;       c2.x = pk2(kt[0], kt[1]); c2.y = pk2(kt[2], kt[3]); d.x = pk2(kt[4], kt[5]); d.y = pk2(kt[6], kt[7]);
;       unsigned char* oq = tl + TL_GQ + st * GQS + k0 * 2; unsigned char* ok = tl + TL_GK + st * GQS + k0 * 2;
;       *(u32x2*)oq = a; *(u32x2*)(oq + 8) = b; *(u32x2*)ok = c2; *(u32x2*)(ok + 8) = d;
;       if (tau == 15) { float* ge = (float*)(tl + TL_GGE) + sc * 64 + k0; *(f32x4*)ge = (f32x4){G[0], G[1], G[2], G[3]}; *(f32x4*)(ge + 4) = (f32x4){G[4], G[5], G[6], G[7]}; } }
.LBB0_611:
	s_or_b64 exec, exec, s[10:11]
	s_waitcnt vmcnt(8)
	v_cvt_f32_f16_sdwa v85, v36 dst_sel:DWORD dst_unused:UNUSED_PAD src0_sel:WORD_1
	v_cvt_f32_f16_e32 v84, v36
	v_cvt_f32_f16_sdwa v89, v28 dst_sel:DWORD dst_unused:UNUSED_PAD src0_sel:WORD_1
	v_pk_add_f32 v[84:85], v[84:85], 1.0 op_sel_hi:[1,0] neg_lo:[1,0] neg_hi:[1,0]
	v_cvt_f32_f16_e32 v88, v28
	v_cvt_f32_f16_sdwa v91, v29 dst_sel:DWORD dst_unused:UNUSED_PAD src0_sel:WORD_1
	v_mul_f32_dpp v84, v84, v84 row_shr:1 row_mask:0xf bank_mask:0xf
	v_mul_f32_dpp v85, v85, v85 row_shr:1 row_mask:0xf bank_mask:0xf
	v_cvt_f32_f16_e32 v90, v29
	v_mul_f32_dpp v84, v84, v84 row_shr:2 row_mask:0xf bank_mask:0xf
	v_mul_f32_dpp v85, v85, v85 row_shr:2 row_mask:0xf bank_mask:0xf
	v_cvt_f32_f16_sdwa v149, v34 dst_sel:DWORD dst_unused:UNUSED_PAD src0_sel:WORD_1
	v_mul_f32_dpp v84, v84, v84 row_shr:4 row_mask:0xf bank_mask:0xf
	v_mul_f32_dpp v85, v85, v85 row_shr:4 row_mask:0xf bank_mask:0xf
	v_cvt_f32_f16_e32 v148, v34
	v_mul_f32_dpp v84, v84, v84 row_shr:8 row_mask:0xf bank_mask:0xf
	v_mul_f32_dpp v85, v85, v85 row_shr:8 row_mask:0xf bank_mask:0xf
	v_max_f32_e32 v86, 0xda24260, v84
	v_max_f32_e32 v87, 0xda24260, v85
	v_rcp_f32_e32 v86, v86
	v_pk_mul_f32 v[118:119], v[84:85], v[88:89]
	v_rcp_f32_e32 v87, v87
	v_cvt_f32_f16_sdwa v89, v32 dst_sel:DWORD dst_unused:UNUSED_PAD src0_sel:WORD_1
	v_cvt_f32_f16_e32 v88, v32
	v_cvt_f32_f16_sdwa v147, v30 dst_sel:DWORD dst_unused:UNUSED_PAD src0_sel:WORD_1
	v_cvt_f32_f16_e32 v146, v30
	v_pk_mul_f32 v[120:121], v[86:87], v[88:89]
	v_cvt_f32_f16_sdwa v87, v37 dst_sel:DWORD dst_unused:UNUSED_PAD src0_sel:WORD_1
	v_cvt_f32_f16_e32 v86, v37
	v_cvt_f32_f16_sdwa v157, v31 dst_sel:DWORD dst_unused:UNUSED_PAD src0_sel:WORD_1
	v_pk_add_f32 v[86:87], v[86:87], 1.0 op_sel_hi:[1,0] neg_lo:[1,0] neg_hi:[1,0]
	v_cvt_f32_f16_e32 v156, v31
	v_cvt_f32_f16_sdwa v159, v35 dst_sel:DWORD dst_unused:UNUSED_PAD src0_sel:WORD_1
	v_mul_f32_dpp v86, v86, v86 row_shr:1 row_mask:0xf bank_mask:0xf
	v_mul_f32_dpp v87, v87, v87 row_shr:1 row_mask:0xf bank_mask:0xf
	v_cvt_f32_f16_e32 v158, v35
	v_mul_f32_dpp v86, v86, v86 row_shr:2 row_mask:0xf bank_mask:0xf
	v_mul_f32_dpp v87, v87, v87 row_shr:2 row_mask:0xf bank_mask:0xf
	v_add_u32_e32 v141, v141, v122
	v_mul_f32_dpp v86, v86, v86 row_shr:4 row_mask:0xf bank_mask:0xf
	v_mul_f32_dpp v87, v87, v87 row_shr:4 row_mask:0xf bank_mask:0xf
	v_cvt_pk_bf16_f32 v118, v118, v119
	v_mul_f32_dpp v86, v86, v86 row_shr:8 row_mask:0xf bank_mask:0xf
	v_mul_f32_dpp v87, v87, v87 row_shr:8 row_mask:0xf bank_mask:0xf
	v_cvt_pk_bf16_f32 v120, v120, v121
	v_max_f32_e32 v88, 0xda24260, v86
	v_max_f32_e32 v89, 0xda24260, v87
	v_rcp_f32_e32 v88, v88
	v_pk_mul_f32 v[142:143], v[86:87], v[90:91]
	v_rcp_f32_e32 v89, v89
	v_cvt_f32_f16_sdwa v91, v33 dst_sel:DWORD dst_unused:UNUSED_PAD src0_sel:WORD_1
	v_cvt_f32_f16_e32 v90, v33
	v_cvt_pk_bf16_f32 v119, v142, v143
	v_pk_mul_f32 v[144:145], v[88:89], v[90:91]
	v_cvt_f32_f16_sdwa v89, v38 dst_sel:DWORD dst_unused:UNUSED_PAD src0_sel:WORD_1
	v_cvt_f32_f16_e32 v88, v38
	v_cvt_pk_bf16_f32 v121, v144, v145
	v_pk_add_f32 v[88:89], v[88:89], 1.0 op_sel_hi:[1,0] neg_lo:[1,0] neg_hi:[1,0]
	s_nop 1
	v_mul_f32_dpp v88, v88, v88 row_shr:1 row_mask:0xf bank_mask:0xf
	v_mul_f32_dpp v89, v89, v89 row_shr:1 row_mask:0xf bank_mask:0xf
	s_nop 0
	v_mul_f32_dpp v88, v88, v88 row_shr:2 row_mask:0xf bank_mask:0xf
	v_mul_f32_dpp v89, v89, v89 row_shr:2 row_mask:0xf bank_mask:0xf
	s_nop 0
	v_mul_f32_dpp v88, v88, v88 row_shr:4 row_mask:0xf bank_mask:0xf
	v_mul_f32_dpp v89, v89, v89 row_shr:4 row_mask:0xf bank_mask:0xf
	s_nop 0
	v_mul_f32_dpp v88, v88, v88 row_shr:8 row_mask:0xf bank_mask:0xf
	v_mul_f32_dpp v89, v89, v89 row_shr:8 row_mask:0xf bank_mask:0xf
	s_nop 0
	v_max_f32_e32 v90, 0xda24260, v88
	v_max_f32_e32 v91, 0xda24260, v89
	v_rcp_f32_e32 v90, v90
	v_rcp_f32_e32 v91, v91
	v_pk_mul_f32 v[146:147], v[88:89], v[146:147]
	v_pk_mul_f32 v[148:149], v[90:91], v[148:149]
	v_cvt_f32_f16_sdwa v91, v39 dst_sel:DWORD dst_unused:UNUSED_PAD src0_sel:WORD_1
	v_cvt_f32_f16_e32 v90, v39
	v_cvt_pk_bf16_f32 v142, v146, v147
	v_add_u32_e32 v146, 0x4200, v141
	v_cvt_pk_bf16_f32 v144, v148, v149
	v_pk_add_f32 v[90:91], v[90:91], 1.0 op_sel_hi:[1,0] neg_lo:[1,0] neg_hi:[1,0]
	v_add_u32_e32 v147, 0x5300, v141
	s_nop 0
	v_mul_f32_dpp v90, v90, v90 row_shr:1 row_mask:0xf bank_mask:0xf
	v_mul_f32_dpp v91, v91, v91 row_shr:1 row_mask:0xf bank_mask:0xf
	s_nop 0
	v_mul_f32_dpp v90, v90, v90 row_shr:2 row_mask:0xf bank_mask:0xf
	v_mul_f32_dpp v91, v91, v91 row_shr:2 row_mask:0xf bank_mask:0xf
	s_nop 0
	v_mul_f32_dpp v90, v90, v90 row_shr:4 row_mask:0xf bank_mask:0xf
	v_mul_f32_dpp v91, v91, v91 row_shr:4 row_mask:0xf bank_mask:0xf
	s_nop 0
	v_mul_f32_dpp v90, v90, v90 row_shr:8 row_mask:0xf bank_mask:0xf
	v_mul_f32_dpp v91, v91, v91 row_shr:8 row_mask:0xf bank_mask:0xf
	s_nop 0
	v_max_f32_e32 v150, 0xda24260, v90
	v_max_f32_e32 v151, 0xda24260, v91
	v_rcp_f32_e32 v150, v150
	v_rcp_f32_e32 v151, v151
	v_pk_mul_f32 v[156:157], v[90:91], v[156:157]
	v_pk_mul_f32 v[150:151], v[150:151], v[158:159]
	v_cvt_pk_bf16_f32 v143, v156, v157
	v_cvt_pk_bf16_f32 v145, v150, v151
	ds_write2_b64 v146, v[118:119], v[142:143] offset1:1
	ds_write2_b64 v147, v[120:121], v[144:145] offset1:1
	s_and_saveexec_b64 s[10:11], s[8:9]
	s_cbranch_execz .LBB0_613
	ds_write_b128 v139, v[84:87] offset:28800
	ds_write_b128 v139, v[88:91] offset:28816
; __device__ __forceinline__ unsigned pk2(float lo, float hi) { f32x2n v = {lo, hi}; bf16x2n b = __builtin_convertvector(v, bf16x2n); return __builtin_bit_cast(unsigned, b); }
;   template <int CTRL> static __device__ __forceinline__ float shr1(float x) { return __int_as_float(__builtin_amdgcn_update_dpp(__float_as_int(1.0f), __float_as_int(x), CTRL, 0xF, 0xF, false)); }
;   static __device__ __forceinline__ float scan16(float x) { x *= shr1<0x111>(x); x *= shr1<0x112>(x); x *= shr1<0x114>(x); x *= shr1<0x118>(x); return x; }
;   __device__ __forceinline__ void gl_prep(const h16x8 (&q)[4], const h16x8 (&k)[4], const h16x8 (&u)[4], const h16x8 (&v)[2], int tb) const {
;     ...
;     for (int it = 0; it < 4; ++it) { const int bidx = it * 4 + rho, sc = bidx >> 3, k0 = (bidx & 7) * 8, st = sc * 16 + tau;
;       float G[8], qt[8], kt[8];
; #pragma unroll
;       for (int e = 0; e < 8; ++e) { G[e] = scan16(1.f - (float)u[it][e]); qt[e] = (float)q[it][e] * G[e]; kt[e] = (float)k[it][e] * __builtin_amdgcn_rcpf(fmaxf(G[e], 1e-30f)); }
;       u32x2 a, b, c2, d; a.x = pk2(qt[0], qt[1]); a.y = pk2(qt[2], qt[3]); b.x = pk2(qt[4], qt[5]); b.y = pk2(qt[6], qt[7]);
;       c2.x = pk2(kt[0], kt[1]); c2.y = pk2(kt[2], kt[3]); d.x = pk2(kt[4], kt[5]); d.y = pk2(kt[6], kt[7]);
;       unsigned char* oq = tl + TL_GQ + st * GQS + k0 * 2; unsigned char* ok = tl + TL_GK + st * GQS + k0 * 2;
;       *(u32x2*)oq = a; *(u32x2*)(oq + 8) = b; *(u32x2*)ok = c2; *(u32x2*)(ok + 8) = d;
;       if (tau == 15) { float* ge = (float*)(tl + TL_GGE) + sc * 64 + k0; *(f32x4*)ge = (f32x4){G[0], G[1], G[2], G[3]}; *(f32x4*)(ge + 4) = (f32x4){G[4], G[5], G[6], G[7]}; } }
.LBB0_613:
	s_or_b64 exec, exec, s[10:11]
	s_waitcnt vmcnt(5)
	v_cvt_f32_f16_sdwa v85, v48 dst_sel:DWORD dst_unused:UNUSED_PAD src0_sel:WORD_1
	v_cvt_f32_f16_e32 v84, v48
	v_cvt_f32_f16_sdwa v89, v40 dst_sel:DWORD dst_unused:UNUSED_PAD src0_sel:WORD_1
	v_pk_add_f32 v[84:85], v[84:85], 1.0 op_sel_hi:[1,0] neg_lo:[1,0] neg_hi:[1,0]
	v_cvt_f32_f16_e32 v88, v40
	v_cvt_f32_f16_sdwa v91, v41 dst_sel:DWORD dst_unused:UNUSED_PAD src0_sel:WORD_1
	v_mul_f32_dpp v84, v84, v84 row_shr:1 row_mask:0xf bank_mask:0xf
	v_mul_f32_dpp v85, v85, v85 row_shr:1 row_mask:0xf bank_mask:0xf
	v_cvt_f32_f16_e32 v90, v41
	v_mul_f32_dpp v84, v84, v84 row_shr:2 row_mask:0xf bank_mask:0xf
	v_mul_f32_dpp v85, v85, v85 row_shr:2 row_mask:0xf bank_mask:0xf
	v_cvt_f32_f16_sdwa v149, v46 dst_sel:DWORD dst_unused:UNUSED_PAD src0_sel:WORD_1
	v_mul_f32_dpp v84, v84, v84 row_shr:4 row_mask:0xf bank_mask:0xf
	v_mul_f32_dpp v85, v85, v85 row_shr:4 row_mask:0xf bank_mask:0xf
	v_cvt_f32_f16_e32 v148, v46
	v_mul_f32_dpp v84, v84, v84 row_shr:8 row_mask:0xf bank_mask:0xf
	v_mul_f32_dpp v85, v85, v85 row_shr:8 row_mask:0xf bank_mask:0xf
	v_max_f32_e32 v86, 0xda24260, v84
	v_max_f32_e32 v87, 0xda24260, v85
	v_rcp_f32_e32 v86, v86
	v_pk_mul_f32 v[118:119], v[84:85], v[88:89]
	v_rcp_f32_e32 v87, v87
	v_cvt_f32_f16_sdwa v89, v44 dst_sel:DWORD dst_unused:UNUSED_PAD src0_sel:WORD_1
	v_cvt_f32_f16_e32 v88, v44
	v_cvt_f32_f16_sdwa v147, v42 dst_sel:DWORD dst_unused:UNUSED_PAD src0_sel:WORD_1
	v_cvt_f32_f16_e32 v146, v42
	v_pk_mul_f32 v[120:121], v[86:87], v[88:89]
	v_cvt_f32_f16_sdwa v87, v49 dst_sel:DWORD dst_unused:UNUSED_PAD src0_sel:WORD_1
	v_cvt_f32_f16_e32 v86, v49
	v_cvt_f32_f16_sdwa v157, v43 dst_sel:DWORD dst_unused:UNUSED_PAD src0_sel:WORD_1
	v_pk_add_f32 v[86:87], v[86:87], 1.0 op_sel_hi:[1,0] neg_lo:[1,0] neg_hi:[1,0]
	v_cvt_f32_f16_e32 v156, v43
	v_cvt_f32_f16_sdwa v159, v47 dst_sel:DWORD dst_unused:UNUSED_PAD src0_sel:WORD_1
	v_mul_f32_dpp v86, v86, v86 row_shr:1 row_mask:0xf bank_mask:0xf
	v_mul_f32_dpp v87, v87, v87 row_shr:1 row_mask:0xf bank_mask:0xf
	v_cvt_f32_f16_e32 v158, v47
	v_mul_f32_dpp v86, v86, v86 row_shr:2 row_mask:0xf bank_mask:0xf
	v_mul_f32_dpp v87, v87, v87 row_shr:2 row_mask:0xf bank_mask:0xf
	v_cvt_pk_bf16_f32 v118, v118, v119
	v_mul_f32_dpp v86, v86, v86 row_shr:4 row_mask:0xf bank_mask:0xf
	v_mul_f32_dpp v87, v87, v87 row_shr:4 row_mask:0xf bank_mask:0xf
	v_cvt_pk_bf16_f32 v120, v120, v121
	v_mul_f32_dpp v86, v86, v86 row_shr:8 row_mask:0xf bank_mask:0xf
	v_mul_f32_dpp v87, v87, v87 row_shr:8 row_mask:0xf bank_mask:0xf
	s_nop 0
	v_max_f32_e32 v88, 0xda24260, v86
	v_max_f32_e32 v89, 0xda24260, v87
	v_rcp_f32_e32 v88, v88
	v_pk_mul_f32 v[142:143], v[86:87], v[90:91]
	v_rcp_f32_e32 v89, v89
	v_cvt_f32_f16_sdwa v91, v45 dst_sel:DWORD dst_unused:UNUSED_PAD src0_sel:WORD_1
	v_cvt_f32_f16_e32 v90, v45
	v_cvt_pk_bf16_f32 v119, v142, v143
	v_pk_mul_f32 v[144:145], v[88:89], v[90:91]
	v_cvt_f32_f16_sdwa v89, v50 dst_sel:DWORD dst_unused:UNUSED_PAD src0_sel:WORD_1
	v_cvt_f32_f16_e32 v88, v50
	v_cvt_pk_bf16_f32 v121, v144, v145
	v_pk_add_f32 v[88:89], v[88:89], 1.0 op_sel_hi:[1,0] neg_lo:[1,0] neg_hi:[1,0]
	s_nop 1
	v_mul_f32_dpp v88, v88, v88 row_shr:1 row_mask:0xf bank_mask:0xf
	v_mul_f32_dpp v89, v89, v89 row_shr:1 row_mask:0xf bank_mask:0xf
	s_nop 0
	v_mul_f32_dpp v88, v88, v88 row_shr:2 row_mask:0xf bank_mask:0xf
	v_mul_f32_dpp v89, v89, v89 row_shr:2 row_mask:0xf bank_mask:0xf
	s_nop 0
	v_mul_f32_dpp v88, v88, v88 row_shr:4 row_mask:0xf bank_mask:0xf
	v_mul_f32_dpp v89, v89, v89 row_shr:4 row_mask:0xf bank_mask:0xf
	s_nop 0
	v_mul_f32_dpp v88, v88, v88 row_shr:8 row_mask:0xf bank_mask:0xf
	v_mul_f32_dpp v89, v89, v89 row_shr:8 row_mask:0xf bank_mask:0xf
	s_nop 0
	v_max_f32_e32 v90, 0xda24260, v88
	v_max_f32_e32 v91, 0xda24260, v89
	v_rcp_f32_e32 v90, v90
	v_rcp_f32_e32 v91, v91
	v_pk_mul_f32 v[146:147], v[88:89], v[146:147]
	v_pk_mul_f32 v[148:149], v[90:91], v[148:149]
	v_cvt_f32_f16_sdwa v91, v51 dst_sel:DWORD dst_unused:UNUSED_PAD src0_sel:WORD_1
	v_cvt_f32_f16_e32 v90, v51
	v_cvt_pk_bf16_f32 v142, v146, v147
	v_add_u32_e32 v146, 0x4a80, v140
	v_cvt_pk_bf16_f32 v144, v148, v149
	v_pk_add_f32 v[90:91], v[90:91], 1.0 op_sel_hi:[1,0] neg_lo:[1,0] neg_hi:[1,0]
	s_nop 1
	v_mul_f32_dpp v90, v90, v90 row_shr:1 row_mask:0xf bank_mask:0xf
	v_mul_f32_dpp v91, v91, v91 row_shr:1 row_mask:0xf bank_mask:0xf
	s_nop 0
	v_mul_f32_dpp v90, v90, v90 row_shr:2 row_mask:0xf bank_mask:0xf
	v_mul_f32_dpp v91, v91, v91 row_shr:2 row_mask:0xf bank_mask:0xf
	s_nop 0
	v_mul_f32_dpp v90, v90, v90 row_shr:4 row_mask:0xf bank_mask:0xf
	v_mul_f32_dpp v91, v91, v91 row_shr:4 row_mask:0xf bank_mask:0xf
	s_nop 0
	v_mul_f32_dpp v90, v90, v90 row_shr:8 row_mask:0xf bank_mask:0xf
	v_mul_f32_dpp v91, v91, v91 row_shr:8 row_mask:0xf bank_mask:0xf
	s_nop 0
	v_max_f32_e32 v150, 0xda24260, v90
	v_max_f32_e32 v151, 0xda24260, v91
	v_rcp_f32_e32 v150, v150
	v_rcp_f32_e32 v151, v151
	v_pk_mul_f32 v[156:157], v[90:91], v[156:157]
	v_pk_mul_f32 v[150:151], v[150:151], v[158:159]
	v_cvt_pk_bf16_f32 v143, v156, v157
	v_cvt_pk_bf16_f32 v145, v150, v151
	ds_write2_b64 v146, v[118:119], v[142:143] offset1:1
	v_add_u32_e32 v118, 0x5b80, v140
	ds_write2_b64 v118, v[120:121], v[144:145] offset1:1
	s_and_saveexec_b64 s[10:11], s[8:9]
	s_cbranch_execz .LBB0_615
	ds_write_b128 v139, v[84:87] offset:28928
	ds_write_b128 v139, v[88:91] offset:28944
; __device__ __forceinline__ unsigned pk2(float lo, float hi) { f32x2n v = {lo, hi}; bf16x2n b = __builtin_convertvector(v, bf16x2n); return __builtin_bit_cast(unsigned, b); }
;   template <int CTRL> static __device__ __forceinline__ float shr1(float x) { return __int_as_float(__builtin_amdgcn_update_dpp(__float_as_int(1.0f), __float_as_int(x), CTRL, 0xF, 0xF, false)); }
;   static __device__ __forceinline__ float scan16(float x) { x *= shr1<0x111>(x); x *= shr1<0x112>(x); x *= shr1<0x114>(x); x *= shr1<0x118>(x); return x; }
;   __device__ __forceinline__ void gl_prep(const h16x8 (&q)[4], const h16x8 (&k)[4], const h16x8 (&u)[4], const h16x8 (&v)[2], int tb) const {
;     ...
;     for (int it = 0; it < 4; ++it) { const int bidx = it * 4 + rho, sc = bidx >> 3, k0 = (bidx & 7) * 8, st = sc * 16 + tau;
;       float G[8], qt[8], kt[8];
; #pragma unroll
;       for (int e = 0; e < 8; ++e) { G[e] = scan16(1.f - (float)u[it][e]); qt[e] = (float)q[it][e] * G[e]; kt[e] = (float)k[it][e] * __builtin_amdgcn_rcpf(fmaxf(G[e], 1e-30f)); }
;       u32x2 a, b, c2, d; a.x = pk2(qt[0], qt[1]); a.y = pk2(qt[2], qt[3]); b.x = pk2(qt[4], qt[5]); b.y = pk2(qt[6], qt[7]);
;       c2.x = pk2(kt[0], kt[1]); c2.y = pk2(kt[2], kt[3]); d.x = pk2(kt[4], kt[5]); d.y = pk2(kt[6], kt[7]);
;       unsigned char* oq = tl + TL_GQ + st * GQS + k0 * 2; unsigned char* ok = tl + TL_GK + st * GQS + k0 * 2;
;       *(u32x2*)oq = a; *(u32x2*)(oq + 8) = b; *(u32x2*)ok = c2; *(u32x2*)(ok + 8) = d;
;       if (tau == 15) { float* ge = (float*)(tl + TL_GGE) + sc * 64 + k0; *(f32x4*)ge = (f32x4){G[0], G[1], G[2], G[3]}; *(f32x4*)(ge + 4) = (f32x4){G[4], G[5], G[6], G[7]}; } }
.LBB0_615:
	s_or_b64 exec, exec, s[10:11]
	s_waitcnt vmcnt(2)
	v_cvt_f32_f16_sdwa v85, v60 dst_sel:DWORD dst_unused:UNUSED_PAD src0_sel:WORD_1
	v_cvt_f32_f16_e32 v84, v60
	v_cvt_f32_f16_sdwa v89, v52 dst_sel:DWORD dst_unused:UNUSED_PAD src0_sel:WORD_1
	v_pk_add_f32 v[84:85], v[84:85], 1.0 op_sel_hi:[1,0] neg_lo:[1,0] neg_hi:[1,0]
	v_cvt_f32_f16_e32 v88, v52
	v_cvt_f32_f16_sdwa v91, v53 dst_sel:DWORD dst_unused:UNUSED_PAD src0_sel:WORD_1
	v_mul_f32_dpp v84, v84, v84 row_shr:1 row_mask:0xf bank_mask:0xf
	v_mul_f32_dpp v85, v85, v85 row_shr:1 row_mask:0xf bank_mask:0xf
	v_cvt_f32_f16_e32 v90, v53
	v_mul_f32_dpp v84, v84, v84 row_shr:2 row_mask:0xf bank_mask:0xf
	v_mul_f32_dpp v85, v85, v85 row_shr:2 row_mask:0xf bank_mask:0xf
	v_cvt_f32_f16_sdwa v149, v58 dst_sel:DWORD dst_unused:UNUSED_PAD src0_sel:WORD_1
	v_mul_f32_dpp v84, v84, v84 row_shr:4 row_mask:0xf bank_mask:0xf
	v_mul_f32_dpp v85, v85, v85 row_shr:4 row_mask:0xf bank_mask:0xf
	v_cvt_f32_f16_e32 v148, v58
	v_mul_f32_dpp v84, v84, v84 row_shr:8 row_mask:0xf bank_mask:0xf
	v_mul_f32_dpp v85, v85, v85 row_shr:8 row_mask:0xf bank_mask:0xf
	v_max_f32_e32 v86, 0xda24260, v84
	v_max_f32_e32 v87, 0xda24260, v85
	v_rcp_f32_e32 v86, v86
	v_pk_mul_f32 v[118:119], v[84:85], v[88:89]
	v_rcp_f32_e32 v87, v87
	v_cvt_f32_f16_sdwa v89, v56 dst_sel:DWORD dst_unused:UNUSED_PAD src0_sel:WORD_1
	v_cvt_f32_f16_e32 v88, v56
	v_cvt_f32_f16_sdwa v147, v54 dst_sel:DWORD dst_unused:UNUSED_PAD src0_sel:WORD_1
	v_cvt_f32_f16_e32 v146, v54
	v_pk_mul_f32 v[120:121], v[86:87], v[88:89]
	v_cvt_f32_f16_sdwa v87, v61 dst_sel:DWORD dst_unused:UNUSED_PAD src0_sel:WORD_1
	v_cvt_f32_f16_e32 v86, v61
	v_cvt_f32_f16_sdwa v157, v55 dst_sel:DWORD dst_unused:UNUSED_PAD src0_sel:WORD_1
	v_pk_add_f32 v[86:87], v[86:87], 1.0 op_sel_hi:[1,0] neg_lo:[1,0] neg_hi:[1,0]
	v_cvt_f32_f16_e32 v156, v55
	v_cvt_f32_f16_sdwa v159, v59 dst_sel:DWORD dst_unused:UNUSED_PAD src0_sel:WORD_1
	v_mul_f32_dpp v86, v86, v86 row_shr:1 row_mask:0xf bank_mask:0xf
	v_mul_f32_dpp v87, v87, v87 row_shr:1 row_mask:0xf bank_mask:0xf
	v_cvt_f32_f16_e32 v158, v59
	v_mul_f32_dpp v86, v86, v86 row_shr:2 row_mask:0xf bank_mask:0xf
	v_mul_f32_dpp v87, v87, v87 row_shr:2 row_mask:0xf bank_mask:0xf
	v_cvt_pk_bf16_f32 v118, v118, v119
	v_mul_f32_dpp v86, v86, v86 row_shr:4 row_mask:0xf bank_mask:0xf
	v_mul_f32_dpp v87, v87, v87 row_shr:4 row_mask:0xf bank_mask:0xf
	v_cvt_pk_bf16_f32 v120, v120, v121
	v_mul_f32_dpp v86, v86, v86 row_shr:8 row_mask:0xf bank_mask:0xf
	v_mul_f32_dpp v87, v87, v87 row_shr:8 row_mask:0xf bank_mask:0xf
	s_nop 0
	v_max_f32_e32 v88, 0xda24260, v86
	v_max_f32_e32 v89, 0xda24260, v87
	v_rcp_f32_e32 v88, v88
	v_pk_mul_f32 v[142:143], v[86:87], v[90:91]
	v_rcp_f32_e32 v89, v89
	v_cvt_f32_f16_sdwa v91, v57 dst_sel:DWORD dst_unused:UNUSED_PAD src0_sel:WORD_1
	v_cvt_f32_f16_e32 v90, v57
	v_cvt_pk_bf16_f32 v119, v142, v143
	v_pk_mul_f32 v[144:145], v[88:89], v[90:91]
	v_cvt_f32_f16_sdwa v89, v62 dst_sel:DWORD dst_unused:UNUSED_PAD src0_sel:WORD_1
	v_cvt_f32_f16_e32 v88, v62
	v_cvt_pk_bf16_f32 v121, v144, v145
	v_pk_add_f32 v[88:89], v[88:89], 1.0 op_sel_hi:[1,0] neg_lo:[1,0] neg_hi:[1,0]
	s_nop 1
	v_mul_f32_dpp v88, v88, v88 row_shr:1 row_mask:0xf bank_mask:0xf
	v_mul_f32_dpp v89, v89, v89 row_shr:1 row_mask:0xf bank_mask:0xf
	s_nop 0
	v_mul_f32_dpp v88, v88, v88 row_shr:2 row_mask:0xf bank_mask:0xf
	v_mul_f32_dpp v89, v89, v89 row_shr:2 row_mask:0xf bank_mask:0xf
	s_nop 0
	v_mul_f32_dpp v88, v88, v88 row_shr:4 row_mask:0xf bank_mask:0xf
	v_mul_f32_dpp v89, v89, v89 row_shr:4 row_mask:0xf bank_mask:0xf
	s_nop 0
	v_mul_f32_dpp v88, v88, v88 row_shr:8 row_mask:0xf bank_mask:0xf
	v_mul_f32_dpp v89, v89, v89 row_shr:8 row_mask:0xf bank_mask:0xf
	s_nop 0
	v_max_f32_e32 v90, 0xda24260, v88
	v_max_f32_e32 v91, 0xda24260, v89
	v_rcp_f32_e32 v90, v90
	v_rcp_f32_e32 v91, v91
	v_pk_mul_f32 v[146:147], v[88:89], v[146:147]
	v_pk_mul_f32 v[148:149], v[90:91], v[148:149]
	v_cvt_f32_f16_sdwa v91, v63 dst_sel:DWORD dst_unused:UNUSED_PAD src0_sel:WORD_1
	v_cvt_f32_f16_e32 v90, v63
	v_cvt_pk_bf16_f32 v142, v146, v147
	v_cvt_pk_bf16_f32 v144, v148, v149
	v_pk_add_f32 v[90:91], v[90:91], 1.0 op_sel_hi:[1,0] neg_lo:[1,0] neg_hi:[1,0]
	s_nop 1
	v_mul_f32_dpp v90, v90, v90 row_shr:1 row_mask:0xf bank_mask:0xf
	v_mul_f32_dpp v91, v91, v91 row_shr:1 row_mask:0xf bank_mask:0xf
	s_nop 0
	v_mul_f32_dpp v90, v90, v90 row_shr:2 row_mask:0xf bank_mask:0xf
	v_mul_f32_dpp v91, v91, v91 row_shr:2 row_mask:0xf bank_mask:0xf
	s_nop 0
	v_mul_f32_dpp v90, v90, v90 row_shr:4 row_mask:0xf bank_mask:0xf
	v_mul_f32_dpp v91, v91, v91 row_shr:4 row_mask:0xf bank_mask:0xf
	s_nop 0
	v_mul_f32_dpp v90, v90, v90 row_shr:8 row_mask:0xf bank_mask:0xf
	v_mul_f32_dpp v91, v91, v91 row_shr:8 row_mask:0xf bank_mask:0xf
	s_nop 0
	v_max_f32_e32 v140, 0xda24260, v90
	v_rcp_f32_e32 v150, v140
	v_max_f32_e32 v140, 0xda24260, v91
	v_rcp_f32_e32 v151, v140
	v_pk_mul_f32 v[156:157], v[90:91], v[156:157]
	v_add_u32_e32 v140, 0x4a80, v141
	v_cvt_pk_bf16_f32 v143, v156, v157
	v_pk_mul_f32 v[150:151], v[150:151], v[158:159]
	ds_write2_b64 v140, v[118:119], v[142:143] offset1:1
	v_cvt_pk_bf16_f32 v145, v150, v151
	v_add_u32_e32 v118, 0x5b80, v141
	ds_write2_b64 v118, v[120:121], v[144:145] offset1:1
	s_and_saveexec_b64 s[10:11], s[8:9]
	s_cbranch_execz .LBB0_617
	ds_write_b128 v139, v[84:87] offset:29056
	ds_write_b128 v139, v[88:91] offset:29072

; __device__ __forceinline__ unsigned pk2(float lo, float hi) { f32x2n v = {lo, hi}; bf16x2n b = __builtin_convertvector(v, bf16x2n); return __builtin_bit_cast(unsigned, b); }
;   __device__ __forceinline__ const char* larow(int t0, int st) const { return wsb + WS_PNG + (size_t)(bl * TPB + seq_pos(t0 + st, dl)) * (NNGP * 2); }
;   template <int CTRL> static __device__ __forceinline__ float shr1(float x) { return __int_as_float(__builtin_amdgcn_update_dpp(__float_as_int(1.0f), __float_as_int(x), CTRL, 0xF, 0xF, false)); }
;   static __device__ __forceinline__ float scan16(float x) { x *= shr1<0x111>(x); x *= shr1<0x112>(x); x *= shr1<0x114>(x); x *= shr1<0x118>(x); return x; }
;   __device__ __forceinline__ void hg_load(h16x8 (&q)[8], h16x8 (&u)[8], int t0) const { const int rho = lane >> 4, tau = lane & 15;
; #pragma unroll
;     for (int it = 0; it < 8; ++it) { const int bidx = it * 4 + rho, sc = bidx >> 4, k0 = (bidx & 15) * 8; const char* rp = larow(t0, sc * 16 + tau);
;       q[it] = *(const h16x8*)(rp + (O_HQ + hl * 128 + k0) * 2); u[it] = *(const h16x8*)(rp + (O_HF + dl * 512 + hl * 128 + k0) * 2); } }
;   __device__ __forceinline__ void hg_prep(const h16x8 (&q)[8], const h16x8 (&u)[8], int tb) const { unsigned char* tl = smem + SC_TL + tb * SC_TLB; const int rho = lane >> 4, tau = lane & 15;
; #pragma unroll
;     for (int it = 0; it < 8; ++it) { const int bidx = it * 4 + rho, sc = bidx >> 4, k0 = (bidx & 15) * 8, st = sc * 16 + tau;
;       float G[8], qt[8], kt[8];
; #pragma unroll
;       for (int e = 0; e < 8; ++e) { const float uu = (float)u[it][e]; G[e] = scan16(1.f - uu); qt[e] = (float)q[it][e] * G[e]; kt[e] = uu * __builtin_amdgcn_rcpf(fmaxf(G[e], 1e-30f)); }
;       u32x2 a, b, c2, d; a.x = pk2(qt[0], qt[1]); a.y = pk2(qt[2], qt[3]); b.x = pk2(qt[4], qt[5]); b.y = pk2(qt[6], qt[7]);
;       c2.x = pk2(kt[0], kt[1]); c2.y = pk2(kt[2], kt[3]); d.x = pk2(kt[4], kt[5]); d.y = pk2(kt[6], kt[7]);
;       unsigned char* oq = tl + TL_HQ + st * HQS + k0 * 2; unsigned char* ok = tl + TL_HK + st * HQS + k0 * 2;
;       *(u32x2*)oq = a; *(u32x2*)(oq + 8) = b; *(u32x2*)ok = c2; *(u32x2*)(ok + 8) = d;
;       if (tau == 15) { float* ge = (float*)(tl + TL_HGE) + sc * 128 + k0; *(f32x4*)ge = (f32x4){G[0], G[1], G[2], G[3]}; *(f32x4*)(ge + 4) = (f32x4){G[4], G[5], G[6], G[7]}; } } }
.LBB0_619:
	s_and_b64 vcc, exec, s[10:11]
	s_cbranch_vccz .LBB0_662
	s_lshl_b32 s8, s19, 7
	s_addk_i32 s8, 0x780
	s_lshl_b32 s9, s19, 8
	s_lshl_b32 s10, s18, 10
	v_or_b32_e32 v0, s8, v101
	s_or_b32 s9, s9, s10
	v_lshlrev_b32_e32 v0, 1, v0
	v_mov_b32_e32 v1, v2
	s_addk_i32 s9, 0x1300
	s_waitcnt vmcnt(13)
	v_lshl_add_u64 v[16:17], v[92:93], 0, v[0:1]
	v_or_b32_e32 v112, s9, v103
	v_mov_b32_e32 v113, v2
	global_load_dwordx4 v[72:75], v[16:17], off
	v_lshl_add_u64 v[16:17], v[92:93], 0, v[112:113]
	global_load_dwordx4 v[76:79], v[16:17], off
	v_or_b32_e32 v16, s8, v137
	v_lshlrev_b32_e32 v114, 1, v16
	v_mov_b32_e32 v115, v2
	v_lshlrev_b32_e32 v134, 1, v137
	v_lshl_add_u64 v[16:17], v[92:93], 0, v[114:115]
	v_or_b32_e32 v116, s9, v134
	v_mov_b32_e32 v117, v2
	global_load_dwordx4 v[68:71], v[16:17], off
	v_lshl_add_u64 v[16:17], v[92:93], 0, v[116:117]
	v_or_b32_e32 v89, 64, v101
	global_load_dwordx4 v[64:67], v[16:17], off
	v_or_b32_e32 v16, s8, v89
	v_lshlrev_b32_e32 v118, 1, v16
	v_mov_b32_e32 v119, v2
	v_lshlrev_b32_e32 v135, 1, v89
	v_lshl_add_u64 v[16:17], v[92:93], 0, v[118:119]
	v_or_b32_e32 v120, s9, v135
	v_mov_b32_e32 v121, v2
	global_load_dwordx4 v[56:59], v[16:17], off
	v_lshl_add_u64 v[16:17], v[92:93], 0, v[120:121]
	v_or_b32_e32 v88, 0x60, v101
	global_load_dwordx4 v[60:63], v[16:17], off
	v_or_b32_e32 v16, s8, v88
	v_lshlrev_b32_e32 v122, 1, v16
	v_mov_b32_e32 v123, v2
	v_lshlrev_b32_e32 v136, 1, v88
	v_lshl_add_u64 v[16:17], v[92:93], 0, v[122:123]
	v_or_b32_e32 v124, s9, v136
	v_mov_b32_e32 v125, v2
	global_load_dwordx4 v[48:51], v[16:17], off
	v_lshl_add_u64 v[16:17], v[92:93], 0, v[124:125]
	global_load_dwordx4 v[52:55], v[16:17], off
	v_or_b32_e32 v18, s47, v138
	v_mov_b64_e32 v[16:17], s[12:13]
	v_mad_i64_i32 v[16:17], s[8:9], v18, s81, v[16:17]
	v_lshl_add_u64 v[18:19], v[16:17], 0, v[0:1]
	global_load_dwordx4 v[44:47], v[18:19], off
	v_lshl_add_u64 v[18:19], v[16:17], 0, v[112:113]
	global_load_dwordx4 v[40:43], v[18:19], off
	v_lshl_add_u64 v[18:19], v[16:17], 0, v[114:115]
	global_load_dwordx4 v[36:39], v[18:19], off
	v_lshl_add_u64 v[18:19], v[16:17], 0, v[116:117]
	global_load_dwordx4 v[32:35], v[18:19], off
	v_lshl_add_u64 v[18:19], v[16:17], 0, v[118:119]
	global_load_dwordx4 v[28:31], v[18:19], off
	v_lshl_add_u64 v[18:19], v[16:17], 0, v[120:121]
	global_load_dwordx4 v[24:27], v[18:19], off
	v_lshl_add_u64 v[18:19], v[16:17], 0, v[122:123]
	v_lshl_add_u64 v[16:17], v[16:17], 0, v[124:125]
	global_load_dwordx4 v[20:23], v[18:19], off
	global_load_dwordx4 v[16:19], v[16:17], off
	s_movk_i32 s10, 0x108
	v_cmp_eq_u32_e64 s[8:9], 15, v3
	s_waitcnt vmcnt(15)
	v_cvt_f32_f16_e32 v86, v72
	v_cvt_f32_f16_sdwa v87, v72 dst_sel:DWORD dst_unused:UNUSED_PAD src0_sel:WORD_1
	s_waitcnt vmcnt(14)
	v_cvt_f32_f16_e32 v82, v76
	v_cvt_f32_f16_sdwa v83, v76 dst_sel:DWORD dst_unused:UNUSED_PAD src0_sel:WORD_1
	v_cvt_f32_f16_e32 v92, v78
	v_cvt_f32_f16_sdwa v93, v78 dst_sel:DWORD dst_unused:UNUSED_PAD src0_sel:WORD_1
	v_cvt_f32_f16_e32 v96, v74
	v_pk_add_f32 v[80:81], v[82:83], 1.0 op_sel_hi:[1,0] neg_lo:[1,0] neg_hi:[1,0]
	v_cvt_f32_f16_sdwa v97, v74 dst_sel:DWORD dst_unused:UNUSED_PAD src0_sel:WORD_1
	s_nop 0
	v_mul_f32_dpp v80, v80, v80 row_shr:1 row_mask:0xf bank_mask:0xf
	v_mul_f32_dpp v81, v81, v81 row_shr:1 row_mask:0xf bank_mask:0xf
	s_nop 0
	v_mul_f32_dpp v80, v80, v80 row_shr:2 row_mask:0xf bank_mask:0xf
	v_mul_f32_dpp v81, v81, v81 row_shr:2 row_mask:0xf bank_mask:0xf
	s_nop 0
	v_mul_f32_dpp v80, v80, v80 row_shr:4 row_mask:0xf bank_mask:0xf
	v_mul_f32_dpp v81, v81, v81 row_shr:4 row_mask:0xf bank_mask:0xf
	s_nop 0
	v_mul_f32_dpp v80, v80, v80 row_shr:8 row_mask:0xf bank_mask:0xf
	v_mul_f32_dpp v81, v81, v81 row_shr:8 row_mask:0xf bank_mask:0xf
	s_nop 0
	v_max_f32_e32 v76, 0xda24260, v80
	v_max_f32_e32 v72, 0xda24260, v81
	v_rcp_f32_e32 v84, v76
	v_rcp_f32_e32 v85, v72
	v_cvt_f32_f16_e32 v76, v77
	v_cvt_f32_f16_sdwa v77, v77 dst_sel:DWORD dst_unused:UNUSED_PAD src0_sel:WORD_1
	v_pk_mul_f32 v[86:87], v[80:81], v[86:87]
	v_pk_mul_f32 v[84:85], v[84:85], v[82:83]
	v_cvt_pk_bf16_f32 v86, v86, v87
	v_pk_add_f32 v[82:83], v[76:77], 1.0 op_sel_hi:[1,0] neg_lo:[1,0] neg_hi:[1,0]
	s_nop 1
	v_mul_f32_dpp v82, v82, v82 row_shr:1 row_mask:0xf bank_mask:0xf
	v_mul_f32_dpp v83, v83, v83 row_shr:1 row_mask:0xf bank_mask:0xf
	s_nop 0
	v_mul_f32_dpp v82, v82, v82 row_shr:2 row_mask:0xf bank_mask:0xf
	v_mul_f32_dpp v83, v83, v83 row_shr:2 row_mask:0xf bank_mask:0xf
	s_nop 0
	v_mul_f32_dpp v82, v82, v82 row_shr:4 row_mask:0xf bank_mask:0xf
	v_mul_f32_dpp v83, v83, v83 row_shr:4 row_mask:0xf bank_mask:0xf
	v_mov_b32_e32 v91, 1.0
	s_nop 0
	v_mul_f32_dpp v82, v82, v82 row_shr:8 row_mask:0xf bank_mask:0xf
	v_mul_f32_dpp v83, v83, v83 row_shr:8 row_mask:0xf bank_mask:0xf
	v_cvt_f32_f16_e32 v90, v73
	v_max_f32_e32 v72, 0xda24260, v82
	v_cvt_f32_f16_sdwa v91, v73 dst_sel:DWORD dst_unused:UNUSED_PAD src0_sel:WORD_1
	v_max_f32_e32 v73, 0xda24260, v83
	v_rcp_f32_e32 v72, v72
	v_rcp_f32_e32 v73, v73
	v_pk_mul_f32 v[90:91], v[82:83], v[90:91]
	v_pk_mul_f32 v[72:73], v[72:73], v[76:77]
	v_pk_add_f32 v[76:77], v[92:93], 1.0 op_sel_hi:[1,0] neg_lo:[1,0] neg_hi:[1,0]
	v_cvt_pk_bf16_f32 v87, v90, v91
	s_nop 0
	v_mul_f32_dpp v76, v76, v76 row_shr:1 row_mask:0xf bank_mask:0xf
	v_mul_f32_dpp v77, v77, v77 row_shr:1 row_mask:0xf bank_mask:0xf
	s_nop 0
	v_mul_f32_dpp v76, v76, v76 row_shr:2 row_mask:0xf bank_mask:0xf
	v_mul_f32_dpp v77, v77, v77 row_shr:2 row_mask:0xf bank_mask:0xf
	s_nop 0
	v_mul_f32_dpp v76, v76, v76 row_shr:4 row_mask:0xf bank_mask:0xf
	v_mul_f32_dpp v77, v77, v77 row_shr:4 row_mask:0xf bank_mask:0xf
	s_nop 0
; __device__ __forceinline__ unsigned pk2(float lo, float hi) { f32x2n v = {lo, hi}; bf16x2n b = __builtin_convertvector(v, bf16x2n); return __builtin_bit_cast(unsigned, b); }
;   template <int CTRL> static __device__ __forceinline__ float shr1(float x) { return __int_as_float(__builtin_amdgcn_update_dpp(__float_as_int(1.0f), __float_as_int(x), CTRL, 0xF, 0xF, false)); }
;   static __device__ __forceinline__ float scan16(float x) { x *= shr1<0x111>(x); x *= shr1<0x112>(x); x *= shr1<0x114>(x); x *= shr1<0x118>(x); return x; }
;   __device__ __forceinline__ void hg_prep(const h16x8 (&q)[8], const h16x8 (&u)[8], int tb) const { unsigned char* tl = smem + SC_TL + tb * SC_TLB; const int rho = lane >> 4, tau = lane & 15;
; #pragma unroll
;     for (int it = 0; it < 8; ++it) { const int bidx = it * 4 + rho, sc = bidx >> 4, k0 = (bidx & 15) * 8, st = sc * 16 + tau;
;       float G[8], qt[8], kt[8];
; #pragma unroll
;       for (int e = 0; e < 8; ++e) { const float uu = (float)u[it][e]; G[e] = scan16(1.f - uu); qt[e] = (float)q[it][e] * G[e]; kt[e] = uu * __builtin_amdgcn_rcpf(fmaxf(G[e], 1e-30f)); }
;       u32x2 a, b, c2, d; a.x = pk2(qt[0], qt[1]); a.y = pk2(qt[2], qt[3]); b.x = pk2(qt[4], qt[5]); b.y = pk2(qt[6], qt[7]);
;       c2.x = pk2(kt[0], kt[1]); c2.y = pk2(kt[2], kt[3]); d.x = pk2(kt[4], kt[5]); d.y = pk2(kt[6], kt[7]);
;       unsigned char* oq = tl + TL_HQ + st * HQS + k0 * 2; unsigned char* ok = tl + TL_HK + st * HQS + k0 * 2;
;       *(u32x2*)oq = a; *(u32x2*)(oq + 8) = b; *(u32x2*)ok = c2; *(u32x2*)(ok + 8) = d;
;       if (tau == 15) { float* ge = (float*)(tl + TL_HGE) + sc * 128 + k0; *(f32x4*)ge = (f32x4){G[0], G[1], G[2], G[3]}; *(f32x4*)(ge + 4) = (f32x4){G[4], G[5], G[6], G[7]}; } } }
	v_mul_f32_dpp v76, v76, v76 row_shr:8 row_mask:0xf bank_mask:0xf
	v_mul_f32_dpp v77, v77, v77 row_shr:8 row_mask:0xf bank_mask:0xf
	s_nop 0
	v_max_f32_e32 v78, 0xda24260, v76
	v_max_f32_e32 v74, 0xda24260, v77
	v_rcp_f32_e32 v94, v78
	v_rcp_f32_e32 v95, v74
	v_pk_mul_f32 v[96:97], v[76:77], v[96:97]
	v_pk_mul_f32 v[92:93], v[94:95], v[92:93]
	v_cvt_f32_f16_e32 v94, v79
	v_cvt_f32_f16_sdwa v95, v79 dst_sel:DWORD dst_unused:UNUSED_PAD src0_sel:WORD_1
	v_cvt_pk_bf16_f32 v90, v96, v97
	v_pk_add_f32 v[78:79], v[94:95], 1.0 op_sel_hi:[1,0] neg_lo:[1,0] neg_hi:[1,0]
	s_nop 1
	v_mul_f32_dpp v78, v78, v78 row_shr:1 row_mask:0xf bank_mask:0xf
	v_mul_f32_dpp v79, v79, v79 row_shr:1 row_mask:0xf bank_mask:0xf
	s_nop 0
	v_mul_f32_dpp v78, v78, v78 row_shr:2 row_mask:0xf bank_mask:0xf
	v_mul_f32_dpp v79, v79, v79 row_shr:2 row_mask:0xf bank_mask:0xf
	s_nop 0
	v_mul_f32_dpp v78, v78, v78 row_shr:4 row_mask:0xf bank_mask:0xf
	v_mul_f32_dpp v79, v79, v79 row_shr:4 row_mask:0xf bank_mask:0xf
	v_mov_b32_e32 v99, 1.0
	s_nop 0
	v_mul_f32_dpp v78, v78, v78 row_shr:8 row_mask:0xf bank_mask:0xf
	v_mul_f32_dpp v79, v79, v79 row_shr:8 row_mask:0xf bank_mask:0xf
	v_cvt_f32_f16_e32 v98, v75
	v_max_f32_e32 v74, 0xda24260, v78
	v_cvt_f32_f16_sdwa v99, v75 dst_sel:DWORD dst_unused:UNUSED_PAD src0_sel:WORD_1
	v_max_f32_e32 v75, 0xda24260, v79
	v_rcp_f32_e32 v74, v74
	v_rcp_f32_e32 v75, v75
	v_pk_mul_f32 v[98:99], v[78:79], v[98:99]
	v_pk_mul_f32 v[74:75], v[74:75], v[94:95]
	v_cvt_pk_bf16_f32 v94, v84, v85
	v_mad_u32_u24 v85, v3, s10, 0
	v_cvt_pk_bf16_f32 v95, v72, v73
	v_cvt_pk_bf16_f32 v73, v74, v75
	v_add_u32_e32 v74, v85, v103
	v_cvt_pk_bf16_f32 v91, v98, v99
	v_add_u32_e32 v75, 0xc000, v74
	v_lshl_add_u32 v84, v101, 2, 0
	v_cvt_pk_bf16_f32 v72, v92, v93
	v_add_u32_e32 v74, 0xe100, v74
	ds_write2_b64 v75, v[86:87], v[90:91] offset1:1
	ds_write2_b64 v74, v[94:95], v[72:73] offset1:1
	s_and_saveexec_b64 s[10:11], s[8:9]
	s_cbranch_execz .LBB0_622
	v_add_u32_e32 v72, 0x12c00, v84
	ds_write_b128 v72, v[80:83]
	ds_write_b128 v72, v[76:79] offset:16
.LBB0_622:
	s_or_b64 exec, exec, s[10:11]
	s_waitcnt vmcnt(12)
	v_cvt_f32_f16_sdwa v77, v64 dst_sel:DWORD dst_unused:UNUSED_PAD src0_sel:WORD_1
	v_cvt_f32_f16_e32 v76, v64
	v_cvt_f32_f16_sdwa v75, v68 dst_sel:DWORD dst_unused:UNUSED_PAD src0_sel:WORD_1
	v_pk_add_f32 v[72:73], v[76:77], 1.0 op_sel_hi:[1,0] neg_lo:[1,0] neg_hi:[1,0]
	v_cvt_f32_f16_e32 v74, v68
	v_cvt_f32_f16_e32 v68, v65
	v_mul_f32_dpp v72, v72, v72 row_shr:1 row_mask:0xf bank_mask:0xf
	v_mul_f32_dpp v73, v73, v73 row_shr:1 row_mask:0xf bank_mask:0xf
	v_cvt_f32_f16_sdwa v87, v66 dst_sel:DWORD dst_unused:UNUSED_PAD src0_sel:WORD_1
	v_mul_f32_dpp v72, v72, v72 row_shr:2 row_mask:0xf bank_mask:0xf
	v_mul_f32_dpp v73, v73, v73 row_shr:2 row_mask:0xf bank_mask:0xf
	v_cvt_f32_f16_e32 v86, v66
	v_mul_f32_dpp v72, v72, v72 row_shr:4 row_mask:0xf bank_mask:0xf
	v_mul_f32_dpp v73, v73, v73 row_shr:4 row_mask:0xf bank_mask:0xf
	s_nop 0
	v_mul_f32_dpp v72, v72, v72 row_shr:8 row_mask:0xf bank_mask:0xf
	v_mul_f32_dpp v73, v73, v73 row_shr:8 row_mask:0xf bank_mask:0xf
	v_max_f32_e32 v64, 0xda24260, v72
	v_rcp_f32_e32 v78, v64
	v_max_f32_e32 v64, 0xda24260, v73
	v_rcp_f32_e32 v79, v64
	v_pk_mul_f32 v[80:81], v[72:73], v[74:75]
	v_pk_mul_f32 v[76:77], v[78:79], v[76:77]
	v_cvt_f32_f16_sdwa v79, v69 dst_sel:DWORD dst_unused:UNUSED_PAD src0_sel:WORD_1
	v_cvt_f32_f16_e32 v78, v69
	v_cvt_f32_f16_sdwa v69, v65 dst_sel:DWORD dst_unused:UNUSED_PAD src0_sel:WORD_1
	v_cvt_f32_f16_sdwa v83, v70 dst_sel:DWORD dst_unused:UNUSED_PAD src0_sel:WORD_1
	v_cvt_f32_f16_e32 v82, v70
	v_cvt_f32_f16_e32 v70, v67
	v_pk_add_f32 v[64:65], v[68:69], 1.0 op_sel_hi:[1,0] neg_lo:[1,0] neg_hi:[1,0]
	s_nop 1
	v_mul_f32_dpp v64, v64, v64 row_shr:1 row_mask:0xf bank_mask:0xf
	v_mul_f32_dpp v65, v65, v65 row_shr:1 row_mask:0xf bank_mask:0xf
	v_cvt_pk_bf16_f32 v76, v76, v77
	v_mul_f32_dpp v64, v64, v64 row_shr:2 row_mask:0xf bank_mask:0xf
	v_mul_f32_dpp v65, v65, v65 row_shr:2 row_mask:0xf bank_mask:0xf
	v_cvt_pk_bf16_f32 v80, v80, v81
	v_mul_f32_dpp v64, v64, v64 row_shr:4 row_mask:0xf bank_mask:0xf
	v_mul_f32_dpp v65, v65, v65 row_shr:4 row_mask:0xf bank_mask:0xf
	s_nop 0
	v_mul_f32_dpp v64, v64, v64 row_shr:8 row_mask:0xf bank_mask:0xf
	v_mul_f32_dpp v65, v65, v65 row_shr:8 row_mask:0xf bank_mask:0xf
	v_mov_b64_e32 v[74:75], v[64:65]
	s_nop 0
	v_max_f32_e32 v64, 0xda24260, v74
	v_max_f32_e32 v65, 0xda24260, v75
	v_rcp_f32_e32 v64, v64
	v_rcp_f32_e32 v65, v65
	v_pk_mul_f32 v[78:79], v[74:75], v[78:79]
	v_pk_mul_f32 v[68:69], v[64:65], v[68:69]
	v_pk_add_f32 v[64:65], v[86:87], 1.0 op_sel_hi:[1,0] neg_lo:[1,0] neg_hi:[1,0]
	v_cvt_pk_bf16_f32 v77, v68, v69
	v_cvt_pk_bf16_f32 v81, v78, v79
	v_mul_f32_dpp v64, v64, v64 row_shr:1 row_mask:0xf bank_mask:0xf
	v_mul_f32_dpp v65, v65, v65 row_shr:1 row_mask:0xf bank_mask:0xf
	s_nop 0
	v_mul_f32_dpp v64, v64, v64 row_shr:2 row_mask:0xf bank_mask:0xf
	v_mul_f32_dpp v65, v65, v65 row_shr:2 row_mask:0xf bank_mask:0xf
	s_nop 0
	v_mul_f32_dpp v64, v64, v64 row_shr:4 row_mask:0xf bank_mask:0xf
	v_mul_f32_dpp v65, v65, v65 row_shr:4 row_mask:0xf bank_mask:0xf
	s_nop 0
	v_mul_f32_dpp v64, v64, v64 row_shr:8 row_mask:0xf bank_mask:0xf
	v_mul_f32_dpp v65, v65, v65 row_shr:8 row_mask:0xf bank_mask:0xf
	s_nop 0
	v_max_f32_e32 v66, 0xda24260, v64
	v_rcp_f32_e32 v90, v66
	v_max_f32_e32 v66, 0xda24260, v65
	v_rcp_f32_e32 v91, v66
	v_pk_mul_f32 v[82:83], v[64:65], v[82:83]
	v_pk_mul_f32 v[86:87], v[90:91], v[86:87]
	v_cvt_f32_f16_sdwa v91, v71 dst_sel:DWORD dst_unused:UNUSED_PAD src0_sel:WORD_1
	v_cvt_f32_f16_e32 v90, v71
	v_cvt_f32_f16_sdwa v71, v67 dst_sel:DWORD dst_unused:UNUSED_PAD src0_sel:WORD_1
	v_cvt_pk_bf16_f32 v78, v82, v83
	v_cvt_pk_bf16_f32 v68, v86, v87
	v_pk_add_f32 v[66:67], v[70:71], 1.0 op_sel_hi:[1,0] neg_lo:[1,0] neg_hi:[1,0]
	s_nop 1
	v_mul_f32_dpp v66, v66, v66 row_shr:1 row_mask:0xf bank_mask:0xf
	v_mul_f32_dpp v67, v67, v67 row_shr:1 row_mask:0xf bank_mask:0xf
	s_nop 0
	v_mul_f32_dpp v66, v66, v66 row_shr:2 row_mask:0xf bank_mask:0xf
	v_mul_f32_dpp v67, v67, v67 row_shr:2 row_mask:0xf bank_mask:0xf
	s_nop 0
	v_mul_f32_dpp v66, v66, v66 row_shr:4 row_mask:0xf bank_mask:0xf
	v_mul_f32_dpp v67, v67, v67 row_shr:4 row_mask:0xf bank_mask:0xf
	s_nop 0
	v_mul_f32_dpp v66, v66, v66 row_shr:8 row_mask:0xf bank_mask:0xf
	v_mul_f32_dpp v67, v67, v67 row_shr:8 row_mask:0xf bank_mask:0xf
	s_nop 0
	v_max_f32_e32 v92, 0xda24260, v66
	v_max_f32_e32 v93, 0xda24260, v67
	v_rcp_f32_e32 v92, v92
	v_rcp_f32_e32 v93, v93
	v_pk_mul_f32 v[90:91], v[66:67], v[90:91]
	v_pk_mul_f32 v[70:71], v[92:93], v[70:71]
	s_nop 0
	v_cvt_pk_bf16_f32 v69, v70, v71
	v_add_u32_e32 v70, v85, v134
	v_cvt_pk_bf16_f32 v79, v90, v91
	v_add_u32_e32 v71, 0xc000, v70
	v_add_u32_e32 v70, 0xe100, v70
	ds_write2_b64 v71, v[80:81], v[78:79] offset1:1
	ds_write2_b64 v70, v[76:77], v[68:69] offset1:1
	v_lshl_add_u32 v68, v137, 2, 0
	s_and_saveexec_b64 s[10:11], s[8:9]
	s_cbranch_execz .LBB0_624
	v_add_u32_e32 v69, 0x12c00, v68
	ds_write_b128 v69, v[72:75]
	ds_write_b128 v69, v[64:67] offset:16
; __device__ __forceinline__ unsigned pk2(float lo, float hi) { f32x2n v = {lo, hi}; bf16x2n b = __builtin_convertvector(v, bf16x2n); return __builtin_bit_cast(unsigned, b); }
;   template <int CTRL> static __device__ __forceinline__ float shr1(float x) { return __int_as_float(__builtin_amdgcn_update_dpp(__float_as_int(1.0f), __float_as_int(x), CTRL, 0xF, 0xF, false)); }
;   static __device__ __forceinline__ float scan16(float x) { x *= shr1<0x111>(x); x *= shr1<0x112>(x); x *= shr1<0x114>(x); x *= shr1<0x118>(x); return x; }
;   __device__ __forceinline__ void hg_prep(const h16x8 (&q)[8], const h16x8 (&u)[8], int tb) const { unsigned char* tl = smem + SC_TL + tb * SC_TLB; const int rho = lane >> 4, tau = lane & 15;
; #pragma unroll
;     for (int it = 0; it < 8; ++it) { const int bidx = it * 4 + rho, sc = bidx >> 4, k0 = (bidx & 15) * 8, st = sc * 16 + tau;
;       float G[8], qt[8], kt[8];
; #pragma unroll
;       for (int e = 0; e < 8; ++e) { const float uu = (float)u[it][e]; G[e] = scan16(1.f - uu); qt[e] = (float)q[it][e] * G[e]; kt[e] = uu * __builtin_amdgcn_rcpf(fmaxf(G[e], 1e-30f)); }
;       u32x2 a, b, c2, d; a.x = pk2(qt[0], qt[1]); a.y = pk2(qt[2], qt[3]); b.x = pk2(qt[4], qt[5]); b.y = pk2(qt[6], qt[7]);
;       c2.x = pk2(kt[0], kt[1]); c2.y = pk2(kt[2], kt[3]); d.x = pk2(kt[4], kt[5]); d.y = pk2(kt[6], kt[7]);
;       unsigned char* oq = tl + TL_HQ + st * HQS + k0 * 2; unsigned char* ok = tl + TL_HK + st * HQS + k0 * 2;
;       *(u32x2*)oq = a; *(u32x2*)(oq + 8) = b; *(u32x2*)ok = c2; *(u32x2*)(ok + 8) = d;
;       if (tau == 15) { float* ge = (float*)(tl + TL_HGE) + sc * 128 + k0; *(f32x4*)ge = (f32x4){G[0], G[1], G[2], G[3]}; *(f32x4*)(ge + 4) = (f32x4){G[4], G[5], G[6], G[7]}; } } }
.LBB0_624:
	s_or_b64 exec, exec, s[10:11]
	s_waitcnt vmcnt(10)
	v_cvt_f32_f16_sdwa v71, v60 dst_sel:DWORD dst_unused:UNUSED_PAD src0_sel:WORD_1
	v_cvt_f32_f16_e32 v70, v60
	v_cvt_f32_f16_sdwa v67, v56 dst_sel:DWORD dst_unused:UNUSED_PAD src0_sel:WORD_1
	v_pk_add_f32 v[64:65], v[70:71], 1.0 op_sel_hi:[1,0] neg_lo:[1,0] neg_hi:[1,0]
	v_cvt_f32_f16_e32 v66, v56
	v_cvt_f32_f16_sdwa v79, v62 dst_sel:DWORD dst_unused:UNUSED_PAD src0_sel:WORD_1
	v_mul_f32_dpp v64, v64, v64 row_shr:1 row_mask:0xf bank_mask:0xf
	v_mul_f32_dpp v65, v65, v65 row_shr:1 row_mask:0xf bank_mask:0xf
	v_cvt_f32_f16_e32 v78, v62
	v_mul_f32_dpp v64, v64, v64 row_shr:2 row_mask:0xf bank_mask:0xf
	v_mul_f32_dpp v65, v65, v65 row_shr:2 row_mask:0xf bank_mask:0xf
	s_nop 0
	v_mul_f32_dpp v64, v64, v64 row_shr:4 row_mask:0xf bank_mask:0xf
	v_mul_f32_dpp v65, v65, v65 row_shr:4 row_mask:0xf bank_mask:0xf
	s_nop 0
	v_mul_f32_dpp v64, v64, v64 row_shr:8 row_mask:0xf bank_mask:0xf
	v_mul_f32_dpp v65, v65, v65 row_shr:8 row_mask:0xf bank_mask:0xf
	v_cvt_f32_f16_sdwa v77, v58 dst_sel:DWORD dst_unused:UNUSED_PAD src0_sel:WORD_1
	v_max_f32_e32 v56, 0xda24260, v64
	v_rcp_f32_e32 v72, v56
	v_max_f32_e32 v56, 0xda24260, v65
	v_rcp_f32_e32 v73, v56
	v_cvt_f32_f16_e32 v56, v61
	v_pk_mul_f32 v[74:75], v[64:65], v[66:67]
	v_pk_mul_f32 v[70:71], v[72:73], v[70:71]
	v_cvt_f32_f16_sdwa v73, v57 dst_sel:DWORD dst_unused:UNUSED_PAD src0_sel:WORD_1
	v_cvt_f32_f16_e32 v72, v57
	v_cvt_f32_f16_sdwa v57, v61 dst_sel:DWORD dst_unused:UNUSED_PAD src0_sel:WORD_1
	v_cvt_f32_f16_e32 v76, v58
	v_cvt_f32_f16_sdwa v83, v63 dst_sel:DWORD dst_unused:UNUSED_PAD src0_sel:WORD_1
	v_pk_add_f32 v[60:61], v[56:57], 1.0 op_sel_hi:[1,0] neg_lo:[1,0] neg_hi:[1,0]
	v_cvt_f32_f16_e32 v82, v63
	s_nop 0
	v_mul_f32_dpp v60, v60, v60 row_shr:1 row_mask:0xf bank_mask:0xf
	v_mul_f32_dpp v61, v61, v61 row_shr:1 row_mask:0xf bank_mask:0xf
	s_nop 0
	v_mul_f32_dpp v60, v60, v60 row_shr:2 row_mask:0xf bank_mask:0xf
	v_mul_f32_dpp v61, v61, v61 row_shr:2 row_mask:0xf bank_mask:0xf
	v_cvt_pk_bf16_f32 v70, v70, v71
	v_mul_f32_dpp v60, v60, v60 row_shr:4 row_mask:0xf bank_mask:0xf
	v_mul_f32_dpp v61, v61, v61 row_shr:4 row_mask:0xf bank_mask:0xf
	v_cvt_pk_bf16_f32 v74, v74, v75
	v_mul_f32_dpp v60, v60, v60 row_shr:8 row_mask:0xf bank_mask:0xf
	v_mul_f32_dpp v61, v61, v61 row_shr:8 row_mask:0xf bank_mask:0xf
	v_mov_b64_e32 v[66:67], v[60:61]
	s_nop 0
	v_max_f32_e32 v60, 0xda24260, v66
	v_max_f32_e32 v61, 0xda24260, v67
	v_rcp_f32_e32 v60, v60
	v_rcp_f32_e32 v61, v61
	v_pk_mul_f32 v[72:73], v[66:67], v[72:73]
	v_pk_mul_f32 v[60:61], v[60:61], v[56:57]
	v_pk_add_f32 v[56:57], v[78:79], 1.0 op_sel_hi:[1,0] neg_lo:[1,0] neg_hi:[1,0]
	v_cvt_pk_bf16_f32 v71, v60, v61
	v_cvt_pk_bf16_f32 v75, v72, v73
	v_mul_f32_dpp v56, v56, v56 row_shr:1 row_mask:0xf bank_mask:0xf
	v_mul_f32_dpp v57, v57, v57 row_shr:1 row_mask:0xf bank_mask:0xf
	s_nop 0
	v_mul_f32_dpp v56, v56, v56 row_shr:2 row_mask:0xf bank_mask:0xf
	v_mul_f32_dpp v57, v57, v57 row_shr:2 row_mask:0xf bank_mask:0xf
	s_nop 0
	v_mul_f32_dpp v56, v56, v56 row_shr:4 row_mask:0xf bank_mask:0xf
	v_mul_f32_dpp v57, v57, v57 row_shr:4 row_mask:0xf bank_mask:0xf
	s_nop 0
	v_mul_f32_dpp v56, v56, v56 row_shr:8 row_mask:0xf bank_mask:0xf
	v_mul_f32_dpp v57, v57, v57 row_shr:8 row_mask:0xf bank_mask:0xf
	s_nop 0
	v_max_f32_e32 v58, 0xda24260, v56
	v_rcp_f32_e32 v80, v58
	v_max_f32_e32 v58, 0xda24260, v57
	v_rcp_f32_e32 v81, v58
	v_pk_mul_f32 v[76:77], v[56:57], v[76:77]
	v_pk_mul_f32 v[78:79], v[80:81], v[78:79]
	v_cvt_f32_f16_sdwa v81, v59 dst_sel:DWORD dst_unused:UNUSED_PAD src0_sel:WORD_1
	v_cvt_f32_f16_e32 v80, v59
	v_pk_add_f32 v[58:59], v[82:83], 1.0 op_sel_hi:[1,0] neg_lo:[1,0] neg_hi:[1,0]
	v_cvt_pk_bf16_f32 v72, v76, v77
	v_cvt_pk_bf16_f32 v60, v78, v79
	v_mul_f32_dpp v58, v58, v58 row_shr:1 row_mask:0xf bank_mask:0xf
	v_mul_f32_dpp v59, v59, v59 row_shr:1 row_mask:0xf bank_mask:0xf
	s_nop 0
	v_mul_f32_dpp v58, v58, v58 row_shr:2 row_mask:0xf bank_mask:0xf
	v_mul_f32_dpp v59, v59, v59 row_shr:2 row_mask:0xf bank_mask:0xf
	s_nop 0
	v_mul_f32_dpp v58, v58, v58 row_shr:4 row_mask:0xf bank_mask:0xf
	v_mul_f32_dpp v59, v59, v59 row_shr:4 row_mask:0xf bank_mask:0xf
	s_nop 0
	v_mul_f32_dpp v58, v58, v58 row_shr:8 row_mask:0xf bank_mask:0xf
	v_mul_f32_dpp v59, v59, v59 row_shr:8 row_mask:0xf bank_mask:0xf
	s_nop 0
	v_max_f32_e32 v62, 0xda24260, v58
	v_max_f32_e32 v63, 0xda24260, v59
	v_rcp_f32_e32 v62, v62
	v_rcp_f32_e32 v63, v63
	v_pk_mul_f32 v[80:81], v[58:59], v[80:81]
	v_pk_mul_f32 v[62:63], v[62:63], v[82:83]
	s_nop 0
	v_cvt_pk_bf16_f32 v61, v62, v63
	v_add_u32_e32 v62, v85, v135
	v_cvt_pk_bf16_f32 v73, v80, v81
	v_add_u32_e32 v63, 0xc000, v62
	v_add_u32_e32 v62, 0xe100, v62
	ds_write2_b64 v63, v[74:75], v[72:73] offset1:1
	ds_write2_b64 v62, v[70:71], v[60:61] offset1:1
	v_lshl_add_u32 v60, v89, 2, 0
	s_and_saveexec_b64 s[10:11], s[8:9]
	s_cbranch_execz .LBB0_626
	v_add_u32_e32 v61, 0x12c00, v60
	ds_write_b128 v61, v[64:67]
	ds_write_b128 v61, v[56:59] offset:16
; __device__ __forceinline__ unsigned pk2(float lo, float hi) { f32x2n v = {lo, hi}; bf16x2n b = __builtin_convertvector(v, bf16x2n); return __builtin_bit_cast(unsigned, b); }
;   template <int CTRL> static __device__ __forceinline__ float shr1(float x) { return __int_as_float(__builtin_amdgcn_update_dpp(__float_as_int(1.0f), __float_as_int(x), CTRL, 0xF, 0xF, false)); }
;   static __device__ __forceinline__ float scan16(float x) { x *= shr1<0x111>(x); x *= shr1<0x112>(x); x *= shr1<0x114>(x); x *= shr1<0x118>(x); return x; }
;   __device__ __forceinline__ void hg_prep(const h16x8 (&q)[8], const h16x8 (&u)[8], int tb) const { unsigned char* tl = smem + SC_TL + tb * SC_TLB; const int rho = lane >> 4, tau = lane & 15;
; #pragma unroll
;     for (int it = 0; it < 8; ++it) { const int bidx = it * 4 + rho, sc = bidx >> 4, k0 = (bidx & 15) * 8, st = sc * 16 + tau;
;       float G[8], qt[8], kt[8];
; #pragma unroll
;       for (int e = 0; e < 8; ++e) { const float uu = (float)u[it][e]; G[e] = scan16(1.f - uu); qt[e] = (float)q[it][e] * G[e]; kt[e] = uu * __builtin_amdgcn_rcpf(fmaxf(G[e], 1e-30f)); }
;       u32x2 a, b, c2, d; a.x = pk2(qt[0], qt[1]); a.y = pk2(qt[2], qt[3]); b.x = pk2(qt[4], qt[5]); b.y = pk2(qt[6], qt[7]);
;       c2.x = pk2(kt[0], kt[1]); c2.y = pk2(kt[2], kt[3]); d.x = pk2(kt[4], kt[5]); d.y = pk2(kt[6], kt[7]);
;       unsigned char* oq = tl + TL_HQ + st * HQS + k0 * 2; unsigned char* ok = tl + TL_HK + st * HQS + k0 * 2;
;       *(u32x2*)oq = a; *(u32x2*)(oq + 8) = b; *(u32x2*)ok = c2; *(u32x2*)(ok + 8) = d;
;       if (tau == 15) { float* ge = (float*)(tl + TL_HGE) + sc * 128 + k0; *(f32x4*)ge = (f32x4){G[0], G[1], G[2], G[3]}; *(f32x4*)(ge + 4) = (f32x4){G[4], G[5], G[6], G[7]}; } } }
.LBB0_626:
	s_or_b64 exec, exec, s[10:11]
	s_waitcnt vmcnt(8)
	v_cvt_f32_f16_sdwa v63, v52 dst_sel:DWORD dst_unused:UNUSED_PAD src0_sel:WORD_1
	v_cvt_f32_f16_e32 v62, v52
	v_cvt_f32_f16_sdwa v59, v48 dst_sel:DWORD dst_unused:UNUSED_PAD src0_sel:WORD_1
	v_pk_add_f32 v[56:57], v[62:63], 1.0 op_sel_hi:[1,0] neg_lo:[1,0] neg_hi:[1,0]
	v_cvt_f32_f16_e32 v58, v48
	v_cvt_f32_f16_sdwa v73, v54 dst_sel:DWORD dst_unused:UNUSED_PAD src0_sel:WORD_1
	v_mul_f32_dpp v56, v56, v56 row_shr:1 row_mask:0xf bank_mask:0xf
	v_mul_f32_dpp v57, v57, v57 row_shr:1 row_mask:0xf bank_mask:0xf
	v_cvt_f32_f16_e32 v72, v54
	v_mul_f32_dpp v56, v56, v56 row_shr:2 row_mask:0xf bank_mask:0xf
	v_mul_f32_dpp v57, v57, v57 row_shr:2 row_mask:0xf bank_mask:0xf
	s_nop 0
	v_mul_f32_dpp v56, v56, v56 row_shr:4 row_mask:0xf bank_mask:0xf
	v_mul_f32_dpp v57, v57, v57 row_shr:4 row_mask:0xf bank_mask:0xf
	s_nop 0
	v_mul_f32_dpp v56, v56, v56 row_shr:8 row_mask:0xf bank_mask:0xf
	v_mul_f32_dpp v57, v57, v57 row_shr:8 row_mask:0xf bank_mask:0xf
	v_cvt_f32_f16_sdwa v71, v50 dst_sel:DWORD dst_unused:UNUSED_PAD src0_sel:WORD_1
	v_max_f32_e32 v48, 0xda24260, v56
	v_rcp_f32_e32 v64, v48
	v_max_f32_e32 v48, 0xda24260, v57
	v_rcp_f32_e32 v65, v48
	v_cvt_f32_f16_e32 v48, v53
	v_pk_mul_f32 v[66:67], v[56:57], v[58:59]
	v_pk_mul_f32 v[62:63], v[64:65], v[62:63]
	v_cvt_f32_f16_sdwa v65, v49 dst_sel:DWORD dst_unused:UNUSED_PAD src0_sel:WORD_1
	v_cvt_f32_f16_e32 v64, v49
	v_cvt_f32_f16_sdwa v49, v53 dst_sel:DWORD dst_unused:UNUSED_PAD src0_sel:WORD_1
	v_cvt_f32_f16_e32 v70, v50
	v_cvt_f32_f16_sdwa v77, v55 dst_sel:DWORD dst_unused:UNUSED_PAD src0_sel:WORD_1
	v_pk_add_f32 v[52:53], v[48:49], 1.0 op_sel_hi:[1,0] neg_lo:[1,0] neg_hi:[1,0]
	v_cvt_f32_f16_e32 v76, v55
	s_nop 0
	v_mul_f32_dpp v52, v52, v52 row_shr:1 row_mask:0xf bank_mask:0xf
	v_mul_f32_dpp v53, v53, v53 row_shr:1 row_mask:0xf bank_mask:0xf
	s_nop 0
	v_mul_f32_dpp v52, v52, v52 row_shr:2 row_mask:0xf bank_mask:0xf
	v_mul_f32_dpp v53, v53, v53 row_shr:2 row_mask:0xf bank_mask:0xf
	v_cvt_pk_bf16_f32 v62, v62, v63
	v_mul_f32_dpp v52, v52, v52 row_shr:4 row_mask:0xf bank_mask:0xf
	v_mul_f32_dpp v53, v53, v53 row_shr:4 row_mask:0xf bank_mask:0xf
	v_cvt_pk_bf16_f32 v66, v66, v67
	v_mul_f32_dpp v52, v52, v52 row_shr:8 row_mask:0xf bank_mask:0xf
	v_mul_f32_dpp v53, v53, v53 row_shr:8 row_mask:0xf bank_mask:0xf
	v_mov_b64_e32 v[58:59], v[52:53]
	s_nop 0
	v_max_f32_e32 v52, 0xda24260, v58
	v_max_f32_e32 v53, 0xda24260, v59
	v_rcp_f32_e32 v52, v52
	v_rcp_f32_e32 v53, v53
	v_pk_mul_f32 v[64:65], v[58:59], v[64:65]
	v_pk_mul_f32 v[52:53], v[52:53], v[48:49]
	v_pk_add_f32 v[48:49], v[72:73], 1.0 op_sel_hi:[1,0] neg_lo:[1,0] neg_hi:[1,0]
	v_cvt_pk_bf16_f32 v63, v52, v53
	v_cvt_pk_bf16_f32 v67, v64, v65
	v_mul_f32_dpp v48, v48, v48 row_shr:1 row_mask:0xf bank_mask:0xf
	v_mul_f32_dpp v49, v49, v49 row_shr:1 row_mask:0xf bank_mask:0xf
	s_nop 0
	v_mul_f32_dpp v48, v48, v48 row_shr:2 row_mask:0xf bank_mask:0xf
	v_mul_f32_dpp v49, v49, v49 row_shr:2 row_mask:0xf bank_mask:0xf
	s_nop 0
	v_mul_f32_dpp v48, v48, v48 row_shr:4 row_mask:0xf bank_mask:0xf
	v_mul_f32_dpp v49, v49, v49 row_shr:4 row_mask:0xf bank_mask:0xf
	s_nop 0
	v_mul_f32_dpp v48, v48, v48 row_shr:8 row_mask:0xf bank_mask:0xf
	v_mul_f32_dpp v49, v49, v49 row_shr:8 row_mask:0xf bank_mask:0xf
	s_nop 0
	v_max_f32_e32 v50, 0xda24260, v48
	v_rcp_f32_e32 v74, v50
	v_max_f32_e32 v50, 0xda24260, v49
	v_rcp_f32_e32 v75, v50
	v_pk_mul_f32 v[70:71], v[48:49], v[70:71]
	v_pk_mul_f32 v[72:73], v[74:75], v[72:73]
	v_cvt_f32_f16_sdwa v75, v51 dst_sel:DWORD dst_unused:UNUSED_PAD src0_sel:WORD_1
	v_cvt_f32_f16_e32 v74, v51
	v_pk_add_f32 v[50:51], v[76:77], 1.0 op_sel_hi:[1,0] neg_lo:[1,0] neg_hi:[1,0]
	v_cvt_pk_bf16_f32 v64, v70, v71
	v_cvt_pk_bf16_f32 v52, v72, v73
	v_mul_f32_dpp v50, v50, v50 row_shr:1 row_mask:0xf bank_mask:0xf
	v_mul_f32_dpp v51, v51, v51 row_shr:1 row_mask:0xf bank_mask:0xf
	s_nop 0
	v_mul_f32_dpp v50, v50, v50 row_shr:2 row_mask:0xf bank_mask:0xf
	v_mul_f32_dpp v51, v51, v51 row_shr:2 row_mask:0xf bank_mask:0xf
	s_nop 0
	v_mul_f32_dpp v50, v50, v50 row_shr:4 row_mask:0xf bank_mask:0xf
	v_mul_f32_dpp v51, v51, v51 row_shr:4 row_mask:0xf bank_mask:0xf
	s_nop 0
	v_mul_f32_dpp v50, v50, v50 row_shr:8 row_mask:0xf bank_mask:0xf
	v_mul_f32_dpp v51, v51, v51 row_shr:8 row_mask:0xf bank_mask:0xf
	s_nop 0
	v_max_f32_e32 v54, 0xda24260, v50
	v_max_f32_e32 v55, 0xda24260, v51
	v_rcp_f32_e32 v54, v54
	v_rcp_f32_e32 v55, v55
	v_pk_mul_f32 v[74:75], v[50:51], v[74:75]
	v_pk_mul_f32 v[54:55], v[54:55], v[76:77]
	s_nop 0
	v_cvt_pk_bf16_f32 v53, v54, v55
	v_add_u32_e32 v54, v85, v136
	v_cvt_pk_bf16_f32 v65, v74, v75
	v_add_u32_e32 v55, 0xc000, v54
	v_add_u32_e32 v54, 0xe100, v54
	ds_write2_b64 v55, v[66:67], v[64:65] offset1:1
	ds_write2_b64 v54, v[62:63], v[52:53] offset1:1
	v_lshl_add_u32 v52, v88, 2, 0
	s_and_saveexec_b64 s[10:11], s[8:9]
	s_cbranch_execz .LBB0_628
	v_add_u32_e32 v53, 0x12c00, v52
	ds_write_b128 v53, v[56:59]
	ds_write_b128 v53, v[48:51] offset:16
; __device__ __forceinline__ unsigned pk2(float lo, float hi) { f32x2n v = {lo, hi}; bf16x2n b = __builtin_convertvector(v, bf16x2n); return __builtin_bit_cast(unsigned, b); }
;   template <int CTRL> static __device__ __forceinline__ float shr1(float x) { return __int_as_float(__builtin_amdgcn_update_dpp(__float_as_int(1.0f), __float_as_int(x), CTRL, 0xF, 0xF, false)); }
;   static __device__ __forceinline__ float scan16(float x) { x *= shr1<0x111>(x); x *= shr1<0x112>(x); x *= shr1<0x114>(x); x *= shr1<0x118>(x); return x; }
;   __device__ __forceinline__ void hg_prep(const h16x8 (&q)[8], const h16x8 (&u)[8], int tb) const { unsigned char* tl = smem + SC_TL + tb * SC_TLB; const int rho = lane >> 4, tau = lane & 15;
; #pragma unroll
;     for (int it = 0; it < 8; ++it) { const int bidx = it * 4 + rho, sc = bidx >> 4, k0 = (bidx & 15) * 8, st = sc * 16 + tau;
;       float G[8], qt[8], kt[8];
; #pragma unroll
;       for (int e = 0; e < 8; ++e) { const float uu = (float)u[it][e]; G[e] = scan16(1.f - uu); qt[e] = (float)q[it][e] * G[e]; kt[e] = uu * __builtin_amdgcn_rcpf(fmaxf(G[e], 1e-30f)); }
;       u32x2 a, b, c2, d; a.x = pk2(qt[0], qt[1]); a.y = pk2(qt[2], qt[3]); b.x = pk2(qt[4], qt[5]); b.y = pk2(qt[6], qt[7]);
;       c2.x = pk2(kt[0], kt[1]); c2.y = pk2(kt[2], kt[3]); d.x = pk2(kt[4], kt[5]); d.y = pk2(kt[6], kt[7]);
;       unsigned char* oq = tl + TL_HQ + st * HQS + k0 * 2; unsigned char* ok = tl + TL_HK + st * HQS + k0 * 2;
;       *(u32x2*)oq = a; *(u32x2*)(oq + 8) = b; *(u32x2*)ok = c2; *(u32x2*)(ok + 8) = d;
;       if (tau == 15) { float* ge = (float*)(tl + TL_HGE) + sc * 128 + k0; *(f32x4*)ge = (f32x4){G[0], G[1], G[2], G[3]}; *(f32x4*)(ge + 4) = (f32x4){G[4], G[5], G[6], G[7]}; } } }
.LBB0_628:
	s_or_b64 exec, exec, s[10:11]
	s_waitcnt vmcnt(6)
	v_cvt_f32_f16_sdwa v55, v40 dst_sel:DWORD dst_unused:UNUSED_PAD src0_sel:WORD_1
	v_cvt_f32_f16_e32 v54, v40
	v_cvt_f32_f16_sdwa v51, v44 dst_sel:DWORD dst_unused:UNUSED_PAD src0_sel:WORD_1
	v_pk_add_f32 v[48:49], v[54:55], 1.0 op_sel_hi:[1,0] neg_lo:[1,0] neg_hi:[1,0]
	v_cvt_f32_f16_e32 v50, v44
	v_cvt_f32_f16_e32 v44, v41
	v_mul_f32_dpp v48, v48, v48 row_shr:1 row_mask:0xf bank_mask:0xf
	v_mul_f32_dpp v49, v49, v49 row_shr:1 row_mask:0xf bank_mask:0xf
	v_cvt_f32_f16_sdwa v65, v42 dst_sel:DWORD dst_unused:UNUSED_PAD src0_sel:WORD_1
	v_mul_f32_dpp v48, v48, v48 row_shr:2 row_mask:0xf bank_mask:0xf
	v_mul_f32_dpp v49, v49, v49 row_shr:2 row_mask:0xf bank_mask:0xf
	v_cvt_f32_f16_e32 v64, v42
	v_mul_f32_dpp v48, v48, v48 row_shr:4 row_mask:0xf bank_mask:0xf
	v_mul_f32_dpp v49, v49, v49 row_shr:4 row_mask:0xf bank_mask:0xf
	s_nop 0
	v_mul_f32_dpp v48, v48, v48 row_shr:8 row_mask:0xf bank_mask:0xf
	v_mul_f32_dpp v49, v49, v49 row_shr:8 row_mask:0xf bank_mask:0xf
	v_max_f32_e32 v40, 0xda24260, v48
	v_rcp_f32_e32 v56, v40
	v_max_f32_e32 v40, 0xda24260, v49
	v_rcp_f32_e32 v57, v40
	v_pk_mul_f32 v[58:59], v[48:49], v[50:51]
	v_pk_mul_f32 v[54:55], v[56:57], v[54:55]
	v_cvt_f32_f16_sdwa v57, v45 dst_sel:DWORD dst_unused:UNUSED_PAD src0_sel:WORD_1
	v_cvt_f32_f16_e32 v56, v45
	v_cvt_f32_f16_sdwa v45, v41 dst_sel:DWORD dst_unused:UNUSED_PAD src0_sel:WORD_1
	v_cvt_f32_f16_sdwa v63, v46 dst_sel:DWORD dst_unused:UNUSED_PAD src0_sel:WORD_1
	v_cvt_f32_f16_e32 v62, v46
	v_cvt_f32_f16_e32 v46, v43
	v_pk_add_f32 v[40:41], v[44:45], 1.0 op_sel_hi:[1,0] neg_lo:[1,0] neg_hi:[1,0]
	s_nop 1
	v_mul_f32_dpp v40, v40, v40 row_shr:1 row_mask:0xf bank_mask:0xf
	v_mul_f32_dpp v41, v41, v41 row_shr:1 row_mask:0xf bank_mask:0xf
	s_movk_i32 s10, 0x108
	v_mul_f32_dpp v40, v40, v40 row_shr:2 row_mask:0xf bank_mask:0xf
	v_mul_f32_dpp v41, v41, v41 row_shr:2 row_mask:0xf bank_mask:0xf
	v_cvt_pk_bf16_f32 v54, v54, v55
	v_mul_f32_dpp v40, v40, v40 row_shr:4 row_mask:0xf bank_mask:0xf
	v_mul_f32_dpp v41, v41, v41 row_shr:4 row_mask:0xf bank_mask:0xf
	v_cvt_pk_bf16_f32 v58, v58, v59
	v_mul_f32_dpp v40, v40, v40 row_shr:8 row_mask:0xf bank_mask:0xf
	v_mul_f32_dpp v41, v41, v41 row_shr:8 row_mask:0xf bank_mask:0xf
	v_mov_b64_e32 v[50:51], v[40:41]
	s_nop 0
	v_max_f32_e32 v40, 0xda24260, v50
	v_max_f32_e32 v41, 0xda24260, v51
	v_rcp_f32_e32 v40, v40
	v_rcp_f32_e32 v41, v41
	v_pk_mul_f32 v[56:57], v[50:51], v[56:57]
	v_pk_mul_f32 v[44:45], v[40:41], v[44:45]
	v_pk_add_f32 v[40:41], v[64:65], 1.0 op_sel_hi:[1,0] neg_lo:[1,0] neg_hi:[1,0]
	v_cvt_pk_bf16_f32 v55, v44, v45
	v_mad_u32_u24 v44, v105, s10, 0
	v_mul_f32_dpp v40, v40, v40 row_shr:1 row_mask:0xf bank_mask:0xf
	v_mul_f32_dpp v41, v41, v41 row_shr:1 row_mask:0xf bank_mask:0xf
	v_add_u32_e32 v45, v44, v103
	v_mul_f32_dpp v40, v40, v40 row_shr:2 row_mask:0xf bank_mask:0xf
	v_mul_f32_dpp v41, v41, v41 row_shr:2 row_mask:0xf bank_mask:0xf
	v_cvt_pk_bf16_f32 v59, v56, v57
	v_mul_f32_dpp v40, v40, v40 row_shr:4 row_mask:0xf bank_mask:0xf
	v_mul_f32_dpp v41, v41, v41 row_shr:4 row_mask:0xf bank_mask:0xf
	s_nop 0
	v_mul_f32_dpp v40, v40, v40 row_shr:8 row_mask:0xf bank_mask:0xf
	v_mul_f32_dpp v41, v41, v41 row_shr:8 row_mask:0xf bank_mask:0xf
	s_nop 0
	v_max_f32_e32 v42, 0xda24260, v40
	v_rcp_f32_e32 v66, v42
	v_max_f32_e32 v42, 0xda24260, v41
	v_rcp_f32_e32 v67, v42
	v_pk_mul_f32 v[62:63], v[40:41], v[62:63]
	v_pk_mul_f32 v[64:65], v[66:67], v[64:65]
	v_cvt_f32_f16_sdwa v67, v47 dst_sel:DWORD dst_unused:UNUSED_PAD src0_sel:WORD_1
	v_cvt_f32_f16_e32 v66, v47
	v_cvt_f32_f16_sdwa v47, v43 dst_sel:DWORD dst_unused:UNUSED_PAD src0_sel:WORD_1
	v_cvt_pk_bf16_f32 v56, v62, v63
	v_cvt_pk_bf16_f32 v62, v64, v65
	v_pk_add_f32 v[42:43], v[46:47], 1.0 op_sel_hi:[1,0] neg_lo:[1,0] neg_hi:[1,0]
	s_nop 1
	v_mul_f32_dpp v42, v42, v42 row_shr:1 row_mask:0xf bank_mask:0xf
	v_mul_f32_dpp v43, v43, v43 row_shr:1 row_mask:0xf bank_mask:0xf
	s_nop 0
	v_mul_f32_dpp v42, v42, v42 row_shr:2 row_mask:0xf bank_mask:0xf
	v_mul_f32_dpp v43, v43, v43 row_shr:2 row_mask:0xf bank_mask:0xf
	s_nop 0
	v_mul_f32_dpp v42, v42, v42 row_shr:4 row_mask:0xf bank_mask:0xf
	v_mul_f32_dpp v43, v43, v43 row_shr:4 row_mask:0xf bank_mask:0xf
	s_nop 0
	v_mul_f32_dpp v42, v42, v42 row_shr:8 row_mask:0xf bank_mask:0xf
	v_mul_f32_dpp v43, v43, v43 row_shr:8 row_mask:0xf bank_mask:0xf
	s_nop 0
	v_max_f32_e32 v53, 0xda24260, v42
	v_rcp_f32_e32 v70, v53
	v_max_f32_e32 v53, 0xda24260, v43
	v_rcp_f32_e32 v71, v53
	v_pk_mul_f32 v[66:67], v[42:43], v[66:67]
	v_pk_mul_f32 v[46:47], v[70:71], v[46:47]
	v_cvt_pk_bf16_f32 v57, v66, v67
	v_cvt_pk_bf16_f32 v63, v46, v47
	v_add_u32_e32 v46, 0xc000, v45
	v_add_u32_e32 v45, 0xe100, v45
	ds_write2_b64 v46, v[58:59], v[56:57] offset1:1
	ds_write2_b64 v45, v[54:55], v[62:63] offset1:1
	s_and_saveexec_b64 s[10:11], s[8:9]
	s_cbranch_execz .LBB0_630
	v_add_u32_e32 v45, 0x12e00, v84
	ds_write_b128 v45, v[48:51]
	ds_write_b128 v45, v[40:43] offset:16
; __device__ __forceinline__ unsigned pk2(float lo, float hi) { f32x2n v = {lo, hi}; bf16x2n b = __builtin_convertvector(v, bf16x2n); return __builtin_bit_cast(unsigned, b); }
;   template <int CTRL> static __device__ __forceinline__ float shr1(float x) { return __int_as_float(__builtin_amdgcn_update_dpp(__float_as_int(1.0f), __float_as_int(x), CTRL, 0xF, 0xF, false)); }
;   static __device__ __forceinline__ float scan16(float x) { x *= shr1<0x111>(x); x *= shr1<0x112>(x); x *= shr1<0x114>(x); x *= shr1<0x118>(x); return x; }
;   __device__ __forceinline__ void hg_prep(const h16x8 (&q)[8], const h16x8 (&u)[8], int tb) const { unsigned char* tl = smem + SC_TL + tb * SC_TLB; const int rho = lane >> 4, tau = lane & 15;
; #pragma unroll
;     for (int it = 0; it < 8; ++it) { const int bidx = it * 4 + rho, sc = bidx >> 4, k0 = (bidx & 15) * 8, st = sc * 16 + tau;
;       float G[8], qt[8], kt[8];
; #pragma unroll
;       for (int e = 0; e < 8; ++e) { const float uu = (float)u[it][e]; G[e] = scan16(1.f - uu); qt[e] = (float)q[it][e] * G[e]; kt[e] = uu * __builtin_amdgcn_rcpf(fmaxf(G[e], 1e-30f)); }
;       u32x2 a, b, c2, d; a.x = pk2(qt[0], qt[1]); a.y = pk2(qt[2], qt[3]); b.x = pk2(qt[4], qt[5]); b.y = pk2(qt[6], qt[7]);
;       c2.x = pk2(kt[0], kt[1]); c2.y = pk2(kt[2], kt[3]); d.x = pk2(kt[4], kt[5]); d.y = pk2(kt[6], kt[7]);
;       unsigned char* oq = tl + TL_HQ + st * HQS + k0 * 2; unsigned char* ok = tl + TL_HK + st * HQS + k0 * 2;
;       *(u32x2*)oq = a; *(u32x2*)(oq + 8) = b; *(u32x2*)ok = c2; *(u32x2*)(ok + 8) = d;
;       if (tau == 15) { float* ge = (float*)(tl + TL_HGE) + sc * 128 + k0; *(f32x4*)ge = (f32x4){G[0], G[1], G[2], G[3]}; *(f32x4*)(ge + 4) = (f32x4){G[4], G[5], G[6], G[7]}; } } }
.LBB0_630:
	s_or_b64 exec, exec, s[10:11]
	s_waitcnt vmcnt(4)
	v_cvt_f32_f16_sdwa v47, v32 dst_sel:DWORD dst_unused:UNUSED_PAD src0_sel:WORD_1
	v_cvt_f32_f16_e32 v46, v32
	v_cvt_f32_f16_sdwa v43, v36 dst_sel:DWORD dst_unused:UNUSED_PAD src0_sel:WORD_1
	v_pk_add_f32 v[40:41], v[46:47], 1.0 op_sel_hi:[1,0] neg_lo:[1,0] neg_hi:[1,0]
	v_cvt_f32_f16_e32 v42, v36
	v_cvt_f32_f16_e32 v36, v33
	v_mul_f32_dpp v40, v40, v40 row_shr:1 row_mask:0xf bank_mask:0xf
	v_mul_f32_dpp v41, v41, v41 row_shr:1 row_mask:0xf bank_mask:0xf
	v_cvt_f32_f16_sdwa v57, v34 dst_sel:DWORD dst_unused:UNUSED_PAD src0_sel:WORD_1
	v_mul_f32_dpp v40, v40, v40 row_shr:2 row_mask:0xf bank_mask:0xf
	v_mul_f32_dpp v41, v41, v41 row_shr:2 row_mask:0xf bank_mask:0xf
	v_cvt_f32_f16_e32 v56, v34
	v_mul_f32_dpp v40, v40, v40 row_shr:4 row_mask:0xf bank_mask:0xf
	v_mul_f32_dpp v41, v41, v41 row_shr:4 row_mask:0xf bank_mask:0xf
	s_nop 0
	v_mul_f32_dpp v40, v40, v40 row_shr:8 row_mask:0xf bank_mask:0xf
	v_mul_f32_dpp v41, v41, v41 row_shr:8 row_mask:0xf bank_mask:0xf
	v_max_f32_e32 v32, 0xda24260, v40
	v_rcp_f32_e32 v48, v32
	v_max_f32_e32 v32, 0xda24260, v41
	v_rcp_f32_e32 v49, v32
	v_pk_mul_f32 v[50:51], v[40:41], v[42:43]
	v_pk_mul_f32 v[46:47], v[48:49], v[46:47]
	v_cvt_f32_f16_sdwa v49, v37 dst_sel:DWORD dst_unused:UNUSED_PAD src0_sel:WORD_1
	v_cvt_f32_f16_e32 v48, v37
	v_cvt_f32_f16_sdwa v37, v33 dst_sel:DWORD dst_unused:UNUSED_PAD src0_sel:WORD_1
	v_cvt_f32_f16_sdwa v55, v38 dst_sel:DWORD dst_unused:UNUSED_PAD src0_sel:WORD_1
	v_cvt_f32_f16_e32 v54, v38
	v_cvt_f32_f16_e32 v38, v35
	v_pk_add_f32 v[32:33], v[36:37], 1.0 op_sel_hi:[1,0] neg_lo:[1,0] neg_hi:[1,0]
	s_nop 1
	v_mul_f32_dpp v32, v32, v32 row_shr:1 row_mask:0xf bank_mask:0xf
	v_mul_f32_dpp v33, v33, v33 row_shr:1 row_mask:0xf bank_mask:0xf
	v_cvt_pk_bf16_f32 v46, v46, v47
	v_mul_f32_dpp v32, v32, v32 row_shr:2 row_mask:0xf bank_mask:0xf
	v_mul_f32_dpp v33, v33, v33 row_shr:2 row_mask:0xf bank_mask:0xf
	v_cvt_pk_bf16_f32 v50, v50, v51
	v_mul_f32_dpp v32, v32, v32 row_shr:4 row_mask:0xf bank_mask:0xf
	v_mul_f32_dpp v33, v33, v33 row_shr:4 row_mask:0xf bank_mask:0xf
	s_nop 0
	v_mul_f32_dpp v32, v32, v32 row_shr:8 row_mask:0xf bank_mask:0xf
	v_mul_f32_dpp v33, v33, v33 row_shr:8 row_mask:0xf bank_mask:0xf
	v_mov_b64_e32 v[42:43], v[32:33]
	s_nop 0
	v_max_f32_e32 v32, 0xda24260, v42
	v_max_f32_e32 v33, 0xda24260, v43
	v_rcp_f32_e32 v32, v32
	v_rcp_f32_e32 v33, v33
	v_pk_mul_f32 v[48:49], v[42:43], v[48:49]
	v_pk_mul_f32 v[36:37], v[32:33], v[36:37]
	v_pk_add_f32 v[32:33], v[56:57], 1.0 op_sel_hi:[1,0] neg_lo:[1,0] neg_hi:[1,0]
	v_cvt_pk_bf16_f32 v47, v36, v37
	v_cvt_pk_bf16_f32 v51, v48, v49
	v_mul_f32_dpp v32, v32, v32 row_shr:1 row_mask:0xf bank_mask:0xf
	v_mul_f32_dpp v33, v33, v33 row_shr:1 row_mask:0xf bank_mask:0xf
	s_nop 0
	v_mul_f32_dpp v32, v32, v32 row_shr:2 row_mask:0xf bank_mask:0xf
	v_mul_f32_dpp v33, v33, v33 row_shr:2 row_mask:0xf bank_mask:0xf
	s_nop 0
	v_mul_f32_dpp v32, v32, v32 row_shr:4 row_mask:0xf bank_mask:0xf
	v_mul_f32_dpp v33, v33, v33 row_shr:4 row_mask:0xf bank_mask:0xf
	s_nop 0
	v_mul_f32_dpp v32, v32, v32 row_shr:8 row_mask:0xf bank_mask:0xf
	v_mul_f32_dpp v33, v33, v33 row_shr:8 row_mask:0xf bank_mask:0xf
	s_nop 0
	v_max_f32_e32 v34, 0xda24260, v32
	v_rcp_f32_e32 v58, v34
	v_max_f32_e32 v34, 0xda24260, v33
	v_rcp_f32_e32 v59, v34
	v_pk_mul_f32 v[54:55], v[32:33], v[54:55]
	v_pk_mul_f32 v[56:57], v[58:59], v[56:57]
	v_cvt_f32_f16_sdwa v59, v39 dst_sel:DWORD dst_unused:UNUSED_PAD src0_sel:WORD_1
	v_cvt_f32_f16_e32 v58, v39
	v_cvt_f32_f16_sdwa v39, v35 dst_sel:DWORD dst_unused:UNUSED_PAD src0_sel:WORD_1
	v_cvt_pk_bf16_f32 v48, v54, v55
	v_cvt_pk_bf16_f32 v36, v56, v57
	v_pk_add_f32 v[34:35], v[38:39], 1.0 op_sel_hi:[1,0] neg_lo:[1,0] neg_hi:[1,0]
	s_nop 1
	v_mul_f32_dpp v34, v34, v34 row_shr:1 row_mask:0xf bank_mask:0xf
	v_mul_f32_dpp v35, v35, v35 row_shr:1 row_mask:0xf bank_mask:0xf
	s_nop 0
	v_mul_f32_dpp v34, v34, v34 row_shr:2 row_mask:0xf bank_mask:0xf
	v_mul_f32_dpp v35, v35, v35 row_shr:2 row_mask:0xf bank_mask:0xf
	s_nop 0
	v_mul_f32_dpp v34, v34, v34 row_shr:4 row_mask:0xf bank_mask:0xf
	v_mul_f32_dpp v35, v35, v35 row_shr:4 row_mask:0xf bank_mask:0xf
	s_nop 0
	v_mul_f32_dpp v34, v34, v34 row_shr:8 row_mask:0xf bank_mask:0xf
	v_mul_f32_dpp v35, v35, v35 row_shr:8 row_mask:0xf bank_mask:0xf
	s_nop 0
	v_max_f32_e32 v45, 0xda24260, v34
	v_rcp_f32_e32 v62, v45
	v_max_f32_e32 v45, 0xda24260, v35
	v_rcp_f32_e32 v63, v45
	v_pk_mul_f32 v[58:59], v[34:35], v[58:59]
	v_pk_mul_f32 v[38:39], v[62:63], v[38:39]
	s_nop 0
	v_cvt_pk_bf16_f32 v37, v38, v39
	v_add_u32_e32 v38, v44, v134
	v_cvt_pk_bf16_f32 v49, v58, v59
	v_add_u32_e32 v39, 0xc000, v38
	v_add_u32_e32 v38, 0xe100, v38
	ds_write2_b64 v39, v[50:51], v[48:49] offset1:1
	ds_write2_b64 v38, v[46:47], v[36:37] offset1:1
	s_and_saveexec_b64 s[10:11], s[8:9]
	s_cbranch_execz .LBB0_632
	v_add_u32_e32 v36, 0x12e00, v68
	ds_write_b128 v36, v[40:43]
	ds_write_b128 v36, v[32:35] offset:16
; __device__ __forceinline__ unsigned pk2(float lo, float hi) { f32x2n v = {lo, hi}; bf16x2n b = __builtin_convertvector(v, bf16x2n); return __builtin_bit_cast(unsigned, b); }
;   template <int CTRL> static __device__ __forceinline__ float shr1(float x) { return __int_as_float(__builtin_amdgcn_update_dpp(__float_as_int(1.0f), __float_as_int(x), CTRL, 0xF, 0xF, false)); }
;   static __device__ __forceinline__ float scan16(float x) { x *= shr1<0x111>(x); x *= shr1<0x112>(x); x *= shr1<0x114>(x); x *= shr1<0x118>(x); return x; }
;   __device__ __forceinline__ void hg_prep(const h16x8 (&q)[8], const h16x8 (&u)[8], int tb) const { unsigned char* tl = smem + SC_TL + tb * SC_TLB; const int rho = lane >> 4, tau = lane & 15;
; #pragma unroll
;     for (int it = 0; it < 8; ++it) { const int bidx = it * 4 + rho, sc = bidx >> 4, k0 = (bidx & 15) * 8, st = sc * 16 + tau;
;       float G[8], qt[8], kt[8];
; #pragma unroll
;       for (int e = 0; e < 8; ++e) { const float uu = (float)u[it][e]; G[e] = scan16(1.f - uu); qt[e] = (float)q[it][e] * G[e]; kt[e] = uu * __builtin_amdgcn_rcpf(fmaxf(G[e], 1e-30f)); }
;       u32x2 a, b, c2, d; a.x = pk2(qt[0], qt[1]); a.y = pk2(qt[2], qt[3]); b.x = pk2(qt[4], qt[5]); b.y = pk2(qt[6], qt[7]);
;       c2.x = pk2(kt[0], kt[1]); c2.y = pk2(kt[2], kt[3]); d.x = pk2(kt[4], kt[5]); d.y = pk2(kt[6], kt[7]);
;       unsigned char* oq = tl + TL_HQ + st * HQS + k0 * 2; unsigned char* ok = tl + TL_HK + st * HQS + k0 * 2;
;       *(u32x2*)oq = a; *(u32x2*)(oq + 8) = b; *(u32x2*)ok = c2; *(u32x2*)(ok + 8) = d;
;       if (tau == 15) { float* ge = (float*)(tl + TL_HGE) + sc * 128 + k0; *(f32x4*)ge = (f32x4){G[0], G[1], G[2], G[3]}; *(f32x4*)(ge + 4) = (f32x4){G[4], G[5], G[6], G[7]}; } } }
.LBB0_632:
	s_or_b64 exec, exec, s[10:11]
	s_waitcnt vmcnt(2)
	v_cvt_f32_f16_sdwa v37, v24 dst_sel:DWORD dst_unused:UNUSED_PAD src0_sel:WORD_1
	v_cvt_f32_f16_e32 v36, v24
	v_cvt_f32_f16_sdwa v35, v28 dst_sel:DWORD dst_unused:UNUSED_PAD src0_sel:WORD_1
	v_pk_add_f32 v[32:33], v[36:37], 1.0 op_sel_hi:[1,0] neg_lo:[1,0] neg_hi:[1,0]
	v_cvt_f32_f16_e32 v34, v28
	v_cvt_f32_f16_e32 v28, v25
	v_mul_f32_dpp v32, v32, v32 row_shr:1 row_mask:0xf bank_mask:0xf
	v_mul_f32_dpp v33, v33, v33 row_shr:1 row_mask:0xf bank_mask:0xf
	v_cvt_f32_f16_sdwa v47, v26 dst_sel:DWORD dst_unused:UNUSED_PAD src0_sel:WORD_1
	v_mul_f32_dpp v32, v32, v32 row_shr:2 row_mask:0xf bank_mask:0xf
	v_mul_f32_dpp v33, v33, v33 row_shr:2 row_mask:0xf bank_mask:0xf
	v_cvt_f32_f16_e32 v46, v26
	v_mul_f32_dpp v32, v32, v32 row_shr:4 row_mask:0xf bank_mask:0xf
	v_mul_f32_dpp v33, v33, v33 row_shr:4 row_mask:0xf bank_mask:0xf
	s_nop 0
	v_mul_f32_dpp v32, v32, v32 row_shr:8 row_mask:0xf bank_mask:0xf
	v_mul_f32_dpp v33, v33, v33 row_shr:8 row_mask:0xf bank_mask:0xf
	v_max_f32_e32 v24, 0xda24260, v32
	v_rcp_f32_e32 v38, v24
	v_max_f32_e32 v24, 0xda24260, v33
	v_rcp_f32_e32 v39, v24
	v_pk_mul_f32 v[40:41], v[32:33], v[34:35]
	v_pk_mul_f32 v[36:37], v[38:39], v[36:37]
	v_cvt_f32_f16_sdwa v39, v29 dst_sel:DWORD dst_unused:UNUSED_PAD src0_sel:WORD_1
	v_cvt_f32_f16_e32 v38, v29
	v_cvt_f32_f16_sdwa v29, v25 dst_sel:DWORD dst_unused:UNUSED_PAD src0_sel:WORD_1
	v_cvt_f32_f16_sdwa v43, v30 dst_sel:DWORD dst_unused:UNUSED_PAD src0_sel:WORD_1
	v_cvt_f32_f16_e32 v42, v30
	v_cvt_f32_f16_e32 v30, v27
	v_pk_add_f32 v[24:25], v[28:29], 1.0 op_sel_hi:[1,0] neg_lo:[1,0] neg_hi:[1,0]
	s_nop 1
	v_mul_f32_dpp v24, v24, v24 row_shr:1 row_mask:0xf bank_mask:0xf
	v_mul_f32_dpp v25, v25, v25 row_shr:1 row_mask:0xf bank_mask:0xf
	v_cvt_pk_bf16_f32 v36, v36, v37
	v_mul_f32_dpp v24, v24, v24 row_shr:2 row_mask:0xf bank_mask:0xf
	v_mul_f32_dpp v25, v25, v25 row_shr:2 row_mask:0xf bank_mask:0xf
	v_cvt_pk_bf16_f32 v40, v40, v41
	v_mul_f32_dpp v24, v24, v24 row_shr:4 row_mask:0xf bank_mask:0xf
	v_mul_f32_dpp v25, v25, v25 row_shr:4 row_mask:0xf bank_mask:0xf
	s_nop 0
	v_mul_f32_dpp v24, v24, v24 row_shr:8 row_mask:0xf bank_mask:0xf
	v_mul_f32_dpp v25, v25, v25 row_shr:8 row_mask:0xf bank_mask:0xf
	v_mov_b64_e32 v[34:35], v[24:25]
	s_nop 0
	v_max_f32_e32 v24, 0xda24260, v34
	v_max_f32_e32 v25, 0xda24260, v35
	v_rcp_f32_e32 v24, v24
	v_rcp_f32_e32 v25, v25
	v_pk_mul_f32 v[38:39], v[34:35], v[38:39]
	v_pk_mul_f32 v[28:29], v[24:25], v[28:29]
	v_pk_add_f32 v[24:25], v[46:47], 1.0 op_sel_hi:[1,0] neg_lo:[1,0] neg_hi:[1,0]
	v_cvt_pk_bf16_f32 v37, v28, v29
	v_cvt_pk_bf16_f32 v41, v38, v39
	v_mul_f32_dpp v24, v24, v24 row_shr:1 row_mask:0xf bank_mask:0xf
	v_mul_f32_dpp v25, v25, v25 row_shr:1 row_mask:0xf bank_mask:0xf
	s_nop 0
	v_mul_f32_dpp v24, v24, v24 row_shr:2 row_mask:0xf bank_mask:0xf
	v_mul_f32_dpp v25, v25, v25 row_shr:2 row_mask:0xf bank_mask:0xf
	s_nop 0
	v_mul_f32_dpp v24, v24, v24 row_shr:4 row_mask:0xf bank_mask:0xf
	v_mul_f32_dpp v25, v25, v25 row_shr:4 row_mask:0xf bank_mask:0xf
	s_nop 0
	v_mul_f32_dpp v24, v24, v24 row_shr:8 row_mask:0xf bank_mask:0xf
	v_mul_f32_dpp v25, v25, v25 row_shr:8 row_mask:0xf bank_mask:0xf
	s_nop 0
	v_max_f32_e32 v26, 0xda24260, v24
	v_rcp_f32_e32 v48, v26
	v_max_f32_e32 v26, 0xda24260, v25
	v_rcp_f32_e32 v49, v26
	v_pk_mul_f32 v[42:43], v[24:25], v[42:43]
	v_pk_mul_f32 v[46:47], v[48:49], v[46:47]
	v_cvt_f32_f16_sdwa v49, v31 dst_sel:DWORD dst_unused:UNUSED_PAD src0_sel:WORD_1
	v_cvt_f32_f16_e32 v48, v31
	v_cvt_f32_f16_sdwa v31, v27 dst_sel:DWORD dst_unused:UNUSED_PAD src0_sel:WORD_1
	v_cvt_pk_bf16_f32 v38, v42, v43
	v_cvt_pk_bf16_f32 v28, v46, v47
	v_pk_add_f32 v[26:27], v[30:31], 1.0 op_sel_hi:[1,0] neg_lo:[1,0] neg_hi:[1,0]
	s_nop 1
	v_mul_f32_dpp v26, v26, v26 row_shr:1 row_mask:0xf bank_mask:0xf
	v_mul_f32_dpp v27, v27, v27 row_shr:1 row_mask:0xf bank_mask:0xf
	s_nop 0
	v_mul_f32_dpp v26, v26, v26 row_shr:2 row_mask:0xf bank_mask:0xf
	v_mul_f32_dpp v27, v27, v27 row_shr:2 row_mask:0xf bank_mask:0xf
	s_nop 0
	v_mul_f32_dpp v26, v26, v26 row_shr:4 row_mask:0xf bank_mask:0xf
	v_mul_f32_dpp v27, v27, v27 row_shr:4 row_mask:0xf bank_mask:0xf
	s_nop 0
	v_mul_f32_dpp v26, v26, v26 row_shr:8 row_mask:0xf bank_mask:0xf
	v_mul_f32_dpp v27, v27, v27 row_shr:8 row_mask:0xf bank_mask:0xf
	s_nop 0
	v_max_f32_e32 v45, 0xda24260, v26
	v_rcp_f32_e32 v50, v45
	v_max_f32_e32 v45, 0xda24260, v27
	v_rcp_f32_e32 v51, v45
	v_pk_mul_f32 v[48:49], v[26:27], v[48:49]
	v_pk_mul_f32 v[30:31], v[50:51], v[30:31]
	s_nop 0
	v_cvt_pk_bf16_f32 v29, v30, v31
	v_add_u32_e32 v30, v44, v135
	v_cvt_pk_bf16_f32 v39, v48, v49
	v_add_u32_e32 v31, 0xc000, v30
	v_add_u32_e32 v30, 0xe100, v30
	ds_write2_b64 v31, v[40:41], v[38:39] offset1:1
	ds_write2_b64 v30, v[36:37], v[28:29] offset1:1
	s_and_saveexec_b64 s[10:11], s[8:9]
	s_cbranch_execz .LBB0_634
	v_add_u32_e32 v28, 0x12e00, v60
	ds_write_b128 v28, v[32:35]
	ds_write_b128 v28, v[24:27] offset:16
; __device__ __forceinline__ unsigned pk2(float lo, float hi) { f32x2n v = {lo, hi}; bf16x2n b = __builtin_convertvector(v, bf16x2n); return __builtin_bit_cast(unsigned, b); }
;   template <int CTRL> static __device__ __forceinline__ float shr1(float x) { return __int_as_float(__builtin_amdgcn_update_dpp(__float_as_int(1.0f), __float_as_int(x), CTRL, 0xF, 0xF, false)); }
;   static __device__ __forceinline__ float scan16(float x) { x *= shr1<0x111>(x); x *= shr1<0x112>(x); x *= shr1<0x114>(x); x *= shr1<0x118>(x); return x; }
;   __device__ __forceinline__ void hg_prep(const h16x8 (&q)[8], const h16x8 (&u)[8], int tb) const { unsigned char* tl = smem + SC_TL + tb * SC_TLB; const int rho = lane >> 4, tau = lane & 15;
; #pragma unroll
;     for (int it = 0; it < 8; ++it) { const int bidx = it * 4 + rho, sc = bidx >> 4, k0 = (bidx & 15) * 8, st = sc * 16 + tau;
;       float G[8], qt[8], kt[8];
; #pragma unroll
;       for (int e = 0; e < 8; ++e) { const float uu = (float)u[it][e]; G[e] = scan16(1.f - uu); qt[e] = (float)q[it][e] * G[e]; kt[e] = uu * __builtin_amdgcn_rcpf(fmaxf(G[e], 1e-30f)); }
;       u32x2 a, b, c2, d; a.x = pk2(qt[0], qt[1]); a.y = pk2(qt[2], qt[3]); b.x = pk2(qt[4], qt[5]); b.y = pk2(qt[6], qt[7]);
;       c2.x = pk2(kt[0], kt[1]); c2.y = pk2(kt[2], kt[3]); d.x = pk2(kt[4], kt[5]); d.y = pk2(kt[6], kt[7]);
;       unsigned char* oq = tl + TL_HQ + st * HQS + k0 * 2; unsigned char* ok = tl + TL_HK + st * HQS + k0 * 2;
;       *(u32x2*)oq = a; *(u32x2*)(oq + 8) = b; *(u32x2*)ok = c2; *(u32x2*)(ok + 8) = d;
;       if (tau == 15) { float* ge = (float*)(tl + TL_HGE) + sc * 128 + k0; *(f32x4*)ge = (f32x4){G[0], G[1], G[2], G[3]}; *(f32x4*)(ge + 4) = (f32x4){G[4], G[5], G[6], G[7]}; } } }
.LBB0_634:
	s_or_b64 exec, exec, s[10:11]
	s_waitcnt vmcnt(0)
	v_cvt_f32_f16_sdwa v29, v16 dst_sel:DWORD dst_unused:UNUSED_PAD src0_sel:WORD_1
	v_cvt_f32_f16_e32 v28, v16
	v_cvt_f32_f16_sdwa v27, v20 dst_sel:DWORD dst_unused:UNUSED_PAD src0_sel:WORD_1
	v_pk_add_f32 v[24:25], v[28:29], 1.0 op_sel_hi:[1,0] neg_lo:[1,0] neg_hi:[1,0]
	v_cvt_f32_f16_e32 v26, v20
	v_cvt_f32_f16_e32 v20, v17
	v_mul_f32_dpp v24, v24, v24 row_shr:1 row_mask:0xf bank_mask:0xf
	v_mul_f32_dpp v25, v25, v25 row_shr:1 row_mask:0xf bank_mask:0xf
	v_cvt_f32_f16_sdwa v37, v18 dst_sel:DWORD dst_unused:UNUSED_PAD src0_sel:WORD_1
	v_mul_f32_dpp v24, v24, v24 row_shr:2 row_mask:0xf bank_mask:0xf
	v_mul_f32_dpp v25, v25, v25 row_shr:2 row_mask:0xf bank_mask:0xf
	v_cvt_f32_f16_e32 v36, v18
	v_mul_f32_dpp v24, v24, v24 row_shr:4 row_mask:0xf bank_mask:0xf
	v_mul_f32_dpp v25, v25, v25 row_shr:4 row_mask:0xf bank_mask:0xf
	s_nop 0
	v_mul_f32_dpp v24, v24, v24 row_shr:8 row_mask:0xf bank_mask:0xf
	v_mul_f32_dpp v25, v25, v25 row_shr:8 row_mask:0xf bank_mask:0xf
	v_max_f32_e32 v16, 0xda24260, v24
	v_rcp_f32_e32 v30, v16
	v_max_f32_e32 v16, 0xda24260, v25
	v_rcp_f32_e32 v31, v16
	v_pk_mul_f32 v[32:33], v[24:25], v[26:27]
	v_pk_mul_f32 v[28:29], v[30:31], v[28:29]
	v_cvt_f32_f16_sdwa v31, v21 dst_sel:DWORD dst_unused:UNUSED_PAD src0_sel:WORD_1
	v_cvt_f32_f16_e32 v30, v21
	v_cvt_f32_f16_sdwa v21, v17 dst_sel:DWORD dst_unused:UNUSED_PAD src0_sel:WORD_1
	v_cvt_f32_f16_sdwa v35, v22 dst_sel:DWORD dst_unused:UNUSED_PAD src0_sel:WORD_1
	v_cvt_f32_f16_e32 v34, v22
	v_cvt_f32_f16_e32 v22, v19
	v_pk_add_f32 v[16:17], v[20:21], 1.0 op_sel_hi:[1,0] neg_lo:[1,0] neg_hi:[1,0]
	s_nop 1
	v_mul_f32_dpp v16, v16, v16 row_shr:1 row_mask:0xf bank_mask:0xf
	v_mul_f32_dpp v17, v17, v17 row_shr:1 row_mask:0xf bank_mask:0xf
	v_cvt_pk_bf16_f32 v28, v28, v29
	v_mul_f32_dpp v16, v16, v16 row_shr:2 row_mask:0xf bank_mask:0xf
	v_mul_f32_dpp v17, v17, v17 row_shr:2 row_mask:0xf bank_mask:0xf
	v_cvt_pk_bf16_f32 v32, v32, v33
	v_mul_f32_dpp v16, v16, v16 row_shr:4 row_mask:0xf bank_mask:0xf
	v_mul_f32_dpp v17, v17, v17 row_shr:4 row_mask:0xf bank_mask:0xf
	s_nop 0
	v_mul_f32_dpp v16, v16, v16 row_shr:8 row_mask:0xf bank_mask:0xf
	v_mul_f32_dpp v17, v17, v17 row_shr:8 row_mask:0xf bank_mask:0xf
	v_mov_b64_e32 v[26:27], v[16:17]
	s_nop 0
	v_max_f32_e32 v16, 0xda24260, v26
	v_max_f32_e32 v17, 0xda24260, v27
	v_rcp_f32_e32 v16, v16
	v_rcp_f32_e32 v17, v17
	v_pk_mul_f32 v[30:31], v[26:27], v[30:31]
	v_pk_mul_f32 v[20:21], v[16:17], v[20:21]
	v_pk_add_f32 v[16:17], v[36:37], 1.0 op_sel_hi:[1,0] neg_lo:[1,0] neg_hi:[1,0]
	v_cvt_pk_bf16_f32 v29, v20, v21
	v_cvt_pk_bf16_f32 v33, v30, v31
	v_mul_f32_dpp v16, v16, v16 row_shr:1 row_mask:0xf bank_mask:0xf
	v_mul_f32_dpp v17, v17, v17 row_shr:1 row_mask:0xf bank_mask:0xf
	s_nop 0
	v_mul_f32_dpp v16, v16, v16 row_shr:2 row_mask:0xf bank_mask:0xf
	v_mul_f32_dpp v17, v17, v17 row_shr:2 row_mask:0xf bank_mask:0xf
	s_nop 0
	v_mul_f32_dpp v16, v16, v16 row_shr:4 row_mask:0xf bank_mask:0xf
	v_mul_f32_dpp v17, v17, v17 row_shr:4 row_mask:0xf bank_mask:0xf
	s_nop 0
	v_mul_f32_dpp v16, v16, v16 row_shr:8 row_mask:0xf bank_mask:0xf
	v_mul_f32_dpp v17, v17, v17 row_shr:8 row_mask:0xf bank_mask:0xf
	s_nop 0
	v_max_f32_e32 v18, 0xda24260, v16
	v_rcp_f32_e32 v38, v18
	v_max_f32_e32 v18, 0xda24260, v17
	v_rcp_f32_e32 v39, v18
	v_pk_mul_f32 v[34:35], v[16:17], v[34:35]
	v_pk_mul_f32 v[36:37], v[38:39], v[36:37]
	v_cvt_f32_f16_sdwa v39, v23 dst_sel:DWORD dst_unused:UNUSED_PAD src0_sel:WORD_1
	v_cvt_f32_f16_e32 v38, v23
	v_cvt_f32_f16_sdwa v23, v19 dst_sel:DWORD dst_unused:UNUSED_PAD src0_sel:WORD_1
	v_cvt_pk_bf16_f32 v30, v34, v35
	v_cvt_pk_bf16_f32 v20, v36, v37
	v_pk_add_f32 v[18:19], v[22:23], 1.0 op_sel_hi:[1,0] neg_lo:[1,0] neg_hi:[1,0]
	s_nop 1
	v_mul_f32_dpp v18, v18, v18 row_shr:1 row_mask:0xf bank_mask:0xf
	v_mul_f32_dpp v19, v19, v19 row_shr:1 row_mask:0xf bank_mask:0xf
	s_nop 0
	v_mul_f32_dpp v18, v18, v18 row_shr:2 row_mask:0xf bank_mask:0xf
	v_mul_f32_dpp v19, v19, v19 row_shr:2 row_mask:0xf bank_mask:0xf
	s_nop 0
	v_mul_f32_dpp v18, v18, v18 row_shr:4 row_mask:0xf bank_mask:0xf
	v_mul_f32_dpp v19, v19, v19 row_shr:4 row_mask:0xf bank_mask:0xf
	s_nop 0
	v_mul_f32_dpp v18, v18, v18 row_shr:8 row_mask:0xf bank_mask:0xf
	v_mul_f32_dpp v19, v19, v19 row_shr:8 row_mask:0xf bank_mask:0xf
	s_nop 0
	v_max_f32_e32 v40, 0xda24260, v18
	v_max_f32_e32 v41, 0xda24260, v19
	v_rcp_f32_e32 v40, v40
	v_rcp_f32_e32 v41, v41
	v_pk_mul_f32 v[38:39], v[18:19], v[38:39]
	v_pk_mul_f32 v[22:23], v[40:41], v[22:23]
	s_nop 0
	v_cvt_pk_bf16_f32 v21, v22, v23
	v_add_u32_e32 v22, v44, v136
	v_cvt_pk_bf16_f32 v31, v38, v39
	v_add_u32_e32 v23, 0xc000, v22
	v_add_u32_e32 v22, 0xe100, v22
	ds_write2_b64 v23, v[32:33], v[30:31] offset1:1
	ds_write2_b64 v22, v[28:29], v[20:21] offset1:1
	s_and_saveexec_b64 s[10:11], s[8:9]
	s_cbranch_execz .LBB0_636
	v_add_u32_e32 v20, 0x12e00, v52
	ds_write_b128 v20, v[24:27]
	ds_write_b128 v20, v[16:19] offset:16

; __device__ __forceinline__ unsigned pk2(float lo, float hi) { f32x2n v = {lo, hi}; bf16x2n b = __builtin_convertvector(v, bf16x2n); return __builtin_bit_cast(unsigned, b); }
;   template <int CTRL> static __device__ __forceinline__ float shr1(float x) { return __int_as_float(__builtin_amdgcn_update_dpp(__float_as_int(1.0f), __float_as_int(x), CTRL, 0xF, 0xF, false)); }
;   static __device__ __forceinline__ float scan16(float x) { x *= shr1<0x111>(x); x *= shr1<0x112>(x); x *= shr1<0x114>(x); x *= shr1<0x118>(x); return x; }
;   __device__ __forceinline__ void hg_prep(const h16x8 (&q)[8], const h16x8 (&u)[8], int tb) const { unsigned char* tl = smem + SC_TL + tb * SC_TLB; const int rho = lane >> 4, tau = lane & 15;
; #pragma unroll
;     for (int it = 0; it < 8; ++it) { const int bidx = it * 4 + rho, sc = bidx >> 4, k0 = (bidx & 15) * 8, st = sc * 16 + tau;
;       float G[8], qt[8], kt[8];
; #pragma unroll
;       for (int e = 0; e < 8; ++e) { const float uu = (float)u[it][e]; G[e] = scan16(1.f - uu); qt[e] = (float)q[it][e] * G[e]; kt[e] = uu * __builtin_amdgcn_rcpf(fmaxf(G[e], 1e-30f)); }
;       u32x2 a, b, c2, d; a.x = pk2(qt[0], qt[1]); a.y = pk2(qt[2], qt[3]); b.x = pk2(qt[4], qt[5]); b.y = pk2(qt[6], qt[7]);
;       c2.x = pk2(kt[0], kt[1]); c2.y = pk2(kt[2], kt[3]); d.x = pk2(kt[4], kt[5]); d.y = pk2(kt[6], kt[7]);
;       unsigned char* oq = tl + TL_HQ + st * HQS + k0 * 2; unsigned char* ok = tl + TL_HK + st * HQS + k0 * 2;
;       *(u32x2*)oq = a; *(u32x2*)(oq + 8) = b; *(u32x2*)ok = c2; *(u32x2*)(ok + 8) = d;
;       if (tau == 15) { float* ge = (float*)(tl + TL_HGE) + sc * 128 + k0; *(f32x4*)ge = (f32x4){G[0], G[1], G[2], G[3]}; *(f32x4*)(ge + 4) = (f32x4){G[4], G[5], G[6], G[7]}; } } }
.LBB0_645:
	s_waitcnt vmcnt(14)
	v_cvt_f32_f16_sdwa v95, v20 dst_sel:DWORD dst_unused:UNUSED_PAD src0_sel:WORD_1
	v_cvt_f32_f16_e32 v94, v20
	v_cvt_f32_f16_sdwa v99, v16 dst_sel:DWORD dst_unused:UNUSED_PAD src0_sel:WORD_1
	v_pk_add_f32 v[92:93], v[94:95], 1.0 op_sel_hi:[1,0] neg_lo:[1,0] neg_hi:[1,0]
	v_cvt_f32_f16_e32 v98, v16
	s_nop 0
	v_mul_f32_dpp v92, v92, v92 row_shr:1 row_mask:0xf bank_mask:0xf
	v_mul_f32_dpp v93, v93, v93 row_shr:1 row_mask:0xf bank_mask:0xf
	s_nop 0
	v_mul_f32_dpp v92, v92, v92 row_shr:2 row_mask:0xf bank_mask:0xf
	v_mul_f32_dpp v93, v93, v93 row_shr:2 row_mask:0xf bank_mask:0xf
	v_cvt_f32_f16_sdwa v157, v23 dst_sel:DWORD dst_unused:UNUSED_PAD src0_sel:WORD_1
	v_mul_f32_dpp v92, v92, v92 row_shr:4 row_mask:0xf bank_mask:0xf
	v_mul_f32_dpp v93, v93, v93 row_shr:4 row_mask:0xf bank_mask:0xf
	v_cvt_f32_f16_e32 v156, v23
	v_mul_f32_dpp v92, v92, v92 row_shr:8 row_mask:0xf bank_mask:0xf
	v_mul_f32_dpp v93, v93, v93 row_shr:8 row_mask:0xf bank_mask:0xf
	v_max_f32_e32 v96, 0xda24260, v92
	v_max_f32_e32 v97, 0xda24260, v93
	v_rcp_f32_e32 v96, v96
	v_rcp_f32_e32 v97, v97
	v_pk_mul_f32 v[140:141], v[92:93], v[98:99]
	v_pk_mul_f32 v[142:143], v[96:97], v[94:95]
	v_cvt_f32_f16_sdwa v97, v21 dst_sel:DWORD dst_unused:UNUSED_PAD src0_sel:WORD_1
	v_cvt_f32_f16_e32 v96, v21
	s_bitcmp1_b32 s23, 0
	v_cvt_f32_f16_sdwa v145, v17 dst_sel:DWORD dst_unused:UNUSED_PAD src0_sel:WORD_1
	v_pk_add_f32 v[94:95], v[96:97], 1.0 op_sel_hi:[1,0] neg_lo:[1,0] neg_hi:[1,0]
	v_cvt_f32_f16_e32 v144, v17
	v_cvt_f32_f16_sdwa v151, v18 dst_sel:DWORD dst_unused:UNUSED_PAD src0_sel:WORD_1
	v_mul_f32_dpp v94, v94, v94 row_shr:1 row_mask:0xf bank_mask:0xf
	v_mul_f32_dpp v95, v95, v95 row_shr:1 row_mask:0xf bank_mask:0xf
	v_cvt_f32_f16_e32 v150, v18
	v_mul_f32_dpp v94, v94, v94 row_shr:2 row_mask:0xf bank_mask:0xf
	v_mul_f32_dpp v95, v95, v95 row_shr:2 row_mask:0xf bank_mask:0xf
	v_cvt_f32_f16_sdwa v161, v19 dst_sel:DWORD dst_unused:UNUSED_PAD src0_sel:WORD_1
	v_mul_f32_dpp v94, v94, v94 row_shr:4 row_mask:0xf bank_mask:0xf
	v_mul_f32_dpp v95, v95, v95 row_shr:4 row_mask:0xf bank_mask:0xf
	v_cvt_f32_f16_e32 v160, v19
	v_mul_f32_dpp v94, v94, v94 row_shr:8 row_mask:0xf bank_mask:0xf
	v_mul_f32_dpp v95, v95, v95 row_shr:8 row_mask:0xf bank_mask:0xf
	s_cselect_b32 s10, 0x7200, 0
	v_max_f32_e32 v98, 0xda24260, v94
	v_max_f32_e32 v99, 0xda24260, v95
	v_rcp_f32_e32 v98, v98
	v_rcp_f32_e32 v99, v99
	s_add_i32 s27, s10, 0
	v_pk_mul_f32 v[144:145], v[94:95], v[144:145]
	s_add_i32 s10, s27, 0xc000
	v_pk_mul_f32 v[146:147], v[98:99], v[96:97]
	v_cvt_f32_f16_sdwa v99, v22 dst_sel:DWORD dst_unused:UNUSED_PAD src0_sel:WORD_1
	v_cvt_f32_f16_e32 v98, v22
	v_cvt_pk_bf16_f32 v142, v142, v143
	v_cvt_pk_bf16_f32 v143, v146, v147
	v_pk_add_f32 v[96:97], v[98:99], 1.0 op_sel_hi:[1,0] neg_lo:[1,0] neg_hi:[1,0]
	s_nop 1
	v_mul_f32_dpp v96, v96, v96 row_shr:1 row_mask:0xf bank_mask:0xf
	v_mul_f32_dpp v97, v97, v97 row_shr:1 row_mask:0xf bank_mask:0xf
	s_nop 0
	v_mul_f32_dpp v96, v96, v96 row_shr:2 row_mask:0xf bank_mask:0xf
	v_mul_f32_dpp v97, v97, v97 row_shr:2 row_mask:0xf bank_mask:0xf
	s_nop 0
	v_mul_f32_dpp v96, v96, v96 row_shr:4 row_mask:0xf bank_mask:0xf
	v_mul_f32_dpp v97, v97, v97 row_shr:4 row_mask:0xf bank_mask:0xf
	s_nop 0
	v_mul_f32_dpp v96, v96, v96 row_shr:8 row_mask:0xf bank_mask:0xf
	v_mul_f32_dpp v97, v97, v97 row_shr:8 row_mask:0xf bank_mask:0xf
	s_nop 0
	v_max_f32_e32 v139, 0xda24260, v96
	v_rcp_f32_e32 v148, v139
	v_max_f32_e32 v139, 0xda24260, v97
	v_rcp_f32_e32 v149, v139
	v_pk_mul_f32 v[150:151], v[96:97], v[150:151]
	v_pk_mul_f32 v[148:149], v[148:149], v[98:99]
	v_pk_add_f32 v[98:99], v[156:157], 1.0 op_sel_hi:[1,0] neg_lo:[1,0] neg_hi:[1,0]
	v_cvt_pk_bf16_f32 v146, v148, v149
	s_nop 0
	v_mul_f32_dpp v98, v98, v98 row_shr:1 row_mask:0xf bank_mask:0xf
	v_mul_f32_dpp v99, v99, v99 row_shr:1 row_mask:0xf bank_mask:0xf
	s_nop 0
	v_mul_f32_dpp v98, v98, v98 row_shr:2 row_mask:0xf bank_mask:0xf
	v_mul_f32_dpp v99, v99, v99 row_shr:2 row_mask:0xf bank_mask:0xf
	s_nop 0
	v_mul_f32_dpp v98, v98, v98 row_shr:4 row_mask:0xf bank_mask:0xf
	v_mul_f32_dpp v99, v99, v99 row_shr:4 row_mask:0xf bank_mask:0xf
	s_nop 0
	v_mul_f32_dpp v98, v98, v98 row_shr:8 row_mask:0xf bank_mask:0xf
	v_mul_f32_dpp v99, v99, v99 row_shr:8 row_mask:0xf bank_mask:0xf
	s_nop 0
	v_max_f32_e32 v139, 0xda24260, v98
	v_rcp_f32_e32 v158, v139
	v_max_f32_e32 v139, 0xda24260, v99
	v_rcp_f32_e32 v159, v139
	v_pk_mul_f32 v[160:161], v[98:99], v[160:161]
	v_pk_mul_f32 v[156:157], v[158:159], v[156:157]
	v_cvt_pk_bf16_f32 v158, v140, v141
	v_add_u32_e32 v140, s27, v137
	v_add_u32_e32 v139, v140, v103
	v_cvt_pk_bf16_f32 v159, v144, v145
	v_cvt_pk_bf16_f32 v144, v150, v151
	v_cvt_pk_bf16_f32 v145, v160, v161
	v_add_u32_e32 v141, 0xc000, v139
	v_add_u32_e32 v139, 0xe100, v139
	v_cvt_pk_bf16_f32 v147, v156, v157
	ds_write2_b64 v141, v[158:159], v[144:145] offset1:1
	ds_write2_b64 v139, v[142:143], v[146:147] offset1:1
	v_lshl_add_u32 v139, v101, 2, s10
	s_and_saveexec_b64 s[10:11], s[8:9]
	s_cbranch_execz .LBB0_647
	ds_write_b128 v139, v[92:95] offset:27648
	ds_write_b128 v139, v[96:99] offset:27664
; __device__ __forceinline__ unsigned pk2(float lo, float hi) { f32x2n v = {lo, hi}; bf16x2n b = __builtin_convertvector(v, bf16x2n); return __builtin_bit_cast(unsigned, b); }
;   template <int CTRL> static __device__ __forceinline__ float shr1(float x) { return __int_as_float(__builtin_amdgcn_update_dpp(__float_as_int(1.0f), __float_as_int(x), CTRL, 0xF, 0xF, false)); }
;   static __device__ __forceinline__ float scan16(float x) { x *= shr1<0x111>(x); x *= shr1<0x112>(x); x *= shr1<0x114>(x); x *= shr1<0x118>(x); return x; }
;   __device__ __forceinline__ void hg_prep(const h16x8 (&q)[8], const h16x8 (&u)[8], int tb) const { unsigned char* tl = smem + SC_TL + tb * SC_TLB; const int rho = lane >> 4, tau = lane & 15;
; #pragma unroll
;     for (int it = 0; it < 8; ++it) { const int bidx = it * 4 + rho, sc = bidx >> 4, k0 = (bidx & 15) * 8, st = sc * 16 + tau;
;       float G[8], qt[8], kt[8];
; #pragma unroll
;       for (int e = 0; e < 8; ++e) { const float uu = (float)u[it][e]; G[e] = scan16(1.f - uu); qt[e] = (float)q[it][e] * G[e]; kt[e] = uu * __builtin_amdgcn_rcpf(fmaxf(G[e], 1e-30f)); }
;       u32x2 a, b, c2, d; a.x = pk2(qt[0], qt[1]); a.y = pk2(qt[2], qt[3]); b.x = pk2(qt[4], qt[5]); b.y = pk2(qt[6], qt[7]);
;       c2.x = pk2(kt[0], kt[1]); c2.y = pk2(kt[2], kt[3]); d.x = pk2(kt[4], kt[5]); d.y = pk2(kt[6], kt[7]);
;       unsigned char* oq = tl + TL_HQ + st * HQS + k0 * 2; unsigned char* ok = tl + TL_HK + st * HQS + k0 * 2;
;       *(u32x2*)oq = a; *(u32x2*)(oq + 8) = b; *(u32x2*)ok = c2; *(u32x2*)(ok + 8) = d;
;       if (tau == 15) { float* ge = (float*)(tl + TL_HGE) + sc * 128 + k0; *(f32x4*)ge = (f32x4){G[0], G[1], G[2], G[3]}; *(f32x4*)(ge + 4) = (f32x4){G[4], G[5], G[6], G[7]}; } } }
.LBB0_647:
	s_or_b64 exec, exec, s[10:11]
	s_waitcnt vmcnt(12)
	v_cvt_f32_f16_sdwa v95, v28 dst_sel:DWORD dst_unused:UNUSED_PAD src0_sel:WORD_1
	v_cvt_f32_f16_e32 v94, v28
	v_cvt_f32_f16_sdwa v99, v24 dst_sel:DWORD dst_unused:UNUSED_PAD src0_sel:WORD_1
	v_pk_add_f32 v[92:93], v[94:95], 1.0 op_sel_hi:[1,0] neg_lo:[1,0] neg_hi:[1,0]
	v_cvt_f32_f16_e32 v98, v24
	s_nop 0
	v_mul_f32_dpp v92, v92, v92 row_shr:1 row_mask:0xf bank_mask:0xf
	v_mul_f32_dpp v93, v93, v93 row_shr:1 row_mask:0xf bank_mask:0xf
	s_nop 0
	v_mul_f32_dpp v92, v92, v92 row_shr:2 row_mask:0xf bank_mask:0xf
	v_mul_f32_dpp v93, v93, v93 row_shr:2 row_mask:0xf bank_mask:0xf
	v_cvt_f32_f16_sdwa v159, v31 dst_sel:DWORD dst_unused:UNUSED_PAD src0_sel:WORD_1
	v_mul_f32_dpp v92, v92, v92 row_shr:4 row_mask:0xf bank_mask:0xf
	v_mul_f32_dpp v93, v93, v93 row_shr:4 row_mask:0xf bank_mask:0xf
	v_cvt_f32_f16_e32 v158, v31
	v_mul_f32_dpp v92, v92, v92 row_shr:8 row_mask:0xf bank_mask:0xf
	v_mul_f32_dpp v93, v93, v93 row_shr:8 row_mask:0xf bank_mask:0xf
	v_max_f32_e32 v96, 0xda24260, v92
	v_max_f32_e32 v97, 0xda24260, v93
	v_rcp_f32_e32 v96, v96
	v_rcp_f32_e32 v97, v97
	v_pk_mul_f32 v[142:143], v[92:93], v[98:99]
	v_pk_mul_f32 v[144:145], v[96:97], v[94:95]
	v_cvt_f32_f16_sdwa v97, v29 dst_sel:DWORD dst_unused:UNUSED_PAD src0_sel:WORD_1
	v_cvt_f32_f16_e32 v96, v29
	v_cvt_f32_f16_sdwa v147, v25 dst_sel:DWORD dst_unused:UNUSED_PAD src0_sel:WORD_1
	v_cvt_f32_f16_e32 v146, v25
	v_pk_add_f32 v[94:95], v[96:97], 1.0 op_sel_hi:[1,0] neg_lo:[1,0] neg_hi:[1,0]
	v_cvt_f32_f16_sdwa v157, v26 dst_sel:DWORD dst_unused:UNUSED_PAD src0_sel:WORD_1
	v_cvt_f32_f16_e32 v156, v26
	v_mul_f32_dpp v94, v94, v94 row_shr:1 row_mask:0xf bank_mask:0xf
	v_mul_f32_dpp v95, v95, v95 row_shr:1 row_mask:0xf bank_mask:0xf
	v_cvt_f32_f16_sdwa v163, v27 dst_sel:DWORD dst_unused:UNUSED_PAD src0_sel:WORD_1
	v_mul_f32_dpp v94, v94, v94 row_shr:2 row_mask:0xf bank_mask:0xf
	v_mul_f32_dpp v95, v95, v95 row_shr:2 row_mask:0xf bank_mask:0xf
	v_cvt_f32_f16_e32 v162, v27
	v_mul_f32_dpp v94, v94, v94 row_shr:4 row_mask:0xf bank_mask:0xf
	v_mul_f32_dpp v95, v95, v95 row_shr:4 row_mask:0xf bank_mask:0xf
	v_cvt_pk_bf16_f32 v142, v142, v143
	v_mul_f32_dpp v94, v94, v94 row_shr:8 row_mask:0xf bank_mask:0xf
	v_mul_f32_dpp v95, v95, v95 row_shr:8 row_mask:0xf bank_mask:0xf
	v_cvt_pk_bf16_f32 v144, v144, v145
	v_max_f32_e32 v98, 0xda24260, v94
	v_max_f32_e32 v99, 0xda24260, v95
	v_rcp_f32_e32 v98, v98
	v_rcp_f32_e32 v99, v99
	v_pk_mul_f32 v[146:147], v[94:95], v[146:147]
	v_pk_mul_f32 v[148:149], v[98:99], v[96:97]
	v_cvt_f32_f16_sdwa v99, v30 dst_sel:DWORD dst_unused:UNUSED_PAD src0_sel:WORD_1
	v_cvt_f32_f16_e32 v98, v30
	v_cvt_pk_bf16_f32 v143, v146, v147
	v_cvt_pk_bf16_f32 v145, v148, v149
	v_pk_add_f32 v[96:97], v[98:99], 1.0 op_sel_hi:[1,0] neg_lo:[1,0] neg_hi:[1,0]
	s_nop 1
	v_mul_f32_dpp v96, v96, v96 row_shr:1 row_mask:0xf bank_mask:0xf
	v_mul_f32_dpp v97, v97, v97 row_shr:1 row_mask:0xf bank_mask:0xf
	s_nop 0
	v_mul_f32_dpp v96, v96, v96 row_shr:2 row_mask:0xf bank_mask:0xf
	v_mul_f32_dpp v97, v97, v97 row_shr:2 row_mask:0xf bank_mask:0xf
	s_nop 0
	v_mul_f32_dpp v96, v96, v96 row_shr:4 row_mask:0xf bank_mask:0xf
	v_mul_f32_dpp v97, v97, v97 row_shr:4 row_mask:0xf bank_mask:0xf
	s_nop 0
	v_mul_f32_dpp v96, v96, v96 row_shr:8 row_mask:0xf bank_mask:0xf
	v_mul_f32_dpp v97, v97, v97 row_shr:8 row_mask:0xf bank_mask:0xf
	s_nop 0
	v_max_f32_e32 v141, 0xda24260, v96
	v_rcp_f32_e32 v150, v141
	v_max_f32_e32 v141, 0xda24260, v97
	v_rcp_f32_e32 v151, v141
	v_pk_mul_f32 v[156:157], v[96:97], v[156:157]
	v_pk_mul_f32 v[150:151], v[150:151], v[98:99]
	v_pk_add_f32 v[98:99], v[158:159], 1.0 op_sel_hi:[1,0] neg_lo:[1,0] neg_hi:[1,0]
	v_cvt_pk_bf16_f32 v146, v156, v157
	v_cvt_pk_bf16_f32 v148, v150, v151
	v_mul_f32_dpp v98, v98, v98 row_shr:1 row_mask:0xf bank_mask:0xf
	v_mul_f32_dpp v99, v99, v99 row_shr:1 row_mask:0xf bank_mask:0xf
	s_nop 0
	v_mul_f32_dpp v98, v98, v98 row_shr:2 row_mask:0xf bank_mask:0xf
	v_mul_f32_dpp v99, v99, v99 row_shr:2 row_mask:0xf bank_mask:0xf
	s_nop 0
	v_mul_f32_dpp v98, v98, v98 row_shr:4 row_mask:0xf bank_mask:0xf
	v_mul_f32_dpp v99, v99, v99 row_shr:4 row_mask:0xf bank_mask:0xf
	s_nop 0
	v_mul_f32_dpp v98, v98, v98 row_shr:8 row_mask:0xf bank_mask:0xf
	v_mul_f32_dpp v99, v99, v99 row_shr:8 row_mask:0xf bank_mask:0xf
	s_nop 0
	v_max_f32_e32 v141, 0xda24260, v98
	v_rcp_f32_e32 v160, v141
	v_max_f32_e32 v141, 0xda24260, v99
	v_rcp_f32_e32 v161, v141
	v_pk_mul_f32 v[162:163], v[98:99], v[162:163]
	v_add_u32_e32 v141, v140, v134
	v_cvt_pk_bf16_f32 v147, v162, v163
	v_pk_mul_f32 v[158:159], v[160:161], v[158:159]
	v_add_u32_e32 v150, 0xc000, v141
	v_cvt_pk_bf16_f32 v149, v158, v159
	v_add_u32_e32 v141, 0xe100, v141
	ds_write2_b64 v150, v[142:143], v[146:147] offset1:1
	ds_write2_b64 v141, v[144:145], v[148:149] offset1:1
	s_and_saveexec_b64 s[10:11], s[8:9]
	s_cbranch_execz .LBB0_649
	ds_write_b128 v139, v[92:95] offset:27776
	ds_write_b128 v139, v[96:99] offset:27792
; __device__ __forceinline__ unsigned pk2(float lo, float hi) { f32x2n v = {lo, hi}; bf16x2n b = __builtin_convertvector(v, bf16x2n); return __builtin_bit_cast(unsigned, b); }
;   template <int CTRL> static __device__ __forceinline__ float shr1(float x) { return __int_as_float(__builtin_amdgcn_update_dpp(__float_as_int(1.0f), __float_as_int(x), CTRL, 0xF, 0xF, false)); }
;   static __device__ __forceinline__ float scan16(float x) { x *= shr1<0x111>(x); x *= shr1<0x112>(x); x *= shr1<0x114>(x); x *= shr1<0x118>(x); return x; }
;   __device__ __forceinline__ void hg_prep(const h16x8 (&q)[8], const h16x8 (&u)[8], int tb) const { unsigned char* tl = smem + SC_TL + tb * SC_TLB; const int rho = lane >> 4, tau = lane & 15;
; #pragma unroll
;     for (int it = 0; it < 8; ++it) { const int bidx = it * 4 + rho, sc = bidx >> 4, k0 = (bidx & 15) * 8, st = sc * 16 + tau;
;       float G[8], qt[8], kt[8];
; #pragma unroll
;       for (int e = 0; e < 8; ++e) { const float uu = (float)u[it][e]; G[e] = scan16(1.f - uu); qt[e] = (float)q[it][e] * G[e]; kt[e] = uu * __builtin_amdgcn_rcpf(fmaxf(G[e], 1e-30f)); }
;       u32x2 a, b, c2, d; a.x = pk2(qt[0], qt[1]); a.y = pk2(qt[2], qt[3]); b.x = pk2(qt[4], qt[5]); b.y = pk2(qt[6], qt[7]);
;       c2.x = pk2(kt[0], kt[1]); c2.y = pk2(kt[2], kt[3]); d.x = pk2(kt[4], kt[5]); d.y = pk2(kt[6], kt[7]);
;       unsigned char* oq = tl + TL_HQ + st * HQS + k0 * 2; unsigned char* ok = tl + TL_HK + st * HQS + k0 * 2;
;       *(u32x2*)oq = a; *(u32x2*)(oq + 8) = b; *(u32x2*)ok = c2; *(u32x2*)(ok + 8) = d;
;       if (tau == 15) { float* ge = (float*)(tl + TL_HGE) + sc * 128 + k0; *(f32x4*)ge = (f32x4){G[0], G[1], G[2], G[3]}; *(f32x4*)(ge + 4) = (f32x4){G[4], G[5], G[6], G[7]}; } } }
.LBB0_649:
	s_or_b64 exec, exec, s[10:11]
	s_waitcnt vmcnt(10)
	v_cvt_f32_f16_sdwa v95, v36 dst_sel:DWORD dst_unused:UNUSED_PAD src0_sel:WORD_1
	v_cvt_f32_f16_e32 v94, v36
	v_cvt_f32_f16_sdwa v99, v32 dst_sel:DWORD dst_unused:UNUSED_PAD src0_sel:WORD_1
	v_pk_add_f32 v[92:93], v[94:95], 1.0 op_sel_hi:[1,0] neg_lo:[1,0] neg_hi:[1,0]
	v_cvt_f32_f16_e32 v98, v32
	s_nop 0
	v_mul_f32_dpp v92, v92, v92 row_shr:1 row_mask:0xf bank_mask:0xf
	v_mul_f32_dpp v93, v93, v93 row_shr:1 row_mask:0xf bank_mask:0xf
	s_nop 0
	v_mul_f32_dpp v92, v92, v92 row_shr:2 row_mask:0xf bank_mask:0xf
	v_mul_f32_dpp v93, v93, v93 row_shr:2 row_mask:0xf bank_mask:0xf
	v_cvt_f32_f16_sdwa v159, v39 dst_sel:DWORD dst_unused:UNUSED_PAD src0_sel:WORD_1
	v_mul_f32_dpp v92, v92, v92 row_shr:4 row_mask:0xf bank_mask:0xf
	v_mul_f32_dpp v93, v93, v93 row_shr:4 row_mask:0xf bank_mask:0xf
	v_cvt_f32_f16_e32 v158, v39
	v_mul_f32_dpp v92, v92, v92 row_shr:8 row_mask:0xf bank_mask:0xf
	v_mul_f32_dpp v93, v93, v93 row_shr:8 row_mask:0xf bank_mask:0xf
	v_max_f32_e32 v96, 0xda24260, v92
	v_max_f32_e32 v97, 0xda24260, v93
	v_rcp_f32_e32 v96, v96
	v_rcp_f32_e32 v97, v97
	v_pk_mul_f32 v[142:143], v[92:93], v[98:99]
	v_pk_mul_f32 v[144:145], v[96:97], v[94:95]
	v_cvt_f32_f16_sdwa v97, v37 dst_sel:DWORD dst_unused:UNUSED_PAD src0_sel:WORD_1
	v_cvt_f32_f16_e32 v96, v37
	v_cvt_f32_f16_sdwa v147, v33 dst_sel:DWORD dst_unused:UNUSED_PAD src0_sel:WORD_1
	v_cvt_f32_f16_e32 v146, v33
	v_pk_add_f32 v[94:95], v[96:97], 1.0 op_sel_hi:[1,0] neg_lo:[1,0] neg_hi:[1,0]
	v_cvt_f32_f16_sdwa v157, v34 dst_sel:DWORD dst_unused:UNUSED_PAD src0_sel:WORD_1
	v_cvt_f32_f16_e32 v156, v34
	v_mul_f32_dpp v94, v94, v94 row_shr:1 row_mask:0xf bank_mask:0xf
	v_mul_f32_dpp v95, v95, v95 row_shr:1 row_mask:0xf bank_mask:0xf
	v_cvt_f32_f16_sdwa v163, v35 dst_sel:DWORD dst_unused:UNUSED_PAD src0_sel:WORD_1
	v_mul_f32_dpp v94, v94, v94 row_shr:2 row_mask:0xf bank_mask:0xf
	v_mul_f32_dpp v95, v95, v95 row_shr:2 row_mask:0xf bank_mask:0xf
	v_cvt_f32_f16_e32 v162, v35
	v_mul_f32_dpp v94, v94, v94 row_shr:4 row_mask:0xf bank_mask:0xf
	v_mul_f32_dpp v95, v95, v95 row_shr:4 row_mask:0xf bank_mask:0xf
	v_cvt_pk_bf16_f32 v142, v142, v143
	v_mul_f32_dpp v94, v94, v94 row_shr:8 row_mask:0xf bank_mask:0xf
	v_mul_f32_dpp v95, v95, v95 row_shr:8 row_mask:0xf bank_mask:0xf
	v_cvt_pk_bf16_f32 v144, v144, v145
	v_max_f32_e32 v98, 0xda24260, v94
	v_max_f32_e32 v99, 0xda24260, v95
	v_rcp_f32_e32 v98, v98
	v_rcp_f32_e32 v99, v99
	v_pk_mul_f32 v[146:147], v[94:95], v[146:147]
	v_pk_mul_f32 v[148:149], v[98:99], v[96:97]
	v_cvt_f32_f16_sdwa v99, v38 dst_sel:DWORD dst_unused:UNUSED_PAD src0_sel:WORD_1
	v_cvt_f32_f16_e32 v98, v38
	v_cvt_pk_bf16_f32 v143, v146, v147
	v_cvt_pk_bf16_f32 v145, v148, v149
	v_pk_add_f32 v[96:97], v[98:99], 1.0 op_sel_hi:[1,0] neg_lo:[1,0] neg_hi:[1,0]
	s_nop 1
	v_mul_f32_dpp v96, v96, v96 row_shr:1 row_mask:0xf bank_mask:0xf
	v_mul_f32_dpp v97, v97, v97 row_shr:1 row_mask:0xf bank_mask:0xf
	s_nop 0
	v_mul_f32_dpp v96, v96, v96 row_shr:2 row_mask:0xf bank_mask:0xf
	v_mul_f32_dpp v97, v97, v97 row_shr:2 row_mask:0xf bank_mask:0xf
	s_nop 0
	v_mul_f32_dpp v96, v96, v96 row_shr:4 row_mask:0xf bank_mask:0xf
	v_mul_f32_dpp v97, v97, v97 row_shr:4 row_mask:0xf bank_mask:0xf
	s_nop 0
	v_mul_f32_dpp v96, v96, v96 row_shr:8 row_mask:0xf bank_mask:0xf
	v_mul_f32_dpp v97, v97, v97 row_shr:8 row_mask:0xf bank_mask:0xf
	s_nop 0
	v_max_f32_e32 v141, 0xda24260, v96
	v_rcp_f32_e32 v150, v141
	v_max_f32_e32 v141, 0xda24260, v97
	v_rcp_f32_e32 v151, v141
	v_pk_mul_f32 v[156:157], v[96:97], v[156:157]
	v_pk_mul_f32 v[150:151], v[150:151], v[98:99]
	v_pk_add_f32 v[98:99], v[158:159], 1.0 op_sel_hi:[1,0] neg_lo:[1,0] neg_hi:[1,0]
	v_cvt_pk_bf16_f32 v146, v156, v157
	v_cvt_pk_bf16_f32 v148, v150, v151
	v_mul_f32_dpp v98, v98, v98 row_shr:1 row_mask:0xf bank_mask:0xf
	v_mul_f32_dpp v99, v99, v99 row_shr:1 row_mask:0xf bank_mask:0xf
	s_nop 0
	v_mul_f32_dpp v98, v98, v98 row_shr:2 row_mask:0xf bank_mask:0xf
	v_mul_f32_dpp v99, v99, v99 row_shr:2 row_mask:0xf bank_mask:0xf
	s_nop 0
	v_mul_f32_dpp v98, v98, v98 row_shr:4 row_mask:0xf bank_mask:0xf
	v_mul_f32_dpp v99, v99, v99 row_shr:4 row_mask:0xf bank_mask:0xf
	s_nop 0
	v_mul_f32_dpp v98, v98, v98 row_shr:8 row_mask:0xf bank_mask:0xf
	v_mul_f32_dpp v99, v99, v99 row_shr:8 row_mask:0xf bank_mask:0xf
	s_nop 0
	v_max_f32_e32 v141, 0xda24260, v98
	v_rcp_f32_e32 v160, v141
	v_max_f32_e32 v141, 0xda24260, v99
	v_rcp_f32_e32 v161, v141
	v_pk_mul_f32 v[162:163], v[98:99], v[162:163]
	v_add_u32_e32 v141, v140, v135
	v_cvt_pk_bf16_f32 v147, v162, v163
	v_pk_mul_f32 v[158:159], v[160:161], v[158:159]
	v_add_u32_e32 v150, 0xc000, v141
	v_cvt_pk_bf16_f32 v149, v158, v159
	v_add_u32_e32 v141, 0xe100, v141
	ds_write2_b64 v150, v[142:143], v[146:147] offset1:1
	ds_write2_b64 v141, v[144:145], v[148:149] offset1:1
	s_and_saveexec_b64 s[10:11], s[8:9]
	s_cbranch_execz .LBB0_651
	ds_write_b128 v139, v[92:95] offset:27904
	ds_write_b128 v139, v[96:99] offset:27920
; __device__ __forceinline__ unsigned pk2(float lo, float hi) { f32x2n v = {lo, hi}; bf16x2n b = __builtin_convertvector(v, bf16x2n); return __builtin_bit_cast(unsigned, b); }
;   template <int CTRL> static __device__ __forceinline__ float shr1(float x) { return __int_as_float(__builtin_amdgcn_update_dpp(__float_as_int(1.0f), __float_as_int(x), CTRL, 0xF, 0xF, false)); }
;   static __device__ __forceinline__ float scan16(float x) { x *= shr1<0x111>(x); x *= shr1<0x112>(x); x *= shr1<0x114>(x); x *= shr1<0x118>(x); return x; }
;   __device__ __forceinline__ void hg_prep(const h16x8 (&q)[8], const h16x8 (&u)[8], int tb) const { unsigned char* tl = smem + SC_TL + tb * SC_TLB; const int rho = lane >> 4, tau = lane & 15;
; #pragma unroll
;     for (int it = 0; it < 8; ++it) { const int bidx = it * 4 + rho, sc = bidx >> 4, k0 = (bidx & 15) * 8, st = sc * 16 + tau;
;       float G[8], qt[8], kt[8];
; #pragma unroll
;       for (int e = 0; e < 8; ++e) { const float uu = (float)u[it][e]; G[e] = scan16(1.f - uu); qt[e] = (float)q[it][e] * G[e]; kt[e] = uu * __builtin_amdgcn_rcpf(fmaxf(G[e], 1e-30f)); }
;       u32x2 a, b, c2, d; a.x = pk2(qt[0], qt[1]); a.y = pk2(qt[2], qt[3]); b.x = pk2(qt[4], qt[5]); b.y = pk2(qt[6], qt[7]);
;       c2.x = pk2(kt[0], kt[1]); c2.y = pk2(kt[2], kt[3]); d.x = pk2(kt[4], kt[5]); d.y = pk2(kt[6], kt[7]);
;       unsigned char* oq = tl + TL_HQ + st * HQS + k0 * 2; unsigned char* ok = tl + TL_HK + st * HQS + k0 * 2;
;       *(u32x2*)oq = a; *(u32x2*)(oq + 8) = b; *(u32x2*)ok = c2; *(u32x2*)(ok + 8) = d;
;       if (tau == 15) { float* ge = (float*)(tl + TL_HGE) + sc * 128 + k0; *(f32x4*)ge = (f32x4){G[0], G[1], G[2], G[3]}; *(f32x4*)(ge + 4) = (f32x4){G[4], G[5], G[6], G[7]}; } } }
.LBB0_651:
	s_or_b64 exec, exec, s[10:11]
	s_waitcnt vmcnt(8)
	v_cvt_f32_f16_sdwa v95, v44 dst_sel:DWORD dst_unused:UNUSED_PAD src0_sel:WORD_1
	v_cvt_f32_f16_e32 v94, v44
	v_cvt_f32_f16_sdwa v99, v40 dst_sel:DWORD dst_unused:UNUSED_PAD src0_sel:WORD_1
	v_pk_add_f32 v[92:93], v[94:95], 1.0 op_sel_hi:[1,0] neg_lo:[1,0] neg_hi:[1,0]
	v_cvt_f32_f16_e32 v98, v40
	s_nop 0
	v_mul_f32_dpp v92, v92, v92 row_shr:1 row_mask:0xf bank_mask:0xf
	v_mul_f32_dpp v93, v93, v93 row_shr:1 row_mask:0xf bank_mask:0xf
	s_nop 0
	v_mul_f32_dpp v92, v92, v92 row_shr:2 row_mask:0xf bank_mask:0xf
	v_mul_f32_dpp v93, v93, v93 row_shr:2 row_mask:0xf bank_mask:0xf
	v_cvt_f32_f16_sdwa v159, v47 dst_sel:DWORD dst_unused:UNUSED_PAD src0_sel:WORD_1
	v_mul_f32_dpp v92, v92, v92 row_shr:4 row_mask:0xf bank_mask:0xf
	v_mul_f32_dpp v93, v93, v93 row_shr:4 row_mask:0xf bank_mask:0xf
	v_cvt_f32_f16_e32 v158, v47
	v_mul_f32_dpp v92, v92, v92 row_shr:8 row_mask:0xf bank_mask:0xf
	v_mul_f32_dpp v93, v93, v93 row_shr:8 row_mask:0xf bank_mask:0xf
	v_max_f32_e32 v96, 0xda24260, v92
	v_max_f32_e32 v97, 0xda24260, v93
	v_rcp_f32_e32 v96, v96
	v_rcp_f32_e32 v97, v97
	v_pk_mul_f32 v[142:143], v[92:93], v[98:99]
	v_pk_mul_f32 v[144:145], v[96:97], v[94:95]
	v_cvt_f32_f16_sdwa v97, v45 dst_sel:DWORD dst_unused:UNUSED_PAD src0_sel:WORD_1
	v_cvt_f32_f16_e32 v96, v45
	v_cvt_f32_f16_sdwa v147, v41 dst_sel:DWORD dst_unused:UNUSED_PAD src0_sel:WORD_1
	v_cvt_f32_f16_e32 v146, v41
	v_pk_add_f32 v[94:95], v[96:97], 1.0 op_sel_hi:[1,0] neg_lo:[1,0] neg_hi:[1,0]
	v_cvt_f32_f16_sdwa v157, v42 dst_sel:DWORD dst_unused:UNUSED_PAD src0_sel:WORD_1
	v_cvt_f32_f16_e32 v156, v42
	v_mul_f32_dpp v94, v94, v94 row_shr:1 row_mask:0xf bank_mask:0xf
	v_mul_f32_dpp v95, v95, v95 row_shr:1 row_mask:0xf bank_mask:0xf
	v_cvt_f32_f16_sdwa v163, v43 dst_sel:DWORD dst_unused:UNUSED_PAD src0_sel:WORD_1
	v_mul_f32_dpp v94, v94, v94 row_shr:2 row_mask:0xf bank_mask:0xf
	v_mul_f32_dpp v95, v95, v95 row_shr:2 row_mask:0xf bank_mask:0xf
	v_cvt_f32_f16_e32 v162, v43
	v_mul_f32_dpp v94, v94, v94 row_shr:4 row_mask:0xf bank_mask:0xf
	v_mul_f32_dpp v95, v95, v95 row_shr:4 row_mask:0xf bank_mask:0xf
	v_add_u32_e32 v140, v140, v136
	v_mul_f32_dpp v94, v94, v94 row_shr:8 row_mask:0xf bank_mask:0xf
	v_mul_f32_dpp v95, v95, v95 row_shr:8 row_mask:0xf bank_mask:0xf
	v_cvt_pk_bf16_f32 v142, v142, v143
	v_max_f32_e32 v98, 0xda24260, v94
	v_max_f32_e32 v99, 0xda24260, v95
	v_rcp_f32_e32 v98, v98
	v_rcp_f32_e32 v99, v99
	v_pk_mul_f32 v[146:147], v[94:95], v[146:147]
	v_cvt_pk_bf16_f32 v144, v144, v145
	v_cvt_pk_bf16_f32 v143, v146, v147
	v_pk_mul_f32 v[148:149], v[98:99], v[96:97]
	v_cvt_f32_f16_sdwa v99, v46 dst_sel:DWORD dst_unused:UNUSED_PAD src0_sel:WORD_1
	v_cvt_f32_f16_e32 v98, v46
	v_cvt_pk_bf16_f32 v145, v148, v149
	v_pk_add_f32 v[96:97], v[98:99], 1.0 op_sel_hi:[1,0] neg_lo:[1,0] neg_hi:[1,0]
	s_nop 1
	v_mul_f32_dpp v96, v96, v96 row_shr:1 row_mask:0xf bank_mask:0xf
	v_mul_f32_dpp v97, v97, v97 row_shr:1 row_mask:0xf bank_mask:0xf
	s_nop 0
	v_mul_f32_dpp v96, v96, v96 row_shr:2 row_mask:0xf bank_mask:0xf
	v_mul_f32_dpp v97, v97, v97 row_shr:2 row_mask:0xf bank_mask:0xf
	s_nop 0
	v_mul_f32_dpp v96, v96, v96 row_shr:4 row_mask:0xf bank_mask:0xf
	v_mul_f32_dpp v97, v97, v97 row_shr:4 row_mask:0xf bank_mask:0xf
	s_nop 0
	v_mul_f32_dpp v96, v96, v96 row_shr:8 row_mask:0xf bank_mask:0xf
	v_mul_f32_dpp v97, v97, v97 row_shr:8 row_mask:0xf bank_mask:0xf
	s_nop 0
	v_max_f32_e32 v141, 0xda24260, v96
	v_rcp_f32_e32 v150, v141
	v_max_f32_e32 v141, 0xda24260, v97
	v_rcp_f32_e32 v151, v141
	v_pk_mul_f32 v[156:157], v[96:97], v[156:157]
	v_pk_mul_f32 v[150:151], v[150:151], v[98:99]
	v_pk_add_f32 v[98:99], v[158:159], 1.0 op_sel_hi:[1,0] neg_lo:[1,0] neg_hi:[1,0]
	v_cvt_pk_bf16_f32 v146, v156, v157
	v_cvt_pk_bf16_f32 v148, v150, v151
	v_mul_f32_dpp v98, v98, v98 row_shr:1 row_mask:0xf bank_mask:0xf
	v_mul_f32_dpp v99, v99, v99 row_shr:1 row_mask:0xf bank_mask:0xf
	s_nop 0
	v_mul_f32_dpp v98, v98, v98 row_shr:2 row_mask:0xf bank_mask:0xf
	v_mul_f32_dpp v99, v99, v99 row_shr:2 row_mask:0xf bank_mask:0xf
	s_nop 0
	v_mul_f32_dpp v98, v98, v98 row_shr:4 row_mask:0xf bank_mask:0xf
	v_mul_f32_dpp v99, v99, v99 row_shr:4 row_mask:0xf bank_mask:0xf
	s_nop 0
	v_mul_f32_dpp v98, v98, v98 row_shr:8 row_mask:0xf bank_mask:0xf
	v_mul_f32_dpp v99, v99, v99 row_shr:8 row_mask:0xf bank_mask:0xf
	s_nop 0
	v_max_f32_e32 v141, 0xda24260, v98
	v_rcp_f32_e32 v160, v141
	v_max_f32_e32 v141, 0xda24260, v99
	v_rcp_f32_e32 v161, v141
	v_pk_mul_f32 v[162:163], v[98:99], v[162:163]
	v_add_u32_e32 v141, 0xc000, v140
	v_cvt_pk_bf16_f32 v147, v162, v163
	v_pk_mul_f32 v[158:159], v[160:161], v[158:159]
	v_add_u32_e32 v140, 0xe100, v140
	v_cvt_pk_bf16_f32 v149, v158, v159
	ds_write2_b64 v141, v[142:143], v[146:147] offset1:1
	ds_write2_b64 v140, v[144:145], v[148:149] offset1:1
	s_and_saveexec_b64 s[10:11], s[8:9]
	s_cbranch_execz .LBB0_653
	ds_write_b128 v139, v[92:95] offset:28032
	ds_write_b128 v139, v[96:99] offset:28048
; __device__ __forceinline__ unsigned pk2(float lo, float hi) { f32x2n v = {lo, hi}; bf16x2n b = __builtin_convertvector(v, bf16x2n); return __builtin_bit_cast(unsigned, b); }
;   template <int CTRL> static __device__ __forceinline__ float shr1(float x) { return __int_as_float(__builtin_amdgcn_update_dpp(__float_as_int(1.0f), __float_as_int(x), CTRL, 0xF, 0xF, false)); }
;   static __device__ __forceinline__ float scan16(float x) { x *= shr1<0x111>(x); x *= shr1<0x112>(x); x *= shr1<0x114>(x); x *= shr1<0x118>(x); return x; }
;   __device__ __forceinline__ void hg_prep(const h16x8 (&q)[8], const h16x8 (&u)[8], int tb) const { unsigned char* tl = smem + SC_TL + tb * SC_TLB; const int rho = lane >> 4, tau = lane & 15;
; #pragma unroll
;     for (int it = 0; it < 8; ++it) { const int bidx = it * 4 + rho, sc = bidx >> 4, k0 = (bidx & 15) * 8, st = sc * 16 + tau;
;       float G[8], qt[8], kt[8];
; #pragma unroll
;       for (int e = 0; e < 8; ++e) { const float uu = (float)u[it][e]; G[e] = scan16(1.f - uu); qt[e] = (float)q[it][e] * G[e]; kt[e] = uu * __builtin_amdgcn_rcpf(fmaxf(G[e], 1e-30f)); }
;       u32x2 a, b, c2, d; a.x = pk2(qt[0], qt[1]); a.y = pk2(qt[2], qt[3]); b.x = pk2(qt[4], qt[5]); b.y = pk2(qt[6], qt[7]);
;       c2.x = pk2(kt[0], kt[1]); c2.y = pk2(kt[2], kt[3]); d.x = pk2(kt[4], kt[5]); d.y = pk2(kt[6], kt[7]);
;       unsigned char* oq = tl + TL_HQ + st * HQS + k0 * 2; unsigned char* ok = tl + TL_HK + st * HQS + k0 * 2;
;       *(u32x2*)oq = a; *(u32x2*)(oq + 8) = b; *(u32x2*)ok = c2; *(u32x2*)(ok + 8) = d;
;       if (tau == 15) { float* ge = (float*)(tl + TL_HGE) + sc * 128 + k0; *(f32x4*)ge = (f32x4){G[0], G[1], G[2], G[3]}; *(f32x4*)(ge + 4) = (f32x4){G[4], G[5], G[6], G[7]}; } } }
.LBB0_653:
	s_or_b64 exec, exec, s[10:11]
	s_waitcnt vmcnt(6)
	v_cvt_f32_f16_sdwa v95, v52 dst_sel:DWORD dst_unused:UNUSED_PAD src0_sel:WORD_1
	v_cvt_f32_f16_e32 v94, v52
	v_cvt_f32_f16_sdwa v99, v48 dst_sel:DWORD dst_unused:UNUSED_PAD src0_sel:WORD_1
	v_pk_add_f32 v[92:93], v[94:95], 1.0 op_sel_hi:[1,0] neg_lo:[1,0] neg_hi:[1,0]
	v_cvt_f32_f16_e32 v98, v48
	s_nop 0
	v_mul_f32_dpp v92, v92, v92 row_shr:1 row_mask:0xf bank_mask:0xf
	v_mul_f32_dpp v93, v93, v93 row_shr:1 row_mask:0xf bank_mask:0xf
	s_nop 0
	v_mul_f32_dpp v92, v92, v92 row_shr:2 row_mask:0xf bank_mask:0xf
	v_mul_f32_dpp v93, v93, v93 row_shr:2 row_mask:0xf bank_mask:0xf
	v_cvt_f32_f16_sdwa v157, v55 dst_sel:DWORD dst_unused:UNUSED_PAD src0_sel:WORD_1
	v_mul_f32_dpp v92, v92, v92 row_shr:4 row_mask:0xf bank_mask:0xf
	v_mul_f32_dpp v93, v93, v93 row_shr:4 row_mask:0xf bank_mask:0xf
	v_cvt_f32_f16_e32 v156, v55
	v_mul_f32_dpp v92, v92, v92 row_shr:8 row_mask:0xf bank_mask:0xf
	v_mul_f32_dpp v93, v93, v93 row_shr:8 row_mask:0xf bank_mask:0xf
	v_max_f32_e32 v96, 0xda24260, v92
	v_max_f32_e32 v97, 0xda24260, v93
	v_rcp_f32_e32 v96, v96
	v_rcp_f32_e32 v97, v97
	v_pk_mul_f32 v[140:141], v[92:93], v[98:99]
	v_pk_mul_f32 v[142:143], v[96:97], v[94:95]
	v_cvt_f32_f16_sdwa v97, v53 dst_sel:DWORD dst_unused:UNUSED_PAD src0_sel:WORD_1
	v_cvt_f32_f16_e32 v96, v53
	v_cvt_f32_f16_sdwa v145, v49 dst_sel:DWORD dst_unused:UNUSED_PAD src0_sel:WORD_1
	v_cvt_f32_f16_e32 v144, v49
	v_pk_add_f32 v[94:95], v[96:97], 1.0 op_sel_hi:[1,0] neg_lo:[1,0] neg_hi:[1,0]
	v_cvt_f32_f16_sdwa v151, v50 dst_sel:DWORD dst_unused:UNUSED_PAD src0_sel:WORD_1
	v_cvt_f32_f16_e32 v150, v50
	v_mul_f32_dpp v94, v94, v94 row_shr:1 row_mask:0xf bank_mask:0xf
	v_mul_f32_dpp v95, v95, v95 row_shr:1 row_mask:0xf bank_mask:0xf
	v_cvt_f32_f16_sdwa v161, v51 dst_sel:DWORD dst_unused:UNUSED_PAD src0_sel:WORD_1
	v_mul_f32_dpp v94, v94, v94 row_shr:2 row_mask:0xf bank_mask:0xf
	v_mul_f32_dpp v95, v95, v95 row_shr:2 row_mask:0xf bank_mask:0xf
	v_cvt_f32_f16_e32 v160, v51
	v_mul_f32_dpp v94, v94, v94 row_shr:4 row_mask:0xf bank_mask:0xf
	v_mul_f32_dpp v95, v95, v95 row_shr:4 row_mask:0xf bank_mask:0xf
	v_cvt_pk_bf16_f32 v142, v142, v143
	v_mul_f32_dpp v94, v94, v94 row_shr:8 row_mask:0xf bank_mask:0xf
	v_mul_f32_dpp v95, v95, v95 row_shr:8 row_mask:0xf bank_mask:0xf
	s_nop 0
	v_max_f32_e32 v98, 0xda24260, v94
	v_max_f32_e32 v99, 0xda24260, v95
	v_rcp_f32_e32 v98, v98
	v_rcp_f32_e32 v99, v99
	v_pk_mul_f32 v[144:145], v[94:95], v[144:145]
	v_pk_mul_f32 v[146:147], v[98:99], v[96:97]
	v_cvt_f32_f16_sdwa v99, v54 dst_sel:DWORD dst_unused:UNUSED_PAD src0_sel:WORD_1
	v_cvt_f32_f16_e32 v98, v54
	v_cvt_pk_bf16_f32 v143, v146, v147
	v_pk_add_f32 v[96:97], v[98:99], 1.0 op_sel_hi:[1,0] neg_lo:[1,0] neg_hi:[1,0]
	s_nop 1
	v_mul_f32_dpp v96, v96, v96 row_shr:1 row_mask:0xf bank_mask:0xf
	v_mul_f32_dpp v97, v97, v97 row_shr:1 row_mask:0xf bank_mask:0xf
	s_nop 0
	v_mul_f32_dpp v96, v96, v96 row_shr:2 row_mask:0xf bank_mask:0xf
	v_mul_f32_dpp v97, v97, v97 row_shr:2 row_mask:0xf bank_mask:0xf
	s_nop 0
	v_mul_f32_dpp v96, v96, v96 row_shr:4 row_mask:0xf bank_mask:0xf
	v_mul_f32_dpp v97, v97, v97 row_shr:4 row_mask:0xf bank_mask:0xf
	s_nop 0
	v_mul_f32_dpp v96, v96, v96 row_shr:8 row_mask:0xf bank_mask:0xf
	v_mul_f32_dpp v97, v97, v97 row_shr:8 row_mask:0xf bank_mask:0xf
	s_nop 0
	v_max_f32_e32 v148, 0xda24260, v96
	v_max_f32_e32 v149, 0xda24260, v97
	v_rcp_f32_e32 v148, v148
	v_rcp_f32_e32 v149, v149
	v_pk_mul_f32 v[150:151], v[96:97], v[150:151]
	v_pk_mul_f32 v[148:149], v[148:149], v[98:99]
	v_pk_add_f32 v[98:99], v[156:157], 1.0 op_sel_hi:[1,0] neg_lo:[1,0] neg_hi:[1,0]
	v_cvt_pk_bf16_f32 v146, v148, v149
	s_nop 0
	v_mul_f32_dpp v98, v98, v98 row_shr:1 row_mask:0xf bank_mask:0xf
	v_mul_f32_dpp v99, v99, v99 row_shr:1 row_mask:0xf bank_mask:0xf
	s_nop 0
	v_mul_f32_dpp v98, v98, v98 row_shr:2 row_mask:0xf bank_mask:0xf
	v_mul_f32_dpp v99, v99, v99 row_shr:2 row_mask:0xf bank_mask:0xf
	s_nop 0
	v_mul_f32_dpp v98, v98, v98 row_shr:4 row_mask:0xf bank_mask:0xf
	v_mul_f32_dpp v99, v99, v99 row_shr:4 row_mask:0xf bank_mask:0xf
	s_nop 0
	v_mul_f32_dpp v98, v98, v98 row_shr:8 row_mask:0xf bank_mask:0xf
	v_mul_f32_dpp v99, v99, v99 row_shr:8 row_mask:0xf bank_mask:0xf
	s_nop 0
	v_max_f32_e32 v158, 0xda24260, v98
	v_max_f32_e32 v159, 0xda24260, v99
	v_rcp_f32_e32 v158, v158
	v_rcp_f32_e32 v159, v159
	v_pk_mul_f32 v[160:161], v[98:99], v[160:161]
	v_pk_mul_f32 v[156:157], v[158:159], v[156:157]
	v_cvt_pk_bf16_f32 v158, v140, v141
	v_add_u32_e32 v140, s27, v105
	v_add_u32_e32 v141, v140, v103
	v_cvt_pk_bf16_f32 v159, v144, v145
	v_cvt_pk_bf16_f32 v144, v150, v151
	v_cvt_pk_bf16_f32 v145, v160, v161
	v_add_u32_e32 v148, 0xc000, v141
	v_cvt_pk_bf16_f32 v147, v156, v157
	v_add_u32_e32 v141, 0xe100, v141
	ds_write2_b64 v148, v[158:159], v[144:145] offset1:1
	ds_write2_b64 v141, v[142:143], v[146:147] offset1:1
	s_and_saveexec_b64 s[10:11], s[8:9]
	s_cbranch_execz .LBB0_655
	ds_write_b128 v139, v[92:95] offset:28160
	ds_write_b128 v139, v[96:99] offset:28176
; __device__ __forceinline__ unsigned pk2(float lo, float hi) { f32x2n v = {lo, hi}; bf16x2n b = __builtin_convertvector(v, bf16x2n); return __builtin_bit_cast(unsigned, b); }
;   template <int CTRL> static __device__ __forceinline__ float shr1(float x) { return __int_as_float(__builtin_amdgcn_update_dpp(__float_as_int(1.0f), __float_as_int(x), CTRL, 0xF, 0xF, false)); }
;   static __device__ __forceinline__ float scan16(float x) { x *= shr1<0x111>(x); x *= shr1<0x112>(x); x *= shr1<0x114>(x); x *= shr1<0x118>(x); return x; }
;   __device__ __forceinline__ void hg_prep(const h16x8 (&q)[8], const h16x8 (&u)[8], int tb) const { unsigned char* tl = smem + SC_TL + tb * SC_TLB; const int rho = lane >> 4, tau = lane & 15;
; #pragma unroll
;     for (int it = 0; it < 8; ++it) { const int bidx = it * 4 + rho, sc = bidx >> 4, k0 = (bidx & 15) * 8, st = sc * 16 + tau;
;       float G[8], qt[8], kt[8];
; #pragma unroll
;       for (int e = 0; e < 8; ++e) { const float uu = (float)u[it][e]; G[e] = scan16(1.f - uu); qt[e] = (float)q[it][e] * G[e]; kt[e] = uu * __builtin_amdgcn_rcpf(fmaxf(G[e], 1e-30f)); }
;       u32x2 a, b, c2, d; a.x = pk2(qt[0], qt[1]); a.y = pk2(qt[2], qt[3]); b.x = pk2(qt[4], qt[5]); b.y = pk2(qt[6], qt[7]);
;       c2.x = pk2(kt[0], kt[1]); c2.y = pk2(kt[2], kt[3]); d.x = pk2(kt[4], kt[5]); d.y = pk2(kt[6], kt[7]);
;       unsigned char* oq = tl + TL_HQ + st * HQS + k0 * 2; unsigned char* ok = tl + TL_HK + st * HQS + k0 * 2;
;       *(u32x2*)oq = a; *(u32x2*)(oq + 8) = b; *(u32x2*)ok = c2; *(u32x2*)(ok + 8) = d;
;       if (tau == 15) { float* ge = (float*)(tl + TL_HGE) + sc * 128 + k0; *(f32x4*)ge = (f32x4){G[0], G[1], G[2], G[3]}; *(f32x4*)(ge + 4) = (f32x4){G[4], G[5], G[6], G[7]}; } } }
.LBB0_655:
	s_or_b64 exec, exec, s[10:11]
	s_waitcnt vmcnt(4)
	v_cvt_f32_f16_sdwa v95, v60 dst_sel:DWORD dst_unused:UNUSED_PAD src0_sel:WORD_1
	v_cvt_f32_f16_e32 v94, v60
	v_cvt_f32_f16_sdwa v99, v56 dst_sel:DWORD dst_unused:UNUSED_PAD src0_sel:WORD_1
	v_pk_add_f32 v[92:93], v[94:95], 1.0 op_sel_hi:[1,0] neg_lo:[1,0] neg_hi:[1,0]
	v_cvt_f32_f16_e32 v98, v56
	s_nop 0
	v_mul_f32_dpp v92, v92, v92 row_shr:1 row_mask:0xf bank_mask:0xf
	v_mul_f32_dpp v93, v93, v93 row_shr:1 row_mask:0xf bank_mask:0xf
	s_nop 0
	v_mul_f32_dpp v92, v92, v92 row_shr:2 row_mask:0xf bank_mask:0xf
	v_mul_f32_dpp v93, v93, v93 row_shr:2 row_mask:0xf bank_mask:0xf
	v_cvt_f32_f16_sdwa v159, v63 dst_sel:DWORD dst_unused:UNUSED_PAD src0_sel:WORD_1
	v_mul_f32_dpp v92, v92, v92 row_shr:4 row_mask:0xf bank_mask:0xf
	v_mul_f32_dpp v93, v93, v93 row_shr:4 row_mask:0xf bank_mask:0xf
	v_cvt_f32_f16_e32 v158, v63
	v_mul_f32_dpp v92, v92, v92 row_shr:8 row_mask:0xf bank_mask:0xf
	v_mul_f32_dpp v93, v93, v93 row_shr:8 row_mask:0xf bank_mask:0xf
	v_max_f32_e32 v96, 0xda24260, v92
	v_max_f32_e32 v97, 0xda24260, v93
	v_rcp_f32_e32 v96, v96
	v_rcp_f32_e32 v97, v97
	v_pk_mul_f32 v[142:143], v[92:93], v[98:99]
	v_pk_mul_f32 v[144:145], v[96:97], v[94:95]
	v_cvt_f32_f16_sdwa v97, v61 dst_sel:DWORD dst_unused:UNUSED_PAD src0_sel:WORD_1
	v_cvt_f32_f16_e32 v96, v61
	v_cvt_f32_f16_sdwa v147, v57 dst_sel:DWORD dst_unused:UNUSED_PAD src0_sel:WORD_1
	v_cvt_f32_f16_e32 v146, v57
	v_pk_add_f32 v[94:95], v[96:97], 1.0 op_sel_hi:[1,0] neg_lo:[1,0] neg_hi:[1,0]
	v_cvt_f32_f16_sdwa v157, v58 dst_sel:DWORD dst_unused:UNUSED_PAD src0_sel:WORD_1
	v_cvt_f32_f16_e32 v156, v58
	v_mul_f32_dpp v94, v94, v94 row_shr:1 row_mask:0xf bank_mask:0xf
	v_mul_f32_dpp v95, v95, v95 row_shr:1 row_mask:0xf bank_mask:0xf
	v_cvt_f32_f16_sdwa v163, v59 dst_sel:DWORD dst_unused:UNUSED_PAD src0_sel:WORD_1
	v_mul_f32_dpp v94, v94, v94 row_shr:2 row_mask:0xf bank_mask:0xf
	v_mul_f32_dpp v95, v95, v95 row_shr:2 row_mask:0xf bank_mask:0xf
	v_cvt_f32_f16_e32 v162, v59
	v_mul_f32_dpp v94, v94, v94 row_shr:4 row_mask:0xf bank_mask:0xf
	v_mul_f32_dpp v95, v95, v95 row_shr:4 row_mask:0xf bank_mask:0xf
	v_cvt_pk_bf16_f32 v142, v142, v143
	v_mul_f32_dpp v94, v94, v94 row_shr:8 row_mask:0xf bank_mask:0xf
	v_mul_f32_dpp v95, v95, v95 row_shr:8 row_mask:0xf bank_mask:0xf
	v_cvt_pk_bf16_f32 v144, v144, v145
	v_max_f32_e32 v98, 0xda24260, v94
	v_max_f32_e32 v99, 0xda24260, v95
	v_rcp_f32_e32 v98, v98
	v_rcp_f32_e32 v99, v99
	v_pk_mul_f32 v[146:147], v[94:95], v[146:147]
	v_pk_mul_f32 v[148:149], v[98:99], v[96:97]
	v_cvt_f32_f16_sdwa v99, v62 dst_sel:DWORD dst_unused:UNUSED_PAD src0_sel:WORD_1
	v_cvt_f32_f16_e32 v98, v62
	v_cvt_pk_bf16_f32 v143, v146, v147
	v_cvt_pk_bf16_f32 v145, v148, v149
	v_pk_add_f32 v[96:97], v[98:99], 1.0 op_sel_hi:[1,0] neg_lo:[1,0] neg_hi:[1,0]
	s_nop 1
	v_mul_f32_dpp v96, v96, v96 row_shr:1 row_mask:0xf bank_mask:0xf
	v_mul_f32_dpp v97, v97, v97 row_shr:1 row_mask:0xf bank_mask:0xf
	s_nop 0
	v_mul_f32_dpp v96, v96, v96 row_shr:2 row_mask:0xf bank_mask:0xf
	v_mul_f32_dpp v97, v97, v97 row_shr:2 row_mask:0xf bank_mask:0xf
	s_nop 0
	v_mul_f32_dpp v96, v96, v96 row_shr:4 row_mask:0xf bank_mask:0xf
	v_mul_f32_dpp v97, v97, v97 row_shr:4 row_mask:0xf bank_mask:0xf
	s_nop 0
	v_mul_f32_dpp v96, v96, v96 row_shr:8 row_mask:0xf bank_mask:0xf
	v_mul_f32_dpp v97, v97, v97 row_shr:8 row_mask:0xf bank_mask:0xf
	s_nop 0
	v_max_f32_e32 v141, 0xda24260, v96
	v_rcp_f32_e32 v150, v141
	v_max_f32_e32 v141, 0xda24260, v97
	v_rcp_f32_e32 v151, v141
	v_pk_mul_f32 v[156:157], v[96:97], v[156:157]
	v_pk_mul_f32 v[150:151], v[150:151], v[98:99]
	v_pk_add_f32 v[98:99], v[158:159], 1.0 op_sel_hi:[1,0] neg_lo:[1,0] neg_hi:[1,0]
	v_cvt_pk_bf16_f32 v146, v156, v157
	v_cvt_pk_bf16_f32 v148, v150, v151
	v_mul_f32_dpp v98, v98, v98 row_shr:1 row_mask:0xf bank_mask:0xf
	v_mul_f32_dpp v99, v99, v99 row_shr:1 row_mask:0xf bank_mask:0xf
	s_nop 0
	v_mul_f32_dpp v98, v98, v98 row_shr:2 row_mask:0xf bank_mask:0xf
	v_mul_f32_dpp v99, v99, v99 row_shr:2 row_mask:0xf bank_mask:0xf
	s_nop 0
	v_mul_f32_dpp v98, v98, v98 row_shr:4 row_mask:0xf bank_mask:0xf
	v_mul_f32_dpp v99, v99, v99 row_shr:4 row_mask:0xf bank_mask:0xf
	s_nop 0
	v_mul_f32_dpp v98, v98, v98 row_shr:8 row_mask:0xf bank_mask:0xf
	v_mul_f32_dpp v99, v99, v99 row_shr:8 row_mask:0xf bank_mask:0xf
	s_nop 0
	v_max_f32_e32 v141, 0xda24260, v98
	v_rcp_f32_e32 v160, v141
	v_max_f32_e32 v141, 0xda24260, v99
	v_rcp_f32_e32 v161, v141
	v_pk_mul_f32 v[162:163], v[98:99], v[162:163]
	v_add_u32_e32 v141, v140, v134
	v_cvt_pk_bf16_f32 v147, v162, v163
	v_pk_mul_f32 v[158:159], v[160:161], v[158:159]
	v_add_u32_e32 v150, 0xc000, v141
	v_cvt_pk_bf16_f32 v149, v158, v159
	v_add_u32_e32 v141, 0xe100, v141
	ds_write2_b64 v150, v[142:143], v[146:147] offset1:1
	ds_write2_b64 v141, v[144:145], v[148:149] offset1:1
	s_and_saveexec_b64 s[10:11], s[8:9]
	s_cbranch_execz .LBB0_657
	ds_write_b128 v139, v[92:95] offset:28288
	ds_write_b128 v139, v[96:99] offset:28304
; __device__ __forceinline__ unsigned pk2(float lo, float hi) { f32x2n v = {lo, hi}; bf16x2n b = __builtin_convertvector(v, bf16x2n); return __builtin_bit_cast(unsigned, b); }
;   template <int CTRL> static __device__ __forceinline__ float shr1(float x) { return __int_as_float(__builtin_amdgcn_update_dpp(__float_as_int(1.0f), __float_as_int(x), CTRL, 0xF, 0xF, false)); }
;   static __device__ __forceinline__ float scan16(float x) { x *= shr1<0x111>(x); x *= shr1<0x112>(x); x *= shr1<0x114>(x); x *= shr1<0x118>(x); return x; }
;   __device__ __forceinline__ void hg_prep(const h16x8 (&q)[8], const h16x8 (&u)[8], int tb) const { unsigned char* tl = smem + SC_TL + tb * SC_TLB; const int rho = lane >> 4, tau = lane & 15;
; #pragma unroll
;     for (int it = 0; it < 8; ++it) { const int bidx = it * 4 + rho, sc = bidx >> 4, k0 = (bidx & 15) * 8, st = sc * 16 + tau;
;       float G[8], qt[8], kt[8];
; #pragma unroll
;       for (int e = 0; e < 8; ++e) { const float uu = (float)u[it][e]; G[e] = scan16(1.f - uu); qt[e] = (float)q[it][e] * G[e]; kt[e] = uu * __builtin_amdgcn_rcpf(fmaxf(G[e], 1e-30f)); }
;       u32x2 a, b, c2, d; a.x = pk2(qt[0], qt[1]); a.y = pk2(qt[2], qt[3]); b.x = pk2(qt[4], qt[5]); b.y = pk2(qt[6], qt[7]);
;       c2.x = pk2(kt[0], kt[1]); c2.y = pk2(kt[2], kt[3]); d.x = pk2(kt[4], kt[5]); d.y = pk2(kt[6], kt[7]);
;       unsigned char* oq = tl + TL_HQ + st * HQS + k0 * 2; unsigned char* ok = tl + TL_HK + st * HQS + k0 * 2;
;       *(u32x2*)oq = a; *(u32x2*)(oq + 8) = b; *(u32x2*)ok = c2; *(u32x2*)(ok + 8) = d;
;       if (tau == 15) { float* ge = (float*)(tl + TL_HGE) + sc * 128 + k0; *(f32x4*)ge = (f32x4){G[0], G[1], G[2], G[3]}; *(f32x4*)(ge + 4) = (f32x4){G[4], G[5], G[6], G[7]}; } } }
.LBB0_657:
	s_or_b64 exec, exec, s[10:11]
	s_waitcnt vmcnt(2)
	v_cvt_f32_f16_sdwa v95, v68 dst_sel:DWORD dst_unused:UNUSED_PAD src0_sel:WORD_1
	v_cvt_f32_f16_e32 v94, v68
	v_cvt_f32_f16_sdwa v99, v64 dst_sel:DWORD dst_unused:UNUSED_PAD src0_sel:WORD_1
	v_pk_add_f32 v[92:93], v[94:95], 1.0 op_sel_hi:[1,0] neg_lo:[1,0] neg_hi:[1,0]
	v_cvt_f32_f16_e32 v98, v64
	s_nop 0
	v_mul_f32_dpp v92, v92, v92 row_shr:1 row_mask:0xf bank_mask:0xf
	v_mul_f32_dpp v93, v93, v93 row_shr:1 row_mask:0xf bank_mask:0xf
	s_nop 0
	v_mul_f32_dpp v92, v92, v92 row_shr:2 row_mask:0xf bank_mask:0xf
	v_mul_f32_dpp v93, v93, v93 row_shr:2 row_mask:0xf bank_mask:0xf
	v_cvt_f32_f16_sdwa v159, v71 dst_sel:DWORD dst_unused:UNUSED_PAD src0_sel:WORD_1
	v_mul_f32_dpp v92, v92, v92 row_shr:4 row_mask:0xf bank_mask:0xf
	v_mul_f32_dpp v93, v93, v93 row_shr:4 row_mask:0xf bank_mask:0xf
	v_cvt_f32_f16_e32 v158, v71
	v_mul_f32_dpp v92, v92, v92 row_shr:8 row_mask:0xf bank_mask:0xf
	v_mul_f32_dpp v93, v93, v93 row_shr:8 row_mask:0xf bank_mask:0xf
	v_max_f32_e32 v96, 0xda24260, v92
	v_max_f32_e32 v97, 0xda24260, v93
	v_rcp_f32_e32 v96, v96
	v_rcp_f32_e32 v97, v97
	v_pk_mul_f32 v[142:143], v[92:93], v[98:99]
	v_pk_mul_f32 v[144:145], v[96:97], v[94:95]
	v_cvt_f32_f16_sdwa v97, v69 dst_sel:DWORD dst_unused:UNUSED_PAD src0_sel:WORD_1
	v_cvt_f32_f16_e32 v96, v69
	v_cvt_f32_f16_sdwa v147, v65 dst_sel:DWORD dst_unused:UNUSED_PAD src0_sel:WORD_1
	v_cvt_f32_f16_e32 v146, v65
	v_pk_add_f32 v[94:95], v[96:97], 1.0 op_sel_hi:[1,0] neg_lo:[1,0] neg_hi:[1,0]
	v_cvt_f32_f16_sdwa v157, v66 dst_sel:DWORD dst_unused:UNUSED_PAD src0_sel:WORD_1
	v_cvt_f32_f16_e32 v156, v66
	v_mul_f32_dpp v94, v94, v94 row_shr:1 row_mask:0xf bank_mask:0xf
	v_mul_f32_dpp v95, v95, v95 row_shr:1 row_mask:0xf bank_mask:0xf
	v_cvt_f32_f16_sdwa v163, v67 dst_sel:DWORD dst_unused:UNUSED_PAD src0_sel:WORD_1
	v_mul_f32_dpp v94, v94, v94 row_shr:2 row_mask:0xf bank_mask:0xf
	v_mul_f32_dpp v95, v95, v95 row_shr:2 row_mask:0xf bank_mask:0xf
	v_cvt_f32_f16_e32 v162, v67
	v_mul_f32_dpp v94, v94, v94 row_shr:4 row_mask:0xf bank_mask:0xf
	v_mul_f32_dpp v95, v95, v95 row_shr:4 row_mask:0xf bank_mask:0xf
	v_cvt_pk_bf16_f32 v142, v142, v143
	v_mul_f32_dpp v94, v94, v94 row_shr:8 row_mask:0xf bank_mask:0xf
	v_mul_f32_dpp v95, v95, v95 row_shr:8 row_mask:0xf bank_mask:0xf
	v_cvt_pk_bf16_f32 v144, v144, v145
	v_max_f32_e32 v98, 0xda24260, v94
	v_max_f32_e32 v99, 0xda24260, v95
	v_rcp_f32_e32 v98, v98
	v_rcp_f32_e32 v99, v99
	v_pk_mul_f32 v[146:147], v[94:95], v[146:147]
	v_pk_mul_f32 v[148:149], v[98:99], v[96:97]
	v_cvt_f32_f16_sdwa v99, v70 dst_sel:DWORD dst_unused:UNUSED_PAD src0_sel:WORD_1
	v_cvt_f32_f16_e32 v98, v70
	v_cvt_pk_bf16_f32 v143, v146, v147
	v_cvt_pk_bf16_f32 v145, v148, v149
	v_pk_add_f32 v[96:97], v[98:99], 1.0 op_sel_hi:[1,0] neg_lo:[1,0] neg_hi:[1,0]
	s_nop 1
	v_mul_f32_dpp v96, v96, v96 row_shr:1 row_mask:0xf bank_mask:0xf
	v_mul_f32_dpp v97, v97, v97 row_shr:1 row_mask:0xf bank_mask:0xf
	s_nop 0
	v_mul_f32_dpp v96, v96, v96 row_shr:2 row_mask:0xf bank_mask:0xf
	v_mul_f32_dpp v97, v97, v97 row_shr:2 row_mask:0xf bank_mask:0xf
	s_nop 0
	v_mul_f32_dpp v96, v96, v96 row_shr:4 row_mask:0xf bank_mask:0xf
	v_mul_f32_dpp v97, v97, v97 row_shr:4 row_mask:0xf bank_mask:0xf
	s_nop 0
	v_mul_f32_dpp v96, v96, v96 row_shr:8 row_mask:0xf bank_mask:0xf
	v_mul_f32_dpp v97, v97, v97 row_shr:8 row_mask:0xf bank_mask:0xf
	s_nop 0
	v_max_f32_e32 v141, 0xda24260, v96
	v_rcp_f32_e32 v150, v141
	v_max_f32_e32 v141, 0xda24260, v97
	v_rcp_f32_e32 v151, v141
	v_pk_mul_f32 v[156:157], v[96:97], v[156:157]
	v_pk_mul_f32 v[150:151], v[150:151], v[98:99]
	v_pk_add_f32 v[98:99], v[158:159], 1.0 op_sel_hi:[1,0] neg_lo:[1,0] neg_hi:[1,0]
	v_cvt_pk_bf16_f32 v146, v156, v157
	v_cvt_pk_bf16_f32 v148, v150, v151
	v_mul_f32_dpp v98, v98, v98 row_shr:1 row_mask:0xf bank_mask:0xf
	v_mul_f32_dpp v99, v99, v99 row_shr:1 row_mask:0xf bank_mask:0xf
	s_nop 0
	v_mul_f32_dpp v98, v98, v98 row_shr:2 row_mask:0xf bank_mask:0xf
	v_mul_f32_dpp v99, v99, v99 row_shr:2 row_mask:0xf bank_mask:0xf
	s_nop 0
	v_mul_f32_dpp v98, v98, v98 row_shr:4 row_mask:0xf bank_mask:0xf
	v_mul_f32_dpp v99, v99, v99 row_shr:4 row_mask:0xf bank_mask:0xf
	s_nop 0
	v_mul_f32_dpp v98, v98, v98 row_shr:8 row_mask:0xf bank_mask:0xf
	v_mul_f32_dpp v99, v99, v99 row_shr:8 row_mask:0xf bank_mask:0xf
	s_nop 0
	v_max_f32_e32 v141, 0xda24260, v98
	v_rcp_f32_e32 v160, v141
	v_max_f32_e32 v141, 0xda24260, v99
	v_rcp_f32_e32 v161, v141
	v_pk_mul_f32 v[162:163], v[98:99], v[162:163]
	v_add_u32_e32 v141, v140, v135
	v_cvt_pk_bf16_f32 v147, v162, v163
	v_pk_mul_f32 v[158:159], v[160:161], v[158:159]
	v_add_u32_e32 v150, 0xc000, v141
	v_cvt_pk_bf16_f32 v149, v158, v159
	v_add_u32_e32 v141, 0xe100, v141
	ds_write2_b64 v150, v[142:143], v[146:147] offset1:1
	ds_write2_b64 v141, v[144:145], v[148:149] offset1:1
	s_and_saveexec_b64 s[10:11], s[8:9]
	s_cbranch_execz .LBB0_659
	ds_write_b128 v139, v[92:95] offset:28416
	ds_write_b128 v139, v[96:99] offset:28432
; __device__ __forceinline__ unsigned pk2(float lo, float hi) { f32x2n v = {lo, hi}; bf16x2n b = __builtin_convertvector(v, bf16x2n); return __builtin_bit_cast(unsigned, b); }
;   template <int CTRL> static __device__ __forceinline__ float shr1(float x) { return __int_as_float(__builtin_amdgcn_update_dpp(__float_as_int(1.0f), __float_as_int(x), CTRL, 0xF, 0xF, false)); }
;   static __device__ __forceinline__ float scan16(float x) { x *= shr1<0x111>(x); x *= shr1<0x112>(x); x *= shr1<0x114>(x); x *= shr1<0x118>(x); return x; }
;   __device__ __forceinline__ void hg_prep(const h16x8 (&q)[8], const h16x8 (&u)[8], int tb) const { unsigned char* tl = smem + SC_TL + tb * SC_TLB; const int rho = lane >> 4, tau = lane & 15;
; #pragma unroll
;     for (int it = 0; it < 8; ++it) { const int bidx = it * 4 + rho, sc = bidx >> 4, k0 = (bidx & 15) * 8, st = sc * 16 + tau;
;       float G[8], qt[8], kt[8];
; #pragma unroll
;       for (int e = 0; e < 8; ++e) { const float uu = (float)u[it][e]; G[e] = scan16(1.f - uu); qt[e] = (float)q[it][e] * G[e]; kt[e] = uu * __builtin_amdgcn_rcpf(fmaxf(G[e], 1e-30f)); }
;       u32x2 a, b, c2, d; a.x = pk2(qt[0], qt[1]); a.y = pk2(qt[2], qt[3]); b.x = pk2(qt[4], qt[5]); b.y = pk2(qt[6], qt[7]);
;       c2.x = pk2(kt[0], kt[1]); c2.y = pk2(kt[2], kt[3]); d.x = pk2(kt[4], kt[5]); d.y = pk2(kt[6], kt[7]);
;       unsigned char* oq = tl + TL_HQ + st * HQS + k0 * 2; unsigned char* ok = tl + TL_HK + st * HQS + k0 * 2;
;       *(u32x2*)oq = a; *(u32x2*)(oq + 8) = b; *(u32x2*)ok = c2; *(u32x2*)(ok + 8) = d;
;       if (tau == 15) { float* ge = (float*)(tl + TL_HGE) + sc * 128 + k0; *(f32x4*)ge = (f32x4){G[0], G[1], G[2], G[3]}; *(f32x4*)(ge + 4) = (f32x4){G[4], G[5], G[6], G[7]}; } } }
.LBB0_659:
	s_or_b64 exec, exec, s[10:11]
	s_waitcnt vmcnt(0)
	v_cvt_f32_f16_sdwa v95, v80 dst_sel:DWORD dst_unused:UNUSED_PAD src0_sel:WORD_1
	v_cvt_f32_f16_e32 v94, v80
	v_cvt_f32_f16_sdwa v99, v72 dst_sel:DWORD dst_unused:UNUSED_PAD src0_sel:WORD_1
	v_pk_add_f32 v[92:93], v[94:95], 1.0 op_sel_hi:[1,0] neg_lo:[1,0] neg_hi:[1,0]
	v_cvt_f32_f16_e32 v98, v72
	s_nop 0
	v_mul_f32_dpp v92, v92, v92 row_shr:1 row_mask:0xf bank_mask:0xf
	v_mul_f32_dpp v93, v93, v93 row_shr:1 row_mask:0xf bank_mask:0xf
	s_nop 0
	v_mul_f32_dpp v92, v92, v92 row_shr:2 row_mask:0xf bank_mask:0xf
	v_mul_f32_dpp v93, v93, v93 row_shr:2 row_mask:0xf bank_mask:0xf
	v_cvt_f32_f16_sdwa v159, v83 dst_sel:DWORD dst_unused:UNUSED_PAD src0_sel:WORD_1
	v_mul_f32_dpp v92, v92, v92 row_shr:4 row_mask:0xf bank_mask:0xf
	v_mul_f32_dpp v93, v93, v93 row_shr:4 row_mask:0xf bank_mask:0xf
	v_cvt_f32_f16_e32 v158, v83
	v_mul_f32_dpp v92, v92, v92 row_shr:8 row_mask:0xf bank_mask:0xf
	v_mul_f32_dpp v93, v93, v93 row_shr:8 row_mask:0xf bank_mask:0xf
	v_max_f32_e32 v96, 0xda24260, v92
	v_max_f32_e32 v97, 0xda24260, v93
	v_rcp_f32_e32 v96, v96
	v_rcp_f32_e32 v97, v97
	v_pk_mul_f32 v[142:143], v[92:93], v[98:99]
	v_pk_mul_f32 v[144:145], v[96:97], v[94:95]
	v_cvt_f32_f16_sdwa v97, v81 dst_sel:DWORD dst_unused:UNUSED_PAD src0_sel:WORD_1
	v_cvt_f32_f16_e32 v96, v81
	v_cvt_f32_f16_sdwa v147, v73 dst_sel:DWORD dst_unused:UNUSED_PAD src0_sel:WORD_1
	v_cvt_f32_f16_e32 v146, v73
	v_pk_add_f32 v[94:95], v[96:97], 1.0 op_sel_hi:[1,0] neg_lo:[1,0] neg_hi:[1,0]
	v_cvt_f32_f16_sdwa v157, v74 dst_sel:DWORD dst_unused:UNUSED_PAD src0_sel:WORD_1
	v_cvt_f32_f16_e32 v156, v74
	v_mul_f32_dpp v94, v94, v94 row_shr:1 row_mask:0xf bank_mask:0xf
	v_mul_f32_dpp v95, v95, v95 row_shr:1 row_mask:0xf bank_mask:0xf
	v_cvt_f32_f16_sdwa v163, v75 dst_sel:DWORD dst_unused:UNUSED_PAD src0_sel:WORD_1
	v_mul_f32_dpp v94, v94, v94 row_shr:2 row_mask:0xf bank_mask:0xf
	v_mul_f32_dpp v95, v95, v95 row_shr:2 row_mask:0xf bank_mask:0xf
	v_cvt_f32_f16_e32 v162, v75
	v_mul_f32_dpp v94, v94, v94 row_shr:4 row_mask:0xf bank_mask:0xf
	v_mul_f32_dpp v95, v95, v95 row_shr:4 row_mask:0xf bank_mask:0xf
	v_add_u32_e32 v140, v140, v136
	v_mul_f32_dpp v94, v94, v94 row_shr:8 row_mask:0xf bank_mask:0xf
	v_mul_f32_dpp v95, v95, v95 row_shr:8 row_mask:0xf bank_mask:0xf
	v_cvt_pk_bf16_f32 v142, v142, v143
	v_max_f32_e32 v98, 0xda24260, v94
	v_max_f32_e32 v99, 0xda24260, v95
	v_rcp_f32_e32 v98, v98
	v_rcp_f32_e32 v99, v99
	v_pk_mul_f32 v[146:147], v[94:95], v[146:147]
	v_cvt_pk_bf16_f32 v144, v144, v145
	v_cvt_pk_bf16_f32 v143, v146, v147
	v_pk_mul_f32 v[148:149], v[98:99], v[96:97]
	v_cvt_f32_f16_sdwa v99, v82 dst_sel:DWORD dst_unused:UNUSED_PAD src0_sel:WORD_1
	v_cvt_f32_f16_e32 v98, v82
	v_cvt_pk_bf16_f32 v145, v148, v149
	v_pk_add_f32 v[96:97], v[98:99], 1.0 op_sel_hi:[1,0] neg_lo:[1,0] neg_hi:[1,0]
	s_nop 1
	v_mul_f32_dpp v96, v96, v96 row_shr:1 row_mask:0xf bank_mask:0xf
	v_mul_f32_dpp v97, v97, v97 row_shr:1 row_mask:0xf bank_mask:0xf
	s_nop 0
	v_mul_f32_dpp v96, v96, v96 row_shr:2 row_mask:0xf bank_mask:0xf
	v_mul_f32_dpp v97, v97, v97 row_shr:2 row_mask:0xf bank_mask:0xf
	s_nop 0
	v_mul_f32_dpp v96, v96, v96 row_shr:4 row_mask:0xf bank_mask:0xf
	v_mul_f32_dpp v97, v97, v97 row_shr:4 row_mask:0xf bank_mask:0xf
	s_nop 0
	v_mul_f32_dpp v96, v96, v96 row_shr:8 row_mask:0xf bank_mask:0xf
	v_mul_f32_dpp v97, v97, v97 row_shr:8 row_mask:0xf bank_mask:0xf
	s_nop 0
	v_max_f32_e32 v141, 0xda24260, v96
	v_rcp_f32_e32 v150, v141
	v_max_f32_e32 v141, 0xda24260, v97
	v_rcp_f32_e32 v151, v141
	v_pk_mul_f32 v[156:157], v[96:97], v[156:157]
	v_pk_mul_f32 v[150:151], v[150:151], v[98:99]
	v_pk_add_f32 v[98:99], v[158:159], 1.0 op_sel_hi:[1,0] neg_lo:[1,0] neg_hi:[1,0]
	v_cvt_pk_bf16_f32 v146, v156, v157
	v_cvt_pk_bf16_f32 v148, v150, v151
	v_mul_f32_dpp v98, v98, v98 row_shr:1 row_mask:0xf bank_mask:0xf
	v_mul_f32_dpp v99, v99, v99 row_shr:1 row_mask:0xf bank_mask:0xf
	s_nop 0
	v_mul_f32_dpp v98, v98, v98 row_shr:2 row_mask:0xf bank_mask:0xf
	v_mul_f32_dpp v99, v99, v99 row_shr:2 row_mask:0xf bank_mask:0xf
	s_nop 0
	v_mul_f32_dpp v98, v98, v98 row_shr:4 row_mask:0xf bank_mask:0xf
	v_mul_f32_dpp v99, v99, v99 row_shr:4 row_mask:0xf bank_mask:0xf
	s_nop 0
	v_mul_f32_dpp v98, v98, v98 row_shr:8 row_mask:0xf bank_mask:0xf
	v_mul_f32_dpp v99, v99, v99 row_shr:8 row_mask:0xf bank_mask:0xf
	s_nop 0
	v_max_f32_e32 v141, 0xda24260, v98
	v_rcp_f32_e32 v160, v141
	v_max_f32_e32 v141, 0xda24260, v99
	v_rcp_f32_e32 v161, v141
	v_pk_mul_f32 v[162:163], v[98:99], v[162:163]
	v_add_u32_e32 v141, 0xc000, v140
	v_cvt_pk_bf16_f32 v147, v162, v163
	v_pk_mul_f32 v[158:159], v[160:161], v[158:159]
	v_add_u32_e32 v140, 0xe100, v140
	v_cvt_pk_bf16_f32 v149, v158, v159
	ds_write2_b64 v141, v[142:143], v[146:147] offset1:1
	ds_write2_b64 v140, v[144:145], v[148:149] offset1:1
	s_and_saveexec_b64 s[10:11], s[8:9]
	s_cbranch_execz .LBB0_661
	ds_write_b128 v139, v[92:95] offset:28544
	ds_write_b128 v139, v[96:99] offset:28560

; __device__ __forceinline__ bf16_t f2bf(float f) { return (bf16_t)(pk2(f, 0.f) & 0xffffu); }
; __device__ __forceinline__ float fmix_lo(unsigned h2, float b, float c) { float d; asm("v_fma_mix_f32 %0, %1, %2, %3 op_sel_hi:[1,0,0]" : "=v"(d) : "v"(h2), "v"(b), "v"(c)); return d; }
; template <int ROLE>
; __device__ __forceinline__ void scan_role(const ScanCtx& cx, KPR p) {
;     ...
;       const unsigned char* cb = smem + (c & 1) * SC_RWB;
;       const unsigned char* lb = cb + ks * 8;
;       const unsigned char* lv = cb + 128 + (rg * 4 + vi) * 2;
;       struct RIn { u32x2 r, kk, u, b, km; h16 v; };
;       auto lds_ld = [&](int st) { RIn x; const unsigned char* q = lb + st * 768;
;         x.r = *(const u32x2*)(q); x.kk = *(const u32x2*)(q + 256); x.u = *(const u32x2*)(q + 384); x.b = *(const u32x2*)(q + 512); x.km = *(const u32x2*)(q + 640);
;         x.v = *(const h16*)(lv + st * 768); return x; };
;       RIn nx = lds_ld(0);
; #pragma unroll
;       for (int hb = 0; hb < SC_CH; hb += 16) {
; #pragma unroll
;       for (int s16 = 0; s16 < 16; ++s16) { const int st = hb + s16; const RIn x = nx; if (st + 1 < SC_CH) nx = lds_ld(st + 1);
;         const float vv = (float)x.v;
;         float ya = fmix_lo(rprev.x, s[0], 0.f), yb = fmix_hi(rprev.x, s[1], 0.f);
;         float sa = fmix_lo(x.kk.x, s[0], 0.f), sb = fmix_hi(x.kk.x, s[1], 0.f);
;         ya = fmix_lo(rprev.y, s[2], ya); yb = fmix_hi(rprev.y, s[3], yb);
;         sa = fmix_lo(x.kk.y, s[2], sa); sb = fmix_hi(x.kk.y, s[3], sb);
;         float t0_ = fmixn_lo(x.u.x, s[0], s[0]), t1_ = fmixn_hi(x.u.x, s[1], s[1]), t2_ = fmixn_lo(x.u.y, s[2], s[2]), t3_ = fmixn_hi(x.u.y, s[3], s[3]);
;         float yy = ya + yb, ss = sa + sb;
;         rowsum16x2(ss, yy);
;         t0_ = fmix_lo(x.km.x, vv, t0_); t1_ = fmix_hi(x.km.x, vv, t1_); t2_ = fmix_lo(x.km.y, vv, t2_); t3_ = fmix_hi(x.km.y, vv, t3_);
;         const float nsa = -ss;
;         s[0] = fmix_lo(x.b.x, nsa, t0_); s[1] = fmix_hi(x.b.x, nsa, t1_); s[2] = fmix_lo(x.b.y, nsa, t2_); s[3] = fmix_hi(x.b.y, nsa, t3_);
;         rprev = x.r;
;         if (s16 == 0) { if (t0 + hb > 0) YO[(size_t)(cx.br * TPB + seq_pos(t0 + hb - 16 + ks, cx.dr)) * NNGP] = f2bf(ks == 15 ? yy : keep); }
;         else keep = ((s16 - 1) == ks) ? yy : keep; }
.LBB0_685:
	s_bitcmp1_b32 s50, 0
	s_cselect_b32 s42, 0x6000, 0
	s_add_i32 s56, s42, 0
	v_add_u32_e32 v54, s56, v51
	v_add_u32_e32 v55, s56, v50
	ds_read2_b64 v[40:43], v54 offset1:32
	ds_read2_b64 v[26:29], v54 offset0:48 offset1:64
	ds_read2_b64 v[16:19], v54 offset0:80 offset1:96
	ds_read_u16 v30, v55 offset:128
	v_fma_mix_f32 v31, v20, v22, v2 op_sel_hi:[1,0,0]
	v_fma_mix_f32 v20, v20, v25, v2 op_sel:[1,0,0] op_sel_hi:[1,0,0]
	s_waitcnt lgkmcnt(3)
	v_fma_mix_f32 v58, v42, v22, v2 op_sel_hi:[1,0,0]
	v_fma_mix_f32 v42, v42, v25, v2 op_sel:[1,0,0] op_sel_hi:[1,0,0]
	ds_read2_b64 v[36:39], v54 offset0:128 offset1:144
	ds_read2_b64 v[32:35], v54 offset0:160 offset1:176
	ds_read_u16 v57, v55 offset:896
	v_fma_mix_f32 v31, v21, v24, v31 op_sel_hi:[1,0,0]
	v_fma_mix_f32 v20, v21, v23, v20 op_sel:[1,0,0] op_sel_hi:[1,0,0]
	v_fma_mix_f32 v21, v43, v24, v58 op_sel_hi:[1,0,0]
	v_fma_mix_f32 v42, v43, v23, v42 op_sel:[1,0,0] op_sel_hi:[1,0,0]
	s_waitcnt lgkmcnt(5)
	v_fma_mix_f32 v22, -v26, v22, v22 op_sel_hi:[1,0,0]
	s_waitcnt lgkmcnt(3)
	v_add_f32_e32 v21, v21, v42
	v_add_f32_e32 v20, v31, v20
	v_fma_mix_f32 v25, -v26, v25, v25 op_sel:[1,0,0] op_sel_hi:[1,0,0]
	v_fma_mix_f32 v22, v16, v30, v22 op_sel_hi:[1,1,0]
	s_cmp_lg_u32 s51, 64
	v_add_f32_dpp v21, v21, v21 quad_perm:[1,0,3,2] row_mask:0xf bank_mask:0xf bound_ctrl:1
	v_add_f32_dpp v20, v20, v20 quad_perm:[1,0,3,2] row_mask:0xf bank_mask:0xf bound_ctrl:1
	v_fma_mix_f32 v16, v16, v30, v25 op_sel:[1,0,0] op_sel_hi:[1,1,0]
	v_fma_mix_f32 v24, -v27, v24, v24 op_sel_hi:[1,0,0]
	v_fma_mix_f32 v23, -v27, v23, v23 op_sel:[1,0,0] op_sel_hi:[1,0,0]
	s_mov_b64 s[42:43], -1
	v_add_f32_dpp v21, v21, v21 quad_perm:[2,3,0,1] row_mask:0xf bank_mask:0xf bound_ctrl:1
	v_add_f32_dpp v20, v20, v20 quad_perm:[2,3,0,1] row_mask:0xf bank_mask:0xf bound_ctrl:1
	v_fma_mix_f32 v24, v17, v30, v24 op_sel_hi:[1,1,0]
	v_fma_mix_f32 v23, v17, v30, v23 op_sel:[1,0,0] op_sel_hi:[1,1,0]
	s_nop 0
	v_add_f32_dpp v21, v21, v21 row_ror:4 row_mask:0xf bank_mask:0xf bound_ctrl:1
	v_add_f32_dpp v20, v20, v20 row_ror:4 row_mask:0xf bank_mask:0xf bound_ctrl:1
	s_nop 0
	v_add_f32_dpp v26, v21, v21 row_ror:8 row_mask:0xf bank_mask:0xf bound_ctrl:1
	v_mov_b32_dpp v21, v20 row_ror:8 row_mask:0xf bank_mask:0xf bound_ctrl:1
	v_fma_mix_f32 v43, v28, -v26, v16 op_sel:[1,0,0] op_sel_hi:[1,0,0]
	v_add_u32_e32 v16, s51, v52
	v_fma_mix_f32 v17, v28, -v26, v22 op_sel_hi:[1,0,0]
	v_fma_mix_f32 v58, v29, -v26, v24 op_sel_hi:[1,0,0]
	v_fma_mix_f32 v59, v29, -v26, v23 op_sel:[1,0,0] op_sel_hi:[1,0,0]
	s_cbranch_scc0 .LBB0_687
	v_add_u32_e32 v42, s51, v52
	v_add_f32_e32 v22, v20, v21
	v_subrev_u32_e32 v20, 64, v42
	v_cmp_lt_i32_e32 vcc, s97, v20
	v_cndmask_b32_e64 v22, v56, v22, s[6:7]
	v_cvt_pk_bf16_f32 v22, v22, s0
	v_cndmask_b32_e32 v21, v186, v187, vcc
	v_add_u32_e32 v21, v53, v21
	v_add3_u32 v21, v21, s53, 64
	v_cndmask_b32_e64 v20, v21, v20, s[4:5]
	v_add_u32_e32 v20, s47, v20
	v_mad_i64_i32 v[20:21], s[42:43], v20, s81, v[48:49]
	global_store_short v[20:21], v22, off
	s_mov_b64 s[42:43], 0

; __device__ __forceinline__ bf16_t f2bf(float f) { return (bf16_t)(pk2(f, 0.f) & 0xffffu); }
; __device__ __forceinline__ float fmix_lo(unsigned h2, float b, float c) { float d; asm("v_fma_mix_f32 %0, %1, %2, %3 op_sel_hi:[1,0,0]" : "=v"(d) : "v"(h2), "v"(b), "v"(c)); return d; }
; __device__ __forceinline__ float fmix_hi(unsigned h2, float b, float c) { float d; asm("v_fma_mix_f32 %0, %1, %2, %3 op_sel:[1,0,0] op_sel_hi:[1,0,0]" : "=v"(d) : "v"(h2), "v"(b), "v"(c)); return d; }
; __device__ __forceinline__ float fmixn_lo(unsigned h2, float b, float c) { float d; asm("v_fma_mix_f32 %0, -%1, %2, %3 op_sel_hi:[1,0,0]" : "=v"(d) : "v"(h2), "v"(b), "v"(c)); return d; }
; __device__ __forceinline__ float fmixn_hi(unsigned h2, float b, float c) { float d; asm("v_fma_mix_f32 %0, -%1, %2, %3 op_sel:[1,0,0] op_sel_hi:[1,0,0]" : "=v"(d) : "v"(h2), "v"(b), "v"(c)); return d; }
; template <int ROLE>
; __device__ __forceinline__ void scan_role(const ScanCtx& cx, KPR p) {
;     ...
;       for (int s16 = 0; s16 < 16; ++s16) { const int st = hb + s16; const RIn x = nx; if (st + 1 < SC_CH) nx = lds_ld(st + 1);
;         const float vv = (float)x.v;
;         float ya = fmix_lo(rprev.x, s[0], 0.f), yb = fmix_hi(rprev.x, s[1], 0.f);
;         float sa = fmix_lo(x.kk.x, s[0], 0.f), sb = fmix_hi(x.kk.x, s[1], 0.f);
;         ya = fmix_lo(rprev.y, s[2], ya); yb = fmix_hi(rprev.y, s[3], yb);
;         sa = fmix_lo(x.kk.y, s[2], sa); sb = fmix_hi(x.kk.y, s[3], sb);
;         float t0_ = fmixn_lo(x.u.x, s[0], s[0]), t1_ = fmixn_hi(x.u.x, s[1], s[1]), t2_ = fmixn_lo(x.u.y, s[2], s[2]), t3_ = fmixn_hi(x.u.y, s[3], s[3]);
;         float yy = ya + yb, ss = sa + sb;
;         rowsum16x2(ss, yy);
;         t0_ = fmix_lo(x.km.x, vv, t0_); t1_ = fmix_hi(x.km.x, vv, t1_); t2_ = fmix_lo(x.km.y, vv, t2_); t3_ = fmix_hi(x.km.y, vv, t3_);
;         const float nsa = -ss;
;         s[0] = fmix_lo(x.b.x, nsa, t0_); s[1] = fmix_hi(x.b.x, nsa, t1_); s[2] = fmix_lo(x.b.y, nsa, t2_); s[3] = fmix_hi(x.b.y, nsa, t3_);
;         rprev = x.r;
;         if (s16 == 0) { if (t0 + hb > 0) YO[(size_t)(cx.br * TPB + seq_pos(t0 + hb - 16 + ks, cx.dr)) * NNGP] = f2bf(ks == 15 ? yy : keep); }
;         else keep = ((s16 - 1) == ks) ? yy : keep; }
.LBB0_689:
	s_waitcnt lgkmcnt(2)
	v_fma_mix_f32 v61, v36, v17, v2 op_sel_hi:[1,0,0]
	v_fma_mix_f32 v36, v36, v43, v2 op_sel:[1,0,0] op_sel_hi:[1,0,0]
	v_fma_mix_f32 v60, v40, v17, v2 op_sel_hi:[1,0,0]
	v_fma_mix_f32 v40, v40, v43, v2 op_sel:[1,0,0] op_sel_hi:[1,0,0]
	v_fma_mix_f32 v17, -v38, v17, v17 op_sel_hi:[1,0,0]
	s_waitcnt lgkmcnt(0)
	v_fma_mix_f32 v36, v37, v59, v36 op_sel:[1,0,0] op_sel_hi:[1,0,0]
	v_fma_mix_f32 v60, v41, v58, v60 op_sel_hi:[1,0,0]
	v_fma_mix_f32 v40, v41, v59, v40 op_sel:[1,0,0] op_sel_hi:[1,0,0]
	v_fma_mix_f32 v41, v37, v58, v61 op_sel_hi:[1,0,0]
	v_fma_mix_f32 v17, v34, v57, v17 op_sel_hi:[1,1,0]
	ds_read2_b64 v[24:27], v54 offset0:192 offset1:224
	v_add_f32_e32 v36, v41, v36
	v_fma_mix_f32 v37, -v38, v43, v43 op_sel:[1,0,0] op_sel_hi:[1,0,0]
	v_fma_mix_f32 v38, -v39, v58, v58 op_sel_hi:[1,0,0]
	v_add_f32_e32 v40, v60, v40
	v_fma_mix_f32 v34, v34, v57, v37 op_sel:[1,0,0] op_sel_hi:[1,1,0]
	v_fma_mix_f32 v39, -v39, v59, v59 op_sel:[1,0,0] op_sel_hi:[1,0,0]
	s_nop 0
	v_add_f32_dpp v36, v36, v36 quad_perm:[1,0,3,2] row_mask:0xf bank_mask:0xf bound_ctrl:1
	v_fma_mix_f32 v37, v35, v57, v38 op_sel_hi:[1,1,0]
	v_fma_mix_f32 v35, v35, v57, v39 op_sel:[1,0,0] op_sel_hi:[1,1,0]
	v_add_f32_dpp v40, v40, v40 quad_perm:[1,0,3,2] row_mask:0xf bank_mask:0xf bound_ctrl:1
	v_add_u32_e32 v16, 0x400, v54
	v_add_f32_dpp v36, v36, v36 quad_perm:[2,3,0,1] row_mask:0xf bank_mask:0xf bound_ctrl:1
	v_add_f32_dpp v40, v40, v40 quad_perm:[2,3,0,1] row_mask:0xf bank_mask:0xf bound_ctrl:1
	ds_read2_b64 v[28:31], v16 offset0:112 offset1:128
	v_add_f32_dpp v36, v36, v36 row_ror:4 row_mask:0xf bank_mask:0xf bound_ctrl:1
	v_add_f32_dpp v40, v40, v40 row_ror:4 row_mask:0xf bank_mask:0xf bound_ctrl:1
	v_add_u32_e32 v16, 0x800, v54
	v_add_f32_dpp v36, v36, v36 row_ror:8 row_mask:0xf bank_mask:0xf bound_ctrl:1
	v_fma_mix_f32 v17, v32, -v36, v17 op_sel_hi:[1,0,0]
	v_fma_mix_f32 v41, v32, -v36, v34 op_sel:[1,0,0] op_sel_hi:[1,0,0]
	v_fma_mix_f32 v43, v33, -v36, v37 op_sel_hi:[1,0,0]
	v_fma_mix_f32 v57, v33, -v36, v35 op_sel:[1,0,0] op_sel_hi:[1,0,0]
	v_add_f32_dpp v32, v40, v40 row_ror:8 row_mask:0xf bank_mask:0xf bound_ctrl:1
	v_fma_mix_f32 v58, v18, v17, v2 op_sel_hi:[1,0,0]
	v_fma_mix_f32 v18, v18, v41, v2 op_sel:[1,0,0] op_sel_hi:[1,0,0]
	s_waitcnt lgkmcnt(1)
	v_fma_mix_f32 v59, v26, v17, v2 op_sel_hi:[1,0,0]
	v_fma_mix_f32 v26, v26, v41, v2 op_sel:[1,0,0] op_sel_hi:[1,0,0]
	ds_read2_b64 v[20:23], v16 offset0:16 offset1:32
	v_fma_mix_f32 v58, v19, v43, v58 op_sel_hi:[1,0,0]
	v_fma_mix_f32 v18, v19, v57, v18 op_sel:[1,0,0] op_sel_hi:[1,0,0]
	v_fma_mix_f32 v19, v27, v43, v59 op_sel_hi:[1,0,0]
	v_fma_mix_f32 v26, v27, v57, v26 op_sel:[1,0,0] op_sel_hi:[1,0,0]
	v_cndmask_b32_e64 v40, v56, v32, s[8:9]
	v_add_f32_e32 v19, v19, v26
	v_add_f32_e32 v18, v58, v18
	ds_read2_b64 v[36:39], v16 offset0:64 offset1:80
	ds_read2_b64 v[32:35], v16 offset0:96 offset1:112
	ds_read_u16 v56, v55 offset:1664
	ds_read_u16 v60, v55 offset:2432
	ds_read_u16 v61, v55 offset:3200
	ds_read_u16 v62, v55 offset:3968
	ds_read_u16 v63, v55 offset:4736
	ds_read_u16 v64, v55 offset:5504
	ds_read_u16 v65, v55 offset:6272
	ds_read_u16 v66, v55 offset:7040
	v_add_f32_dpp v19, v19, v19 quad_perm:[1,0,3,2] row_mask:0xf bank_mask:0xf bound_ctrl:1
	v_add_f32_dpp v18, v18, v18 quad_perm:[1,0,3,2] row_mask:0xf bank_mask:0xf bound_ctrl:1
	s_waitcnt lgkmcnt(11)
	v_fma_mix_f32 v17, -v28, v17, v17 op_sel_hi:[1,0,0]
	s_waitcnt lgkmcnt(7)
	v_add_f32_dpp v19, v19, v19 quad_perm:[2,3,0,1] row_mask:0xf bank_mask:0xf bound_ctrl:1
	v_add_f32_dpp v18, v18, v18 quad_perm:[2,3,0,1] row_mask:0xf bank_mask:0xf bound_ctrl:1
	v_fma_mix_f32 v17, v20, v56, v17 op_sel_hi:[1,1,0]
	v_fma_mix_f32 v27, -v28, v41, v41 op_sel:[1,0,0] op_sel_hi:[1,0,0]
	v_fma_mix_f32 v28, -v29, v43, v43 op_sel_hi:[1,0,0]
	v_fma_mix_f32 v29, -v29, v57, v57 op_sel:[1,0,0] op_sel_hi:[1,0,0]
	s_nop 0
	v_add_f32_dpp v19, v19, v19 row_ror:4 row_mask:0xf bank_mask:0xf bound_ctrl:1
	v_add_f32_dpp v18, v18, v18 row_ror:4 row_mask:0xf bank_mask:0xf bound_ctrl:1
	v_fma_mix_f32 v20, v20, v56, v27 op_sel:[1,0,0] op_sel_hi:[1,1,0]
	v_fma_mix_f32 v26, v21, v56, v28 op_sel_hi:[1,1,0]
	v_fma_mix_f32 v21, v21, v56, v29 op_sel:[1,0,0] op_sel_hi:[1,1,0]
	v_add_u32_e32 v76, 0x4800, v54
	v_add_f32_dpp v19, v19, v19 row_ror:8 row_mask:0xf bank_mask:0xf bound_ctrl:1
	v_fma_mix_f32 v17, v30, -v19, v17 op_sel_hi:[1,0,0]
	v_fma_mix_f32 v30, v30, -v19, v20 op_sel:[1,0,0] op_sel_hi:[1,0,0]
	v_add_f32_dpp v18, v18, v18 row_ror:8 row_mask:0xf bank_mask:0xf bound_ctrl:1
	v_fma_mix_f32 v43, v24, v17, v2 op_sel_hi:[1,0,0]
	v_fma_mix_f32 v24, v24, v30, v2 op_sel:[1,0,0] op_sel_hi:[1,0,0]
	v_fma_mix_f32 v41, v31, -v19, v26 op_sel_hi:[1,0,0]
	v_fma_mix_f32 v31, v31, -v19, v21 op_sel:[1,0,0] op_sel_hi:[1,0,0]
	v_cndmask_b32_e64 v40, v40, v18, s[10:11]
	ds_read2_b64 v[18:21], v16 offset0:128 offset1:160
	ds_read2_b64 v[26:29], v16 offset0:176 offset1:192
	ds_read2_b64 v[56:59], v16 offset0:208 offset1:224
	s_waitcnt lgkmcnt(9)
; __device__ __forceinline__ bf16_t f2bf(float f) { return (bf16_t)(pk2(f, 0.f) & 0xffffu); }
; __device__ __forceinline__ float fmix_lo(unsigned h2, float b, float c) { float d; asm("v_fma_mix_f32 %0, %1, %2, %3 op_sel_hi:[1,0,0]" : "=v"(d) : "v"(h2), "v"(b), "v"(c)); return d; }
; __device__ __forceinline__ float fmix_hi(unsigned h2, float b, float c) { float d; asm("v_fma_mix_f32 %0, %1, %2, %3 op_sel:[1,0,0] op_sel_hi:[1,0,0]" : "=v"(d) : "v"(h2), "v"(b), "v"(c)); return d; }
; __device__ __forceinline__ float fmixn_lo(unsigned h2, float b, float c) { float d; asm("v_fma_mix_f32 %0, -%1, %2, %3 op_sel_hi:[1,0,0]" : "=v"(d) : "v"(h2), "v"(b), "v"(c)); return d; }
; __device__ __forceinline__ float fmixn_hi(unsigned h2, float b, float c) { float d; asm("v_fma_mix_f32 %0, -%1, %2, %3 op_sel:[1,0,0] op_sel_hi:[1,0,0]" : "=v"(d) : "v"(h2), "v"(b), "v"(c)); return d; }
; template <int ROLE>
; __device__ __forceinline__ void scan_role(const ScanCtx& cx, KPR p) {
;     ...
;       for (int s16 = 0; s16 < 16; ++s16) { const int st = hb + s16; const RIn x = nx; if (st + 1 < SC_CH) nx = lds_ld(st + 1);
;         const float vv = (float)x.v;
;         float ya = fmix_lo(rprev.x, s[0], 0.f), yb = fmix_hi(rprev.x, s[1], 0.f);
;         float sa = fmix_lo(x.kk.x, s[0], 0.f), sb = fmix_hi(x.kk.x, s[1], 0.f);
;         ya = fmix_lo(rprev.y, s[2], ya); yb = fmix_hi(rprev.y, s[3], yb);
;         sa = fmix_lo(x.kk.y, s[2], sa); sb = fmix_hi(x.kk.y, s[3], sb);
;         float t0_ = fmixn_lo(x.u.x, s[0], s[0]), t1_ = fmixn_hi(x.u.x, s[1], s[1]), t2_ = fmixn_lo(x.u.y, s[2], s[2]), t3_ = fmixn_hi(x.u.y, s[3], s[3]);
;         float yy = ya + yb, ss = sa + sb;
;         rowsum16x2(ss, yy);
;         t0_ = fmix_lo(x.km.x, vv, t0_); t1_ = fmix_hi(x.km.x, vv, t1_); t2_ = fmix_lo(x.km.y, vv, t2_); t3_ = fmix_hi(x.km.y, vv, t3_);
;         const float nsa = -ss;
;         s[0] = fmix_lo(x.b.x, nsa, t0_); s[1] = fmix_hi(x.b.x, nsa, t1_); s[2] = fmix_lo(x.b.y, nsa, t2_); s[3] = fmix_hi(x.b.y, nsa, t3_);
;         rprev = x.r;
;         if (s16 == 0) { if (t0 + hb > 0) YO[(size_t)(cx.br * TPB + seq_pos(t0 + hb - 16 + ks, cx.dr)) * NNGP] = f2bf(ks == 15 ? yy : keep); }
;         else keep = ((s16 - 1) == ks) ? yy : keep; }
	v_cvt_f32_f16_e32 v16, v60
	v_fma_mix_f32 v60, v36, v17, v2 op_sel_hi:[1,0,0]
	v_fma_mix_f32 v36, v36, v30, v2 op_sel:[1,0,0] op_sel_hi:[1,0,0]
	v_fma_mix_f32 v43, v25, v41, v43 op_sel_hi:[1,0,0]
	v_fma_mix_f32 v24, v25, v31, v24 op_sel:[1,0,0] op_sel_hi:[1,0,0]
	v_fma_mix_f32 v17, -v38, v17, v17 op_sel_hi:[1,0,0]
	v_fma_mix_f32 v30, -v38, v30, v30 op_sel:[1,0,0] op_sel_hi:[1,0,0]
	s_nop 0
	v_fma_mix_f32 v25, v37, v41, v60 op_sel_hi:[1,0,0]
	v_fma_mix_f32 v36, v37, v31, v36 op_sel:[1,0,0] op_sel_hi:[1,0,0]
	v_fma_mix_f32 v37, -v39, v41, v41 op_sel_hi:[1,0,0]
	v_add_f32_e32 v24, v43, v24
	v_add_f32_e32 v25, v25, v36
	v_fma_mix_f32 v17, v34, v16, v17 op_sel_hi:[1,0,0]
	v_fma_mix_f32 v31, -v39, v31, v31 op_sel:[1,0,0] op_sel_hi:[1,0,0]
	v_fma_mix_f32 v30, v34, v16, v30 op_sel:[1,0,0] op_sel_hi:[1,0,0]
	v_fma_mix_f32 v34, v35, v16, v37 op_sel_hi:[1,0,0]
	s_nop 0
	v_add_f32_dpp v24, v24, v24 quad_perm:[1,0,3,2] row_mask:0xf bank_mask:0xf bound_ctrl:1
	v_add_f32_dpp v25, v25, v25 quad_perm:[1,0,3,2] row_mask:0xf bank_mask:0xf bound_ctrl:1
	v_fma_mix_f32 v16, v35, v16, v31 op_sel:[1,0,0] op_sel_hi:[1,0,0]
	v_add_u32_e32 v43, 0x1000, v54
	v_add_f32_dpp v24, v24, v24 quad_perm:[2,3,0,1] row_mask:0xf bank_mask:0xf bound_ctrl:1
	v_add_f32_dpp v25, v25, v25 quad_perm:[2,3,0,1] row_mask:0xf bank_mask:0xf bound_ctrl:1
	s_nop 0
	v_add_f32_dpp v24, v24, v24 row_ror:4 row_mask:0xf bank_mask:0xf bound_ctrl:1
	v_add_f32_dpp v25, v25, v25 row_ror:4 row_mask:0xf bank_mask:0xf bound_ctrl:1
	s_nop 0
	v_add_f32_dpp v24, v24, v24 row_ror:8 row_mask:0xf bank_mask:0xf bound_ctrl:1
	v_add_f32_dpp v25, v25, v25 row_ror:8 row_mask:0xf bank_mask:0xf bound_ctrl:1
	v_fma_mix_f32 v17, v32, -v25, v17 op_sel_hi:[1,0,0]
	v_fma_mix_f32 v38, v32, -v25, v30 op_sel:[1,0,0] op_sel_hi:[1,0,0]
	v_fma_mix_f32 v16, v33, -v25, v16 op_sel:[1,0,0] op_sel_hi:[1,0,0]
	v_cndmask_b32_e64 v24, v40, v24, s[12:13]
	s_waitcnt lgkmcnt(2)
	v_fma_mix_f32 v41, v20, v17, v2 op_sel_hi:[1,0,0]
	v_fma_mix_f32 v20, v20, v38, v2 op_sel:[1,0,0] op_sel_hi:[1,0,0]
	v_fma_mix_f32 v40, v22, v17, v2 op_sel_hi:[1,0,0]
	v_fma_mix_f32 v22, v22, v38, v2 op_sel:[1,0,0] op_sel_hi:[1,0,0]
	v_fma_mix_f32 v39, v33, -v25, v34 op_sel_hi:[1,0,0]
	ds_read2_b64 v[30:33], v43 offset1:16
	ds_read2_b64 v[34:37], v43 offset0:32 offset1:48
	v_fma_mix_f32 v20, v21, v16, v20 op_sel:[1,0,0] op_sel_hi:[1,0,0]
	v_fma_mix_f32 v40, v23, v39, v40 op_sel_hi:[1,0,0]
	v_fma_mix_f32 v22, v23, v16, v22 op_sel:[1,0,0] op_sel_hi:[1,0,0]
	v_fma_mix_f32 v23, v21, v39, v41 op_sel_hi:[1,0,0]
	s_waitcnt lgkmcnt(3)
	v_fma_mix_f32 v17, -v26, v17, v17 op_sel_hi:[1,0,0]
	v_add_f32_e32 v20, v23, v20
	v_fma_mix_f32 v21, -v26, v38, v38 op_sel:[1,0,0] op_sel_hi:[1,0,0]
	v_fma_mix_f32 v16, -v27, v16, v16 op_sel:[1,0,0] op_sel_hi:[1,0,0]
	v_add_f32_e32 v22, v40, v22
	s_waitcnt lgkmcnt(2)
	v_fma_mix_f32 v17, v56, v61, v17 op_sel_hi:[1,1,0]
	v_fma_mix_f32 v21, v56, v61, v21 op_sel:[1,0,0] op_sel_hi:[1,1,0]
	v_add_f32_dpp v20, v20, v20 quad_perm:[1,0,3,2] row_mask:0xf bank_mask:0xf bound_ctrl:1
	v_fma_mix_f32 v16, v57, v61, v16 op_sel:[1,0,0] op_sel_hi:[1,1,0]
	v_fma_mix_f32 v26, -v27, v39, v39 op_sel_hi:[1,0,0]
	v_add_f32_dpp v22, v22, v22 quad_perm:[1,0,3,2] row_mask:0xf bank_mask:0xf bound_ctrl:1
	v_fma_mix_f32 v23, v57, v61, v26 op_sel_hi:[1,1,0]
	v_add_f32_dpp v20, v20, v20 quad_perm:[2,3,0,1] row_mask:0xf bank_mask:0xf bound_ctrl:1
	v_add_f32_dpp v22, v22, v22 quad_perm:[2,3,0,1] row_mask:0xf bank_mask:0xf bound_ctrl:1
	s_nop 0
	v_add_f32_dpp v20, v20, v20 row_ror:4 row_mask:0xf bank_mask:0xf bound_ctrl:1
	v_add_f32_dpp v22, v22, v22 row_ror:4 row_mask:0xf bank_mask:0xf bound_ctrl:1
	s_nop 0
	v_add_f32_dpp v20, v20, v20 row_ror:8 row_mask:0xf bank_mask:0xf bound_ctrl:1
	v_xor_b32_e32 v20, 0x80000000, v20
	v_fma_mix_f32 v17, v28, v20, v17 op_sel_hi:[1,0,0]
	v_fma_mix_f32 v28, v28, v20, v21 op_sel:[1,0,0] op_sel_hi:[1,0,0]
	v_fma_mix_f32 v56, v29, v20, v23 op_sel_hi:[1,0,0]
	v_fma_mix_f32 v16, v29, v20, v16 op_sel:[1,0,0] op_sel_hi:[1,0,0]
	s_nop 0
	v_fma_mix_f32 v60, v18, v17, v2 op_sel_hi:[1,0,0]
	v_fma_mix_f32 v18, v18, v28, v2 op_sel:[1,0,0] op_sel_hi:[1,0,0]
	s_waitcnt lgkmcnt(1)
	v_fma_mix_f32 v61, v30, v17, v2 op_sel_hi:[1,0,0]
	v_fma_mix_f32 v30, v30, v28, v2 op_sel:[1,0,0] op_sel_hi:[1,0,0]
	v_add_f32_dpp v20, v22, v22 row_ror:8 row_mask:0xf bank_mask:0xf bound_ctrl:1
	v_fma_mix_f32 v60, v19, v56, v60 op_sel_hi:[1,0,0]
	v_fma_mix_f32 v18, v19, v16, v18 op_sel:[1,0,0] op_sel_hi:[1,0,0]
	v_fma_mix_f32 v19, v31, v56, v61 op_sel_hi:[1,0,0]
	v_fma_mix_f32 v30, v31, v16, v30 op_sel:[1,0,0] op_sel_hi:[1,0,0]
	v_cndmask_b32_e64 v29, v24, v20, s[14:15]
	v_add_f32_e32 v19, v19, v30
	ds_read2_b64 v[20:23], v43 offset0:64 offset1:96
	ds_read2_b64 v[24:27], v43 offset0:112 offset1:128
	ds_read2_b64 v[38:41], v43 offset0:144 offset1:160
	v_add_f32_dpp v19, v19, v19 quad_perm:[1,0,3,2] row_mask:0xf bank_mask:0xf bound_ctrl:1
	v_fma_mix_f32 v17, -v32, v17, v17 op_sel_hi:[1,0,0]
	v_fma_mix_f32 v28, -v32, v28, v28 op_sel:[1,0,0] op_sel_hi:[1,0,0]
	v_fma_mix_f32 v16, -v33, v16, v16 op_sel:[1,0,0] op_sel_hi:[1,0,0]
	v_add_f32_e32 v18, v60, v18
	s_waitcnt lgkmcnt(3)
; __device__ __forceinline__ bf16_t f2bf(float f) { return (bf16_t)(pk2(f, 0.f) & 0xffffu); }
; __device__ __forceinline__ float fmix_lo(unsigned h2, float b, float c) { float d; asm("v_fma_mix_f32 %0, %1, %2, %3 op_sel_hi:[1,0,0]" : "=v"(d) : "v"(h2), "v"(b), "v"(c)); return d; }
; __device__ __forceinline__ float fmix_hi(unsigned h2, float b, float c) { float d; asm("v_fma_mix_f32 %0, %1, %2, %3 op_sel:[1,0,0] op_sel_hi:[1,0,0]" : "=v"(d) : "v"(h2), "v"(b), "v"(c)); return d; }
; __device__ __forceinline__ float fmixn_lo(unsigned h2, float b, float c) { float d; asm("v_fma_mix_f32 %0, -%1, %2, %3 op_sel_hi:[1,0,0]" : "=v"(d) : "v"(h2), "v"(b), "v"(c)); return d; }
; __device__ __forceinline__ float fmixn_hi(unsigned h2, float b, float c) { float d; asm("v_fma_mix_f32 %0, -%1, %2, %3 op_sel:[1,0,0] op_sel_hi:[1,0,0]" : "=v"(d) : "v"(h2), "v"(b), "v"(c)); return d; }
; template <int ROLE>
; __device__ __forceinline__ void scan_role(const ScanCtx& cx, KPR p) {
;     ...
;       for (int s16 = 0; s16 < 16; ++s16) { const int st = hb + s16; const RIn x = nx; if (st + 1 < SC_CH) nx = lds_ld(st + 1);
;         const float vv = (float)x.v;
;         float ya = fmix_lo(rprev.x, s[0], 0.f), yb = fmix_hi(rprev.x, s[1], 0.f);
;         float sa = fmix_lo(x.kk.x, s[0], 0.f), sb = fmix_hi(x.kk.x, s[1], 0.f);
;         ya = fmix_lo(rprev.y, s[2], ya); yb = fmix_hi(rprev.y, s[3], yb);
;         sa = fmix_lo(x.kk.y, s[2], sa); sb = fmix_hi(x.kk.y, s[3], sb);
;         float t0_ = fmixn_lo(x.u.x, s[0], s[0]), t1_ = fmixn_hi(x.u.x, s[1], s[1]), t2_ = fmixn_lo(x.u.y, s[2], s[2]), t3_ = fmixn_hi(x.u.y, s[3], s[3]);
;         float yy = ya + yb, ss = sa + sb;
;         rowsum16x2(ss, yy);
;         t0_ = fmix_lo(x.km.x, vv, t0_); t1_ = fmix_hi(x.km.x, vv, t1_); t2_ = fmix_lo(x.km.y, vv, t2_); t3_ = fmix_hi(x.km.y, vv, t3_);
;         const float nsa = -ss;
;         s[0] = fmix_lo(x.b.x, nsa, t0_); s[1] = fmix_hi(x.b.x, nsa, t1_); s[2] = fmix_lo(x.b.y, nsa, t2_); s[3] = fmix_hi(x.b.y, nsa, t3_);
;         rprev = x.r;
;         if (s16 == 0) { if (t0 + hb > 0) YO[(size_t)(cx.br * TPB + seq_pos(t0 + hb - 16 + ks, cx.dr)) * NNGP] = f2bf(ks == 15 ? yy : keep); }
;         else keep = ((s16 - 1) == ks) ? yy : keep; }
	v_fma_mix_f32 v17, v36, v62, v17 op_sel_hi:[1,1,0]
	v_add_f32_dpp v19, v19, v19 quad_perm:[2,3,0,1] row_mask:0xf bank_mask:0xf bound_ctrl:1
	v_fma_mix_f32 v31, -v33, v56, v56 op_sel_hi:[1,0,0]
	v_fma_mix_f32 v28, v36, v62, v28 op_sel:[1,0,0] op_sel_hi:[1,1,0]
	v_fma_mix_f32 v16, v37, v62, v16 op_sel:[1,0,0] op_sel_hi:[1,1,0]
	v_add_f32_dpp v18, v18, v18 quad_perm:[1,0,3,2] row_mask:0xf bank_mask:0xf bound_ctrl:1
	v_fma_mix_f32 v30, v37, v62, v31 op_sel_hi:[1,1,0]
	s_nop 0
	v_add_f32_dpp v19, v19, v19 row_ror:4 row_mask:0xf bank_mask:0xf bound_ctrl:1
	v_add_u32_e32 v60, 0x1800, v54
	v_add_f32_dpp v18, v18, v18 quad_perm:[2,3,0,1] row_mask:0xf bank_mask:0xf bound_ctrl:1
	v_add_f32_dpp v19, v19, v19 row_ror:8 row_mask:0xf bank_mask:0xf bound_ctrl:1
	v_fma_mix_f32 v17, v34, -v19, v17 op_sel_hi:[1,0,0]
	v_fma_mix_f32 v36, v34, -v19, v28 op_sel:[1,0,0] op_sel_hi:[1,0,0]
	v_fma_mix_f32 v16, v35, -v19, v16 op_sel:[1,0,0] op_sel_hi:[1,0,0]
	v_add_f32_dpp v18, v18, v18 row_ror:4 row_mask:0xf bank_mask:0xf bound_ctrl:1
	s_waitcnt lgkmcnt(2)
	v_fma_mix_f32 v57, v22, v17, v2 op_sel_hi:[1,0,0]
	v_fma_mix_f32 v22, v22, v36, v2 op_sel:[1,0,0] op_sel_hi:[1,0,0]
	v_fma_mix_f32 v37, v35, -v19, v30 op_sel_hi:[1,0,0]
	v_fma_mix_f32 v56, v58, v36, v2 op_sel:[1,0,0] op_sel_hi:[1,0,0]
	v_fma_mix_f32 v22, v23, v16, v22 op_sel:[1,0,0] op_sel_hi:[1,0,0]
	v_fma_mix_f32 v57, v23, v37, v57 op_sel_hi:[1,0,0]
	v_add_f32_dpp v18, v18, v18 row_ror:8 row_mask:0xf bank_mask:0xf bound_ctrl:1
	v_add_f32_e32 v22, v57, v22
	v_cndmask_b32_e64 v18, v29, v18, s[16:17]
	ds_read2_b64 v[28:31], v43 offset0:192 offset1:208
	ds_read2_b64 v[32:35], v43 offset0:224 offset1:240
	v_add_f32_dpp v22, v22, v22 quad_perm:[1,0,3,2] row_mask:0xf bank_mask:0xf bound_ctrl:1
	v_fma_mix_f32 v43, v58, v17, v2 op_sel_hi:[1,0,0]
	v_fma_mix_f32 v56, v59, v16, v56 op_sel:[1,0,0] op_sel_hi:[1,0,0]
	s_waitcnt lgkmcnt(3)
	v_fma_mix_f32 v17, -v24, v17, v17 op_sel_hi:[1,0,0]
	v_fma_mix_f32 v23, -v24, v36, v36 op_sel:[1,0,0] op_sel_hi:[1,0,0]
	v_fma_mix_f32 v24, -v25, v37, v37 op_sel_hi:[1,0,0]
	s_nop 0
	v_add_f32_dpp v22, v22, v22 quad_perm:[2,3,0,1] row_mask:0xf bank_mask:0xf bound_ctrl:1
	v_fma_mix_f32 v43, v59, v37, v43 op_sel_hi:[1,0,0]
	v_fma_mix_f32 v16, -v25, v16, v16 op_sel:[1,0,0] op_sel_hi:[1,0,0]
	s_waitcnt lgkmcnt(2)
	v_fma_mix_f32 v17, v38, v63, v17 op_sel_hi:[1,1,0]
	v_fma_mix_f32 v23, v38, v63, v23 op_sel:[1,0,0] op_sel_hi:[1,1,0]
	v_fma_mix_f32 v24, v39, v63, v24 op_sel_hi:[1,1,0]
	s_nop 0
	v_add_f32_dpp v22, v22, v22 row_ror:4 row_mask:0xf bank_mask:0xf bound_ctrl:1
	v_add_f32_e32 v25, v43, v56
	v_fma_mix_f32 v16, v39, v63, v16 op_sel:[1,0,0] op_sel_hi:[1,1,0]
	v_add_f32_dpp v22, v22, v22 row_ror:8 row_mask:0xf bank_mask:0xf bound_ctrl:1
	v_add_f32_dpp v25, v25, v25 quad_perm:[1,0,3,2] row_mask:0xf bank_mask:0xf bound_ctrl:1
	v_fma_mix_f32 v43, v26, -v22, v17 op_sel_hi:[1,0,0]
	v_fma_mix_f32 v26, v26, -v22, v23 op_sel:[1,0,0] op_sel_hi:[1,0,0]
	v_fma_mix_f32 v56, v27, -v22, v24 op_sel_hi:[1,0,0]
	v_fma_mix_f32 v27, v27, -v22, v16 op_sel:[1,0,0] op_sel_hi:[1,0,0]
	s_nop 0
	v_add_f32_dpp v25, v25, v25 quad_perm:[2,3,0,1] row_mask:0xf bank_mask:0xf bound_ctrl:1
	v_fma_mix_f32 v59, v20, v43, v2 op_sel_hi:[1,0,0]
	v_fma_mix_f32 v20, v20, v26, v2 op_sel:[1,0,0] op_sel_hi:[1,0,0]
	s_waitcnt lgkmcnt(1)
	v_fma_mix_f32 v61, v28, v43, v2 op_sel_hi:[1,0,0]
	v_fma_mix_f32 v28, v28, v26, v2 op_sel:[1,0,0] op_sel_hi:[1,0,0]
	v_fma_mix_f32 v26, -v30, v26, v26 op_sel:[1,0,0] op_sel_hi:[1,0,0]
	s_nop 0
	v_add_f32_dpp v25, v25, v25 row_ror:4 row_mask:0xf bank_mask:0xf bound_ctrl:1
	v_fma_mix_f32 v59, v21, v56, v59 op_sel_hi:[1,0,0]
	v_fma_mix_f32 v20, v21, v27, v20 op_sel:[1,0,0] op_sel_hi:[1,0,0]
	v_fma_mix_f32 v21, v29, v56, v61 op_sel_hi:[1,0,0]
	v_fma_mix_f32 v28, v29, v27, v28 op_sel:[1,0,0] op_sel_hi:[1,0,0]
	v_fma_mix_f32 v29, -v30, v43, v43 op_sel_hi:[1,0,0]
	s_nop 1
	v_add_f32_dpp v16, v25, v25 row_ror:8 row_mask:0xf bank_mask:0xf bound_ctrl:1
	v_add_f32_e32 v21, v21, v28
	v_cndmask_b32_e64 v57, v18, v16, s[18:19]
	ds_read2_b64 v[36:39], v60 offset1:32
	ds_read2_b64 v[22:25], v60 offset0:48 offset1:64
	ds_read2_b64 v[16:19], v60 offset0:80 offset1:96
	v_add_f32_dpp v21, v21, v21 quad_perm:[1,0,3,2] row_mask:0xf bank_mask:0xf bound_ctrl:1
	v_add_f32_e32 v20, v59, v20
	v_fma_mix_f32 v30, -v31, v56, v56 op_sel_hi:[1,0,0]
	s_waitcnt lgkmcnt(3)
	v_fma_mix_f32 v28, v34, v64, v29 op_sel_hi:[1,1,0]
	v_fma_mix_f32 v26, v34, v64, v26 op_sel:[1,0,0] op_sel_hi:[1,1,0]
	v_fma_mix_f32 v27, -v31, v27, v27 op_sel:[1,0,0] op_sel_hi:[1,0,0]
	v_add_f32_dpp v21, v21, v21 quad_perm:[2,3,0,1] row_mask:0xf bank_mask:0xf bound_ctrl:1
	v_add_f32_dpp v20, v20, v20 quad_perm:[1,0,3,2] row_mask:0xf bank_mask:0xf bound_ctrl:1
	v_fma_mix_f32 v29, v35, v64, v30 op_sel_hi:[1,1,0]
	v_fma_mix_f32 v27, v35, v64, v27 op_sel:[1,0,0] op_sel_hi:[1,1,0]
	v_add_f32_dpp v21, v21, v21 row_ror:4 row_mask:0xf bank_mask:0xf bound_ctrl:1
	v_add_f32_dpp v20, v20, v20 quad_perm:[2,3,0,1] row_mask:0xf bank_mask:0xf bound_ctrl:1
	s_nop 0
	v_add_f32_dpp v21, v21, v21 row_ror:8 row_mask:0xf bank_mask:0xf bound_ctrl:1
	v_add_f32_dpp v20, v20, v20 row_ror:4 row_mask:0xf bank_mask:0xf bound_ctrl:1
	v_fma_mix_f32 v28, v32, -v21, v28 op_sel_hi:[1,0,0]
	v_fma_mix_f32 v26, v32, -v21, v26 op_sel:[1,0,0] op_sel_hi:[1,0,0]
	v_fma_mix_f32 v29, v33, -v21, v29 op_sel_hi:[1,0,0]
	v_fma_mix_f32 v21, v33, -v21, v27 op_sel:[1,0,0] op_sel_hi:[1,0,0]
	s_nop 0
	v_add_f32_dpp v20, v20, v20 row_ror:8 row_mask:0xf bank_mask:0xf bound_ctrl:1
	v_fma_mix_f32 v30, v40, v28, v2 op_sel_hi:[1,0,0]
	v_fma_mix_f32 v31, v40, v26, v2 op_sel:[1,0,0] op_sel_hi:[1,0,0]
	s_waitcnt lgkmcnt(2)
; __device__ __forceinline__ bf16_t f2bf(float f) { return (bf16_t)(pk2(f, 0.f) & 0xffffu); }
; __device__ __forceinline__ float fmix_lo(unsigned h2, float b, float c) { float d; asm("v_fma_mix_f32 %0, %1, %2, %3 op_sel_hi:[1,0,0]" : "=v"(d) : "v"(h2), "v"(b), "v"(c)); return d; }
; __device__ __forceinline__ float fmix_hi(unsigned h2, float b, float c) { float d; asm("v_fma_mix_f32 %0, %1, %2, %3 op_sel:[1,0,0] op_sel_hi:[1,0,0]" : "=v"(d) : "v"(h2), "v"(b), "v"(c)); return d; }
; __device__ __forceinline__ float fmixn_lo(unsigned h2, float b, float c) { float d; asm("v_fma_mix_f32 %0, -%1, %2, %3 op_sel_hi:[1,0,0]" : "=v"(d) : "v"(h2), "v"(b), "v"(c)); return d; }
; __device__ __forceinline__ float fmixn_hi(unsigned h2, float b, float c) { float d; asm("v_fma_mix_f32 %0, -%1, %2, %3 op_sel:[1,0,0] op_sel_hi:[1,0,0]" : "=v"(d) : "v"(h2), "v"(b), "v"(c)); return d; }
; template <int ROLE>
; __device__ __forceinline__ void scan_role(const ScanCtx& cx, KPR p) {
;     ...
;       for (int s16 = 0; s16 < 16; ++s16) { const int st = hb + s16; const RIn x = nx; if (st + 1 < SC_CH) nx = lds_ld(st + 1);
;         const float vv = (float)x.v;
;         float ya = fmix_lo(rprev.x, s[0], 0.f), yb = fmix_hi(rprev.x, s[1], 0.f);
;         float sa = fmix_lo(x.kk.x, s[0], 0.f), sb = fmix_hi(x.kk.x, s[1], 0.f);
;         ya = fmix_lo(rprev.y, s[2], ya); yb = fmix_hi(rprev.y, s[3], yb);
;         sa = fmix_lo(x.kk.y, s[2], sa); sb = fmix_hi(x.kk.y, s[3], sb);
;         float t0_ = fmixn_lo(x.u.x, s[0], s[0]), t1_ = fmixn_hi(x.u.x, s[1], s[1]), t2_ = fmixn_lo(x.u.y, s[2], s[2]), t3_ = fmixn_hi(x.u.y, s[3], s[3]);
;         float yy = ya + yb, ss = sa + sb;
;         rowsum16x2(ss, yy);
;         t0_ = fmix_lo(x.km.x, vv, t0_); t1_ = fmix_hi(x.km.x, vv, t1_); t2_ = fmix_lo(x.km.y, vv, t2_); t3_ = fmix_hi(x.km.y, vv, t3_);
;         const float nsa = -ss;
;         s[0] = fmix_lo(x.b.x, nsa, t0_); s[1] = fmix_hi(x.b.x, nsa, t1_); s[2] = fmix_lo(x.b.y, nsa, t2_); s[3] = fmix_hi(x.b.y, nsa, t3_);
;         rprev = x.r;
;         if (s16 == 0) { if (t0 + hb > 0) YO[(size_t)(cx.br * TPB + seq_pos(t0 + hb - 16 + ks, cx.dr)) * NNGP] = f2bf(ks == 15 ? yy : keep); }
;         else keep = ((s16 - 1) == ks) ? yy : keep; }
	v_fma_mix_f32 v40, v38, v28, v2 op_sel_hi:[1,0,0]
	v_fma_mix_f32 v38, v38, v26, v2 op_sel:[1,0,0] op_sel_hi:[1,0,0]
	s_waitcnt lgkmcnt(1)
	v_fma_mix_f32 v28, -v22, v28, v28 op_sel_hi:[1,0,0]
	v_fma_mix_f32 v22, -v22, v26, v26 op_sel:[1,0,0] op_sel_hi:[1,0,0]
	v_fma_mix_f32 v30, v41, v29, v30 op_sel_hi:[1,0,0]
	v_fma_mix_f32 v26, -v23, v29, v29 op_sel_hi:[1,0,0]
	v_fma_mix_f32 v40, v39, v29, v40 op_sel_hi:[1,0,0]
	v_fma_mix_f32 v38, v39, v21, v38 op_sel:[1,0,0] op_sel_hi:[1,0,0]
	v_cndmask_b32_e64 v20, v57, v20, s[20:21]
	v_add_f32_e32 v29, v40, v38
	ds_read2_b64 v[32:35], v60 offset0:128 offset1:144
	ds_read2_b64 v[56:59], v60 offset0:160 offset1:176
	v_add_f32_dpp v29, v29, v29 quad_perm:[1,0,3,2] row_mask:0xf bank_mask:0xf bound_ctrl:1
	v_fma_mix_f32 v31, v41, v21, v31 op_sel:[1,0,0] op_sel_hi:[1,0,0]
	v_fma_mix_f32 v21, -v23, v21, v21 op_sel:[1,0,0] op_sel_hi:[1,0,0]
	s_waitcnt lgkmcnt(2)
	v_fma_mix_f32 v28, v16, v65, v28 op_sel_hi:[1,1,0]
	v_fma_mix_f32 v16, v16, v65, v22 op_sel:[1,0,0] op_sel_hi:[1,1,0]
	v_add_f32_dpp v29, v29, v29 quad_perm:[2,3,0,1] row_mask:0xf bank_mask:0xf bound_ctrl:1
	v_fma_mix_f32 v22, v17, v65, v26 op_sel_hi:[1,1,0]
	v_fma_mix_f32 v17, v17, v65, v21 op_sel:[1,0,0] op_sel_hi:[1,1,0]
	v_add_f32_e32 v23, v30, v31
	s_nop 0
	v_add_f32_dpp v29, v29, v29 row_ror:4 row_mask:0xf bank_mask:0xf bound_ctrl:1
	v_add_f32_dpp v23, v23, v23 quad_perm:[1,0,3,2] row_mask:0xf bank_mask:0xf bound_ctrl:1
	s_nop 0
	v_add_f32_dpp v29, v29, v29 row_ror:8 row_mask:0xf bank_mask:0xf bound_ctrl:1
	v_fma_mix_f32 v38, v24, -v29, v28 op_sel_hi:[1,0,0]
	v_fma_mix_f32 v39, v24, -v29, v16 op_sel:[1,0,0] op_sel_hi:[1,0,0]
	v_fma_mix_f32 v40, v25, -v29, v22 op_sel_hi:[1,0,0]
	v_fma_mix_f32 v17, v25, -v29, v17 op_sel:[1,0,0] op_sel_hi:[1,0,0]
	ds_read2_b64 v[24:27], v60 offset0:192 offset1:224
	s_waitcnt lgkmcnt(2)
	v_fma_mix_f32 v61, v32, v38, v2 op_sel_hi:[1,0,0]
	v_fma_mix_f32 v32, v32, v39, v2 op_sel:[1,0,0] op_sel_hi:[1,0,0]
	v_fma_mix_f32 v60, v36, v38, v2 op_sel_hi:[1,0,0]
	v_fma_mix_f32 v36, v36, v39, v2 op_sel:[1,0,0] op_sel_hi:[1,0,0]
	v_add_f32_dpp v23, v23, v23 quad_perm:[2,3,0,1] row_mask:0xf bank_mask:0xf bound_ctrl:1
	v_fma_mix_f32 v32, v33, v17, v32 op_sel:[1,0,0] op_sel_hi:[1,0,0]
	v_fma_mix_f32 v60, v37, v40, v60 op_sel_hi:[1,0,0]
	v_fma_mix_f32 v36, v37, v17, v36 op_sel:[1,0,0] op_sel_hi:[1,0,0]
	v_fma_mix_f32 v37, v33, v40, v61 op_sel_hi:[1,0,0]
	v_fma_mix_f32 v33, -v34, v38, v38 op_sel_hi:[1,0,0]
	v_fma_mix_f32 v34, -v34, v39, v39 op_sel:[1,0,0] op_sel_hi:[1,0,0]
	v_fma_mix_f32 v17, -v35, v17, v17 op_sel:[1,0,0] op_sel_hi:[1,0,0]
	v_fma_mix_f32 v38, -v35, v40, v40 op_sel_hi:[1,0,0]
	s_nop 0
	v_add_f32_e32 v35, v60, v36
	v_add_f32_e32 v32, v37, v32
	s_waitcnt lgkmcnt(1)
	v_fma_mix_f32 v33, v58, v66, v33 op_sel_hi:[1,1,0]
	v_fma_mix_f32 v34, v58, v66, v34 op_sel:[1,0,0] op_sel_hi:[1,1,0]
	v_fma_mix_f32 v36, v59, v66, v38 op_sel_hi:[1,1,0]
	v_fma_mix_f32 v17, v59, v66, v17 op_sel:[1,0,0] op_sel_hi:[1,1,0]
	v_add_f32_dpp v23, v23, v23 row_ror:4 row_mask:0xf bank_mask:0xf bound_ctrl:1
	v_add_f32_dpp v32, v32, v32 quad_perm:[1,0,3,2] row_mask:0xf bank_mask:0xf bound_ctrl:1
	v_add_f32_dpp v35, v35, v35 quad_perm:[1,0,3,2] row_mask:0xf bank_mask:0xf bound_ctrl:1
	v_add_f32_dpp v16, v23, v23 row_ror:8 row_mask:0xf bank_mask:0xf bound_ctrl:1
	v_add_f32_dpp v32, v32, v32 quad_perm:[2,3,0,1] row_mask:0xf bank_mask:0xf bound_ctrl:1
	v_add_f32_dpp v35, v35, v35 quad_perm:[2,3,0,1] row_mask:0xf bank_mask:0xf bound_ctrl:1
	v_cndmask_b32_e64 v41, v20, v16, s[22:23]
	v_add_f32_dpp v32, v32, v32 row_ror:4 row_mask:0xf bank_mask:0xf bound_ctrl:1
	v_add_u32_e32 v16, 0x1c00, v54
	v_add_f32_dpp v35, v35, v35 row_ror:4 row_mask:0xf bank_mask:0xf bound_ctrl:1
	v_add_f32_dpp v32, v32, v32 row_ror:8 row_mask:0xf bank_mask:0xf bound_ctrl:1
	v_xor_b32_e32 v32, 0x80000000, v32
	v_fma_mix_f32 v40, v56, v32, v33 op_sel_hi:[1,0,0]
	v_fma_mix_f32 v43, v56, v32, v34 op_sel:[1,0,0] op_sel_hi:[1,0,0]
	v_fma_mix_f32 v56, v57, v32, v36 op_sel_hi:[1,0,0]
	v_fma_mix_f32 v17, v57, v32, v17 op_sel:[1,0,0] op_sel_hi:[1,0,0]
	ds_read2_b64 v[28:31], v16 offset0:112 offset1:128
	v_fma_mix_f32 v58, v18, v40, v2 op_sel_hi:[1,0,0]
	v_fma_mix_f32 v18, v18, v43, v2 op_sel:[1,0,0] op_sel_hi:[1,0,0]
	s_waitcnt lgkmcnt(1)
	v_fma_mix_f32 v59, v26, v40, v2 op_sel_hi:[1,0,0]
	v_fma_mix_f32 v26, v26, v43, v2 op_sel:[1,0,0] op_sel_hi:[1,0,0]
	v_add_u32_e32 v16, 0x2000, v54
	v_fma_mix_f32 v58, v19, v56, v58 op_sel_hi:[1,0,0]
	v_fma_mix_f32 v18, v19, v17, v18 op_sel:[1,0,0] op_sel_hi:[1,0,0]
	v_fma_mix_f32 v19, v27, v56, v59 op_sel_hi:[1,0,0]
	v_fma_mix_f32 v26, v27, v17, v26 op_sel:[1,0,0] op_sel_hi:[1,0,0]
	v_add_f32_dpp v32, v35, v35 row_ror:8 row_mask:0xf bank_mask:0xf bound_ctrl:1
	v_add_f32_e32 v18, v58, v18
	v_add_f32_e32 v19, v19, v26
	ds_read2_b64 v[20:23], v16 offset0:16 offset1:32
	v_add_f32_dpp v18, v18, v18 quad_perm:[1,0,3,2] row_mask:0xf bank_mask:0xf bound_ctrl:1
	v_add_f32_dpp v19, v19, v19 quad_perm:[1,0,3,2] row_mask:0xf bank_mask:0xf bound_ctrl:1
	v_cndmask_b32_e64 v41, v41, v32, s[24:25]
	v_add_f32_dpp v18, v18, v18 quad_perm:[2,3,0,1] row_mask:0xf bank_mask:0xf bound_ctrl:1
	v_add_f32_dpp v19, v19, v19 quad_perm:[2,3,0,1] row_mask:0xf bank_mask:0xf bound_ctrl:1
	ds_read2_b64 v[36:39], v16 offset0:64 offset1:80
	ds_read2_b64 v[32:35], v16 offset0:96 offset1:112
	ds_read_u16 v57, v55 offset:7808
	ds_read_u16 v60, v55 offset:8576
	ds_read_u16 v61, v55 offset:9344
	ds_read_u16 v64, v55 offset:10112
	ds_read_u16 v65, v55 offset:10880
	ds_read_u16 v66, v55 offset:11648
	ds_read_u16 v67, v55 offset:12416
	ds_read_u16 v68, v55 offset:13184
	s_waitcnt lgkmcnt(11)
; __device__ __forceinline__ bf16_t f2bf(float f) { return (bf16_t)(pk2(f, 0.f) & 0xffffu); }
; __device__ __forceinline__ float fmix_lo(unsigned h2, float b, float c) { float d; asm("v_fma_mix_f32 %0, %1, %2, %3 op_sel_hi:[1,0,0]" : "=v"(d) : "v"(h2), "v"(b), "v"(c)); return d; }
; __device__ __forceinline__ float fmix_hi(unsigned h2, float b, float c) { float d; asm("v_fma_mix_f32 %0, %1, %2, %3 op_sel:[1,0,0] op_sel_hi:[1,0,0]" : "=v"(d) : "v"(h2), "v"(b), "v"(c)); return d; }
; __device__ __forceinline__ float fmixn_lo(unsigned h2, float b, float c) { float d; asm("v_fma_mix_f32 %0, -%1, %2, %3 op_sel_hi:[1,0,0]" : "=v"(d) : "v"(h2), "v"(b), "v"(c)); return d; }
; __device__ __forceinline__ float fmixn_hi(unsigned h2, float b, float c) { float d; asm("v_fma_mix_f32 %0, -%1, %2, %3 op_sel:[1,0,0] op_sel_hi:[1,0,0]" : "=v"(d) : "v"(h2), "v"(b), "v"(c)); return d; }
; template <int ROLE>
; __device__ __forceinline__ void scan_role(const ScanCtx& cx, KPR p) {
;     ...
;       for (int s16 = 0; s16 < 16; ++s16) { const int st = hb + s16; const RIn x = nx; if (st + 1 < SC_CH) nx = lds_ld(st + 1);
;         const float vv = (float)x.v;
;         float ya = fmix_lo(rprev.x, s[0], 0.f), yb = fmix_hi(rprev.x, s[1], 0.f);
;         float sa = fmix_lo(x.kk.x, s[0], 0.f), sb = fmix_hi(x.kk.x, s[1], 0.f);
;         ya = fmix_lo(rprev.y, s[2], ya); yb = fmix_hi(rprev.y, s[3], yb);
;         sa = fmix_lo(x.kk.y, s[2], sa); sb = fmix_hi(x.kk.y, s[3], sb);
;         float t0_ = fmixn_lo(x.u.x, s[0], s[0]), t1_ = fmixn_hi(x.u.x, s[1], s[1]), t2_ = fmixn_lo(x.u.y, s[2], s[2]), t3_ = fmixn_hi(x.u.y, s[3], s[3]);
;         float yy = ya + yb, ss = sa + sb;
;         rowsum16x2(ss, yy);
;         t0_ = fmix_lo(x.km.x, vv, t0_); t1_ = fmix_hi(x.km.x, vv, t1_); t2_ = fmix_lo(x.km.y, vv, t2_); t3_ = fmix_hi(x.km.y, vv, t3_);
;         const float nsa = -ss;
;         s[0] = fmix_lo(x.b.x, nsa, t0_); s[1] = fmix_hi(x.b.x, nsa, t1_); s[2] = fmix_lo(x.b.y, nsa, t2_); s[3] = fmix_hi(x.b.y, nsa, t3_);
;         rprev = x.r;
;         if (s16 == 0) { if (t0 + hb > 0) YO[(size_t)(cx.br * TPB + seq_pos(t0 + hb - 16 + ks, cx.dr)) * NNGP] = f2bf(ks == 15 ? yy : keep); }
;         else keep = ((s16 - 1) == ks) ? yy : keep; }
	v_fma_mix_f32 v17, -v29, v17, v17 op_sel:[1,0,0] op_sel_hi:[1,0,0]
	v_add_f32_dpp v19, v19, v19 row_ror:4 row_mask:0xf bank_mask:0xf bound_ctrl:1
	v_add_f32_dpp v18, v18, v18 row_ror:4 row_mask:0xf bank_mask:0xf bound_ctrl:1
	s_waitcnt lgkmcnt(7)
	v_fma_mix_f32 v27, -v28, v40, v40 op_sel_hi:[1,0,0]
	v_fma_mix_f32 v40, -v29, v56, v56 op_sel_hi:[1,0,0]
	v_add_f32_dpp v19, v19, v19 row_ror:8 row_mask:0xf bank_mask:0xf bound_ctrl:1
	v_fma_mix_f32 v17, v21, v57, v17 op_sel:[1,0,0] op_sel_hi:[1,1,0]
	v_add_f32_dpp v18, v18, v18 row_ror:8 row_mask:0xf bank_mask:0xf bound_ctrl:1
	v_fma_mix_f32 v28, -v28, v43, v43 op_sel:[1,0,0] op_sel_hi:[1,0,0]
	v_fma_mix_f32 v26, v20, v57, v27 op_sel_hi:[1,1,0]
	v_fma_mix_f32 v27, v21, v57, v40 op_sel_hi:[1,1,0]
	v_fma_mix_f32 v20, v20, v57, v28 op_sel:[1,0,0] op_sel_hi:[1,1,0]
	v_fma_mix_f32 v40, v30, -v19, v26 op_sel_hi:[1,0,0]
	v_fma_mix_f32 v43, v31, -v19, v27 op_sel_hi:[1,0,0]
	v_fma_mix_f32 v17, v31, -v19, v17 op_sel:[1,0,0] op_sel_hi:[1,0,0]
	v_cndmask_b32_e64 v31, v41, v18, s[26:27]
	v_fma_mix_f32 v30, v30, -v19, v20 op_sel:[1,0,0] op_sel_hi:[1,0,0]
	v_fma_mix_f32 v41, v24, v40, v2 op_sel_hi:[1,0,0]
	ds_read2_b64 v[18:21], v16 offset0:128 offset1:160
	ds_read2_b64 v[26:29], v16 offset0:176 offset1:192
	ds_read2_b64 v[56:59], v16 offset0:208 offset1:224
	v_fma_mix_f32 v24, v24, v30, v2 op_sel:[1,0,0] op_sel_hi:[1,0,0]
	s_waitcnt lgkmcnt(9)
	v_cvt_f32_f16_e32 v16, v60
	v_fma_mix_f32 v60, v36, v40, v2 op_sel_hi:[1,0,0]
	v_fma_mix_f32 v36, v36, v30, v2 op_sel:[1,0,0] op_sel_hi:[1,0,0]
	v_fma_mix_f32 v41, v25, v43, v41 op_sel_hi:[1,0,0]
	v_fma_mix_f32 v24, v25, v17, v24 op_sel:[1,0,0] op_sel_hi:[1,0,0]
	v_fma_mix_f32 v30, -v38, v30, v30 op_sel:[1,0,0] op_sel_hi:[1,0,0]
	s_nop 0
	v_fma_mix_f32 v25, v37, v43, v60 op_sel_hi:[1,0,0]
	v_fma_mix_f32 v36, v37, v17, v36 op_sel:[1,0,0] op_sel_hi:[1,0,0]
	v_fma_mix_f32 v37, -v38, v40, v40 op_sel_hi:[1,0,0]
	v_fma_mix_f32 v38, -v39, v43, v43 op_sel_hi:[1,0,0]
	v_fma_mix_f32 v17, -v39, v17, v17 op_sel:[1,0,0] op_sel_hi:[1,0,0]
	v_add_f32_e32 v24, v41, v24
	v_add_f32_e32 v25, v25, v36
	v_fma_mix_f32 v36, v34, v16, v37 op_sel_hi:[1,0,0]
	v_fma_mix_f32 v30, v34, v16, v30 op_sel:[1,0,0] op_sel_hi:[1,0,0]
	v_fma_mix_f32 v34, v35, v16, v38 op_sel_hi:[1,0,0]
	v_fma_mix_f32 v16, v35, v16, v17 op_sel:[1,0,0] op_sel_hi:[1,0,0]
	s_nop 0
	v_add_f32_dpp v24, v24, v24 quad_perm:[1,0,3,2] row_mask:0xf bank_mask:0xf bound_ctrl:1
	v_add_f32_dpp v25, v25, v25 quad_perm:[1,0,3,2] row_mask:0xf bank_mask:0xf bound_ctrl:1
	v_add_u32_e32 v40, 0x2800, v54
	v_add_f32_dpp v24, v24, v24 quad_perm:[2,3,0,1] row_mask:0xf bank_mask:0xf bound_ctrl:1
	v_add_f32_dpp v25, v25, v25 quad_perm:[2,3,0,1] row_mask:0xf bank_mask:0xf bound_ctrl:1
	s_nop 0
	v_add_f32_dpp v24, v24, v24 row_ror:4 row_mask:0xf bank_mask:0xf bound_ctrl:1
	v_add_f32_dpp v25, v25, v25 row_ror:4 row_mask:0xf bank_mask:0xf bound_ctrl:1
	s_nop 1
	v_add_f32_dpp v25, v25, v25 row_ror:8 row_mask:0xf bank_mask:0xf bound_ctrl:1
	v_xor_b32_e32 v17, 0x80000000, v25
	v_fma_mix_f32 v25, v32, v17, v36 op_sel_hi:[1,0,0]
	v_fma_mix_f32 v38, v32, v17, v30 op_sel:[1,0,0] op_sel_hi:[1,0,0]
	v_fma_mix_f32 v16, v33, v17, v16 op_sel:[1,0,0] op_sel_hi:[1,0,0]
	v_fma_mix_f32 v39, v33, v17, v34 op_sel_hi:[1,0,0]
	s_waitcnt lgkmcnt(2)
	v_fma_mix_f32 v43, v20, v25, v2 op_sel_hi:[1,0,0]
	v_fma_mix_f32 v20, v20, v38, v2 op_sel:[1,0,0] op_sel_hi:[1,0,0]
	v_fma_mix_f32 v41, v22, v25, v2 op_sel_hi:[1,0,0]
	v_fma_mix_f32 v22, v22, v38, v2 op_sel:[1,0,0] op_sel_hi:[1,0,0]
	s_nop 0
	v_add_f32_dpp v17, v24, v24 row_ror:8 row_mask:0xf bank_mask:0xf bound_ctrl:1
	v_fma_mix_f32 v20, v21, v16, v20 op_sel:[1,0,0] op_sel_hi:[1,0,0]
	v_fma_mix_f32 v41, v23, v39, v41 op_sel_hi:[1,0,0]
	v_fma_mix_f32 v22, v23, v16, v22 op_sel:[1,0,0] op_sel_hi:[1,0,0]
	v_fma_mix_f32 v23, v21, v39, v43 op_sel_hi:[1,0,0]
	v_cndmask_b32_e64 v17, v31, v17, s[28:29]
	v_add_f32_e32 v20, v23, v20
	ds_read2_b64 v[30:33], v40 offset1:16
	ds_read2_b64 v[34:37], v40 offset0:32 offset1:48
	v_add_f32_dpp v20, v20, v20 quad_perm:[1,0,3,2] row_mask:0xf bank_mask:0xf bound_ctrl:1
	s_waitcnt lgkmcnt(3)
	v_fma_mix_f32 v21, -v26, v25, v25 op_sel_hi:[1,0,0]
	v_fma_mix_f32 v16, -v27, v16, v16 op_sel:[1,0,0] op_sel_hi:[1,0,0]
	v_add_f32_e32 v22, v41, v22
	v_add_f32_dpp v20, v20, v20 quad_perm:[2,3,0,1] row_mask:0xf bank_mask:0xf bound_ctrl:1
	v_fma_mix_f32 v25, -v26, v38, v38 op_sel:[1,0,0] op_sel_hi:[1,0,0]
	v_add_f32_dpp v22, v22, v22 quad_perm:[1,0,3,2] row_mask:0xf bank_mask:0xf bound_ctrl:1
	s_waitcnt lgkmcnt(2)
	v_fma_mix_f32 v21, v56, v61, v21 op_sel_hi:[1,1,0]
	v_fma_mix_f32 v23, v56, v61, v25 op_sel:[1,0,0] op_sel_hi:[1,1,0]
	v_fma_mix_f32 v16, v57, v61, v16 op_sel:[1,0,0] op_sel_hi:[1,1,0]
	v_add_f32_dpp v20, v20, v20 row_ror:4 row_mask:0xf bank_mask:0xf bound_ctrl:1
	v_fma_mix_f32 v26, -v27, v39, v39 op_sel_hi:[1,0,0]
	v_add_f32_dpp v22, v22, v22 quad_perm:[2,3,0,1] row_mask:0xf bank_mask:0xf bound_ctrl:1
	v_fma_mix_f32 v25, v57, v61, v26 op_sel_hi:[1,1,0]
	v_add_f32_dpp v20, v20, v20 row_ror:8 row_mask:0xf bank_mask:0xf bound_ctrl:1
	v_xor_b32_e32 v20, 0x80000000, v20
	v_fma_mix_f32 v38, v28, v20, v21 op_sel_hi:[1,0,0]
	v_fma_mix_f32 v28, v28, v20, v23 op_sel:[1,0,0] op_sel_hi:[1,0,0]
	v_fma_mix_f32 v39, v29, v20, v25 op_sel_hi:[1,0,0]
	v_fma_mix_f32 v16, v29, v20, v16 op_sel:[1,0,0] op_sel_hi:[1,0,0]
	v_add_f32_dpp v22, v22, v22 row_ror:4 row_mask:0xf bank_mask:0xf bound_ctrl:1
	v_fma_mix_f32 v41, v18, v38, v2 op_sel_hi:[1,0,0]
	v_fma_mix_f32 v18, v18, v28, v2 op_sel:[1,0,0] op_sel_hi:[1,0,0]
	s_waitcnt lgkmcnt(1)
; __device__ __forceinline__ bf16_t f2bf(float f) { return (bf16_t)(pk2(f, 0.f) & 0xffffu); }
; __device__ __forceinline__ float fmix_lo(unsigned h2, float b, float c) { float d; asm("v_fma_mix_f32 %0, %1, %2, %3 op_sel_hi:[1,0,0]" : "=v"(d) : "v"(h2), "v"(b), "v"(c)); return d; }
; __device__ __forceinline__ float fmix_hi(unsigned h2, float b, float c) { float d; asm("v_fma_mix_f32 %0, %1, %2, %3 op_sel:[1,0,0] op_sel_hi:[1,0,0]" : "=v"(d) : "v"(h2), "v"(b), "v"(c)); return d; }
; __device__ __forceinline__ float fmixn_lo(unsigned h2, float b, float c) { float d; asm("v_fma_mix_f32 %0, -%1, %2, %3 op_sel_hi:[1,0,0]" : "=v"(d) : "v"(h2), "v"(b), "v"(c)); return d; }
; __device__ __forceinline__ float fmixn_hi(unsigned h2, float b, float c) { float d; asm("v_fma_mix_f32 %0, -%1, %2, %3 op_sel:[1,0,0] op_sel_hi:[1,0,0]" : "=v"(d) : "v"(h2), "v"(b), "v"(c)); return d; }
; template <int ROLE>
; __device__ __forceinline__ void scan_role(const ScanCtx& cx, KPR p) {
;     ...
;       for (int s16 = 0; s16 < 16; ++s16) { const int st = hb + s16; const RIn x = nx; if (st + 1 < SC_CH) nx = lds_ld(st + 1);
;         const float vv = (float)x.v;
;         float ya = fmix_lo(rprev.x, s[0], 0.f), yb = fmix_hi(rprev.x, s[1], 0.f);
;         float sa = fmix_lo(x.kk.x, s[0], 0.f), sb = fmix_hi(x.kk.x, s[1], 0.f);
;         ya = fmix_lo(rprev.y, s[2], ya); yb = fmix_hi(rprev.y, s[3], yb);
;         sa = fmix_lo(x.kk.y, s[2], sa); sb = fmix_hi(x.kk.y, s[3], sb);
;         float t0_ = fmixn_lo(x.u.x, s[0], s[0]), t1_ = fmixn_hi(x.u.x, s[1], s[1]), t2_ = fmixn_lo(x.u.y, s[2], s[2]), t3_ = fmixn_hi(x.u.y, s[3], s[3]);
;         float yy = ya + yb, ss = sa + sb;
;         rowsum16x2(ss, yy);
;         t0_ = fmix_lo(x.km.x, vv, t0_); t1_ = fmix_hi(x.km.x, vv, t1_); t2_ = fmix_lo(x.km.y, vv, t2_); t3_ = fmix_hi(x.km.y, vv, t3_);
;         const float nsa = -ss;
;         s[0] = fmix_lo(x.b.x, nsa, t0_); s[1] = fmix_hi(x.b.x, nsa, t1_); s[2] = fmix_lo(x.b.y, nsa, t2_); s[3] = fmix_hi(x.b.y, nsa, t3_);
;         rprev = x.r;
;         if (s16 == 0) { if (t0 + hb > 0) YO[(size_t)(cx.br * TPB + seq_pos(t0 + hb - 16 + ks, cx.dr)) * NNGP] = f2bf(ks == 15 ? yy : keep); }
;         else keep = ((s16 - 1) == ks) ? yy : keep; }
	v_fma_mix_f32 v43, v30, v38, v2 op_sel_hi:[1,0,0]
	v_fma_mix_f32 v30, v30, v28, v2 op_sel:[1,0,0] op_sel_hi:[1,0,0]
	v_fma_mix_f32 v28, -v32, v28, v28 op_sel:[1,0,0] op_sel_hi:[1,0,0]
	s_nop 0
	v_add_f32_dpp v20, v22, v22 row_ror:8 row_mask:0xf bank_mask:0xf bound_ctrl:1
	v_fma_mix_f32 v41, v19, v39, v41 op_sel_hi:[1,0,0]
	v_fma_mix_f32 v18, v19, v16, v18 op_sel:[1,0,0] op_sel_hi:[1,0,0]
	v_fma_mix_f32 v19, v31, v39, v43 op_sel_hi:[1,0,0]
	v_fma_mix_f32 v30, v31, v16, v30 op_sel:[1,0,0] op_sel_hi:[1,0,0]
	v_cndmask_b32_e64 v17, v17, v20, s[30:31]
	v_add_f32_e32 v19, v19, v30
	ds_read2_b64 v[20:23], v40 offset0:64 offset1:96
	ds_read2_b64 v[24:27], v40 offset0:112 offset1:128
	ds_read2_b64 v[60:63], v40 offset0:144 offset1:160
	v_add_f32_dpp v19, v19, v19 quad_perm:[1,0,3,2] row_mask:0xf bank_mask:0xf bound_ctrl:1
	v_fma_mix_f32 v31, -v32, v38, v38 op_sel_hi:[1,0,0]
	v_fma_mix_f32 v16, -v33, v16, v16 op_sel:[1,0,0] op_sel_hi:[1,0,0]
	v_fma_mix_f32 v32, -v33, v39, v39 op_sel_hi:[1,0,0]
	s_waitcnt lgkmcnt(3)
	v_fma_mix_f32 v30, v36, v64, v31 op_sel_hi:[1,1,0]
	v_add_f32_dpp v19, v19, v19 quad_perm:[2,3,0,1] row_mask:0xf bank_mask:0xf bound_ctrl:1
	v_fma_mix_f32 v28, v36, v64, v28 op_sel:[1,0,0] op_sel_hi:[1,1,0]
	v_fma_mix_f32 v31, v37, v64, v32 op_sel_hi:[1,1,0]
	v_fma_mix_f32 v16, v37, v64, v16 op_sel:[1,0,0] op_sel_hi:[1,1,0]
	v_add_f32_e32 v18, v41, v18
	s_nop 0
	v_add_f32_dpp v19, v19, v19 row_ror:4 row_mask:0xf bank_mask:0xf bound_ctrl:1
	v_add_f32_dpp v18, v18, v18 quad_perm:[1,0,3,2] row_mask:0xf bank_mask:0xf bound_ctrl:1
	s_nop 0
	v_add_f32_dpp v19, v19, v19 row_ror:8 row_mask:0xf bank_mask:0xf bound_ctrl:1
	v_fma_mix_f32 v36, v34, -v19, v30 op_sel_hi:[1,0,0]
	v_fma_mix_f32 v37, v34, -v19, v28 op_sel:[1,0,0] op_sel_hi:[1,0,0]
	v_fma_mix_f32 v38, v35, -v19, v31 op_sel_hi:[1,0,0]
	v_fma_mix_f32 v16, v35, -v19, v16 op_sel:[1,0,0] op_sel_hi:[1,0,0]
	ds_read2_b64 v[28:31], v40 offset0:192 offset1:208
	ds_read2_b64 v[32:35], v40 offset0:224 offset1:240
	s_waitcnt lgkmcnt(4)
	v_fma_mix_f32 v40, v22, v36, v2 op_sel_hi:[1,0,0]
	v_fma_mix_f32 v22, v22, v37, v2 op_sel:[1,0,0] op_sel_hi:[1,0,0]
	v_add_f32_dpp v18, v18, v18 quad_perm:[2,3,0,1] row_mask:0xf bank_mask:0xf bound_ctrl:1
	v_fma_mix_f32 v22, v23, v16, v22 op_sel:[1,0,0] op_sel_hi:[1,0,0]
	v_fma_mix_f32 v40, v23, v38, v40 op_sel_hi:[1,0,0]
	v_fma_mix_f32 v19, v58, v36, v2 op_sel_hi:[1,0,0]
	v_fma_mix_f32 v39, v58, v37, v2 op_sel:[1,0,0] op_sel_hi:[1,0,0]
	s_waitcnt lgkmcnt(3)
	v_fma_mix_f32 v23, -v24, v36, v36 op_sel_hi:[1,0,0]
	s_nop 0
	v_add_f32_dpp v18, v18, v18 row_ror:4 row_mask:0xf bank_mask:0xf bound_ctrl:1
	v_add_f32_e32 v22, v40, v22
	v_fma_mix_f32 v19, v59, v38, v19 op_sel_hi:[1,0,0]
	v_fma_mix_f32 v39, v59, v16, v39 op_sel:[1,0,0] op_sel_hi:[1,0,0]
	v_fma_mix_f32 v24, -v24, v37, v37 op_sel:[1,0,0] op_sel_hi:[1,0,0]
	v_fma_mix_f32 v16, -v25, v16, v16 op_sel:[1,0,0] op_sel_hi:[1,0,0]
	s_nop 0
	v_add_f32_dpp v18, v18, v18 row_ror:8 row_mask:0xf bank_mask:0xf bound_ctrl:1
	v_add_f32_dpp v22, v22, v22 quad_perm:[1,0,3,2] row_mask:0xf bank_mask:0xf bound_ctrl:1
	v_cndmask_b32_e64 v17, v17, v18, s[34:35]
	s_nop 0
	v_add_f32_dpp v22, v22, v22 quad_perm:[2,3,0,1] row_mask:0xf bank_mask:0xf bound_ctrl:1
	v_add_f32_e32 v19, v19, v39
	v_fma_mix_f32 v36, -v25, v38, v38 op_sel_hi:[1,0,0]
	s_waitcnt lgkmcnt(2)
	v_fma_mix_f32 v23, v60, v65, v23 op_sel_hi:[1,1,0]
	v_fma_mix_f32 v24, v60, v65, v24 op_sel:[1,0,0] op_sel_hi:[1,1,0]
	v_fma_mix_f32 v16, v61, v65, v16 op_sel:[1,0,0] op_sel_hi:[1,1,0]
	v_add_f32_dpp v22, v22, v22 row_ror:4 row_mask:0xf bank_mask:0xf bound_ctrl:1
	v_add_f32_dpp v19, v19, v19 quad_perm:[1,0,3,2] row_mask:0xf bank_mask:0xf bound_ctrl:1
	v_fma_mix_f32 v25, v61, v65, v36 op_sel_hi:[1,1,0]
	v_add_u32_e32 v60, 0x3000, v54
	v_add_f32_dpp v22, v22, v22 row_ror:8 row_mask:0xf bank_mask:0xf bound_ctrl:1
	v_fma_mix_f32 v40, v26, -v22, v23 op_sel_hi:[1,0,0]
	v_fma_mix_f32 v26, v26, -v22, v24 op_sel:[1,0,0] op_sel_hi:[1,0,0]
	v_add_f32_dpp v19, v19, v19 quad_perm:[2,3,0,1] row_mask:0xf bank_mask:0xf bound_ctrl:1
	v_fma_mix_f32 v57, v20, v40, v2 op_sel_hi:[1,0,0]
	v_fma_mix_f32 v20, v20, v26, v2 op_sel:[1,0,0] op_sel_hi:[1,0,0]
	v_fma_mix_f32 v41, v27, -v22, v25 op_sel_hi:[1,0,0]
	v_fma_mix_f32 v27, v27, -v22, v16 op_sel:[1,0,0] op_sel_hi:[1,0,0]
	s_waitcnt lgkmcnt(1)
	v_fma_mix_f32 v58, v28, v40, v2 op_sel_hi:[1,0,0]
	v_fma_mix_f32 v28, v28, v26, v2 op_sel:[1,0,0] op_sel_hi:[1,0,0]
	s_nop 0
	v_add_f32_dpp v19, v19, v19 row_ror:4 row_mask:0xf bank_mask:0xf bound_ctrl:1
	v_fma_mix_f32 v57, v21, v41, v57 op_sel_hi:[1,0,0]
	v_fma_mix_f32 v20, v21, v27, v20 op_sel:[1,0,0] op_sel_hi:[1,0,0]
	v_fma_mix_f32 v21, v29, v41, v58 op_sel_hi:[1,0,0]
	v_fma_mix_f32 v28, v29, v27, v28 op_sel:[1,0,0] op_sel_hi:[1,0,0]
	v_fma_mix_f32 v29, -v30, v40, v40 op_sel_hi:[1,0,0]
	s_nop 1
	v_add_f32_dpp v16, v19, v19 row_ror:8 row_mask:0xf bank_mask:0xf bound_ctrl:1
	v_add_f32_e32 v20, v57, v20
	v_add_f32_e32 v21, v21, v28
	v_cndmask_b32_e64 v43, v17, v16, s[36:37]
	v_add_f32_dpp v20, v20, v20 quad_perm:[1,0,3,2] row_mask:0xf bank_mask:0xf bound_ctrl:1
	v_add_f32_dpp v21, v21, v21 quad_perm:[1,0,3,2] row_mask:0xf bank_mask:0xf bound_ctrl:1
	ds_read2_b64 v[36:39], v60 offset1:32
	ds_read2_b64 v[22:25], v60 offset0:48 offset1:64
	ds_read2_b64 v[16:19], v60 offset0:80 offset1:96
	v_add_f32_dpp v21, v21, v21 quad_perm:[2,3,0,1] row_mask:0xf bank_mask:0xf bound_ctrl:1
	v_add_f32_dpp v20, v20, v20 quad_perm:[2,3,0,1] row_mask:0xf bank_mask:0xf bound_ctrl:1
	v_fma_mix_f32 v26, -v30, v26, v26 op_sel:[1,0,0] op_sel_hi:[1,0,0]
	v_fma_mix_f32 v30, -v31, v41, v41 op_sel_hi:[1,0,0]
	v_fma_mix_f32 v27, -v31, v27, v27 op_sel:[1,0,0] op_sel_hi:[1,0,0]
	s_waitcnt lgkmcnt(3)
; __device__ __forceinline__ bf16_t f2bf(float f) { return (bf16_t)(pk2(f, 0.f) & 0xffffu); }
; __device__ __forceinline__ float fmix_lo(unsigned h2, float b, float c) { float d; asm("v_fma_mix_f32 %0, %1, %2, %3 op_sel_hi:[1,0,0]" : "=v"(d) : "v"(h2), "v"(b), "v"(c)); return d; }
; __device__ __forceinline__ float fmix_hi(unsigned h2, float b, float c) { float d; asm("v_fma_mix_f32 %0, %1, %2, %3 op_sel:[1,0,0] op_sel_hi:[1,0,0]" : "=v"(d) : "v"(h2), "v"(b), "v"(c)); return d; }
; __device__ __forceinline__ float fmixn_lo(unsigned h2, float b, float c) { float d; asm("v_fma_mix_f32 %0, -%1, %2, %3 op_sel_hi:[1,0,0]" : "=v"(d) : "v"(h2), "v"(b), "v"(c)); return d; }
; __device__ __forceinline__ float fmixn_hi(unsigned h2, float b, float c) { float d; asm("v_fma_mix_f32 %0, -%1, %2, %3 op_sel:[1,0,0] op_sel_hi:[1,0,0]" : "=v"(d) : "v"(h2), "v"(b), "v"(c)); return d; }
; template <int ROLE>
; __device__ __forceinline__ void scan_role(const ScanCtx& cx, KPR p) {
;     ...
;       for (int s16 = 0; s16 < 16; ++s16) { const int st = hb + s16; const RIn x = nx; if (st + 1 < SC_CH) nx = lds_ld(st + 1);
;         const float vv = (float)x.v;
;         float ya = fmix_lo(rprev.x, s[0], 0.f), yb = fmix_hi(rprev.x, s[1], 0.f);
;         float sa = fmix_lo(x.kk.x, s[0], 0.f), sb = fmix_hi(x.kk.x, s[1], 0.f);
;         ya = fmix_lo(rprev.y, s[2], ya); yb = fmix_hi(rprev.y, s[3], yb);
;         sa = fmix_lo(x.kk.y, s[2], sa); sb = fmix_hi(x.kk.y, s[3], sb);
;         float t0_ = fmixn_lo(x.u.x, s[0], s[0]), t1_ = fmixn_hi(x.u.x, s[1], s[1]), t2_ = fmixn_lo(x.u.y, s[2], s[2]), t3_ = fmixn_hi(x.u.y, s[3], s[3]);
;         float yy = ya + yb, ss = sa + sb;
;         rowsum16x2(ss, yy);
;         t0_ = fmix_lo(x.km.x, vv, t0_); t1_ = fmix_hi(x.km.x, vv, t1_); t2_ = fmix_lo(x.km.y, vv, t2_); t3_ = fmix_hi(x.km.y, vv, t3_);
;         const float nsa = -ss;
;         s[0] = fmix_lo(x.b.x, nsa, t0_); s[1] = fmix_hi(x.b.x, nsa, t1_); s[2] = fmix_lo(x.b.y, nsa, t2_); s[3] = fmix_hi(x.b.y, nsa, t3_);
;         rprev = x.r;
;         if (s16 == 0) { if (t0 + hb > 0) YO[(size_t)(cx.br * TPB + seq_pos(t0 + hb - 16 + ks, cx.dr)) * NNGP] = f2bf(ks == 15 ? yy : keep); }
;         else keep = ((s16 - 1) == ks) ? yy : keep; }
	v_fma_mix_f32 v28, v34, v66, v29 op_sel_hi:[1,1,0]
	v_add_f32_dpp v21, v21, v21 row_ror:4 row_mask:0xf bank_mask:0xf bound_ctrl:1
	v_add_f32_dpp v20, v20, v20 row_ror:4 row_mask:0xf bank_mask:0xf bound_ctrl:1
	v_fma_mix_f32 v26, v34, v66, v26 op_sel:[1,0,0] op_sel_hi:[1,1,0]
	v_fma_mix_f32 v29, v35, v66, v30 op_sel_hi:[1,1,0]
	v_fma_mix_f32 v27, v35, v66, v27 op_sel:[1,0,0] op_sel_hi:[1,1,0]
	v_add_f32_dpp v21, v21, v21 row_ror:8 row_mask:0xf bank_mask:0xf bound_ctrl:1
	v_add_f32_dpp v20, v20, v20 row_ror:8 row_mask:0xf bank_mask:0xf bound_ctrl:1
	v_fma_mix_f32 v28, v32, -v21, v28 op_sel_hi:[1,0,0]
	v_fma_mix_f32 v26, v32, -v21, v26 op_sel:[1,0,0] op_sel_hi:[1,0,0]
	v_fma_mix_f32 v29, v33, -v21, v29 op_sel_hi:[1,0,0]
	v_cndmask_b32_e64 v40, v43, v20, s[38:39]
	v_subrev_u32_e32 v20, 48, v42
	v_fma_mix_f32 v31, v62, v28, v2 op_sel_hi:[1,0,0]
	s_waitcnt lgkmcnt(2)
	v_fma_mix_f32 v42, v38, v28, v2 op_sel_hi:[1,0,0]
	v_fma_mix_f32 v38, v38, v26, v2 op_sel:[1,0,0] op_sel_hi:[1,0,0]
	v_fma_mix_f32 v27, v33, -v21, v27 op_sel:[1,0,0] op_sel_hi:[1,0,0]
	v_fma_mix_f32 v41, v62, v26, v2 op_sel:[1,0,0] op_sel_hi:[1,0,0]
	s_waitcnt lgkmcnt(1)
	v_fma_mix_f32 v28, -v22, v28, v28 op_sel_hi:[1,0,0]
	v_fma_mix_f32 v31, v63, v29, v31 op_sel_hi:[1,0,0]
	v_fma_mix_f32 v42, v39, v29, v42 op_sel_hi:[1,0,0]
	v_fma_mix_f32 v22, -v22, v26, v26 op_sel:[1,0,0] op_sel_hi:[1,0,0]
	v_fma_mix_f32 v38, v39, v27, v38 op_sel:[1,0,0] op_sel_hi:[1,0,0]
	v_fma_mix_f32 v26, -v23, v29, v29 op_sel_hi:[1,0,0]
	ds_read2_b64 v[32:35], v60 offset0:128 offset1:144
	ds_read2_b64 v[56:59], v60 offset0:160 offset1:176
	v_add_f32_e32 v29, v42, v38
	v_fma_mix_f32 v23, -v23, v27, v27 op_sel:[1,0,0] op_sel_hi:[1,0,0]
	s_waitcnt lgkmcnt(2)
	v_fma_mix_f32 v28, v16, v67, v28 op_sel_hi:[1,1,0]
	v_fma_mix_f32 v16, v16, v67, v22 op_sel:[1,0,0] op_sel_hi:[1,1,0]
	v_fma_mix_f32 v41, v63, v27, v41 op_sel:[1,0,0] op_sel_hi:[1,0,0]
	v_fma_mix_f32 v22, v17, v67, v26 op_sel_hi:[1,1,0]
	s_nop 0
	v_add_f32_dpp v29, v29, v29 quad_perm:[1,0,3,2] row_mask:0xf bank_mask:0xf bound_ctrl:1
	v_fma_mix_f32 v17, v17, v67, v23 op_sel:[1,0,0] op_sel_hi:[1,1,0]
	v_add_f32_e32 v27, v31, v41
	v_cmp_lt_u32_e32 vcc, s97, v20
	v_add_f32_dpp v29, v29, v29 quad_perm:[2,3,0,1] row_mask:0xf bank_mask:0xf bound_ctrl:1
	v_add_f32_dpp v27, v27, v27 quad_perm:[1,0,3,2] row_mask:0xf bank_mask:0xf bound_ctrl:1
	v_cndmask_b32_e32 v21, v186, v187, vcc
	v_add_f32_dpp v29, v29, v29 row_ror:4 row_mask:0xf bank_mask:0xf bound_ctrl:1
	v_add_f32_dpp v27, v27, v27 quad_perm:[2,3,0,1] row_mask:0xf bank_mask:0xf bound_ctrl:1
	v_add_u32_e32 v21, v53, v21
	v_add_f32_dpp v29, v29, v29 row_ror:8 row_mask:0xf bank_mask:0xf bound_ctrl:1
	v_fma_mix_f32 v38, v24, -v29, v28 op_sel_hi:[1,0,0]
	v_fma_mix_f32 v16, v24, -v29, v16 op_sel:[1,0,0] op_sel_hi:[1,0,0]
	v_fma_mix_f32 v17, v25, -v29, v17 op_sel:[1,0,0] op_sel_hi:[1,0,0]
	v_fma_mix_f32 v39, v25, -v29, v22 op_sel_hi:[1,0,0]
	v_add_f32_dpp v27, v27, v27 row_ror:4 row_mask:0xf bank_mask:0xf bound_ctrl:1
	s_waitcnt lgkmcnt(1)
	v_fma_mix_f32 v42, v32, v38, v2 op_sel_hi:[1,0,0]
	v_fma_mix_f32 v32, v32, v16, v2 op_sel:[1,0,0] op_sel_hi:[1,0,0]
	v_fma_mix_f32 v41, v36, v38, v2 op_sel_hi:[1,0,0]
	v_fma_mix_f32 v36, v36, v16, v2 op_sel:[1,0,0] op_sel_hi:[1,0,0]
	v_fma_mix_f32 v16, -v34, v16, v16 op_sel:[1,0,0] op_sel_hi:[1,0,0]
	s_nop 0
	v_add_f32_dpp v27, v27, v27 row_ror:8 row_mask:0xf bank_mask:0xf bound_ctrl:1
	v_fma_mix_f32 v32, v33, v17, v32 op_sel:[1,0,0] op_sel_hi:[1,0,0]
	v_fma_mix_f32 v41, v37, v39, v41 op_sel_hi:[1,0,0]
	v_fma_mix_f32 v36, v37, v17, v36 op_sel:[1,0,0] op_sel_hi:[1,0,0]
	v_fma_mix_f32 v37, v33, v39, v42 op_sel_hi:[1,0,0]
	v_add_f32_e32 v32, v37, v32
	v_fma_mix_f32 v33, -v34, v38, v38 op_sel_hi:[1,0,0]
	v_fma_mix_f32 v34, -v35, v39, v39 op_sel_hi:[1,0,0]
	v_fma_mix_f32 v17, -v35, v17, v17 op_sel:[1,0,0] op_sel_hi:[1,0,0]
	s_waitcnt lgkmcnt(0)
	v_fma_mix_f32 v16, v58, v68, v16 op_sel:[1,0,0] op_sel_hi:[1,1,0]
	v_add3_u32 v21, v21, s53, 48
	v_add_f32_dpp v32, v32, v32 quad_perm:[1,0,3,2] row_mask:0xf bank_mask:0xf bound_ctrl:1
	v_cndmask_b32_e64 v22, v40, v27, s[6:7]
	ds_read2_b64 v[24:27], v60 offset0:192 offset1:224
	v_add_f32_dpp v32, v32, v32 quad_perm:[2,3,0,1] row_mask:0xf bank_mask:0xf bound_ctrl:1
	v_fma_mix_f32 v33, v58, v68, v33 op_sel_hi:[1,1,0]
	v_fma_mix_f32 v34, v59, v68, v34 op_sel_hi:[1,1,0]
	v_fma_mix_f32 v17, v59, v68, v17 op_sel:[1,0,0] op_sel_hi:[1,1,0]
	v_cndmask_b32_e64 v20, v21, v20, s[4:5]
	v_add_u32_e32 v20, s47, v20
	v_add_f32_dpp v32, v32, v32 row_ror:4 row_mask:0xf bank_mask:0xf bound_ctrl:1
	v_add_f32_e32 v35, v41, v36
	v_mad_i64_i32 v[20:21], s[42:43], v20, s81, v[48:49]
	v_add_f32_dpp v32, v32, v32 row_ror:8 row_mask:0xf bank_mask:0xf bound_ctrl:1
	v_fma_mix_f32 v43, v56, -v32, v33 op_sel_hi:[1,0,0]
	v_fma_mix_f32 v16, v56, -v32, v16 op_sel:[1,0,0] op_sel_hi:[1,0,0]
	v_fma_mix_f32 v56, v57, -v32, v34 op_sel_hi:[1,0,0]
	v_fma_mix_f32 v17, v57, -v32, v17 op_sel:[1,0,0] op_sel_hi:[1,0,0]
	v_cvt_pk_bf16_f32 v22, v22, s0
	v_fma_mix_f32 v62, v18, v43, v2 op_sel_hi:[1,0,0]
	v_fma_mix_f32 v18, v18, v16, v2 op_sel:[1,0,0] op_sel_hi:[1,0,0]
	s_waitcnt lgkmcnt(0)
; __device__ __forceinline__ bf16_t f2bf(float f) { return (bf16_t)(pk2(f, 0.f) & 0xffffu); }
; __device__ __forceinline__ float fmix_lo(unsigned h2, float b, float c) { float d; asm("v_fma_mix_f32 %0, %1, %2, %3 op_sel_hi:[1,0,0]" : "=v"(d) : "v"(h2), "v"(b), "v"(c)); return d; }
; __device__ __forceinline__ float fmix_hi(unsigned h2, float b, float c) { float d; asm("v_fma_mix_f32 %0, %1, %2, %3 op_sel:[1,0,0] op_sel_hi:[1,0,0]" : "=v"(d) : "v"(h2), "v"(b), "v"(c)); return d; }
; __device__ __forceinline__ float fmixn_lo(unsigned h2, float b, float c) { float d; asm("v_fma_mix_f32 %0, -%1, %2, %3 op_sel_hi:[1,0,0]" : "=v"(d) : "v"(h2), "v"(b), "v"(c)); return d; }
; __device__ __forceinline__ float fmixn_hi(unsigned h2, float b, float c) { float d; asm("v_fma_mix_f32 %0, -%1, %2, %3 op_sel:[1,0,0] op_sel_hi:[1,0,0]" : "=v"(d) : "v"(h2), "v"(b), "v"(c)); return d; }
; template <int ROLE>
; __device__ __forceinline__ void scan_role(const ScanCtx& cx, KPR p) {
;     ...
;       for (int s16 = 0; s16 < 16; ++s16) { const int st = hb + s16; const RIn x = nx; if (st + 1 < SC_CH) nx = lds_ld(st + 1);
;         const float vv = (float)x.v;
;         float ya = fmix_lo(rprev.x, s[0], 0.f), yb = fmix_hi(rprev.x, s[1], 0.f);
;         float sa = fmix_lo(x.kk.x, s[0], 0.f), sb = fmix_hi(x.kk.x, s[1], 0.f);
;         ya = fmix_lo(rprev.y, s[2], ya); yb = fmix_hi(rprev.y, s[3], yb);
;         sa = fmix_lo(x.kk.y, s[2], sa); sb = fmix_hi(x.kk.y, s[3], sb);
;         float t0_ = fmixn_lo(x.u.x, s[0], s[0]), t1_ = fmixn_hi(x.u.x, s[1], s[1]), t2_ = fmixn_lo(x.u.y, s[2], s[2]), t3_ = fmixn_hi(x.u.y, s[3], s[3]);
;         float yy = ya + yb, ss = sa + sb;
;         rowsum16x2(ss, yy);
;         t0_ = fmix_lo(x.km.x, vv, t0_); t1_ = fmix_hi(x.km.x, vv, t1_); t2_ = fmix_lo(x.km.y, vv, t2_); t3_ = fmix_hi(x.km.y, vv, t3_);
;         const float nsa = -ss;
;         s[0] = fmix_lo(x.b.x, nsa, t0_); s[1] = fmix_hi(x.b.x, nsa, t1_); s[2] = fmix_lo(x.b.y, nsa, t2_); s[3] = fmix_hi(x.b.y, nsa, t3_);
;         rprev = x.r;
;         if (s16 == 0) { if (t0 + hb > 0) YO[(size_t)(cx.br * TPB + seq_pos(t0 + hb - 16 + ks, cx.dr)) * NNGP] = f2bf(ks == 15 ? yy : keep); }
;         else keep = ((s16 - 1) == ks) ? yy : keep; }
	v_fma_mix_f32 v63, v26, v43, v2 op_sel_hi:[1,0,0]
	v_fma_mix_f32 v26, v26, v16, v2 op_sel:[1,0,0] op_sel_hi:[1,0,0]
	v_add_f32_dpp v35, v35, v35 quad_perm:[1,0,3,2] row_mask:0xf bank_mask:0xf bound_ctrl:1
	v_fma_mix_f32 v62, v19, v56, v62 op_sel_hi:[1,0,0]
	v_fma_mix_f32 v18, v19, v17, v18 op_sel:[1,0,0] op_sel_hi:[1,0,0]
	v_fma_mix_f32 v19, v27, v56, v63 op_sel_hi:[1,0,0]
	v_fma_mix_f32 v26, v27, v17, v26 op_sel:[1,0,0] op_sel_hi:[1,0,0]
	global_store_short v[20:21], v22, off
	v_add_f32_e32 v19, v19, v26
	v_add_f32_e32 v18, v62, v18
	v_add_u32_e32 v20, 0x3400, v54
	v_add_f32_dpp v19, v19, v19 quad_perm:[1,0,3,2] row_mask:0xf bank_mask:0xf bound_ctrl:1
	v_add_u32_e32 v60, 0x3800, v54
	v_add_f32_dpp v35, v35, v35 quad_perm:[2,3,0,1] row_mask:0xf bank_mask:0xf bound_ctrl:1
	v_add_f32_dpp v18, v18, v18 quad_perm:[1,0,3,2] row_mask:0xf bank_mask:0xf bound_ctrl:1
	v_add_f32_dpp v19, v19, v19 quad_perm:[2,3,0,1] row_mask:0xf bank_mask:0xf bound_ctrl:1
	ds_read2_b64 v[28:31], v20 offset0:112 offset1:128
	ds_read2_b64 v[20:23], v60 offset0:16 offset1:32
	v_add_f32_dpp v41, v35, v35 row_ror:4 row_mask:0xf bank_mask:0xf bound_ctrl:1
	ds_read2_b64 v[36:39], v60 offset0:64 offset1:80
	ds_read2_b64 v[32:35], v60 offset0:96 offset1:112
	ds_read_u16 v57, v55 offset:13952
	ds_read_u16 v58, v55 offset:14720
	ds_read_u16 v59, v55 offset:15488
	ds_read_u16 v61, v55 offset:16256
	ds_read_u16 v70, v55 offset:17024
	ds_read_u16 v71, v55 offset:17792
	ds_read_u16 v74, v55 offset:18560
	ds_read_u16 v75, v55 offset:19328
	v_add_f32_dpp v18, v18, v18 quad_perm:[2,3,0,1] row_mask:0xf bank_mask:0xf bound_ctrl:1
	v_add_f32_dpp v19, v19, v19 row_ror:4 row_mask:0xf bank_mask:0xf bound_ctrl:1
	s_waitcnt lgkmcnt(7)
	v_fma_mix_f32 v27, -v28, v43, v43 op_sel_hi:[1,0,0]
	v_fma_mix_f32 v16, -v28, v16, v16 op_sel:[1,0,0] op_sel_hi:[1,0,0]
	v_fma_mix_f32 v17, -v29, v17, v17 op_sel:[1,0,0] op_sel_hi:[1,0,0]
	v_add_f32_dpp v43, v18, v18 row_ror:4 row_mask:0xf bank_mask:0xf bound_ctrl:1
	v_add_f32_dpp v18, v19, v19 row_ror:8 row_mask:0xf bank_mask:0xf bound_ctrl:1
	v_fma_mix_f32 v28, -v29, v56, v56 op_sel_hi:[1,0,0]
	v_fma_mix_f32 v19, v20, v57, v27 op_sel_hi:[1,1,0]
	v_fma_mix_f32 v16, v20, v57, v16 op_sel:[1,0,0] op_sel_hi:[1,1,0]
	v_fma_mix_f32 v17, v21, v57, v17 op_sel:[1,0,0] op_sel_hi:[1,1,0]
	v_fma_mix_f32 v20, v21, v57, v28 op_sel_hi:[1,1,0]
	v_fma_mix_f32 v21, v30, -v18, v19 op_sel_hi:[1,0,0]
	v_fma_mix_f32 v30, v30, -v18, v16 op_sel:[1,0,0] op_sel_hi:[1,0,0]
	v_mov_b32_dpp v42, v41 row_ror:8 row_mask:0xf bank_mask:0xf bound_ctrl:1
	v_fma_mix_f32 v57, v24, v21, v2 op_sel_hi:[1,0,0]
	v_fma_mix_f32 v24, v24, v30, v2 op_sel:[1,0,0] op_sel_hi:[1,0,0]
	v_fma_mix_f32 v20, v31, -v18, v20 op_sel_hi:[1,0,0]
	v_fma_mix_f32 v31, v31, -v18, v17 op_sel:[1,0,0] op_sel_hi:[1,0,0]
	ds_read2_b64 v[16:19], v60 offset0:128 offset1:160
	ds_read2_b64 v[26:29], v60 offset0:176 offset1:192
	ds_read2_b64 v[62:65], v60 offset0:208 offset1:224
	s_waitcnt lgkmcnt(9)
	v_cvt_f32_f16_e32 v60, v58
	v_fma_mix_f32 v58, v36, v21, v2 op_sel_hi:[1,0,0]
	v_fma_mix_f32 v36, v36, v30, v2 op_sel:[1,0,0] op_sel_hi:[1,0,0]
	v_fma_mix_f32 v57, v25, v20, v57 op_sel_hi:[1,0,0]
	v_fma_mix_f32 v24, v25, v31, v24 op_sel:[1,0,0] op_sel_hi:[1,0,0]
	v_fma_mix_f32 v21, -v38, v21, v21 op_sel_hi:[1,0,0]
	v_fma_mix_f32 v30, -v38, v30, v30 op_sel:[1,0,0] op_sel_hi:[1,0,0]
	s_nop 0
	v_fma_mix_f32 v25, v37, v20, v58 op_sel_hi:[1,0,0]
	v_fma_mix_f32 v36, v37, v31, v36 op_sel:[1,0,0] op_sel_hi:[1,0,0]
	v_fma_mix_f32 v20, -v39, v20, v20 op_sel_hi:[1,0,0]
	v_add_f32_e32 v24, v57, v24
	v_add_f32_e32 v25, v25, v36
	v_fma_mix_f32 v21, v34, v60, v21 op_sel_hi:[1,0,0]
	v_fma_mix_f32 v31, -v39, v31, v31 op_sel:[1,0,0] op_sel_hi:[1,0,0]
	v_fma_mix_f32 v20, v35, v60, v20 op_sel_hi:[1,0,0]
	s_waitcnt lgkmcnt(8)
	v_cvt_f32_f16_e32 v39, v59
	v_add_f32_dpp v24, v24, v24 quad_perm:[1,0,3,2] row_mask:0xf bank_mask:0xf bound_ctrl:1
	v_add_f32_dpp v25, v25, v25 quad_perm:[1,0,3,2] row_mask:0xf bank_mask:0xf bound_ctrl:1
	v_add_u32_e32 v38, 0x4000, v54
	v_add_f32_dpp v24, v24, v24 quad_perm:[2,3,0,1] row_mask:0xf bank_mask:0xf bound_ctrl:1
	v_add_f32_dpp v25, v25, v25 quad_perm:[2,3,0,1] row_mask:0xf bank_mask:0xf bound_ctrl:1
	v_mov_b32_dpp v56, v43 row_ror:8 row_mask:0xf bank_mask:0xf bound_ctrl:1
	v_add_f32_dpp v57, v24, v24 row_ror:4 row_mask:0xf bank_mask:0xf bound_ctrl:1
	v_add_f32_dpp v25, v25, v25 row_ror:4 row_mask:0xf bank_mask:0xf bound_ctrl:1
	s_andn2_b64 vcc, exec, s[86:87]
	v_mov_b32_dpp v58, v57 row_ror:8 row_mask:0xf bank_mask:0xf bound_ctrl:1
	v_add_f32_dpp v24, v25, v25 row_ror:8 row_mask:0xf bank_mask:0xf bound_ctrl:1
	v_fma_mix_f32 v25, v34, v60, v30 op_sel:[1,0,0] op_sel_hi:[1,0,0]
	v_fma_mix_f32 v30, v35, v60, v31 op_sel:[1,0,0] op_sel_hi:[1,0,0]
	v_fma_mix_f32 v21, v32, -v24, v21 op_sel_hi:[1,0,0]
	v_fma_mix_f32 v25, v32, -v24, v25 op_sel:[1,0,0] op_sel_hi:[1,0,0]
	v_fma_mix_f32 v20, v33, -v24, v20 op_sel_hi:[1,0,0]
	v_fma_mix_f32 v24, v33, -v24, v30 op_sel:[1,0,0] op_sel_hi:[1,0,0]
	ds_read2_b64 v[30:33], v38 offset1:16
	ds_read2_b64 v[34:37], v38 offset0:32 offset1:48
	s_waitcnt lgkmcnt(4)
	v_fma_mix_f32 v60, v18, v21, v2 op_sel_hi:[1,0,0]
	v_fma_mix_f32 v18, v18, v25, v2 op_sel:[1,0,0] op_sel_hi:[1,0,0]
	v_fma_mix_f32 v59, v22, v21, v2 op_sel_hi:[1,0,0]
	v_fma_mix_f32 v22, v22, v25, v2 op_sel:[1,0,0] op_sel_hi:[1,0,0]
	s_nop 0
	v_fma_mix_f32 v18, v19, v24, v18 op_sel:[1,0,0] op_sel_hi:[1,0,0]
	v_fma_mix_f32 v59, v23, v20, v59 op_sel_hi:[1,0,0]
	v_fma_mix_f32 v22, v23, v24, v22 op_sel:[1,0,0] op_sel_hi:[1,0,0]
	v_fma_mix_f32 v23, v19, v20, v60 op_sel_hi:[1,0,0]
	s_waitcnt lgkmcnt(3)
; __device__ __forceinline__ bf16_t f2bf(float f) { return (bf16_t)(pk2(f, 0.f) & 0xffffu); }
; __device__ __forceinline__ float fmix_lo(unsigned h2, float b, float c) { float d; asm("v_fma_mix_f32 %0, %1, %2, %3 op_sel_hi:[1,0,0]" : "=v"(d) : "v"(h2), "v"(b), "v"(c)); return d; }
; __device__ __forceinline__ float fmix_hi(unsigned h2, float b, float c) { float d; asm("v_fma_mix_f32 %0, %1, %2, %3 op_sel:[1,0,0] op_sel_hi:[1,0,0]" : "=v"(d) : "v"(h2), "v"(b), "v"(c)); return d; }
; __device__ __forceinline__ float fmixn_lo(unsigned h2, float b, float c) { float d; asm("v_fma_mix_f32 %0, -%1, %2, %3 op_sel_hi:[1,0,0]" : "=v"(d) : "v"(h2), "v"(b), "v"(c)); return d; }
; __device__ __forceinline__ float fmixn_hi(unsigned h2, float b, float c) { float d; asm("v_fma_mix_f32 %0, -%1, %2, %3 op_sel:[1,0,0] op_sel_hi:[1,0,0]" : "=v"(d) : "v"(h2), "v"(b), "v"(c)); return d; }
; template <int ROLE>
; __device__ __forceinline__ void scan_role(const ScanCtx& cx, KPR p) {
;     ...
;       for (int s16 = 0; s16 < 16; ++s16) { const int st = hb + s16; const RIn x = nx; if (st + 1 < SC_CH) nx = lds_ld(st + 1);
;         const float vv = (float)x.v;
;         float ya = fmix_lo(rprev.x, s[0], 0.f), yb = fmix_hi(rprev.x, s[1], 0.f);
;         float sa = fmix_lo(x.kk.x, s[0], 0.f), sb = fmix_hi(x.kk.x, s[1], 0.f);
;         ya = fmix_lo(rprev.y, s[2], ya); yb = fmix_hi(rprev.y, s[3], yb);
;         sa = fmix_lo(x.kk.y, s[2], sa); sb = fmix_hi(x.kk.y, s[3], sb);
;         float t0_ = fmixn_lo(x.u.x, s[0], s[0]), t1_ = fmixn_hi(x.u.x, s[1], s[1]), t2_ = fmixn_lo(x.u.y, s[2], s[2]), t3_ = fmixn_hi(x.u.y, s[3], s[3]);
;         float yy = ya + yb, ss = sa + sb;
;         rowsum16x2(ss, yy);
;         t0_ = fmix_lo(x.km.x, vv, t0_); t1_ = fmix_hi(x.km.x, vv, t1_); t2_ = fmix_lo(x.km.y, vv, t2_); t3_ = fmix_hi(x.km.y, vv, t3_);
;         const float nsa = -ss;
;         s[0] = fmix_lo(x.b.x, nsa, t0_); s[1] = fmix_hi(x.b.x, nsa, t1_); s[2] = fmix_lo(x.b.y, nsa, t2_); s[3] = fmix_hi(x.b.y, nsa, t3_);
;         rprev = x.r;
;         if (s16 == 0) { if (t0 + hb > 0) YO[(size_t)(cx.br * TPB + seq_pos(t0 + hb - 16 + ks, cx.dr)) * NNGP] = f2bf(ks == 15 ? yy : keep); }
;         else keep = ((s16 - 1) == ks) ? yy : keep; }
	v_fma_mix_f32 v19, -v26, v21, v21 op_sel_hi:[1,0,0]
	v_fma_mix_f32 v21, -v26, v25, v25 op_sel:[1,0,0] op_sel_hi:[1,0,0]
	v_fma_mix_f32 v20, -v27, v20, v20 op_sel_hi:[1,0,0]
	v_fma_mix_f32 v24, -v27, v24, v24 op_sel:[1,0,0] op_sel_hi:[1,0,0]
	v_add_f32_e32 v22, v59, v22
	v_add_f32_e32 v18, v23, v18
	s_waitcnt lgkmcnt(2)
	v_fma_mix_f32 v19, v62, v39, v19 op_sel_hi:[1,0,0]
	v_fma_mix_f32 v21, v62, v39, v21 op_sel:[1,0,0] op_sel_hi:[1,0,0]
	v_fma_mix_f32 v20, v63, v39, v20 op_sel_hi:[1,0,0]
	v_add_f32_dpp v22, v22, v22 quad_perm:[1,0,3,2] row_mask:0xf bank_mask:0xf bound_ctrl:1
	v_add_f32_dpp v18, v18, v18 quad_perm:[1,0,3,2] row_mask:0xf bank_mask:0xf bound_ctrl:1
	s_nop 0
	v_add_f32_dpp v22, v22, v22 quad_perm:[2,3,0,1] row_mask:0xf bank_mask:0xf bound_ctrl:1
	v_add_f32_dpp v18, v18, v18 quad_perm:[2,3,0,1] row_mask:0xf bank_mask:0xf bound_ctrl:1
	s_nop 0
	v_add_f32_dpp v59, v22, v22 row_ror:4 row_mask:0xf bank_mask:0xf bound_ctrl:1
	v_add_f32_dpp v18, v18, v18 row_ror:4 row_mask:0xf bank_mask:0xf bound_ctrl:1
	v_fma_mix_f32 v22, v63, v39, v24 op_sel:[1,0,0] op_sel_hi:[1,0,0]
	s_nop 0
	v_mov_b32_dpp v60, v59 row_ror:8 row_mask:0xf bank_mask:0xf bound_ctrl:1
	v_add_f32_dpp v18, v18, v18 row_ror:8 row_mask:0xf bank_mask:0xf bound_ctrl:1
	v_fma_mix_f32 v19, v28, -v18, v19 op_sel_hi:[1,0,0]
	v_fma_mix_f32 v28, v28, -v18, v21 op_sel:[1,0,0] op_sel_hi:[1,0,0]
	v_fma_mix_f32 v39, v29, -v18, v20 op_sel_hi:[1,0,0]
	v_fma_mix_f32 v18, v29, -v18, v22 op_sel:[1,0,0] op_sel_hi:[1,0,0]
	v_cvt_f32_f16_e32 v29, v61
	v_fma_mix_f32 v61, v16, v19, v2 op_sel_hi:[1,0,0]
	v_fma_mix_f32 v16, v16, v28, v2 op_sel:[1,0,0] op_sel_hi:[1,0,0]
	s_waitcnt lgkmcnt(1)
	v_fma_mix_f32 v62, v30, v19, v2 op_sel_hi:[1,0,0]
	v_fma_mix_f32 v30, v30, v28, v2 op_sel:[1,0,0] op_sel_hi:[1,0,0]
	ds_read2_b64 v[20:23], v38 offset0:64 offset1:96
	ds_read2_b64 v[24:27], v38 offset0:112 offset1:128
	ds_read2_b64 v[66:69], v38 offset0:144 offset1:160
	v_fma_mix_f32 v61, v17, v39, v61 op_sel_hi:[1,0,0]
	v_fma_mix_f32 v16, v17, v18, v16 op_sel:[1,0,0] op_sel_hi:[1,0,0]
	v_fma_mix_f32 v17, v31, v39, v62 op_sel_hi:[1,0,0]
	v_fma_mix_f32 v30, v31, v18, v30 op_sel:[1,0,0] op_sel_hi:[1,0,0]
	v_fma_mix_f32 v19, -v32, v19, v19 op_sel_hi:[1,0,0]
	v_fma_mix_f32 v28, -v32, v28, v28 op_sel:[1,0,0] op_sel_hi:[1,0,0]
	v_fma_mix_f32 v31, -v33, v39, v39 op_sel_hi:[1,0,0]
	s_nop 0
	v_add_f32_e32 v16, v61, v16
	v_add_f32_e32 v17, v17, v30
	v_fma_mix_f32 v18, -v33, v18, v18 op_sel:[1,0,0] op_sel_hi:[1,0,0]
	s_nop 0
	v_add_f32_dpp v16, v16, v16 quad_perm:[1,0,3,2] row_mask:0xf bank_mask:0xf bound_ctrl:1
	v_add_f32_dpp v17, v17, v17 quad_perm:[1,0,3,2] row_mask:0xf bank_mask:0xf bound_ctrl:1
	s_waitcnt lgkmcnt(3)
	v_fma_mix_f32 v18, v37, v29, v18 op_sel:[1,0,0] op_sel_hi:[1,0,0]
	v_add_f32_dpp v16, v16, v16 quad_perm:[2,3,0,1] row_mask:0xf bank_mask:0xf bound_ctrl:1
	v_add_f32_dpp v17, v17, v17 quad_perm:[2,3,0,1] row_mask:0xf bank_mask:0xf bound_ctrl:1
	s_nop 0
	v_add_f32_dpp v61, v16, v16 row_ror:4 row_mask:0xf bank_mask:0xf bound_ctrl:1
	v_add_f32_dpp v17, v17, v17 row_ror:4 row_mask:0xf bank_mask:0xf bound_ctrl:1
	s_nop 0
	v_mov_b32_dpp v62, v61 row_ror:8 row_mask:0xf bank_mask:0xf bound_ctrl:1
	v_add_f32_dpp v16, v17, v17 row_ror:8 row_mask:0xf bank_mask:0xf bound_ctrl:1
	v_fma_mix_f32 v17, v36, v29, v19 op_sel_hi:[1,0,0]
	v_fma_mix_f32 v19, v36, v29, v28 op_sel:[1,0,0] op_sel_hi:[1,0,0]
	v_fma_mix_f32 v17, v34, -v16, v17 op_sel_hi:[1,0,0]
	v_fma_mix_f32 v19, v34, -v16, v19 op_sel:[1,0,0] op_sel_hi:[1,0,0]
	v_fma_mix_f32 v28, v37, v29, v31 op_sel_hi:[1,0,0]
	s_waitcnt lgkmcnt(2)
	v_fma_mix_f32 v39, v22, v17, v2 op_sel_hi:[1,0,0]
	v_fma_mix_f32 v22, v22, v19, v2 op_sel:[1,0,0] op_sel_hi:[1,0,0]
	v_fma_mix_f32 v36, v35, -v16, v28 op_sel_hi:[1,0,0]
	v_fma_mix_f32 v16, v35, -v16, v18 op_sel:[1,0,0] op_sel_hi:[1,0,0]
	ds_read2_b64 v[28:31], v38 offset0:192 offset1:208
	ds_read2_b64 v[32:35], v38 offset0:224 offset1:240
	v_fma_mix_f32 v22, v23, v16, v22 op_sel:[1,0,0] op_sel_hi:[1,0,0]
	v_fma_mix_f32 v39, v23, v36, v39 op_sel_hi:[1,0,0]
	v_fma_mix_f32 v38, v64, v19, v2 op_sel:[1,0,0] op_sel_hi:[1,0,0]
	v_add_f32_e32 v22, v39, v22
	v_fma_mix_f32 v37, v64, v17, v2 op_sel_hi:[1,0,0]
	v_fma_mix_f32 v38, v65, v16, v38 op_sel:[1,0,0] op_sel_hi:[1,0,0]
	s_waitcnt lgkmcnt(3)
	v_fma_mix_f32 v17, -v24, v17, v17 op_sel_hi:[1,0,0]
	v_fma_mix_f32 v19, -v24, v19, v19 op_sel:[1,0,0] op_sel_hi:[1,0,0]
	v_fma_mix_f32 v23, -v25, v36, v36 op_sel_hi:[1,0,0]
	s_nop 0
	v_add_f32_dpp v22, v22, v22 quad_perm:[1,0,3,2] row_mask:0xf bank_mask:0xf bound_ctrl:1
	v_fma_mix_f32 v16, -v25, v16, v16 op_sel:[1,0,0] op_sel_hi:[1,0,0]
	v_fma_mix_f32 v37, v65, v36, v37 op_sel_hi:[1,0,0]
	s_waitcnt lgkmcnt(2)
	v_fma_mix_f32 v17, v66, v70, v17 op_sel_hi:[1,1,0]
	v_fma_mix_f32 v19, v66, v70, v19 op_sel:[1,0,0] op_sel_hi:[1,1,0]
	v_fma_mix_f32 v23, v67, v70, v23 op_sel_hi:[1,1,0]
	s_nop 0
	v_add_f32_dpp v22, v22, v22 quad_perm:[2,3,0,1] row_mask:0xf bank_mask:0xf bound_ctrl:1
	v_fma_mix_f32 v16, v67, v70, v16 op_sel:[1,0,0] op_sel_hi:[1,1,0]
	v_add_f32_e32 v24, v37, v38
	v_cvt_f32_f16_e32 v67, v71
	v_add_f32_dpp v22, v22, v22 row_ror:4 row_mask:0xf bank_mask:0xf bound_ctrl:1
	v_add_f32_dpp v24, v24, v24 quad_perm:[1,0,3,2] row_mask:0xf bank_mask:0xf bound_ctrl:1
	s_nop 0
	v_add_f32_dpp v22, v22, v22 row_ror:8 row_mask:0xf bank_mask:0xf bound_ctrl:1
	v_fma_mix_f32 v65, v26, -v22, v17 op_sel_hi:[1,0,0]
	v_fma_mix_f32 v26, v26, -v22, v19 op_sel:[1,0,0] op_sel_hi:[1,0,0]
	v_fma_mix_f32 v66, v27, -v22, v23 op_sel_hi:[1,0,0]
	v_fma_mix_f32 v27, v27, -v22, v16 op_sel:[1,0,0] op_sel_hi:[1,0,0]
	v_add_f32_dpp v24, v24, v24 quad_perm:[2,3,0,1] row_mask:0xf bank_mask:0xf bound_ctrl:1
	v_fma_mix_f32 v70, v20, v65, v2 op_sel_hi:[1,0,0]
	v_fma_mix_f32 v20, v20, v26, v2 op_sel:[1,0,0] op_sel_hi:[1,0,0]
	s_waitcnt lgkmcnt(1)
; __device__ __forceinline__ bf16_t f2bf(float f) { return (bf16_t)(pk2(f, 0.f) & 0xffffu); }
; __device__ __forceinline__ float fmix_lo(unsigned h2, float b, float c) { float d; asm("v_fma_mix_f32 %0, %1, %2, %3 op_sel_hi:[1,0,0]" : "=v"(d) : "v"(h2), "v"(b), "v"(c)); return d; }
; __device__ __forceinline__ float fmix_hi(unsigned h2, float b, float c) { float d; asm("v_fma_mix_f32 %0, %1, %2, %3 op_sel:[1,0,0] op_sel_hi:[1,0,0]" : "=v"(d) : "v"(h2), "v"(b), "v"(c)); return d; }
; __device__ __forceinline__ float fmixn_lo(unsigned h2, float b, float c) { float d; asm("v_fma_mix_f32 %0, -%1, %2, %3 op_sel_hi:[1,0,0]" : "=v"(d) : "v"(h2), "v"(b), "v"(c)); return d; }
; __device__ __forceinline__ float fmixn_hi(unsigned h2, float b, float c) { float d; asm("v_fma_mix_f32 %0, -%1, %2, %3 op_sel:[1,0,0] op_sel_hi:[1,0,0]" : "=v"(d) : "v"(h2), "v"(b), "v"(c)); return d; }
; template <int ROLE>
; __device__ __forceinline__ void scan_role(const ScanCtx& cx, KPR p) {
;     ...
;       for (int s16 = 0; s16 < 16; ++s16) { const int st = hb + s16; const RIn x = nx; if (st + 1 < SC_CH) nx = lds_ld(st + 1);
;         const float vv = (float)x.v;
;         float ya = fmix_lo(rprev.x, s[0], 0.f), yb = fmix_hi(rprev.x, s[1], 0.f);
;         float sa = fmix_lo(x.kk.x, s[0], 0.f), sb = fmix_hi(x.kk.x, s[1], 0.f);
;         ya = fmix_lo(rprev.y, s[2], ya); yb = fmix_hi(rprev.y, s[3], yb);
;         sa = fmix_lo(x.kk.y, s[2], sa); sb = fmix_hi(x.kk.y, s[3], sb);
;         float t0_ = fmixn_lo(x.u.x, s[0], s[0]), t1_ = fmixn_hi(x.u.x, s[1], s[1]), t2_ = fmixn_lo(x.u.y, s[2], s[2]), t3_ = fmixn_hi(x.u.y, s[3], s[3]);
;         float yy = ya + yb, ss = sa + sb;
;         rowsum16x2(ss, yy);
;         t0_ = fmix_lo(x.km.x, vv, t0_); t1_ = fmix_hi(x.km.x, vv, t1_); t2_ = fmix_lo(x.km.y, vv, t2_); t3_ = fmix_hi(x.km.y, vv, t3_);
;         const float nsa = -ss;
;         s[0] = fmix_lo(x.b.x, nsa, t0_); s[1] = fmix_hi(x.b.x, nsa, t1_); s[2] = fmix_lo(x.b.y, nsa, t2_); s[3] = fmix_hi(x.b.y, nsa, t3_);
;         rprev = x.r;
;         if (s16 == 0) { if (t0 + hb > 0) YO[(size_t)(cx.br * TPB + seq_pos(t0 + hb - 16 + ks, cx.dr)) * NNGP] = f2bf(ks == 15 ? yy : keep); }
;         else keep = ((s16 - 1) == ks) ? yy : keep; }
	v_fma_mix_f32 v71, v28, v65, v2 op_sel_hi:[1,0,0]
	v_fma_mix_f32 v28, v28, v26, v2 op_sel:[1,0,0] op_sel_hi:[1,0,0]
	v_fma_mix_f32 v26, -v30, v26, v26 op_sel:[1,0,0] op_sel_hi:[1,0,0]
	s_nop 0
	v_add_f32_dpp v63, v24, v24 row_ror:4 row_mask:0xf bank_mask:0xf bound_ctrl:1
	v_fma_mix_f32 v70, v21, v66, v70 op_sel_hi:[1,0,0]
	v_fma_mix_f32 v20, v21, v27, v20 op_sel:[1,0,0] op_sel_hi:[1,0,0]
	v_fma_mix_f32 v21, v29, v66, v71 op_sel_hi:[1,0,0]
	v_fma_mix_f32 v28, v29, v27, v28 op_sel:[1,0,0] op_sel_hi:[1,0,0]
	ds_read2_b64 v[36:39], v76 offset1:32
	ds_read2_b64 v[22:25], v76 offset0:48 offset1:64
	ds_read2_b64 v[16:19], v76 offset0:80 offset1:96
	v_add_f32_e32 v21, v21, v28
	v_add_f32_e32 v20, v70, v20
	v_fma_mix_f32 v29, -v30, v65, v65 op_sel_hi:[1,0,0]
	v_fma_mix_f32 v30, -v31, v66, v66 op_sel_hi:[1,0,0]
	s_waitcnt lgkmcnt(3)
	v_fma_mix_f32 v26, v34, v67, v26 op_sel:[1,0,0] op_sel_hi:[1,0,0]
	v_fma_mix_f32 v27, -v31, v27, v27 op_sel:[1,0,0] op_sel_hi:[1,0,0]
	v_add_f32_dpp v21, v21, v21 quad_perm:[1,0,3,2] row_mask:0xf bank_mask:0xf bound_ctrl:1
	v_add_f32_dpp v20, v20, v20 quad_perm:[1,0,3,2] row_mask:0xf bank_mask:0xf bound_ctrl:1
	v_fma_mix_f32 v28, v35, v67, v30 op_sel_hi:[1,0,0]
	v_fma_mix_f32 v27, v35, v67, v27 op_sel:[1,0,0] op_sel_hi:[1,0,0]
	v_mov_b32_dpp v64, v63 row_ror:8 row_mask:0xf bank_mask:0xf bound_ctrl:1
	v_add_f32_dpp v21, v21, v21 quad_perm:[2,3,0,1] row_mask:0xf bank_mask:0xf bound_ctrl:1
	v_add_f32_dpp v20, v20, v20 quad_perm:[2,3,0,1] row_mask:0xf bank_mask:0xf bound_ctrl:1
	s_nop 0
	v_add_f32_dpp v21, v21, v21 row_ror:4 row_mask:0xf bank_mask:0xf bound_ctrl:1
	v_add_f32_dpp v65, v20, v20 row_ror:4 row_mask:0xf bank_mask:0xf bound_ctrl:1
	s_nop 0
	v_add_f32_dpp v20, v21, v21 row_ror:8 row_mask:0xf bank_mask:0xf bound_ctrl:1
	v_fma_mix_f32 v21, v34, v67, v29 op_sel_hi:[1,0,0]
	v_fma_mix_f32 v21, v32, -v20, v21 op_sel_hi:[1,0,0]
	v_fma_mix_f32 v26, v32, -v20, v26 op_sel:[1,0,0] op_sel_hi:[1,0,0]
	v_fma_mix_f32 v28, v33, -v20, v28 op_sel_hi:[1,0,0]
	v_fma_mix_f32 v20, v33, -v20, v27 op_sel:[1,0,0] op_sel_hi:[1,0,0]
	ds_read2_b64 v[32:35], v76 offset0:128 offset1:144
	ds_read2_b64 v[70:73], v76 offset0:160 offset1:176
	v_fma_mix_f32 v29, v68, v21, v2 op_sel_hi:[1,0,0]
	s_waitcnt lgkmcnt(4)
	v_fma_mix_f32 v31, v38, v21, v2 op_sel_hi:[1,0,0]
	v_fma_mix_f32 v38, v38, v26, v2 op_sel:[1,0,0] op_sel_hi:[1,0,0]
	v_fma_mix_f32 v30, v68, v26, v2 op_sel:[1,0,0] op_sel_hi:[1,0,0]
	s_waitcnt lgkmcnt(3)
	v_fma_mix_f32 v21, -v22, v21, v21 op_sel_hi:[1,0,0]
	v_fma_mix_f32 v22, -v22, v26, v26 op_sel:[1,0,0] op_sel_hi:[1,0,0]
	v_fma_mix_f32 v29, v69, v28, v29 op_sel_hi:[1,0,0]
	v_fma_mix_f32 v31, v39, v28, v31 op_sel_hi:[1,0,0]
	v_fma_mix_f32 v38, v39, v20, v38 op_sel:[1,0,0] op_sel_hi:[1,0,0]
	v_fma_mix_f32 v26, -v23, v28, v28 op_sel_hi:[1,0,0]
	v_fma_mix_f32 v30, v69, v20, v30 op_sel:[1,0,0] op_sel_hi:[1,0,0]
	v_fma_mix_f32 v20, -v23, v20, v20 op_sel:[1,0,0] op_sel_hi:[1,0,0]
	v_add_f32_e32 v28, v31, v38
	v_add_f32_e32 v23, v29, v30
	s_waitcnt lgkmcnt(2)
	v_fma_mix_f32 v21, v16, v74, v21 op_sel_hi:[1,1,0]
	v_fma_mix_f32 v16, v16, v74, v22 op_sel:[1,0,0] op_sel_hi:[1,1,0]
	v_fma_mix_f32 v22, v17, v74, v26 op_sel_hi:[1,1,0]
	v_fma_mix_f32 v17, v17, v74, v20 op_sel:[1,0,0] op_sel_hi:[1,1,0]
	v_add_f32_dpp v28, v28, v28 quad_perm:[1,0,3,2] row_mask:0xf bank_mask:0xf bound_ctrl:1
	v_add_f32_dpp v23, v23, v23 quad_perm:[1,0,3,2] row_mask:0xf bank_mask:0xf bound_ctrl:1
	v_cvt_f32_f16_e32 v74, v75
	v_add_f32_dpp v28, v28, v28 quad_perm:[2,3,0,1] row_mask:0xf bank_mask:0xf bound_ctrl:1
	v_add_f32_dpp v23, v23, v23 quad_perm:[2,3,0,1] row_mask:0xf bank_mask:0xf bound_ctrl:1
	v_add_u32_e32 v69, 0x5000, v54
	v_add_f32_dpp v28, v28, v28 row_ror:4 row_mask:0xf bank_mask:0xf bound_ctrl:1
	v_add_f32_dpp v67, v23, v23 row_ror:4 row_mask:0xf bank_mask:0xf bound_ctrl:1
	v_mov_b32_dpp v66, v65 row_ror:8 row_mask:0xf bank_mask:0xf bound_ctrl:1
	v_add_f32_dpp v23, v28, v28 row_ror:8 row_mask:0xf bank_mask:0xf bound_ctrl:1
	v_fma_mix_f32 v38, v24, -v23, v21 op_sel_hi:[1,0,0]
	v_fma_mix_f32 v16, v24, -v23, v16 op_sel:[1,0,0] op_sel_hi:[1,0,0]
	v_fma_mix_f32 v39, v25, -v23, v22 op_sel_hi:[1,0,0]
	v_fma_mix_f32 v17, v25, -v23, v17 op_sel:[1,0,0] op_sel_hi:[1,0,0]
	ds_read2_b64 v[24:27], v76 offset0:192 offset1:224
	v_fma_mix_f32 v75, v36, v38, v2 op_sel_hi:[1,0,0]
	v_fma_mix_f32 v36, v36, v16, v2 op_sel:[1,0,0] op_sel_hi:[1,0,0]
	s_waitcnt lgkmcnt(2)
	v_fma_mix_f32 v76, v32, v38, v2 op_sel_hi:[1,0,0]
	v_fma_mix_f32 v32, v32, v16, v2 op_sel:[1,0,0] op_sel_hi:[1,0,0]
	v_add_u32_e32 v20, 0x4c00, v54
	v_fma_mix_f32 v75, v37, v39, v75 op_sel_hi:[1,0,0]
	v_fma_mix_f32 v36, v37, v17, v36 op_sel:[1,0,0] op_sel_hi:[1,0,0]
	v_fma_mix_f32 v37, v33, v39, v76 op_sel_hi:[1,0,0]
	v_fma_mix_f32 v32, v33, v17, v32 op_sel:[1,0,0] op_sel_hi:[1,0,0]
	v_fma_mix_f32 v33, -v34, v38, v38 op_sel_hi:[1,0,0]
	v_fma_mix_f32 v38, -v35, v39, v39 op_sel_hi:[1,0,0]
	v_fma_mix_f32 v35, -v35, v17, v17 op_sel:[1,0,0] op_sel_hi:[1,0,0]
	v_fma_mix_f32 v34, -v34, v16, v16 op_sel:[1,0,0] op_sel_hi:[1,0,0]
	s_nop 0
	v_add_f32_e32 v16, v75, v36
	v_add_f32_e32 v17, v37, v32
	s_waitcnt lgkmcnt(1)
; __device__ __forceinline__ bf16_t f2bf(float f) { return (bf16_t)(pk2(f, 0.f) & 0xffffu); }
; __device__ __forceinline__ float fmix_lo(unsigned h2, float b, float c) { float d; asm("v_fma_mix_f32 %0, %1, %2, %3 op_sel_hi:[1,0,0]" : "=v"(d) : "v"(h2), "v"(b), "v"(c)); return d; }
; __device__ __forceinline__ float fmix_hi(unsigned h2, float b, float c) { float d; asm("v_fma_mix_f32 %0, %1, %2, %3 op_sel:[1,0,0] op_sel_hi:[1,0,0]" : "=v"(d) : "v"(h2), "v"(b), "v"(c)); return d; }
; __device__ __forceinline__ float fmixn_lo(unsigned h2, float b, float c) { float d; asm("v_fma_mix_f32 %0, -%1, %2, %3 op_sel_hi:[1,0,0]" : "=v"(d) : "v"(h2), "v"(b), "v"(c)); return d; }
; __device__ __forceinline__ float fmixn_hi(unsigned h2, float b, float c) { float d; asm("v_fma_mix_f32 %0, -%1, %2, %3 op_sel:[1,0,0] op_sel_hi:[1,0,0]" : "=v"(d) : "v"(h2), "v"(b), "v"(c)); return d; }
; template <int ROLE>
; __device__ __forceinline__ void scan_role(const ScanCtx& cx, KPR p) {
;     ...
;       for (int s16 = 0; s16 < 16; ++s16) { const int st = hb + s16; const RIn x = nx; if (st + 1 < SC_CH) nx = lds_ld(st + 1);
;         const float vv = (float)x.v;
;         float ya = fmix_lo(rprev.x, s[0], 0.f), yb = fmix_hi(rprev.x, s[1], 0.f);
;         float sa = fmix_lo(x.kk.x, s[0], 0.f), sb = fmix_hi(x.kk.x, s[1], 0.f);
;         ya = fmix_lo(rprev.y, s[2], ya); yb = fmix_hi(rprev.y, s[3], yb);
;         sa = fmix_lo(x.kk.y, s[2], sa); sb = fmix_hi(x.kk.y, s[3], sb);
;         float t0_ = fmixn_lo(x.u.x, s[0], s[0]), t1_ = fmixn_hi(x.u.x, s[1], s[1]), t2_ = fmixn_lo(x.u.y, s[2], s[2]), t3_ = fmixn_hi(x.u.y, s[3], s[3]);
;         float yy = ya + yb, ss = sa + sb;
;         rowsum16x2(ss, yy);
;         t0_ = fmix_lo(x.km.x, vv, t0_); t1_ = fmix_hi(x.km.x, vv, t1_); t2_ = fmix_lo(x.km.y, vv, t2_); t3_ = fmix_hi(x.km.y, vv, t3_);
;         const float nsa = -ss;
;         s[0] = fmix_lo(x.b.x, nsa, t0_); s[1] = fmix_hi(x.b.x, nsa, t1_); s[2] = fmix_lo(x.b.y, nsa, t2_); s[3] = fmix_hi(x.b.y, nsa, t3_);
;         rprev = x.r;
;         if (s16 == 0) { if (t0 + hb > 0) YO[(size_t)(cx.br * TPB + seq_pos(t0 + hb - 16 + ks, cx.dr)) * NNGP] = f2bf(ks == 15 ? yy : keep); }
;         else keep = ((s16 - 1) == ks) ? yy : keep; }
	v_fma_mix_f32 v33, v72, v74, v33 op_sel_hi:[1,0,0]
	v_fma_mix_f32 v34, v72, v74, v34 op_sel:[1,0,0] op_sel_hi:[1,0,0]
	v_fma_mix_f32 v36, v73, v74, v38 op_sel_hi:[1,0,0]
	v_fma_mix_f32 v35, v73, v74, v35 op_sel:[1,0,0] op_sel_hi:[1,0,0]
	ds_read2_b64 v[28:31], v20 offset0:112 offset1:128
	v_add_f32_dpp v17, v17, v17 quad_perm:[1,0,3,2] row_mask:0xf bank_mask:0xf bound_ctrl:1
	ds_read2_b64 v[20:23], v69 offset0:16 offset1:32
	v_add_u32_e32 v54, 0x5800, v54
	v_add_f32_dpp v17, v17, v17 quad_perm:[2,3,0,1] row_mask:0xf bank_mask:0xf bound_ctrl:1
	v_add_f32_dpp v16, v16, v16 quad_perm:[1,0,3,2] row_mask:0xf bank_mask:0xf bound_ctrl:1
	v_mov_b32_dpp v68, v67 row_ror:8 row_mask:0xf bank_mask:0xf bound_ctrl:1
	v_add_f32_dpp v17, v17, v17 row_ror:4 row_mask:0xf bank_mask:0xf bound_ctrl:1
	v_add_f32_dpp v16, v16, v16 quad_perm:[2,3,0,1] row_mask:0xf bank_mask:0xf bound_ctrl:1
	s_nop 0
	v_add_f32_dpp v32, v17, v17 row_ror:8 row_mask:0xf bank_mask:0xf bound_ctrl:1
	v_fma_mix_f32 v72, v70, -v32, v33 op_sel_hi:[1,0,0]
	v_fma_mix_f32 v70, v70, -v32, v34 op_sel:[1,0,0] op_sel_hi:[1,0,0]
	v_fma_mix_f32 v73, v71, -v32, v36 op_sel_hi:[1,0,0]
	v_fma_mix_f32 v71, v71, -v32, v35 op_sel:[1,0,0] op_sel_hi:[1,0,0]
	ds_read2_b64 v[36:39], v69 offset0:64 offset1:80
	ds_read2_b64 v[32:35], v69 offset0:96 offset1:112
	ds_read_u16 v74, v55 offset:20096
	ds_read_u16 v78, v55 offset:20864
	ds_read_u16 v79, v55 offset:21632
	ds_read_u16 v80, v55 offset:22400
	ds_read_u16 v82, v55 offset:23168
	ds_read_u16 v55, v55 offset:23936
	v_fma_mix_f32 v75, v18, v72, v2 op_sel_hi:[1,0,0]
	v_fma_mix_f32 v18, v18, v70, v2 op_sel:[1,0,0] op_sel_hi:[1,0,0]
	s_waitcnt lgkmcnt(10)
	v_fma_mix_f32 v76, v26, v72, v2 op_sel_hi:[1,0,0]
	v_fma_mix_f32 v26, v26, v70, v2 op_sel:[1,0,0] op_sel_hi:[1,0,0]
	s_waitcnt lgkmcnt(9)
	v_fma_mix_f32 v72, -v28, v72, v72 op_sel_hi:[1,0,0]
	v_fma_mix_f32 v28, -v28, v70, v70 op_sel:[1,0,0] op_sel_hi:[1,0,0]
	v_fma_mix_f32 v75, v19, v73, v75 op_sel_hi:[1,0,0]
	v_fma_mix_f32 v18, v19, v71, v18 op_sel:[1,0,0] op_sel_hi:[1,0,0]
	v_fma_mix_f32 v19, v27, v73, v76 op_sel_hi:[1,0,0]
	v_fma_mix_f32 v26, v27, v71, v26 op_sel:[1,0,0] op_sel_hi:[1,0,0]
	s_waitcnt lgkmcnt(5)
	v_add_f32_e32 v19, v19, v26
	v_add_f32_e32 v18, v75, v18
	v_fma_mix_f32 v70, -v29, v73, v73 op_sel_hi:[1,0,0]
	v_fma_mix_f32 v29, -v29, v71, v71 op_sel:[1,0,0] op_sel_hi:[1,0,0]
	s_waitcnt lgkmcnt(2)
	v_add_f32_dpp v19, v19, v19 quad_perm:[1,0,3,2] row_mask:0xf bank_mask:0xf bound_ctrl:1
	v_add_f32_dpp v18, v18, v18 quad_perm:[1,0,3,2] row_mask:0xf bank_mask:0xf bound_ctrl:1
	v_add_f32_dpp v16, v16, v16 row_ror:4 row_mask:0xf bank_mask:0xf bound_ctrl:1
	v_add_f32_dpp v19, v19, v19 quad_perm:[2,3,0,1] row_mask:0xf bank_mask:0xf bound_ctrl:1
	v_add_f32_dpp v18, v18, v18 quad_perm:[2,3,0,1] row_mask:0xf bank_mask:0xf bound_ctrl:1
	v_mov_b32_dpp v17, v16 row_ror:8 row_mask:0xf bank_mask:0xf bound_ctrl:1
	v_add_f32_dpp v19, v19, v19 row_ror:4 row_mask:0xf bank_mask:0xf bound_ctrl:1
	v_add_f32_dpp v26, v18, v18 row_ror:4 row_mask:0xf bank_mask:0xf bound_ctrl:1
	s_nop 0
	v_add_f32_dpp v18, v19, v19 row_ror:8 row_mask:0xf bank_mask:0xf bound_ctrl:1
	v_fma_mix_f32 v19, v20, v74, v72 op_sel_hi:[1,1,0]
	v_fma_mix_f32 v20, v20, v74, v28 op_sel:[1,0,0] op_sel_hi:[1,1,0]
	v_fma_mix_f32 v28, v21, v74, v70 op_sel_hi:[1,1,0]
	v_fma_mix_f32 v21, v21, v74, v29 op_sel:[1,0,0] op_sel_hi:[1,1,0]
	v_fma_mix_f32 v29, v30, -v18, v19 op_sel_hi:[1,0,0]
	v_fma_mix_f32 v30, v30, -v18, v20 op_sel:[1,0,0] op_sel_hi:[1,0,0]
	v_fma_mix_f32 v28, v31, -v18, v28 op_sel_hi:[1,0,0]
	v_fma_mix_f32 v31, v31, -v18, v21 op_sel:[1,0,0] op_sel_hi:[1,0,0]
	ds_read2_b64 v[70:73], v69 offset0:128 offset1:160
	ds_read2_b64 v[18:21], v69 offset0:176 offset1:192
	ds_read2_b64 v[74:77], v69 offset0:208 offset1:224
	v_cvt_f32_f16_e32 v69, v78
	v_fma_mix_f32 v78, v24, v29, v2 op_sel_hi:[1,0,0]
	v_fma_mix_f32 v24, v24, v30, v2 op_sel:[1,0,0] op_sel_hi:[1,0,0]
	v_fma_mix_f32 v81, v36, v29, v2 op_sel_hi:[1,0,0]
	v_fma_mix_f32 v36, v36, v30, v2 op_sel:[1,0,0] op_sel_hi:[1,0,0]
	v_fma_mix_f32 v30, -v38, v30, v30 op_sel:[1,0,0] op_sel_hi:[1,0,0]
	v_mov_b32_dpp v27, v26 row_ror:8 row_mask:0xf bank_mask:0xf bound_ctrl:1
	v_fma_mix_f32 v78, v25, v28, v78 op_sel_hi:[1,0,0]
	v_fma_mix_f32 v24, v25, v31, v24 op_sel:[1,0,0] op_sel_hi:[1,0,0]
	v_fma_mix_f32 v25, v37, v28, v81 op_sel_hi:[1,0,0]
	v_fma_mix_f32 v36, v37, v31, v36 op_sel:[1,0,0] op_sel_hi:[1,0,0]
	v_fma_mix_f32 v37, -v38, v29, v29 op_sel_hi:[1,0,0]
	v_fma_mix_f32 v38, -v39, v28, v28 op_sel_hi:[1,0,0]
	v_fma_mix_f32 v31, -v39, v31, v31 op_sel:[1,0,0] op_sel_hi:[1,0,0]
	s_nop 0
	v_add_f32_e32 v24, v78, v24
	v_add_f32_e32 v25, v25, v36
	v_fma_mix_f32 v30, v34, v69, v30 op_sel:[1,0,0] op_sel_hi:[1,0,0]
	v_fma_mix_f32 v31, v35, v69, v31 op_sel:[1,0,0] op_sel_hi:[1,0,0]
	v_cvt_f32_f16_e32 v78, v79
	v_add_f32_dpp v24, v24, v24 quad_perm:[1,0,3,2] row_mask:0xf bank_mask:0xf bound_ctrl:1
	v_add_f32_dpp v25, v25, v25 quad_perm:[1,0,3,2] row_mask:0xf bank_mask:0xf bound_ctrl:1
	s_nop 0
	v_add_f32_dpp v24, v24, v24 quad_perm:[2,3,0,1] row_mask:0xf bank_mask:0xf bound_ctrl:1
	v_add_f32_dpp v25, v25, v25 quad_perm:[2,3,0,1] row_mask:0xf bank_mask:0xf bound_ctrl:1
	s_nop 0
	v_add_f32_dpp v28, v24, v24 row_ror:4 row_mask:0xf bank_mask:0xf bound_ctrl:1
	v_add_f32_dpp v25, v25, v25 row_ror:4 row_mask:0xf bank_mask:0xf bound_ctrl:1
	s_nop 0
	v_mov_b32_dpp v29, v28 row_ror:8 row_mask:0xf bank_mask:0xf bound_ctrl:1
	v_add_f32_dpp v24, v25, v25 row_ror:8 row_mask:0xf bank_mask:0xf bound_ctrl:1
	v_fma_mix_f32 v25, v34, v69, v37 op_sel_hi:[1,0,0]
	v_fma_mix_f32 v34, v35, v69, v38 op_sel_hi:[1,0,0]
	v_fma_mix_f32 v25, v32, -v24, v25 op_sel_hi:[1,0,0]
	v_fma_mix_f32 v30, v32, -v24, v30 op_sel:[1,0,0] op_sel_hi:[1,0,0]
	s_nop 0
	v_fma_mix_f32 v69, v33, -v24, v34 op_sel_hi:[1,0,0]
	v_fma_mix_f32 v24, v33, -v24, v31 op_sel:[1,0,0] op_sel_hi:[1,0,0]
	v_fma_mix_f32 v31, v22, v25, v2 op_sel_hi:[1,0,0]
	v_fma_mix_f32 v22, v22, v30, v2 op_sel:[1,0,0] op_sel_hi:[1,0,0]
	s_waitcnt lgkmcnt(2)
; __device__ __forceinline__ bf16_t f2bf(float f) { return (bf16_t)(pk2(f, 0.f) & 0xffffu); }
; __device__ __forceinline__ float fmix_lo(unsigned h2, float b, float c) { float d; asm("v_fma_mix_f32 %0, %1, %2, %3 op_sel_hi:[1,0,0]" : "=v"(d) : "v"(h2), "v"(b), "v"(c)); return d; }
; __device__ __forceinline__ float fmix_hi(unsigned h2, float b, float c) { float d; asm("v_fma_mix_f32 %0, %1, %2, %3 op_sel:[1,0,0] op_sel_hi:[1,0,0]" : "=v"(d) : "v"(h2), "v"(b), "v"(c)); return d; }
; __device__ __forceinline__ float fmixn_lo(unsigned h2, float b, float c) { float d; asm("v_fma_mix_f32 %0, -%1, %2, %3 op_sel_hi:[1,0,0]" : "=v"(d) : "v"(h2), "v"(b), "v"(c)); return d; }
; __device__ __forceinline__ float fmixn_hi(unsigned h2, float b, float c) { float d; asm("v_fma_mix_f32 %0, -%1, %2, %3 op_sel:[1,0,0] op_sel_hi:[1,0,0]" : "=v"(d) : "v"(h2), "v"(b), "v"(c)); return d; }
; __device__ __forceinline__ void lds_barrier() { asm volatile("s_waitcnt lgkmcnt(0)" ::: "memory"); __builtin_amdgcn_s_barrier(); asm volatile("" ::: "memory"); }
; template <int ROLE>
; __device__ __forceinline__ void scan_role(const ScanCtx& cx, KPR p) {
;     ...
;       for (int s16 = 0; s16 < 16; ++s16) { const int st = hb + s16; const RIn x = nx; if (st + 1 < SC_CH) nx = lds_ld(st + 1);
;         const float vv = (float)x.v;
;         float ya = fmix_lo(rprev.x, s[0], 0.f), yb = fmix_hi(rprev.x, s[1], 0.f);
;         float sa = fmix_lo(x.kk.x, s[0], 0.f), sb = fmix_hi(x.kk.x, s[1], 0.f);
;         ya = fmix_lo(rprev.y, s[2], ya); yb = fmix_hi(rprev.y, s[3], yb);
;         sa = fmix_lo(x.kk.y, s[2], sa); sb = fmix_hi(x.kk.y, s[3], sb);
;         float t0_ = fmixn_lo(x.u.x, s[0], s[0]), t1_ = fmixn_hi(x.u.x, s[1], s[1]), t2_ = fmixn_lo(x.u.y, s[2], s[2]), t3_ = fmixn_hi(x.u.y, s[3], s[3]);
;         float yy = ya + yb, ss = sa + sb;
;         rowsum16x2(ss, yy);
;         t0_ = fmix_lo(x.km.x, vv, t0_); t1_ = fmix_hi(x.km.x, vv, t1_); t2_ = fmix_lo(x.km.y, vv, t2_); t3_ = fmix_hi(x.km.y, vv, t3_);
;         const float nsa = -ss;
;         s[0] = fmix_lo(x.b.x, nsa, t0_); s[1] = fmix_hi(x.b.x, nsa, t1_); s[2] = fmix_lo(x.b.y, nsa, t2_); s[3] = fmix_hi(x.b.y, nsa, t3_);
;         rprev = x.r;
;         if (s16 == 0) { if (t0 + hb > 0) YO[(size_t)(cx.br * TPB + seq_pos(t0 + hb - 16 + ks, cx.dr)) * NNGP] = f2bf(ks == 15 ? yy : keep); }
;         else keep = ((s16 - 1) == ks) ? yy : keep; }
	v_fma_mix_f32 v79, v72, v25, v2 op_sel_hi:[1,0,0]
	v_fma_mix_f32 v72, v72, v30, v2 op_sel:[1,0,0] op_sel_hi:[1,0,0]
	ds_read2_b64 v[32:35], v54 offset1:16
	ds_read2_b64 v[36:39], v54 offset0:32 offset1:48
	v_fma_mix_f32 v31, v23, v69, v31 op_sel_hi:[1,0,0]
	v_fma_mix_f32 v22, v23, v24, v22 op_sel:[1,0,0] op_sel_hi:[1,0,0]
	v_fma_mix_f32 v23, v73, v69, v79 op_sel_hi:[1,0,0]
	v_fma_mix_f32 v72, v73, v24, v72 op_sel:[1,0,0] op_sel_hi:[1,0,0]
	s_waitcnt lgkmcnt(3)
	v_fma_mix_f32 v25, -v18, v25, v25 op_sel_hi:[1,0,0]
	v_fma_mix_f32 v18, -v18, v30, v30 op_sel:[1,0,0] op_sel_hi:[1,0,0]
	v_fma_mix_f32 v69, -v19, v69, v69 op_sel_hi:[1,0,0]
	v_add_f32_e32 v22, v31, v22
	v_add_f32_e32 v23, v23, v72
	v_fma_mix_f32 v19, -v19, v24, v24 op_sel:[1,0,0] op_sel_hi:[1,0,0]
	s_waitcnt lgkmcnt(2)
	v_fma_mix_f32 v18, v74, v78, v18 op_sel:[1,0,0] op_sel_hi:[1,0,0]
	v_fma_mix_f32 v24, v75, v78, v69 op_sel_hi:[1,0,0]
	v_add_f32_dpp v22, v22, v22 quad_perm:[1,0,3,2] row_mask:0xf bank_mask:0xf bound_ctrl:1
	v_add_f32_dpp v23, v23, v23 quad_perm:[1,0,3,2] row_mask:0xf bank_mask:0xf bound_ctrl:1
	v_fma_mix_f32 v19, v75, v78, v19 op_sel:[1,0,0] op_sel_hi:[1,0,0]
	s_nop 0
	v_add_f32_dpp v22, v22, v22 quad_perm:[2,3,0,1] row_mask:0xf bank_mask:0xf bound_ctrl:1
	v_add_f32_dpp v23, v23, v23 quad_perm:[2,3,0,1] row_mask:0xf bank_mask:0xf bound_ctrl:1
	s_nop 0
	v_add_f32_dpp v30, v22, v22 row_ror:4 row_mask:0xf bank_mask:0xf bound_ctrl:1
	v_add_f32_dpp v23, v23, v23 row_ror:4 row_mask:0xf bank_mask:0xf bound_ctrl:1
	s_nop 0
	v_mov_b32_dpp v31, v30 row_ror:8 row_mask:0xf bank_mask:0xf bound_ctrl:1
	v_add_f32_dpp v22, v23, v23 row_ror:8 row_mask:0xf bank_mask:0xf bound_ctrl:1
	v_fma_mix_f32 v23, v74, v78, v25 op_sel_hi:[1,0,0]
	v_fma_mix_f32 v69, v20, -v22, v23 op_sel_hi:[1,0,0]
	v_fma_mix_f32 v78, v20, -v22, v18 op_sel:[1,0,0] op_sel_hi:[1,0,0]
	v_fma_mix_f32 v81, v21, -v22, v19 op_sel:[1,0,0] op_sel_hi:[1,0,0]
	v_fma_mix_f32 v79, v21, -v22, v24 op_sel_hi:[1,0,0]
	ds_read2_b64 v[22:25], v54 offset0:64 offset1:96
	ds_read2_b64 v[72:75], v54 offset0:112 offset1:128
	ds_read2_b64 v[18:21], v54 offset0:144 offset1:160
	s_waitcnt lgkmcnt(4)
	v_fma_mix_f32 v84, v32, v69, v2 op_sel_hi:[1,0,0]
	v_fma_mix_f32 v32, v32, v78, v2 op_sel:[1,0,0] op_sel_hi:[1,0,0]
	v_fma_mix_f32 v83, v70, v69, v2 op_sel_hi:[1,0,0]
	v_fma_mix_f32 v70, v70, v78, v2 op_sel:[1,0,0] op_sel_hi:[1,0,0]
	v_fma_mix_f32 v69, -v34, v69, v69 op_sel_hi:[1,0,0]
	v_fma_mix_f32 v34, -v34, v78, v78 op_sel:[1,0,0] op_sel_hi:[1,0,0]
	v_fma_mix_f32 v78, -v35, v79, v79 op_sel_hi:[1,0,0]
	s_nop 0
	v_fma_mix_f32 v32, v33, v81, v32 op_sel:[1,0,0] op_sel_hi:[1,0,0]
	v_fma_mix_f32 v83, v71, v79, v83 op_sel_hi:[1,0,0]
	v_fma_mix_f32 v70, v71, v81, v70 op_sel:[1,0,0] op_sel_hi:[1,0,0]
	v_fma_mix_f32 v71, v33, v79, v84 op_sel_hi:[1,0,0]
	v_fma_mix_f32 v35, -v35, v81, v81 op_sel:[1,0,0] op_sel_hi:[1,0,0]
	s_waitcnt lgkmcnt(3)
	v_fma_mix_f32 v69, v38, v80, v69 op_sel_hi:[1,1,0]
	v_fma_mix_f32 v34, v38, v80, v34 op_sel:[1,0,0] op_sel_hi:[1,1,0]
	v_fma_mix_f32 v38, v39, v80, v78 op_sel_hi:[1,1,0]
	v_add_f32_e32 v33, v83, v70
	v_add_f32_e32 v32, v71, v32
	v_fma_mix_f32 v35, v39, v80, v35 op_sel:[1,0,0] op_sel_hi:[1,1,0]
	s_nop 0
	v_add_f32_dpp v33, v33, v33 quad_perm:[1,0,3,2] row_mask:0xf bank_mask:0xf bound_ctrl:1
	v_add_f32_dpp v32, v32, v32 quad_perm:[1,0,3,2] row_mask:0xf bank_mask:0xf bound_ctrl:1
	s_nop 0
	v_add_f32_dpp v33, v33, v33 quad_perm:[2,3,0,1] row_mask:0xf bank_mask:0xf bound_ctrl:1
	v_add_f32_dpp v32, v32, v32 quad_perm:[2,3,0,1] row_mask:0xf bank_mask:0xf bound_ctrl:1
	s_nop 1
	v_add_f32_dpp v70, v32, v32 row_ror:4 row_mask:0xf bank_mask:0xf bound_ctrl:1
	v_add_f32_dpp v32, v33, v33 row_ror:4 row_mask:0xf bank_mask:0xf bound_ctrl:1
	s_nop 0
	v_add_f32_dpp v70, v70, v70 row_ror:8 row_mask:0xf bank_mask:0xf bound_ctrl:1
	v_xor_b32_e32 v39, 0x80000000, v70
	v_fma_mix_f32 v69, v36, v39, v69 op_sel_hi:[1,0,0]
	v_fma_mix_f32 v34, v36, v39, v34 op_sel:[1,0,0] op_sel_hi:[1,0,0]
	v_fma_mix_f32 v70, v37, v39, v38 op_sel_hi:[1,0,0]
	v_fma_mix_f32 v35, v37, v39, v35 op_sel:[1,0,0] op_sel_hi:[1,0,0]
	ds_read2_b64 v[36:39], v54 offset0:192 offset1:208
	ds_read2_b64 v[78:81], v54 offset0:224 offset1:240
	v_cvt_f32_f16_e32 v54, v82
	s_waitcnt lgkmcnt(4)
	v_fma_mix_f32 v82, v24, v69, v2 op_sel_hi:[1,0,0]
	v_fma_mix_f32 v24, v24, v34, v2 op_sel:[1,0,0] op_sel_hi:[1,0,0]
	v_fma_mix_f32 v71, v76, v69, v2 op_sel_hi:[1,0,0]
	v_fma_mix_f32 v76, v76, v34, v2 op_sel:[1,0,0] op_sel_hi:[1,0,0]
	s_waitcnt lgkmcnt(0)
	s_barrier
; __device__ __forceinline__ bf16_t f2bf(float f) { return (bf16_t)(pk2(f, 0.f) & 0xffffu); }
; __device__ __forceinline__ void lds_barrier() { asm volatile("s_waitcnt lgkmcnt(0)" ::: "memory"); __builtin_amdgcn_s_barrier(); asm volatile("" ::: "memory"); }
; __device__ __forceinline__ float fmix_lo(unsigned h2, float b, float c) { float d; asm("v_fma_mix_f32 %0, %1, %2, %3 op_sel_hi:[1,0,0]" : "=v"(d) : "v"(h2), "v"(b), "v"(c)); return d; }
; __device__ __forceinline__ float fmix_hi(unsigned h2, float b, float c) { float d; asm("v_fma_mix_f32 %0, %1, %2, %3 op_sel:[1,0,0] op_sel_hi:[1,0,0]" : "=v"(d) : "v"(h2), "v"(b), "v"(c)); return d; }
;   __device__ __forceinline__ void commit(const u32x4 (&stg)[SC_NI], int rwbuf) const {
; #pragma unroll
;     for (int i = 0; i < SC_NI; ++i) *(u32x4*)(smem + rwbuf * SC_RWB + udst[i]) = stg[i]; }
; template <int ROLE>
; __device__ __forceinline__ void scan_role(const ScanCtx& cx, KPR p) {
;     ...
;       for (int s16 = 0; s16 < 16; ++s16) { const int st = hb + s16; const RIn x = nx; if (st + 1 < SC_CH) nx = lds_ld(st + 1);
;         const float vv = (float)x.v;
;         float ya = fmix_lo(rprev.x, s[0], 0.f), yb = fmix_hi(rprev.x, s[1], 0.f);
;         float sa = fmix_lo(x.kk.x, s[0], 0.f), sb = fmix_hi(x.kk.x, s[1], 0.f);
;         ya = fmix_lo(rprev.y, s[2], ya); yb = fmix_hi(rprev.y, s[3], yb);
;         sa = fmix_lo(x.kk.y, s[2], sa); sb = fmix_hi(x.kk.y, s[3], sb);
;         float t0_ = fmixn_lo(x.u.x, s[0], s[0]), t1_ = fmixn_hi(x.u.x, s[1], s[1]), t2_ = fmixn_lo(x.u.y, s[2], s[2]), t3_ = fmixn_hi(x.u.y, s[3], s[3]);
;         float yy = ya + yb, ss = sa + sb;
;         rowsum16x2(ss, yy);
;         t0_ = fmix_lo(x.km.x, vv, t0_); t1_ = fmix_hi(x.km.x, vv, t1_); t2_ = fmix_lo(x.km.y, vv, t2_); t3_ = fmix_hi(x.km.y, vv, t3_);
;         const float nsa = -ss;
;         s[0] = fmix_lo(x.b.x, nsa, t0_); s[1] = fmix_hi(x.b.x, nsa, t1_); s[2] = fmix_lo(x.b.y, nsa, t2_); s[3] = fmix_hi(x.b.y, nsa, t3_);
;         rprev = x.r;
;         if (s16 == 0) { if (t0 + hb > 0) YO[(size_t)(cx.br * TPB + seq_pos(t0 + hb - 16 + ks, cx.dr)) * NNGP] = f2bf(ks == 15 ? yy : keep); }
;         else keep = ((s16 - 1) == ks) ? yy : keep; }
;     ...
;     lds_barrier();
;     if (c + 2 < NCH) cx.commit(stg, c & 1);
	v_fma_mix_f32 v24, v25, v35, v24 op_sel:[1,0,0] op_sel_hi:[1,0,0]
	v_fma_mix_f32 v71, v77, v70, v71 op_sel_hi:[1,0,0]
	v_fma_mix_f32 v76, v77, v35, v76 op_sel:[1,0,0] op_sel_hi:[1,0,0]
	v_fma_mix_f32 v77, v25, v70, v82 op_sel_hi:[1,0,0]
	s_waitcnt lgkmcnt(3)
	v_fma_mix_f32 v25, -v72, v69, v69 op_sel_hi:[1,0,0]
	v_fma_mix_f32 v69, -v72, v34, v34 op_sel:[1,0,0] op_sel_hi:[1,0,0]
	v_fma_mix_f32 v70, -v73, v70, v70 op_sel_hi:[1,0,0]
	v_fma_mix_f32 v72, -v73, v35, v35 op_sel:[1,0,0] op_sel_hi:[1,0,0]
	v_add_f32_e32 v34, v71, v76
	v_add_f32_e32 v24, v77, v24
	s_waitcnt lgkmcnt(2)
	v_fma_mix_f32 v25, v18, v54, v25 op_sel_hi:[1,0,0]
	v_fma_mix_f32 v18, v18, v54, v69 op_sel:[1,0,0] op_sel_hi:[1,0,0]
	v_fma_mix_f32 v69, v19, v54, v70 op_sel_hi:[1,0,0]
	v_fma_mix_f32 v19, v19, v54, v72 op_sel:[1,0,0] op_sel_hi:[1,0,0]
	v_add_f32_dpp v34, v34, v34 quad_perm:[1,0,3,2] row_mask:0xf bank_mask:0xf bound_ctrl:1
	v_add_f32_dpp v24, v24, v24 quad_perm:[1,0,3,2] row_mask:0xf bank_mask:0xf bound_ctrl:1
	v_mov_b32_dpp v33, v32 row_ror:8 row_mask:0xf bank_mask:0xf bound_ctrl:1
	v_add_f32_dpp v34, v34, v34 quad_perm:[2,3,0,1] row_mask:0xf bank_mask:0xf bound_ctrl:1
	v_add_f32_dpp v24, v24, v24 quad_perm:[2,3,0,1] row_mask:0xf bank_mask:0xf bound_ctrl:1
	s_nop 0
	v_add_f32_dpp v34, v34, v34 row_ror:4 row_mask:0xf bank_mask:0xf bound_ctrl:1
	v_add_f32_dpp v24, v24, v24 row_ror:4 row_mask:0xf bank_mask:0xf bound_ctrl:1
	s_nop 0
	v_mov_b32_dpp v35, v34 row_ror:8 row_mask:0xf bank_mask:0xf bound_ctrl:1
	v_add_f32_dpp v24, v24, v24 row_ror:8 row_mask:0xf bank_mask:0xf bound_ctrl:1
	v_fma_mix_f32 v25, v74, -v24, v25 op_sel_hi:[1,0,0]
	v_fma_mix_f32 v18, v74, -v24, v18 op_sel:[1,0,0] op_sel_hi:[1,0,0]
	v_fma_mix_f32 v54, v75, -v24, v69 op_sel_hi:[1,0,0]
	v_fma_mix_f32 v19, v75, -v24, v19 op_sel:[1,0,0] op_sel_hi:[1,0,0]
	v_cvt_f32_f16_e32 v24, v55
	v_fma_mix_f32 v55, v22, v25, v2 op_sel_hi:[1,0,0]
	v_fma_mix_f32 v22, v22, v18, v2 op_sel:[1,0,0] op_sel_hi:[1,0,0]
	s_waitcnt lgkmcnt(1)
	v_fma_mix_f32 v69, v36, v25, v2 op_sel_hi:[1,0,0]
	v_fma_mix_f32 v36, v36, v18, v2 op_sel:[1,0,0] op_sel_hi:[1,0,0]
	v_fma_mix_f32 v25, -v38, v25, v25 op_sel_hi:[1,0,0]
	v_fma_mix_f32 v55, v23, v54, v55 op_sel_hi:[1,0,0]
	v_fma_mix_f32 v22, v23, v19, v22 op_sel:[1,0,0] op_sel_hi:[1,0,0]
	s_nop 0
	v_fma_mix_f32 v23, v37, v54, v69 op_sel_hi:[1,0,0]
	v_fma_mix_f32 v36, v37, v19, v36 op_sel:[1,0,0] op_sel_hi:[1,0,0]
	v_fma_mix_f32 v37, -v38, v18, v18 op_sel:[1,0,0] op_sel_hi:[1,0,0]
	v_fma_mix_f32 v38, -v39, v54, v54 op_sel_hi:[1,0,0]
	v_fma_mix_f32 v39, -v39, v19, v19 op_sel:[1,0,0] op_sel_hi:[1,0,0]
	v_add_f32_e32 v18, v55, v22
	v_add_f32_e32 v19, v23, v36
	s_waitcnt lgkmcnt(0)
	v_fma_mix_f32 v23, v80, v24, v25 op_sel_hi:[1,0,0]
	v_fma_mix_f32 v25, v80, v24, v37 op_sel:[1,0,0] op_sel_hi:[1,0,0]
	v_fma_mix_f32 v36, v81, v24, v38 op_sel_hi:[1,0,0]
	v_fma_mix_f32 v37, v81, v24, v39 op_sel:[1,0,0] op_sel_hi:[1,0,0]
	v_add_f32_dpp v18, v18, v18 quad_perm:[1,0,3,2] row_mask:0xf bank_mask:0xf bound_ctrl:1
	v_add_f32_dpp v19, v19, v19 quad_perm:[1,0,3,2] row_mask:0xf bank_mask:0xf bound_ctrl:1
	s_nop 0
	v_add_f32_dpp v18, v18, v18 quad_perm:[2,3,0,1] row_mask:0xf bank_mask:0xf bound_ctrl:1
	v_add_f32_dpp v19, v19, v19 quad_perm:[2,3,0,1] row_mask:0xf bank_mask:0xf bound_ctrl:1
	s_nop 0
	v_add_f32_dpp v18, v18, v18 row_ror:4 row_mask:0xf bank_mask:0xf bound_ctrl:1
	v_add_f32_dpp v19, v19, v19 row_ror:4 row_mask:0xf bank_mask:0xf bound_ctrl:1
	s_nop 1
	v_add_f32_dpp v22, v19, v19 row_ror:8 row_mask:0xf bank_mask:0xf bound_ctrl:1
	v_mov_b32_dpp v19, v18 row_ror:8 row_mask:0xf bank_mask:0xf bound_ctrl:1
	v_xor_b32_e32 v38, 0x80000000, v22
	v_fma_mix_f32 v22, v78, v38, v23 op_sel_hi:[1,0,0]
	v_fma_mix_f32 v25, v78, v38, v25 op_sel:[1,0,0] op_sel_hi:[1,0,0]
	v_fma_mix_f32 v24, v79, v38, v36 op_sel_hi:[1,0,0]
	v_fma_mix_f32 v23, v79, v38, v37 op_sel:[1,0,0] op_sel_hi:[1,0,0]
	s_cbranch_vccnz .LBB0_682
	v_add_u32_e32 v36, s56, v127
	v_add_u32_e32 v37, s56, v126
	v_add_u32_e32 v38, s56, v128
	s_waitcnt vmcnt(3)
	ds_write_b128 v36, v[4:7]
	s_waitcnt vmcnt(2)
	ds_write_b128 v37, v[8:11]
	s_waitcnt vmcnt(1)
	ds_write_b128 v38, v[12:15]
	s_branch .LBB0_682
